# one static priority raise (s_setprio 1) for waves 4-7 across the GEMM phases, hipcc's per-phase setprio flips replaced by s_nop 0
# baseline (speedup 1.0000x reference)
.LBB0_116:
	s_or_b64 exec, exec, s[4:5]
	s_mov_b64 s[0:1], s[86:87]
	s_waitcnt lgkmcnt(0)
	s_barrier
	v_readfirstlane_b32 s101, v204
	s_nop 3
	s_lshr_b32 s101, s101, 6
	s_cmp_ge_u32 s101, 4
	s_cbranch_scc0 .Lprio_0
	s_setprio 1
.Lprio_0:
	s_load_dwordx4 s[24:27], s[0:1], 0x8
	s_load_dwordx8 s[12:19], s[0:1], 0x20
	s_load_dwordx2 s[28:29], s[0:1], 0x88
	s_load_dwordx2 s[10:11], s[0:1], 0xb8
	s_bitcmp1_b32 s97, 0
	s_cselect_b64 s[30:31], -1, 0
	s_and_b64 vcc, exec, s[30:31]
	s_cbranch_vccnz .LBB0_152
	s_waitcnt lgkmcnt(0)
	v_lshrrev_b32_e32 v0, 3, v204
	v_and_b32_e32 v1, 7, v204
	v_lshlrev_b32_e32 v1, 3, v1
	v_mul_u32_u24_e32 v2, 65, v0
	v_add_lshl_u32 v2, v2, v1, 2
	v_mul_u32_u24_e32 v4, 65, v1
	v_add_lshl_u32 v4, v4, v0, 2
	s_add_u32 s39, s97, 896
	s_mov_b32 s33, s39
	s_lshl_b32 s68, s22, 1
	s_mul_i32 s69, s22, 3
	s_lshl_b32 s21, s22, 2
	s_add_u32 s35, s33, 0
	s_cmp_lt_u32 s35, 4032
	s_cselect_b32 s35, s35, s39
	s_cmp_lt_u32 s35, 1152
	s_cbranch_scc0 .Lcv_a_p0_m1
	s_mov_b64 s[64:65], s[18:19]
	s_mov_b32 s5, 1024
	s_mov_b32 s6, 0x10000000
	s_mov_b32 s7, 16
	s_movk_i32 s8, 896
	s_add_u32 s66, s10, 0x700000
	s_addc_u32 s67, s11, 0
	s_movk_i32 s9, 1024
	s_mov_b32 s20, 0
	s_mov_b64 s[70:71], s[24:25]
	s_branch .Lcv_a_p0_c

.LBB0_158:
	s_ashr_i32 s45, s44, 31
	v_cmp_lt_i64_e32 vcc, s[48:49], v[140:141]
	s_lshl_b64 s[48:49], s[44:45], 19
	s_add_u32 s48, s2, s48
	s_addc_u32 s49, s3, s49
	s_and_b64 s[50:51], vcc, exec
	s_cselect_b32 s7, s49, s9
	s_cselect_b32 s45, s48, s8
	s_ashr_i32 s43, s42, 31
	s_lshl_b64 s[50:51], s[42:43], 19
	s_add_u32 s50, s10, s50
	s_addc_u32 s51, s11, s51
	s_and_b64 s[54:55], vcc, exec
	s_cselect_b32 s43, s51, s53
	s_cselect_b32 s65, s50, s52
	s_add_u32 s8, s8, 0x40080
	s_addc_u32 s9, s9, 0
	s_add_u32 s66, s52, 0x100

	s_addc_u32 s67, s53, 0
	s_mov_b32 s68, -2


	ds_read_b128 v[144:147], v156
	ds_read_b128 v[148:151], v156 offset:1024
	ds_read_b128 v[160:163], v156 offset:2048
	ds_read_b128 v[164:167], v156 offset:3072
	s_add_u32 s52, s8, 0xfffc0080
	s_addc_u32 s53, s9, -1
	s_cmp_eq_u32 s68, 12
	s_cselect_b32 s55, s7, s53
	s_cselect_b32 s54, s45, s52
	s_cselect_b32 s53, s43, s67
	s_cselect_b32 s52, s65, s66
	v_lshl_add_u64 v[200:201], s[8:9], 0, v[136:137]
	s_add_i32 m0, s33, 0xc000
	ds_read_b128 v[168:171], v157
	ds_read_b128 v[172:175], v157 offset:1024
	ds_read_b128 v[176:179], v157 offset:2048
	ds_read_b128 v[180:183], v157 offset:3072
	ds_read_b128 v[184:187], v157 offset:4096
	ds_read_b128 v[188:191], v157 offset:5120
	ds_read_b128 v[192:195], v157 offset:6144
	ds_read_b128 v[196:199], v157 offset:7168
	global_load_lds_dwordx4 v[200:201], off
	v_lshl_add_u64 v[200:201], s[8:9], 0, v[138:139]
	s_add_i32 m0, s33, 0xe000
	s_nop 0
	global_load_lds_dwordx4 v[200:201], off
	s_waitcnt lgkmcnt(8)
	s_barrier
	s_waitcnt lgkmcnt(0)
	s_nop 0
	s_waitcnt lgkmcnt(0)
	v_mfma_f32_16x16x32_bf16 v[124:127], v[144:147], v[168:171], 0
	v_mfma_f32_16x16x32_bf16 v[120:123], v[160:163], v[168:171], 0
	v_mfma_f32_16x16x32_bf16 v[116:119], v[144:147], v[176:179], 0
	v_mfma_f32_16x16x32_bf16 v[108:111], v[160:163], v[176:179], 0
	v_mfma_f32_16x16x32_bf16 v[100:103], v[144:147], v[184:187], 0
	v_mfma_f32_16x16x32_bf16 v[92:95], v[160:163], v[184:187], 0
	v_mfma_f32_16x16x32_bf16 v[84:87], v[144:147], v[192:195], 0
	v_mfma_f32_16x16x32_bf16 v[76:79], v[160:163], v[192:195], 0
	v_mfma_f32_16x16x32_bf16 v[124:127], v[148:151], v[172:175], v[124:127]
	v_mfma_f32_16x16x32_bf16 v[120:123], v[164:167], v[172:175], v[120:123]
	v_mfma_f32_16x16x32_bf16 v[116:119], v[148:151], v[180:183], v[116:119]
	v_mfma_f32_16x16x32_bf16 v[108:111], v[164:167], v[180:183], v[108:111]
	v_mfma_f32_16x16x32_bf16 v[100:103], v[148:151], v[188:191], v[100:103]
	v_mfma_f32_16x16x32_bf16 v[92:95], v[164:167], v[188:191], v[92:95]
	v_mfma_f32_16x16x32_bf16 v[84:87], v[148:151], v[196:199], v[84:87]
	v_mfma_f32_16x16x32_bf16 v[76:79], v[164:167], v[196:199], v[76:79]
	s_nop 0
	s_barrier
	s_add_i32 s69, s60, s1
	v_lshl_add_u64 v[218:219], s[52:53], 0, v[132:133]
	s_mov_b32 m0, s69
	ds_read_b128 v[200:203], v158
	ds_read_b128 v[206:209], v158 offset:1024
	ds_read_b128 v[210:213], v158 offset:2048
	ds_read_b128 v[214:217], v158 offset:3072
	global_load_lds_dwordx4 v[218:219], off
	v_lshl_add_u64 v[220:221], s[52:53], 0, v[128:129]
	s_add_i32 m0, s69, 0x2000
	s_nop 0
	global_load_lds_dwordx4 v[220:221], off
	s_barrier
	s_waitcnt lgkmcnt(0)
	s_nop 0
	s_waitcnt lgkmcnt(0)
	v_mfma_f32_16x16x32_bf16 v[112:115], v[200:203], v[168:171], 0
	v_mfma_f32_16x16x32_bf16 v[104:107], v[210:213], v[168:171], 0
	v_mfma_f32_16x16x32_bf16 v[96:99], v[200:203], v[176:179], 0
	v_mfma_f32_16x16x32_bf16 v[88:91], v[210:213], v[176:179], 0
	v_mfma_f32_16x16x32_bf16 v[80:83], v[200:203], v[184:187], 0
	v_mfma_f32_16x16x32_bf16 v[72:75], v[210:213], v[184:187], 0
	v_mfma_f32_16x16x32_bf16 v[68:71], v[200:203], v[192:195], 0
	v_mfma_f32_16x16x32_bf16 v[64:67], v[210:213], v[192:195], 0
	v_mfma_f32_16x16x32_bf16 v[112:115], v[206:209], v[172:175], v[112:115]
	v_mfma_f32_16x16x32_bf16 v[104:107], v[214:217], v[172:175], v[104:107]
	v_mfma_f32_16x16x32_bf16 v[96:99], v[206:209], v[180:183], v[96:99]
	v_mfma_f32_16x16x32_bf16 v[88:91], v[214:217], v[180:183], v[88:91]
	v_mfma_f32_16x16x32_bf16 v[80:83], v[206:209], v[188:191], v[80:83]
	v_mfma_f32_16x16x32_bf16 v[72:75], v[214:217], v[188:191], v[72:75]
	v_mfma_f32_16x16x32_bf16 v[68:71], v[206:209], v[196:199], v[68:71]
	v_mfma_f32_16x16x32_bf16 v[64:67], v[214:217], v[196:199], v[64:67]
	s_nop 0
	s_mov_b32 m0, s33
	v_lshl_add_u64 v[222:223], s[54:55], 0, v[134:135]
	s_barrier
	ds_read_b128 v[168:171], v157 offset:16384
	ds_read_b128 v[172:175], v157 offset:17408
	ds_read_b128 v[176:179], v157 offset:18432
	ds_read_b128 v[180:183], v157 offset:19456
	ds_read_b128 v[184:187], v157 offset:20480
	ds_read_b128 v[188:191], v157 offset:21504
	ds_read_b128 v[192:195], v157 offset:22528
	ds_read_b128 v[196:199], v157 offset:23552
	global_load_lds_dwordx4 v[222:223], off
	v_lshl_add_u64 v[224:225], s[54:55], 0, v[130:131]
	s_mov_b32 m0, s34
	s_nop 0
	global_load_lds_dwordx4 v[224:225], off
	s_barrier
	s_waitcnt lgkmcnt(0)
	s_nop 0
	s_waitcnt lgkmcnt(0)
	v_mfma_f32_16x16x32_bf16 v[60:63], v[144:147], v[168:171], 0
	v_mfma_f32_16x16x32_bf16 v[56:59], v[160:163], v[168:171], 0
	v_mfma_f32_16x16x32_bf16 v[52:55], v[144:147], v[176:179], 0
	v_mfma_f32_16x16x32_bf16 v[44:47], v[160:163], v[176:179], 0
	v_mfma_f32_16x16x32_bf16 v[36:39], v[144:147], v[184:187], 0
	v_mfma_f32_16x16x32_bf16 v[28:31], v[160:163], v[184:187], 0
	v_mfma_f32_16x16x32_bf16 v[20:23], v[144:147], v[192:195], 0
	v_mfma_f32_16x16x32_bf16 v[12:15], v[160:163], v[192:195], 0
	v_mfma_f32_16x16x32_bf16 v[60:63], v[148:151], v[172:175], v[60:63]
	v_mfma_f32_16x16x32_bf16 v[56:59], v[164:167], v[172:175], v[56:59]
	v_mfma_f32_16x16x32_bf16 v[52:55], v[148:151], v[180:183], v[52:55]
	v_mfma_f32_16x16x32_bf16 v[44:47], v[164:167], v[180:183], v[44:47]
	v_mfma_f32_16x16x32_bf16 v[36:39], v[148:151], v[188:191], v[36:39]
	v_mfma_f32_16x16x32_bf16 v[28:31], v[164:167], v[188:191], v[28:31]
	v_mfma_f32_16x16x32_bf16 v[20:23], v[148:151], v[196:199], v[20:23]
	v_mfma_f32_16x16x32_bf16 v[12:15], v[164:167], v[196:199], v[12:15]
	s_nop 0
	s_barrier
	s_add_u32 s70, s52, 0x40000
	s_addc_u32 s71, s53, 0
	s_add_i32 s69, s61, s1
	v_lshl_add_u64 v[144:145], s[70:71], 0, v[132:133]
	s_mov_b32 m0, s69
	s_nop 0
	global_load_lds_dwordx4 v[144:145], off
	v_lshl_add_u64 v[144:145], s[70:71], 0, v[128:129]
	s_add_i32 m0, s69, 0x2000
	s_nop 0
	global_load_lds_dwordx4 v[144:145], off
	s_waitcnt vmcnt(6)
	s_barrier
	s_nop 0
	v_mfma_f32_16x16x32_bf16 v[48:51], v[200:203], v[168:171], 0
	v_mfma_f32_16x16x32_bf16 v[40:43], v[210:213], v[168:171], 0
	v_mfma_f32_16x16x32_bf16 v[32:35], v[200:203], v[176:179], 0
	v_mfma_f32_16x16x32_bf16 v[24:27], v[210:213], v[176:179], 0
	v_mfma_f32_16x16x32_bf16 v[16:19], v[200:203], v[184:187], 0
	v_mfma_f32_16x16x32_bf16 v[8:11], v[210:213], v[184:187], 0
	v_mfma_f32_16x16x32_bf16 v[4:7], v[200:203], v[192:195], 0
	v_mfma_f32_16x16x32_bf16 v[0:3], v[210:213], v[192:195], 0
	v_mfma_f32_16x16x32_bf16 v[48:51], v[206:209], v[172:175], v[48:51]
	v_mfma_f32_16x16x32_bf16 v[40:43], v[214:217], v[172:175], v[40:43]
	v_mfma_f32_16x16x32_bf16 v[32:35], v[206:209], v[180:183], v[32:35]
	v_mfma_f32_16x16x32_bf16 v[24:27], v[214:217], v[180:183], v[24:27]
	v_mfma_f32_16x16x32_bf16 v[16:19], v[206:209], v[188:191], v[16:19]
	v_mfma_f32_16x16x32_bf16 v[8:11], v[214:217], v[188:191], v[8:11]
	v_mfma_f32_16x16x32_bf16 v[4:7], v[206:209], v[196:199], v[4:7]
	v_mfma_f32_16x16x32_bf16 v[0:3], v[214:217], v[196:199], v[0:3]
	s_nop 0
	s_add_i32 s69, 0, 0x18000
	v_add_u32_e32 v164, s69, v154
	s_barrier
	ds_read_b128 v[144:147], v164
	ds_read_b128 v[148:151], v164 offset:1024
	ds_read_b128 v[160:163], v164 offset:2048
	ds_read_b128 v[164:167], v164 offset:3072
	s_add_u32 s54, s54, 0x40000
	s_addc_u32 s55, s55, 0
	s_mov_b32 m0, s35
	v_lshl_add_u64 v[200:201], s[54:55], 0, v[134:135]
	ds_read_b128 v[168:171], v157 offset:32768
	ds_read_b128 v[172:175], v157 offset:33792
	ds_read_b128 v[176:179], v157 offset:34816
	ds_read_b128 v[180:183], v157 offset:35840
	ds_read_b128 v[184:187], v157 offset:36864
	ds_read_b128 v[188:191], v157 offset:37888
	ds_read_b128 v[192:195], v157 offset:38912
	ds_read_b128 v[196:199], v157 offset:39936
	global_load_lds_dwordx4 v[200:201], off
	v_lshl_add_u64 v[200:201], s[54:55], 0, v[130:131]
	s_mov_b32 m0, s46
	s_nop 0
	global_load_lds_dwordx4 v[200:201], off
	s_waitcnt lgkmcnt(8)
	s_barrier
	s_waitcnt lgkmcnt(0)
	s_nop 0
	s_waitcnt lgkmcnt(0)
	v_mfma_f32_16x16x32_bf16 v[124:127], v[144:147], v[168:171], v[124:127]
	v_mfma_f32_16x16x32_bf16 v[120:123], v[160:163], v[168:171], v[120:123]
	v_mfma_f32_16x16x32_bf16 v[116:119], v[144:147], v[176:179], v[116:119]
	v_mfma_f32_16x16x32_bf16 v[108:111], v[160:163], v[176:179], v[108:111]
	v_mfma_f32_16x16x32_bf16 v[100:103], v[144:147], v[184:187], v[100:103]
	v_mfma_f32_16x16x32_bf16 v[92:95], v[160:163], v[184:187], v[92:95]
	v_mfma_f32_16x16x32_bf16 v[84:87], v[144:147], v[192:195], v[84:87]
	v_mfma_f32_16x16x32_bf16 v[76:79], v[160:163], v[192:195], v[76:79]
	v_mfma_f32_16x16x32_bf16 v[124:127], v[148:151], v[172:175], v[124:127]
	v_mfma_f32_16x16x32_bf16 v[120:123], v[164:167], v[172:175], v[120:123]
	v_mfma_f32_16x16x32_bf16 v[116:119], v[148:151], v[180:183], v[116:119]
	v_mfma_f32_16x16x32_bf16 v[108:111], v[164:167], v[180:183], v[108:111]
	v_mfma_f32_16x16x32_bf16 v[100:103], v[148:151], v[188:191], v[100:103]
	v_mfma_f32_16x16x32_bf16 v[92:95], v[164:167], v[188:191], v[92:95]
	v_mfma_f32_16x16x32_bf16 v[84:87], v[148:151], v[196:199], v[84:87]
	v_mfma_f32_16x16x32_bf16 v[76:79], v[164:167], v[196:199], v[76:79]
	s_nop 0
	s_barrier
	s_add_i32 s54, 0, 0x1c000
	s_add_i32 s55, s69, s1
	v_add_u32_e32 v205, s54, v154
	v_lshl_add_u64 v[218:219], v[218:219], 0, s[40:41]
	s_mov_b32 m0, s55
	ds_read_b128 v[200:203], v205
	ds_read_b128 v[206:209], v205 offset:1024
	ds_read_b128 v[210:213], v205 offset:2048
	ds_read_b128 v[214:217], v205 offset:3072
	global_load_lds_dwordx4 v[218:219], off
	v_lshl_add_u64 v[218:219], v[220:221], 0, s[40:41]
	s_add_i32 m0, s55, 0x2000
	s_nop 0
	global_load_lds_dwordx4 v[218:219], off
	s_barrier
	s_waitcnt lgkmcnt(0)
	s_nop 0
	s_waitcnt lgkmcnt(0)
	v_mfma_f32_16x16x32_bf16 v[112:115], v[200:203], v[168:171], v[112:115]
	v_mfma_f32_16x16x32_bf16 v[104:107], v[210:213], v[168:171], v[104:107]
	v_mfma_f32_16x16x32_bf16 v[96:99], v[200:203], v[176:179], v[96:99]
	v_mfma_f32_16x16x32_bf16 v[88:91], v[210:213], v[176:179], v[88:91]
	v_mfma_f32_16x16x32_bf16 v[80:83], v[200:203], v[184:187], v[80:83]
	v_mfma_f32_16x16x32_bf16 v[72:75], v[210:213], v[184:187], v[72:75]
	v_mfma_f32_16x16x32_bf16 v[68:71], v[200:203], v[192:195], v[68:71]
	v_mfma_f32_16x16x32_bf16 v[64:67], v[210:213], v[192:195], v[64:67]
	v_mfma_f32_16x16x32_bf16 v[112:115], v[206:209], v[172:175], v[112:115]
	v_mfma_f32_16x16x32_bf16 v[104:107], v[214:217], v[172:175], v[104:107]
	v_mfma_f32_16x16x32_bf16 v[96:99], v[206:209], v[180:183], v[96:99]
	v_mfma_f32_16x16x32_bf16 v[88:91], v[214:217], v[180:183], v[88:91]
	v_mfma_f32_16x16x32_bf16 v[80:83], v[206:209], v[188:191], v[80:83]
	v_mfma_f32_16x16x32_bf16 v[72:75], v[214:217], v[188:191], v[72:75]
	v_mfma_f32_16x16x32_bf16 v[68:71], v[206:209], v[196:199], v[68:71]
	v_mfma_f32_16x16x32_bf16 v[64:67], v[214:217], v[196:199], v[64:67]
	s_nop 0
	s_mov_b32 m0, s56
	v_lshl_add_u64 v[218:219], v[222:223], 0, s[40:41]
	s_barrier
	ds_read_b128 v[168:171], v157 offset:49152
	ds_read_b128 v[172:175], v157 offset:50176
	ds_read_b128 v[176:179], v157 offset:51200
	ds_read_b128 v[180:183], v157 offset:52224
	ds_read_b128 v[184:187], v157 offset:53248
	ds_read_b128 v[188:191], v157 offset:54272
	ds_read_b128 v[192:195], v157 offset:55296
	ds_read_b128 v[196:199], v157 offset:56320
	global_load_lds_dwordx4 v[218:219], off
	v_lshl_add_u64 v[218:219], v[224:225], 0, s[40:41]
	s_mov_b32 m0, s57
	s_nop 0
	global_load_lds_dwordx4 v[218:219], off
	s_barrier
	s_waitcnt lgkmcnt(0)
	s_nop 0
	s_waitcnt lgkmcnt(0)
	v_mfma_f32_16x16x32_bf16 v[60:63], v[144:147], v[168:171], v[60:63]
	v_mfma_f32_16x16x32_bf16 v[56:59], v[160:163], v[168:171], v[56:59]
	v_mfma_f32_16x16x32_bf16 v[52:55], v[144:147], v[176:179], v[52:55]
	v_mfma_f32_16x16x32_bf16 v[44:47], v[160:163], v[176:179], v[44:47]
	v_mfma_f32_16x16x32_bf16 v[36:39], v[144:147], v[184:187], v[36:39]
	v_mfma_f32_16x16x32_bf16 v[28:31], v[160:163], v[184:187], v[28:31]
	v_mfma_f32_16x16x32_bf16 v[20:23], v[144:147], v[192:195], v[20:23]
	v_mfma_f32_16x16x32_bf16 v[12:15], v[160:163], v[192:195], v[12:15]
	v_mfma_f32_16x16x32_bf16 v[60:63], v[148:151], v[172:175], v[60:63]
	v_mfma_f32_16x16x32_bf16 v[56:59], v[164:167], v[172:175], v[56:59]
	v_mfma_f32_16x16x32_bf16 v[52:55], v[148:151], v[180:183], v[52:55]
	v_mfma_f32_16x16x32_bf16 v[44:47], v[164:167], v[180:183], v[44:47]
	v_mfma_f32_16x16x32_bf16 v[36:39], v[148:151], v[188:191], v[36:39]
	v_mfma_f32_16x16x32_bf16 v[28:31], v[164:167], v[188:191], v[28:31]
	v_mfma_f32_16x16x32_bf16 v[20:23], v[148:151], v[196:199], v[20:23]
	v_mfma_f32_16x16x32_bf16 v[12:15], v[164:167], v[196:199], v[12:15]
	s_nop 0
	s_barrier
	s_add_u32 s52, s52, 0x40080
	s_addc_u32 s53, s53, 0
	s_add_i32 s54, s54, s1
	v_lshl_add_u64 v[144:145], s[52:53], 0, v[132:133]
	s_mov_b32 m0, s54
	s_nop 0
	global_load_lds_dwordx4 v[144:145], off
	v_lshl_add_u64 v[144:145], s[52:53], 0, v[128:129]
	s_add_i32 m0, s54, 0x2000
	s_nop 0
	global_load_lds_dwordx4 v[144:145], off
	s_waitcnt vmcnt(6)
	s_barrier
	s_nop 0
	v_mfma_f32_16x16x32_bf16 v[48:51], v[200:203], v[168:171], v[48:51]
	v_mfma_f32_16x16x32_bf16 v[40:43], v[210:213], v[168:171], v[40:43]
	v_mfma_f32_16x16x32_bf16 v[32:35], v[200:203], v[176:179], v[32:35]
	v_mfma_f32_16x16x32_bf16 v[24:27], v[210:213], v[176:179], v[24:27]
	v_mfma_f32_16x16x32_bf16 v[16:19], v[200:203], v[184:187], v[16:19]
	v_mfma_f32_16x16x32_bf16 v[8:11], v[210:213], v[184:187], v[8:11]
	v_mfma_f32_16x16x32_bf16 v[4:7], v[200:203], v[192:195], v[4:7]
	v_mfma_f32_16x16x32_bf16 v[0:3], v[210:213], v[192:195], v[0:3]
	v_mfma_f32_16x16x32_bf16 v[48:51], v[206:209], v[172:175], v[48:51]
	v_mfma_f32_16x16x32_bf16 v[40:43], v[214:217], v[172:175], v[40:43]
	v_mfma_f32_16x16x32_bf16 v[32:35], v[206:209], v[180:183], v[32:35]
	v_mfma_f32_16x16x32_bf16 v[24:27], v[214:217], v[180:183], v[24:27]
	v_mfma_f32_16x16x32_bf16 v[16:19], v[206:209], v[188:191], v[16:19]
	v_mfma_f32_16x16x32_bf16 v[8:11], v[214:217], v[188:191], v[8:11]
	v_mfma_f32_16x16x32_bf16 v[4:7], v[206:209], v[196:199], v[4:7]
	v_mfma_f32_16x16x32_bf16 v[0:3], v[214:217], v[196:199], v[0:3]
	s_nop 0
	s_add_i32 s68, s68, 2
	s_add_u32 s8, s8, 0x100
	s_addc_u32 s9, s9, 0
	s_add_u32 s66, s66, 0x100
	s_addc_u32 s67, s67, 0
	s_cmp_gt_u32 s68, 13
	s_barrier
.LBB0_159:
	ds_read_b128 v[144:147], v156
	ds_read_b128 v[148:151], v156 offset:1024
	ds_read_b128 v[160:163], v156 offset:2048
	ds_read_b128 v[164:167], v156 offset:3072
	s_add_u32 s52, s8, 0xfffc0080
	s_addc_u32 s53, s9, -1
	s_cmp_eq_u32 s68, 12
	s_cselect_b32 s55, s7, s53
	s_cselect_b32 s54, s45, s52
	s_cselect_b32 s53, s43, s67
	s_cselect_b32 s52, s65, s66
	v_lshl_add_u64 v[200:201], s[8:9], 0, v[136:137]
	s_add_i32 m0, s33, 0xc000
	ds_read_b128 v[168:171], v157
	ds_read_b128 v[172:175], v157 offset:1024
	ds_read_b128 v[176:179], v157 offset:2048
	ds_read_b128 v[180:183], v157 offset:3072
	ds_read_b128 v[184:187], v157 offset:4096
	ds_read_b128 v[188:191], v157 offset:5120
	ds_read_b128 v[192:195], v157 offset:6144
	ds_read_b128 v[196:199], v157 offset:7168
	global_load_lds_dwordx4 v[200:201], off
	v_lshl_add_u64 v[200:201], s[8:9], 0, v[138:139]
	s_add_i32 m0, s33, 0xe000
	s_nop 0
	global_load_lds_dwordx4 v[200:201], off
	s_waitcnt lgkmcnt(8)
	s_barrier
	s_waitcnt lgkmcnt(0)
	s_nop 0
	s_waitcnt lgkmcnt(0)
	v_mfma_f32_16x16x32_bf16 v[124:127], v[144:147], v[168:171], v[124:127]
	v_mfma_f32_16x16x32_bf16 v[120:123], v[160:163], v[168:171], v[120:123]
	v_mfma_f32_16x16x32_bf16 v[116:119], v[144:147], v[176:179], v[116:119]
	v_mfma_f32_16x16x32_bf16 v[108:111], v[160:163], v[176:179], v[108:111]
	v_mfma_f32_16x16x32_bf16 v[100:103], v[144:147], v[184:187], v[100:103]
	v_mfma_f32_16x16x32_bf16 v[92:95], v[160:163], v[184:187], v[92:95]
	v_mfma_f32_16x16x32_bf16 v[84:87], v[144:147], v[192:195], v[84:87]
	v_mfma_f32_16x16x32_bf16 v[76:79], v[160:163], v[192:195], v[76:79]
	v_mfma_f32_16x16x32_bf16 v[124:127], v[148:151], v[172:175], v[124:127]
	v_mfma_f32_16x16x32_bf16 v[120:123], v[164:167], v[172:175], v[120:123]
	v_mfma_f32_16x16x32_bf16 v[116:119], v[148:151], v[180:183], v[116:119]
	v_mfma_f32_16x16x32_bf16 v[108:111], v[164:167], v[180:183], v[108:111]
	v_mfma_f32_16x16x32_bf16 v[100:103], v[148:151], v[188:191], v[100:103]
	v_mfma_f32_16x16x32_bf16 v[92:95], v[164:167], v[188:191], v[92:95]
	v_mfma_f32_16x16x32_bf16 v[84:87], v[148:151], v[196:199], v[84:87]
	v_mfma_f32_16x16x32_bf16 v[76:79], v[164:167], v[196:199], v[76:79]
	s_nop 0
	s_barrier
	s_add_i32 s69, s60, s1
	v_lshl_add_u64 v[218:219], s[52:53], 0, v[132:133]
	s_mov_b32 m0, s69
	ds_read_b128 v[200:203], v158
	ds_read_b128 v[206:209], v158 offset:1024
	ds_read_b128 v[210:213], v158 offset:2048
	ds_read_b128 v[214:217], v158 offset:3072
	global_load_lds_dwordx4 v[218:219], off
	v_lshl_add_u64 v[220:221], s[52:53], 0, v[128:129]
	s_add_i32 m0, s69, 0x2000
	s_nop 0
	global_load_lds_dwordx4 v[220:221], off
	s_barrier
	s_waitcnt lgkmcnt(0)
	s_nop 0
	s_waitcnt lgkmcnt(0)
	v_mfma_f32_16x16x32_bf16 v[112:115], v[200:203], v[168:171], v[112:115]
	v_mfma_f32_16x16x32_bf16 v[104:107], v[210:213], v[168:171], v[104:107]
	v_mfma_f32_16x16x32_bf16 v[96:99], v[200:203], v[176:179], v[96:99]
	v_mfma_f32_16x16x32_bf16 v[88:91], v[210:213], v[176:179], v[88:91]
	v_mfma_f32_16x16x32_bf16 v[80:83], v[200:203], v[184:187], v[80:83]
	v_mfma_f32_16x16x32_bf16 v[72:75], v[210:213], v[184:187], v[72:75]
	v_mfma_f32_16x16x32_bf16 v[68:71], v[200:203], v[192:195], v[68:71]
	v_mfma_f32_16x16x32_bf16 v[64:67], v[210:213], v[192:195], v[64:67]
	v_mfma_f32_16x16x32_bf16 v[112:115], v[206:209], v[172:175], v[112:115]
	v_mfma_f32_16x16x32_bf16 v[104:107], v[214:217], v[172:175], v[104:107]
	v_mfma_f32_16x16x32_bf16 v[96:99], v[206:209], v[180:183], v[96:99]
	v_mfma_f32_16x16x32_bf16 v[88:91], v[214:217], v[180:183], v[88:91]
	v_mfma_f32_16x16x32_bf16 v[80:83], v[206:209], v[188:191], v[80:83]
	v_mfma_f32_16x16x32_bf16 v[72:75], v[214:217], v[188:191], v[72:75]
	v_mfma_f32_16x16x32_bf16 v[68:71], v[206:209], v[196:199], v[68:71]
	v_mfma_f32_16x16x32_bf16 v[64:67], v[214:217], v[196:199], v[64:67]
	s_nop 0
	s_mov_b32 m0, s33
	v_lshl_add_u64 v[222:223], s[54:55], 0, v[134:135]
	s_barrier
	ds_read_b128 v[168:171], v157 offset:16384
	ds_read_b128 v[172:175], v157 offset:17408
	ds_read_b128 v[176:179], v157 offset:18432
	ds_read_b128 v[180:183], v157 offset:19456
	ds_read_b128 v[184:187], v157 offset:20480
	ds_read_b128 v[188:191], v157 offset:21504
	ds_read_b128 v[192:195], v157 offset:22528
	ds_read_b128 v[196:199], v157 offset:23552
	global_load_lds_dwordx4 v[222:223], off
	v_lshl_add_u64 v[224:225], s[54:55], 0, v[130:131]
	s_mov_b32 m0, s34
	s_nop 0
	global_load_lds_dwordx4 v[224:225], off
	s_barrier
	s_waitcnt lgkmcnt(0)
	s_nop 0
	s_waitcnt lgkmcnt(0)
	v_mfma_f32_16x16x32_bf16 v[60:63], v[144:147], v[168:171], v[60:63]
	v_mfma_f32_16x16x32_bf16 v[56:59], v[160:163], v[168:171], v[56:59]
	v_mfma_f32_16x16x32_bf16 v[52:55], v[144:147], v[176:179], v[52:55]
	v_mfma_f32_16x16x32_bf16 v[44:47], v[160:163], v[176:179], v[44:47]
	v_mfma_f32_16x16x32_bf16 v[36:39], v[144:147], v[184:187], v[36:39]
	v_mfma_f32_16x16x32_bf16 v[28:31], v[160:163], v[184:187], v[28:31]
	v_mfma_f32_16x16x32_bf16 v[20:23], v[144:147], v[192:195], v[20:23]
	v_mfma_f32_16x16x32_bf16 v[12:15], v[160:163], v[192:195], v[12:15]
	v_mfma_f32_16x16x32_bf16 v[60:63], v[148:151], v[172:175], v[60:63]
	v_mfma_f32_16x16x32_bf16 v[56:59], v[164:167], v[172:175], v[56:59]
	v_mfma_f32_16x16x32_bf16 v[52:55], v[148:151], v[180:183], v[52:55]
	v_mfma_f32_16x16x32_bf16 v[44:47], v[164:167], v[180:183], v[44:47]
	v_mfma_f32_16x16x32_bf16 v[36:39], v[148:151], v[188:191], v[36:39]
	v_mfma_f32_16x16x32_bf16 v[28:31], v[164:167], v[188:191], v[28:31]
	v_mfma_f32_16x16x32_bf16 v[20:23], v[148:151], v[196:199], v[20:23]
	v_mfma_f32_16x16x32_bf16 v[12:15], v[164:167], v[196:199], v[12:15]
	s_nop 0
	s_barrier
	s_add_u32 s70, s52, 0x40000
	s_addc_u32 s71, s53, 0
	s_add_i32 s69, s61, s1
	v_lshl_add_u64 v[144:145], s[70:71], 0, v[132:133]
	s_mov_b32 m0, s69
	s_nop 0
	global_load_lds_dwordx4 v[144:145], off
	v_lshl_add_u64 v[144:145], s[70:71], 0, v[128:129]
	s_add_i32 m0, s69, 0x2000
	s_nop 0
	global_load_lds_dwordx4 v[144:145], off
	s_waitcnt vmcnt(6)
	s_cmp_gt_u32 s68, 10
	s_cbranch_scc1 .Lds_P1_a_done
	s_cmp_lt_u32 s68, 6
	s_cbranch_scc1 .Lds_P1_a_st
	s_cmp_eq_u32 s68, 6
	s_cbranch_scc1 .Lds_P1_a_pf
	s_cmp_eq_u32 s68, 8
	s_cbranch_scc1 .Lds_P1_a_c8
	v_ffbh_u32_e32 v252, v241
	v_min_u32_e32 v252, 32, v252
	v_lshlrev_b64 v[240:241], v252, v[240:241]
	v_min_u32_e32 v240, 1, v240
	v_or_b32_e32 v241, v241, v240
	v_cvt_f32_u32_e32 v241, v241
	v_sub_u32_e32 v252, -2, v252
	v_ldexp_f32 v241, v241, v252
	v_add_f32_e32 v241, 0x358637bd, v241
	v_rsq_f32_e32 v252, v241
	v_ffbh_u32_e32 v253, v243
	v_min_u32_e32 v253, 32, v253
	v_lshlrev_b64 v[242:243], v253, v[242:243]
	v_min_u32_e32 v242, 1, v242
	v_or_b32_e32 v243, v243, v242
	v_cvt_f32_u32_e32 v243, v243
	v_sub_u32_e32 v253, -2, v253
	v_ldexp_f32 v243, v243, v253
	v_add_f32_e32 v243, 0x358637bd, v243
	v_rsq_f32_e32 v253, v243
	s_branch .Lds_P1_a_done

.Lds_P1_a_done:
	s_barrier
	s_nop 0
	v_mfma_f32_16x16x32_bf16 v[48:51], v[200:203], v[168:171], v[48:51]
	v_mfma_f32_16x16x32_bf16 v[40:43], v[210:213], v[168:171], v[40:43]
	v_mfma_f32_16x16x32_bf16 v[32:35], v[200:203], v[176:179], v[32:35]
	v_mfma_f32_16x16x32_bf16 v[24:27], v[210:213], v[176:179], v[24:27]
	v_mfma_f32_16x16x32_bf16 v[16:19], v[200:203], v[184:187], v[16:19]
	v_mfma_f32_16x16x32_bf16 v[8:11], v[210:213], v[184:187], v[8:11]
	v_mfma_f32_16x16x32_bf16 v[4:7], v[200:203], v[192:195], v[4:7]
	v_mfma_f32_16x16x32_bf16 v[0:3], v[210:213], v[192:195], v[0:3]
	v_mfma_f32_16x16x32_bf16 v[48:51], v[206:209], v[172:175], v[48:51]
	v_mfma_f32_16x16x32_bf16 v[40:43], v[214:217], v[172:175], v[40:43]
	v_mfma_f32_16x16x32_bf16 v[32:35], v[206:209], v[180:183], v[32:35]
	v_mfma_f32_16x16x32_bf16 v[24:27], v[214:217], v[180:183], v[24:27]
	v_mfma_f32_16x16x32_bf16 v[16:19], v[206:209], v[188:191], v[16:19]
	v_mfma_f32_16x16x32_bf16 v[8:11], v[214:217], v[188:191], v[8:11]
	v_mfma_f32_16x16x32_bf16 v[4:7], v[206:209], v[196:199], v[4:7]
	v_mfma_f32_16x16x32_bf16 v[0:3], v[214:217], v[196:199], v[0:3]
	s_nop 0
	s_add_i32 s69, 0, 0x18000
	v_add_u32_e32 v164, s69, v154
	s_barrier
	ds_read_b128 v[144:147], v164
	ds_read_b128 v[148:151], v164 offset:1024
	ds_read_b128 v[160:163], v164 offset:2048
	ds_read_b128 v[164:167], v164 offset:3072
	s_add_u32 s54, s54, 0x40000
	s_addc_u32 s55, s55, 0
	s_mov_b32 m0, s35
	v_lshl_add_u64 v[200:201], s[54:55], 0, v[134:135]
	ds_read_b128 v[168:171], v157 offset:32768
	ds_read_b128 v[172:175], v157 offset:33792
	ds_read_b128 v[176:179], v157 offset:34816
	ds_read_b128 v[180:183], v157 offset:35840
	ds_read_b128 v[184:187], v157 offset:36864
	ds_read_b128 v[188:191], v157 offset:37888
	ds_read_b128 v[192:195], v157 offset:38912
	ds_read_b128 v[196:199], v157 offset:39936
	global_load_lds_dwordx4 v[200:201], off
	v_lshl_add_u64 v[200:201], s[54:55], 0, v[130:131]
	s_mov_b32 m0, s46
	s_nop 0
	global_load_lds_dwordx4 v[200:201], off
	s_waitcnt lgkmcnt(8)
	s_barrier
	s_waitcnt lgkmcnt(0)
	s_nop 0
	s_waitcnt lgkmcnt(0)
	v_mfma_f32_16x16x32_bf16 v[124:127], v[144:147], v[168:171], v[124:127]
	v_mfma_f32_16x16x32_bf16 v[120:123], v[160:163], v[168:171], v[120:123]
	v_mfma_f32_16x16x32_bf16 v[116:119], v[144:147], v[176:179], v[116:119]
	v_mfma_f32_16x16x32_bf16 v[108:111], v[160:163], v[176:179], v[108:111]
	v_mfma_f32_16x16x32_bf16 v[100:103], v[144:147], v[184:187], v[100:103]
	v_mfma_f32_16x16x32_bf16 v[92:95], v[160:163], v[184:187], v[92:95]
	v_mfma_f32_16x16x32_bf16 v[84:87], v[144:147], v[192:195], v[84:87]
	v_mfma_f32_16x16x32_bf16 v[76:79], v[160:163], v[192:195], v[76:79]
	v_mfma_f32_16x16x32_bf16 v[124:127], v[148:151], v[172:175], v[124:127]
	v_mfma_f32_16x16x32_bf16 v[120:123], v[164:167], v[172:175], v[120:123]
	v_mfma_f32_16x16x32_bf16 v[116:119], v[148:151], v[180:183], v[116:119]
	v_mfma_f32_16x16x32_bf16 v[108:111], v[164:167], v[180:183], v[108:111]
	v_mfma_f32_16x16x32_bf16 v[100:103], v[148:151], v[188:191], v[100:103]
	v_mfma_f32_16x16x32_bf16 v[92:95], v[164:167], v[188:191], v[92:95]
	v_mfma_f32_16x16x32_bf16 v[84:87], v[148:151], v[196:199], v[84:87]
	v_mfma_f32_16x16x32_bf16 v[76:79], v[164:167], v[196:199], v[76:79]
	s_nop 0
	s_barrier
	s_add_i32 s54, 0, 0x1c000
	s_add_i32 s55, s69, s1
	v_add_u32_e32 v205, s54, v154
	v_lshl_add_u64 v[218:219], v[218:219], 0, s[40:41]
	s_mov_b32 m0, s55
	ds_read_b128 v[200:203], v205
	ds_read_b128 v[206:209], v205 offset:1024
	ds_read_b128 v[210:213], v205 offset:2048
	ds_read_b128 v[214:217], v205 offset:3072
	global_load_lds_dwordx4 v[218:219], off
	v_lshl_add_u64 v[218:219], v[220:221], 0, s[40:41]
	s_add_i32 m0, s55, 0x2000
	s_nop 0
	global_load_lds_dwordx4 v[218:219], off
	s_barrier
	s_waitcnt lgkmcnt(0)
	s_nop 0
	s_waitcnt lgkmcnt(0)
	v_mfma_f32_16x16x32_bf16 v[112:115], v[200:203], v[168:171], v[112:115]
	v_mfma_f32_16x16x32_bf16 v[104:107], v[210:213], v[168:171], v[104:107]
	v_mfma_f32_16x16x32_bf16 v[96:99], v[200:203], v[176:179], v[96:99]
	v_mfma_f32_16x16x32_bf16 v[88:91], v[210:213], v[176:179], v[88:91]
	v_mfma_f32_16x16x32_bf16 v[80:83], v[200:203], v[184:187], v[80:83]
	v_mfma_f32_16x16x32_bf16 v[72:75], v[210:213], v[184:187], v[72:75]
	v_mfma_f32_16x16x32_bf16 v[68:71], v[200:203], v[192:195], v[68:71]
	v_mfma_f32_16x16x32_bf16 v[64:67], v[210:213], v[192:195], v[64:67]
	v_mfma_f32_16x16x32_bf16 v[112:115], v[206:209], v[172:175], v[112:115]
	v_mfma_f32_16x16x32_bf16 v[104:107], v[214:217], v[172:175], v[104:107]
	v_mfma_f32_16x16x32_bf16 v[96:99], v[206:209], v[180:183], v[96:99]
	v_mfma_f32_16x16x32_bf16 v[88:91], v[214:217], v[180:183], v[88:91]
	v_mfma_f32_16x16x32_bf16 v[80:83], v[206:209], v[188:191], v[80:83]
	v_mfma_f32_16x16x32_bf16 v[72:75], v[214:217], v[188:191], v[72:75]
	v_mfma_f32_16x16x32_bf16 v[68:71], v[206:209], v[196:199], v[68:71]
	v_mfma_f32_16x16x32_bf16 v[64:67], v[214:217], v[196:199], v[64:67]
	s_nop 0
	s_mov_b32 m0, s56
	v_lshl_add_u64 v[218:219], v[222:223], 0, s[40:41]
	s_barrier
	ds_read_b128 v[168:171], v157 offset:49152
	ds_read_b128 v[172:175], v157 offset:50176
	ds_read_b128 v[176:179], v157 offset:51200
	ds_read_b128 v[180:183], v157 offset:52224
	ds_read_b128 v[184:187], v157 offset:53248
	ds_read_b128 v[188:191], v157 offset:54272
	ds_read_b128 v[192:195], v157 offset:55296
	ds_read_b128 v[196:199], v157 offset:56320
	global_load_lds_dwordx4 v[218:219], off
	v_lshl_add_u64 v[218:219], v[224:225], 0, s[40:41]
	s_mov_b32 m0, s57
	s_nop 0
	global_load_lds_dwordx4 v[218:219], off
	s_barrier
	s_waitcnt lgkmcnt(0)
	s_nop 0
	s_waitcnt lgkmcnt(0)
	v_mfma_f32_16x16x32_bf16 v[60:63], v[144:147], v[168:171], v[60:63]
	v_mfma_f32_16x16x32_bf16 v[56:59], v[160:163], v[168:171], v[56:59]
	v_mfma_f32_16x16x32_bf16 v[52:55], v[144:147], v[176:179], v[52:55]
	v_mfma_f32_16x16x32_bf16 v[44:47], v[160:163], v[176:179], v[44:47]
	v_mfma_f32_16x16x32_bf16 v[36:39], v[144:147], v[184:187], v[36:39]
	v_mfma_f32_16x16x32_bf16 v[28:31], v[160:163], v[184:187], v[28:31]
	v_mfma_f32_16x16x32_bf16 v[20:23], v[144:147], v[192:195], v[20:23]
	v_mfma_f32_16x16x32_bf16 v[12:15], v[160:163], v[192:195], v[12:15]
	v_mfma_f32_16x16x32_bf16 v[60:63], v[148:151], v[172:175], v[60:63]
	v_mfma_f32_16x16x32_bf16 v[56:59], v[164:167], v[172:175], v[56:59]
	v_mfma_f32_16x16x32_bf16 v[52:55], v[148:151], v[180:183], v[52:55]
	v_mfma_f32_16x16x32_bf16 v[44:47], v[164:167], v[180:183], v[44:47]
	v_mfma_f32_16x16x32_bf16 v[36:39], v[148:151], v[188:191], v[36:39]
	v_mfma_f32_16x16x32_bf16 v[28:31], v[164:167], v[188:191], v[28:31]
	v_mfma_f32_16x16x32_bf16 v[20:23], v[148:151], v[196:199], v[20:23]
	v_mfma_f32_16x16x32_bf16 v[12:15], v[164:167], v[196:199], v[12:15]
	s_nop 0
	s_barrier
	s_add_u32 s52, s52, 0x40080
	s_addc_u32 s53, s53, 0
	s_add_i32 s54, s54, s1
	v_lshl_add_u64 v[144:145], s[52:53], 0, v[132:133]
	s_mov_b32 m0, s54
	s_nop 0
	global_load_lds_dwordx4 v[144:145], off
	v_lshl_add_u64 v[144:145], s[52:53], 0, v[128:129]
	s_add_i32 m0, s54, 0x2000
	s_nop 0
	global_load_lds_dwordx4 v[144:145], off
	s_waitcnt vmcnt(6)
	s_cmp_gt_u32 s68, 10
	s_cbranch_scc1 .Lds_P1_b_done
	s_cmp_lt_u32 s68, 6
	s_cbranch_scc1 .Lds_P1_b_st
	s_cmp_eq_u32 s68, 6
	s_cbranch_scc1 .Lds_P1_b_l6
	s_cmp_eq_u32 s68, 8
	s_cbranch_scc1 .Lds_P1_b_c8
	v_ffbh_u32_e32 v254, v245
	v_min_u32_e32 v254, 32, v254
	v_lshlrev_b64 v[244:245], v254, v[244:245]
	v_min_u32_e32 v244, 1, v244
	v_or_b32_e32 v245, v245, v244
	v_cvt_f32_u32_e32 v245, v245
	v_sub_u32_e32 v254, -2, v254
	v_ldexp_f32 v245, v245, v254
	v_add_f32_e32 v245, 0x358637bd, v245
	v_rsq_f32_e32 v254, v245
	v_ffbh_u32_e32 v255, v247
	v_min_u32_e32 v255, 32, v255
	v_lshlrev_b64 v[246:247], v255, v[246:247]
	v_min_u32_e32 v246, 1, v246
	v_or_b32_e32 v247, v247, v246
	v_cvt_f32_u32_e32 v247, v247
	v_sub_u32_e32 v255, -2, v255
	v_ldexp_f32 v247, v247, v255
	v_add_f32_e32 v247, 0x358637bd, v247
	v_rsq_f32_e32 v255, v247
	s_branch .Lds_P1_b_done

.Lds_P1_b_done:
	s_barrier
	s_nop 0
	v_mfma_f32_16x16x32_bf16 v[48:51], v[200:203], v[168:171], v[48:51]
	v_mfma_f32_16x16x32_bf16 v[40:43], v[210:213], v[168:171], v[40:43]
	v_mfma_f32_16x16x32_bf16 v[32:35], v[200:203], v[176:179], v[32:35]
	v_mfma_f32_16x16x32_bf16 v[24:27], v[210:213], v[176:179], v[24:27]
	v_mfma_f32_16x16x32_bf16 v[16:19], v[200:203], v[184:187], v[16:19]
	v_mfma_f32_16x16x32_bf16 v[8:11], v[210:213], v[184:187], v[8:11]
	v_mfma_f32_16x16x32_bf16 v[4:7], v[200:203], v[192:195], v[4:7]
	v_mfma_f32_16x16x32_bf16 v[0:3], v[210:213], v[192:195], v[0:3]
	v_mfma_f32_16x16x32_bf16 v[48:51], v[206:209], v[172:175], v[48:51]
	v_mfma_f32_16x16x32_bf16 v[40:43], v[214:217], v[172:175], v[40:43]
	v_mfma_f32_16x16x32_bf16 v[32:35], v[206:209], v[180:183], v[32:35]
	v_mfma_f32_16x16x32_bf16 v[24:27], v[214:217], v[180:183], v[24:27]
	v_mfma_f32_16x16x32_bf16 v[16:19], v[206:209], v[188:191], v[16:19]
	v_mfma_f32_16x16x32_bf16 v[8:11], v[214:217], v[188:191], v[8:11]
	v_mfma_f32_16x16x32_bf16 v[4:7], v[206:209], v[196:199], v[4:7]
	v_mfma_f32_16x16x32_bf16 v[0:3], v[214:217], v[196:199], v[0:3]
	s_nop 0
	s_add_i32 s68, s68, 2
	s_add_u32 s8, s8, 0x100
	s_addc_u32 s9, s9, 0
	s_add_u32 s66, s66, 0x100
	s_addc_u32 s67, s67, 0
	s_cmp_gt_u32 s68, 13
	s_barrier
	s_cbranch_scc0 .LBB0_159

.LBB0_252:
	v_writelane_b32 v238, s76, 3
	s_nop 1
	v_writelane_b32 v238, s77, 4
	v_writelane_b32 v238, s74, 5
	s_nop 1
	v_writelane_b32 v238, s75, 6
	s_or_b64 exec, exec, s[4:5]
	s_and_b32 s93, s97, 1
	s_cmpk_lt_i32 s97, 0x1000
	s_cselect_b64 s[4:5], -1, 0
	s_and_b32 s8, s97, 7
	s_lshl_b32 s3, s97, 6
	s_lshl_b32 s95, s8, 6
	s_and_b32 s96, s3, 0x1c0
	s_and_b32 s20, s94, 0xfc0
	s_and_b32 s21, s94, 0xfffff000
	s_cmpk_lt_i32 s97, 0x800
	s_cselect_b64 s[28:29], -1, 0
	s_ashr_i32 s6, s97, 8
	s_mov_b64 s[0:1], s[86:87]
	s_ashr_i32 s7, s6, 31
	s_waitcnt lgkmcnt(0)
	s_barrier
	s_setprio 0
	s_mov_b32 s27, 0
	v_writelane_b32 v238, s6, 7
	s_load_dwordx4 s[12:15], s[0:1], 0x40
	s_load_dwordx2 s[18:19], s[0:1], 0x58
	s_load_dwordx2 s[24:25], s[0:1], 0x68
	s_load_dwordx2 s[16:17], s[0:1], 0xb8
	v_writelane_b32 v238, s7, 8
	s_lshl_b64 s[40:41], s[6:7], 12
	s_and_b32 s6, s3, 0xfc0
	s_mov_b32 s7, s27
	v_writelane_b32 v238, s6, 9
	s_lshl_b32 s0, s97, 1
	s_or_b32 s40, s40, s6
	v_writelane_b32 v238, s7, 10
	v_writelane_b32 v238, s0, 11
	s_and_b32 s0, s0, 0x180
	s_and_b32 s2, s22, 7
	s_cmp_lg_u32 s2, 0
	s_cselect_b64 s[30:31], -1, 0
	s_waitcnt lgkmcnt(0)
	s_add_u32 s36, s16, 0x32a0800
	s_addc_u32 s37, s17, 0
	s_add_u32 s38, s12, 0x1000
	s_addc_u32 s39, s13, 0
	s_add_u32 s48, s12, 0x1800
	s_addc_u32 s49, s13, 0
	s_add_u32 s50, s16, 0x3300000
	s_addc_u32 s51, s17, 0
	s_lshl_b32 s2, s8, 8
	s_add_u32 s52, s36, s2
	s_addc_u32 s53, s37, 0
	s_add_u32 s54, s16, 0x7a00000
	s_addc_u32 s55, s17, 0
	s_add_u32 s56, s16, 0x3600000
	s_addc_u32 s57, s17, 0
	s_add_u32 s58, s16, 0x3400000
	s_addc_u32 s59, s17, 0
	s_add_u32 s33, s16, 0x32a0000
	s_addc_u32 s34, s17, 0
	s_add_u32 s35, s16, 0x15a00000
	s_addc_u32 s42, s17, 0
	s_add_u32 s43, s16, 0x3800000
	s_addc_u32 s44, s17, 0
	s_lshl_b32 s2, s0, 1
	s_add_u32 s60, s54, s2
	s_movk_i32 s1, 0x1000
	s_addc_u32 s61, s55, 0
	s_lshl_b32 s88, s22, 7
	s_lshl_b32 s47, s22, 4
	s_lshl_b32 s89, s22, 1
	s_lshl_b32 s90, s22, 6
	s_lshl_b32 s83, s22, 3
	s_lshl_b32 s91, s22, 2
	s_mov_b64 s[62:63], -1
	v_cndmask_b32_e64 v124, 0, 1, s[4:5]
	v_mov_b32_e32 v1, 0
	s_movk_i32 s45, 0x100
	s_movk_i32 s46, 0x1c00
	s_movk_i32 s67, 0xff90
	s_add_i32 s73, 0, 0x6400
	s_movk_i32 s74, 0x80
	s_mov_b32 s75, 0xbe99999a
	v_mov_b32_e32 v125, 0x3d2aaaab
	s_mov_b64 s[64:65], 0xc00
	s_movk_i32 s76, 0x120
	s_add_i32 s92, 0, 0x20000
	s_mov_b32 s66, 0x3f317218
	v_mov_b32_e32 v126, 0x4000
	s_mov_b32 s2, 0
	v_writelane_b32 v238, s8, 12
	s_branch .LBB0_254

.LBB0_882:
	s_or_b64 exec, exec, s[4:5]
	v_readlane_b32 s4, v238, 16
	v_readlane_b32 s5, v238, 17
	s_waitcnt lgkmcnt(0)
	s_barrier
	v_readfirstlane_b32 s101, v204
	s_nop 3
	s_lshr_b32 s101, s101, 6
	s_cmp_ge_u32 s101, 4
	s_cbranch_scc0 .Lprio_1
	s_setprio 1
.Lprio_1:
	s_load_dwordx2 s[10:11], s[4:5], 0x0
	s_waitcnt vmcnt(4)
	v_mov_b32_e32 v8, v204
	s_cmpk_lt_i32 s97, 0x200
	s_cselect_b64 s[6:7], -1, 0
	s_cmpk_gt_i32 s97, 0x1ff
	v_readfirstlane_b32 s0, v8
	s_cbranch_scc1 .LBB0_888
	s_ashr_i32 s1, s97, 31
	s_lshr_b32 s1, s1, 29
	s_add_i32 s1, s97, s1
	s_and_b32 s2, s1, -8
	s_sub_i32 s2, s97, s2
	s_cmp_gt_i32 s2, -1
	s_cbranch_scc0 .LBB0_885
	s_lshl_b32 s12, s2, 6
	s_cbranch_execz .LBB0_886
	s_branch .LBB0_887

.LBB0_899:
	s_ashr_i32 s31, s30, 31
	v_cmp_lt_i64_e32 vcc, s[36:37], v[188:189]
	s_lshl_b64 s[36:37], s[30:31], 19
	s_add_u32 s36, s12, s36
	s_addc_u32 s37, s13, s37
	s_and_b64 s[38:39], vcc, exec
	s_cselect_b32 s31, s37, s55
	s_cselect_b32 s51, s36, s54
	s_ashr_i32 s27, s26, 31
	s_lshl_b64 s[38:39], s[26:27], 19
	s_add_u32 s38, s1, s38
	s_addc_u32 s39, s2, s39
	s_and_b64 s[58:59], vcc, exec
	s_cselect_b32 s27, s39, s57
	s_cselect_b32 s53, s38, s56
	s_add_u32 s54, s54, 0x40080
	s_addc_u32 s55, s55, 0
	s_add_u32 s60, s56, 0x100

	s_addc_u32 s61, s57, 0
	s_mov_b32 s62, -2
	s_waitcnt lgkmcnt(0)


	ds_read_b128 v[128:131], v209
	ds_read_b128 v[132:135], v209 offset:1024
	ds_read_b128 v[136:139], v209 offset:2048
	ds_read_b128 v[140:143], v209 offset:3072
	s_add_u32 s56, s54, 0xfffc0080
	s_addc_u32 s57, s55, -1
	s_cmp_eq_u32 s62, 12
	s_cselect_b32 s59, s31, s57
	s_cselect_b32 s58, s51, s56
	s_cselect_b32 s57, s27, s61
	s_cselect_b32 s56, s53, s60
	v_lshl_add_u64 v[192:193], s[54:55], 0, v[184:185]
	s_add_i32 m0, s21, 0xc000
	ds_read_b128 v[144:147], v210
	ds_read_b128 v[148:151], v210 offset:1024
	ds_read_b128 v[152:155], v210 offset:2048
	ds_read_b128 v[156:159], v210 offset:3072
	ds_read_b128 v[160:163], v210 offset:4096
	ds_read_b128 v[164:167], v210 offset:5120
	ds_read_b128 v[168:171], v210 offset:6144
	ds_read_b128 v[172:175], v210 offset:7168
	global_load_lds_dwordx4 v[192:193], off
	v_lshl_add_u64 v[192:193], s[54:55], 0, v[186:187]
	s_add_i32 m0, s21, 0xe000
	s_nop 0
	global_load_lds_dwordx4 v[192:193], off
	s_waitcnt lgkmcnt(8)
	s_barrier
	s_waitcnt lgkmcnt(0)
	s_nop 0
	s_waitcnt lgkmcnt(0)
	v_mfma_f32_16x16x32_bf16 v[124:127], v[128:131], v[144:147], 0
	v_mfma_f32_16x16x32_bf16 v[120:123], v[136:139], v[144:147], 0
	v_mfma_f32_16x16x32_bf16 v[108:111], v[128:131], v[152:155], 0
	v_mfma_f32_16x16x32_bf16 v[104:107], v[136:139], v[152:155], 0
	v_mfma_f32_16x16x32_bf16 v[92:95], v[128:131], v[160:163], 0
	v_mfma_f32_16x16x32_bf16 v[88:91], v[136:139], v[160:163], 0
	v_mfma_f32_16x16x32_bf16 v[76:79], v[128:131], v[168:171], 0
	v_mfma_f32_16x16x32_bf16 v[72:75], v[136:139], v[168:171], 0
	v_mfma_f32_16x16x32_bf16 v[124:127], v[132:135], v[148:151], v[124:127]
	v_mfma_f32_16x16x32_bf16 v[120:123], v[140:143], v[148:151], v[120:123]
	v_mfma_f32_16x16x32_bf16 v[108:111], v[132:135], v[156:159], v[108:111]
	v_mfma_f32_16x16x32_bf16 v[104:107], v[140:143], v[156:159], v[104:107]
	v_mfma_f32_16x16x32_bf16 v[92:95], v[132:135], v[164:167], v[92:95]
	v_mfma_f32_16x16x32_bf16 v[88:91], v[140:143], v[164:167], v[88:91]
	v_mfma_f32_16x16x32_bf16 v[76:79], v[132:135], v[172:175], v[76:79]
	v_mfma_f32_16x16x32_bf16 v[72:75], v[140:143], v[172:175], v[72:75]
	s_nop 0
	s_barrier
	s_add_i32 s63, s48, s20
	v_lshl_add_u64 v[216:217], s[56:57], 0, v[178:179]
	s_mov_b32 m0, s63
	ds_read_b128 v[192:195], v211
	ds_read_b128 v[196:199], v211 offset:1024
	ds_read_b128 v[200:203], v211 offset:2048
	ds_read_b128 v[212:215], v211 offset:3072
	global_load_lds_dwordx4 v[216:217], off
	v_lshl_add_u64 v[218:219], s[56:57], 0, v[182:183]
	s_add_i32 m0, s63, 0x2000
	s_nop 0
	global_load_lds_dwordx4 v[218:219], off
	s_barrier
	s_waitcnt lgkmcnt(0)
	s_nop 0
	s_waitcnt lgkmcnt(0)
	v_mfma_f32_16x16x32_bf16 v[116:119], v[192:195], v[144:147], 0
	v_mfma_f32_16x16x32_bf16 v[112:115], v[200:203], v[144:147], 0
	v_mfma_f32_16x16x32_bf16 v[100:103], v[192:195], v[152:155], 0
	v_mfma_f32_16x16x32_bf16 v[96:99], v[200:203], v[152:155], 0
	v_mfma_f32_16x16x32_bf16 v[84:87], v[192:195], v[160:163], 0
	v_mfma_f32_16x16x32_bf16 v[80:83], v[200:203], v[160:163], 0
	v_mfma_f32_16x16x32_bf16 v[68:71], v[192:195], v[168:171], 0
	v_mfma_f32_16x16x32_bf16 v[64:67], v[200:203], v[168:171], 0
	v_mfma_f32_16x16x32_bf16 v[116:119], v[196:199], v[148:151], v[116:119]
	v_mfma_f32_16x16x32_bf16 v[112:115], v[212:215], v[148:151], v[112:115]
	v_mfma_f32_16x16x32_bf16 v[100:103], v[196:199], v[156:159], v[100:103]
	v_mfma_f32_16x16x32_bf16 v[96:99], v[212:215], v[156:159], v[96:99]
	v_mfma_f32_16x16x32_bf16 v[84:87], v[196:199], v[164:167], v[84:87]
	v_mfma_f32_16x16x32_bf16 v[80:83], v[212:215], v[164:167], v[80:83]
	v_mfma_f32_16x16x32_bf16 v[68:71], v[196:199], v[172:175], v[68:71]
	v_mfma_f32_16x16x32_bf16 v[64:67], v[212:215], v[172:175], v[64:67]
	s_nop 0
	s_mov_b32 m0, s21
	v_lshl_add_u64 v[220:221], s[58:59], 0, v[176:177]
	s_barrier
	ds_read_b128 v[144:147], v210 offset:16384
	ds_read_b128 v[148:151], v210 offset:17408
	ds_read_b128 v[152:155], v210 offset:18432
	ds_read_b128 v[156:159], v210 offset:19456
	ds_read_b128 v[160:163], v210 offset:20480
	ds_read_b128 v[164:167], v210 offset:21504
	ds_read_b128 v[168:171], v210 offset:22528
	ds_read_b128 v[172:175], v210 offset:23552
	global_load_lds_dwordx4 v[220:221], off
	v_lshl_add_u64 v[222:223], s[58:59], 0, v[180:181]
	s_mov_b32 m0, s33
	s_nop 0
	global_load_lds_dwordx4 v[222:223], off
	s_barrier
	s_waitcnt lgkmcnt(0)
	s_nop 0
	s_waitcnt lgkmcnt(0)
	v_mfma_f32_16x16x32_bf16 v[60:63], v[128:131], v[144:147], 0
	v_mfma_f32_16x16x32_bf16 v[56:59], v[136:139], v[144:147], 0
	v_mfma_f32_16x16x32_bf16 v[44:47], v[128:131], v[152:155], 0
	v_mfma_f32_16x16x32_bf16 v[40:43], v[136:139], v[152:155], 0
	v_mfma_f32_16x16x32_bf16 v[28:31], v[128:131], v[160:163], 0
	v_mfma_f32_16x16x32_bf16 v[24:27], v[136:139], v[160:163], 0
	v_mfma_f32_16x16x32_bf16 v[12:15], v[128:131], v[168:171], 0
	v_mfma_f32_16x16x32_bf16 v[8:11], v[136:139], v[168:171], 0
	v_mfma_f32_16x16x32_bf16 v[60:63], v[132:135], v[148:151], v[60:63]
	v_mfma_f32_16x16x32_bf16 v[56:59], v[140:143], v[148:151], v[56:59]
	v_mfma_f32_16x16x32_bf16 v[44:47], v[132:135], v[156:159], v[44:47]
	v_mfma_f32_16x16x32_bf16 v[40:43], v[140:143], v[156:159], v[40:43]
	v_mfma_f32_16x16x32_bf16 v[28:31], v[132:135], v[164:167], v[28:31]
	v_mfma_f32_16x16x32_bf16 v[24:27], v[140:143], v[164:167], v[24:27]
	v_mfma_f32_16x16x32_bf16 v[12:15], v[132:135], v[172:175], v[12:15]
	v_mfma_f32_16x16x32_bf16 v[8:11], v[140:143], v[172:175], v[8:11]
	s_nop 0
	s_barrier
	s_add_u32 s64, s56, 0x40000
	s_addc_u32 s65, s57, 0
	s_add_i32 s63, s49, s20
	v_lshl_add_u64 v[128:129], s[64:65], 0, v[178:179]
	s_mov_b32 m0, s63
	s_nop 0
	global_load_lds_dwordx4 v[128:129], off
	v_lshl_add_u64 v[128:129], s[64:65], 0, v[182:183]
	s_add_i32 m0, s63, 0x2000
	s_nop 0
	global_load_lds_dwordx4 v[128:129], off
	s_waitcnt vmcnt(6)
	s_barrier
	s_nop 0
	v_mfma_f32_16x16x32_bf16 v[52:55], v[192:195], v[144:147], 0
	v_mfma_f32_16x16x32_bf16 v[48:51], v[200:203], v[144:147], 0
	v_mfma_f32_16x16x32_bf16 v[36:39], v[192:195], v[152:155], 0
	v_mfma_f32_16x16x32_bf16 v[32:35], v[200:203], v[152:155], 0
	v_mfma_f32_16x16x32_bf16 v[20:23], v[192:195], v[160:163], 0
	v_mfma_f32_16x16x32_bf16 v[16:19], v[200:203], v[160:163], 0
	v_mfma_f32_16x16x32_bf16 v[4:7], v[192:195], v[168:171], 0
	v_mfma_f32_16x16x32_bf16 v[0:3], v[200:203], v[168:171], 0
	v_mfma_f32_16x16x32_bf16 v[52:55], v[196:199], v[148:151], v[52:55]
	v_mfma_f32_16x16x32_bf16 v[48:51], v[212:215], v[148:151], v[48:51]
	v_mfma_f32_16x16x32_bf16 v[36:39], v[196:199], v[156:159], v[36:39]
	v_mfma_f32_16x16x32_bf16 v[32:35], v[212:215], v[156:159], v[32:35]
	v_mfma_f32_16x16x32_bf16 v[20:23], v[196:199], v[164:167], v[20:23]
	v_mfma_f32_16x16x32_bf16 v[16:19], v[212:215], v[164:167], v[16:19]
	v_mfma_f32_16x16x32_bf16 v[4:7], v[196:199], v[172:175], v[4:7]
	v_mfma_f32_16x16x32_bf16 v[0:3], v[212:215], v[172:175], v[0:3]
	s_nop 0
	s_add_i32 s63, 0, 0x18000
	v_add_u32_e32 v140, s63, v207
	s_barrier
	ds_read_b128 v[128:131], v140
	ds_read_b128 v[132:135], v140 offset:1024
	ds_read_b128 v[136:139], v140 offset:2048
	ds_read_b128 v[140:143], v140 offset:3072
	s_add_u32 s58, s58, 0x40000
	s_addc_u32 s59, s59, 0
	s_mov_b32 m0, s34
	v_lshl_add_u64 v[192:193], s[58:59], 0, v[176:177]
	ds_read_b128 v[144:147], v210 offset:32768
	ds_read_b128 v[148:151], v210 offset:33792
	ds_read_b128 v[152:155], v210 offset:34816
	ds_read_b128 v[156:159], v210 offset:35840
	ds_read_b128 v[160:163], v210 offset:36864
	ds_read_b128 v[164:167], v210 offset:37888
	ds_read_b128 v[168:171], v210 offset:38912
	ds_read_b128 v[172:175], v210 offset:39936
	global_load_lds_dwordx4 v[192:193], off
	v_lshl_add_u64 v[192:193], s[58:59], 0, v[180:181]
	s_mov_b32 m0, s35
	s_nop 0
	global_load_lds_dwordx4 v[192:193], off
	s_waitcnt lgkmcnt(8)
	s_barrier
	s_waitcnt lgkmcnt(0)
	s_nop 0
	s_waitcnt lgkmcnt(0)
	v_mfma_f32_16x16x32_bf16 v[124:127], v[128:131], v[144:147], v[124:127]
	v_mfma_f32_16x16x32_bf16 v[120:123], v[136:139], v[144:147], v[120:123]
	v_mfma_f32_16x16x32_bf16 v[108:111], v[128:131], v[152:155], v[108:111]
	v_mfma_f32_16x16x32_bf16 v[104:107], v[136:139], v[152:155], v[104:107]
	v_mfma_f32_16x16x32_bf16 v[92:95], v[128:131], v[160:163], v[92:95]
	v_mfma_f32_16x16x32_bf16 v[88:91], v[136:139], v[160:163], v[88:91]
	v_mfma_f32_16x16x32_bf16 v[76:79], v[128:131], v[168:171], v[76:79]
	v_mfma_f32_16x16x32_bf16 v[72:75], v[136:139], v[168:171], v[72:75]
	v_mfma_f32_16x16x32_bf16 v[124:127], v[132:135], v[148:151], v[124:127]
	v_mfma_f32_16x16x32_bf16 v[120:123], v[140:143], v[148:151], v[120:123]
	v_mfma_f32_16x16x32_bf16 v[108:111], v[132:135], v[156:159], v[108:111]
	v_mfma_f32_16x16x32_bf16 v[104:107], v[140:143], v[156:159], v[104:107]
	v_mfma_f32_16x16x32_bf16 v[92:95], v[132:135], v[164:167], v[92:95]
	v_mfma_f32_16x16x32_bf16 v[88:91], v[140:143], v[164:167], v[88:91]
	v_mfma_f32_16x16x32_bf16 v[76:79], v[132:135], v[172:175], v[76:79]
	v_mfma_f32_16x16x32_bf16 v[72:75], v[140:143], v[172:175], v[72:75]
	s_nop 0
	s_barrier
	s_add_i32 s58, 0, 0x1c000
	s_add_i32 s59, s63, s20
	v_add_u32_e32 v212, s58, v207
	v_lshl_add_u64 v[216:217], v[216:217], 0, s[24:25]
	s_mov_b32 m0, s59
	ds_read_b128 v[192:195], v212
	ds_read_b128 v[196:199], v212 offset:1024
	ds_read_b128 v[200:203], v212 offset:2048
	ds_read_b128 v[212:215], v212 offset:3072
	global_load_lds_dwordx4 v[216:217], off
	v_lshl_add_u64 v[216:217], v[218:219], 0, s[24:25]
	s_add_i32 m0, s59, 0x2000
	s_nop 0
	global_load_lds_dwordx4 v[216:217], off
	s_barrier
	s_waitcnt lgkmcnt(0)
	s_nop 0
	s_waitcnt lgkmcnt(0)
	v_mfma_f32_16x16x32_bf16 v[116:119], v[192:195], v[144:147], v[116:119]
	v_mfma_f32_16x16x32_bf16 v[112:115], v[200:203], v[144:147], v[112:115]
	v_mfma_f32_16x16x32_bf16 v[100:103], v[192:195], v[152:155], v[100:103]
	v_mfma_f32_16x16x32_bf16 v[96:99], v[200:203], v[152:155], v[96:99]
	v_mfma_f32_16x16x32_bf16 v[84:87], v[192:195], v[160:163], v[84:87]
	v_mfma_f32_16x16x32_bf16 v[80:83], v[200:203], v[160:163], v[80:83]
	v_mfma_f32_16x16x32_bf16 v[68:71], v[192:195], v[168:171], v[68:71]
	v_mfma_f32_16x16x32_bf16 v[64:67], v[200:203], v[168:171], v[64:67]
	v_mfma_f32_16x16x32_bf16 v[116:119], v[196:199], v[148:151], v[116:119]
	v_mfma_f32_16x16x32_bf16 v[112:115], v[212:215], v[148:151], v[112:115]
	v_mfma_f32_16x16x32_bf16 v[100:103], v[196:199], v[156:159], v[100:103]
	v_mfma_f32_16x16x32_bf16 v[96:99], v[212:215], v[156:159], v[96:99]
	v_mfma_f32_16x16x32_bf16 v[84:87], v[196:199], v[164:167], v[84:87]
	v_mfma_f32_16x16x32_bf16 v[80:83], v[212:215], v[164:167], v[80:83]
	v_mfma_f32_16x16x32_bf16 v[68:71], v[196:199], v[172:175], v[68:71]
	v_mfma_f32_16x16x32_bf16 v[64:67], v[212:215], v[172:175], v[64:67]
	s_nop 0
	s_mov_b32 m0, s43
	v_lshl_add_u64 v[216:217], v[220:221], 0, s[24:25]
	s_barrier
	ds_read_b128 v[144:147], v210 offset:49152
	ds_read_b128 v[148:151], v210 offset:50176
	ds_read_b128 v[152:155], v210 offset:51200
	ds_read_b128 v[156:159], v210 offset:52224
	ds_read_b128 v[160:163], v210 offset:53248
	ds_read_b128 v[164:167], v210 offset:54272
	ds_read_b128 v[168:171], v210 offset:55296
	ds_read_b128 v[172:175], v210 offset:56320
	global_load_lds_dwordx4 v[216:217], off
	v_lshl_add_u64 v[216:217], v[222:223], 0, s[24:25]
	s_mov_b32 m0, s44
	s_nop 0
	global_load_lds_dwordx4 v[216:217], off
	s_barrier
	s_waitcnt lgkmcnt(0)
	s_nop 0
	s_waitcnt lgkmcnt(0)
	v_mfma_f32_16x16x32_bf16 v[60:63], v[128:131], v[144:147], v[60:63]
	v_mfma_f32_16x16x32_bf16 v[56:59], v[136:139], v[144:147], v[56:59]
	v_mfma_f32_16x16x32_bf16 v[44:47], v[128:131], v[152:155], v[44:47]
	v_mfma_f32_16x16x32_bf16 v[40:43], v[136:139], v[152:155], v[40:43]
	v_mfma_f32_16x16x32_bf16 v[28:31], v[128:131], v[160:163], v[28:31]
	v_mfma_f32_16x16x32_bf16 v[24:27], v[136:139], v[160:163], v[24:27]
	v_mfma_f32_16x16x32_bf16 v[12:15], v[128:131], v[168:171], v[12:15]
	v_mfma_f32_16x16x32_bf16 v[8:11], v[136:139], v[168:171], v[8:11]
	v_mfma_f32_16x16x32_bf16 v[60:63], v[132:135], v[148:151], v[60:63]
	v_mfma_f32_16x16x32_bf16 v[56:59], v[140:143], v[148:151], v[56:59]
	v_mfma_f32_16x16x32_bf16 v[44:47], v[132:135], v[156:159], v[44:47]
	v_mfma_f32_16x16x32_bf16 v[40:43], v[140:143], v[156:159], v[40:43]
	v_mfma_f32_16x16x32_bf16 v[28:31], v[132:135], v[164:167], v[28:31]
	v_mfma_f32_16x16x32_bf16 v[24:27], v[140:143], v[164:167], v[24:27]
	v_mfma_f32_16x16x32_bf16 v[12:15], v[132:135], v[172:175], v[12:15]
	v_mfma_f32_16x16x32_bf16 v[8:11], v[140:143], v[172:175], v[8:11]
	s_nop 0
	s_barrier
	s_add_u32 s56, s56, 0x40080
	s_addc_u32 s57, s57, 0
	s_add_i32 s58, s58, s20
	v_lshl_add_u64 v[128:129], s[56:57], 0, v[178:179]
	s_mov_b32 m0, s58
	s_nop 0
	global_load_lds_dwordx4 v[128:129], off
	v_lshl_add_u64 v[128:129], s[56:57], 0, v[182:183]
	s_add_i32 m0, s58, 0x2000
	s_nop 0
	global_load_lds_dwordx4 v[128:129], off
	s_waitcnt vmcnt(6)
	s_barrier
	s_nop 0
	v_mfma_f32_16x16x32_bf16 v[52:55], v[192:195], v[144:147], v[52:55]
	v_mfma_f32_16x16x32_bf16 v[48:51], v[200:203], v[144:147], v[48:51]
	v_mfma_f32_16x16x32_bf16 v[36:39], v[192:195], v[152:155], v[36:39]
	v_mfma_f32_16x16x32_bf16 v[32:35], v[200:203], v[152:155], v[32:35]
	v_mfma_f32_16x16x32_bf16 v[20:23], v[192:195], v[160:163], v[20:23]
	v_mfma_f32_16x16x32_bf16 v[16:19], v[200:203], v[160:163], v[16:19]
	v_mfma_f32_16x16x32_bf16 v[4:7], v[192:195], v[168:171], v[4:7]
	v_mfma_f32_16x16x32_bf16 v[0:3], v[200:203], v[168:171], v[0:3]
	v_mfma_f32_16x16x32_bf16 v[52:55], v[196:199], v[148:151], v[52:55]
	v_mfma_f32_16x16x32_bf16 v[48:51], v[212:215], v[148:151], v[48:51]
	v_mfma_f32_16x16x32_bf16 v[36:39], v[196:199], v[156:159], v[36:39]
	v_mfma_f32_16x16x32_bf16 v[32:35], v[212:215], v[156:159], v[32:35]
	v_mfma_f32_16x16x32_bf16 v[20:23], v[196:199], v[164:167], v[20:23]
	v_mfma_f32_16x16x32_bf16 v[16:19], v[212:215], v[164:167], v[16:19]
	v_mfma_f32_16x16x32_bf16 v[4:7], v[196:199], v[172:175], v[4:7]
	v_mfma_f32_16x16x32_bf16 v[0:3], v[212:215], v[172:175], v[0:3]
	s_nop 0
	s_add_i32 s62, s62, 2
	s_add_u32 s54, s54, 0x100
	s_addc_u32 s55, s55, 0
	s_add_u32 s60, s60, 0x100
	s_addc_u32 s61, s61, 0
	s_cmp_gt_u32 s62, 13
	s_barrier
.LBB0_900:
	ds_read_b128 v[128:131], v209
	ds_read_b128 v[132:135], v209 offset:1024
	ds_read_b128 v[136:139], v209 offset:2048
	ds_read_b128 v[140:143], v209 offset:3072
	s_add_u32 s56, s54, 0xfffc0080
	s_addc_u32 s57, s55, -1
	s_cmp_eq_u32 s62, 12
	s_cselect_b32 s59, s31, s57
	s_cselect_b32 s58, s51, s56
	s_cselect_b32 s57, s27, s61
	s_cselect_b32 s56, s53, s60
	v_lshl_add_u64 v[192:193], s[54:55], 0, v[184:185]
	s_add_i32 m0, s21, 0xc000
	ds_read_b128 v[144:147], v210
	ds_read_b128 v[148:151], v210 offset:1024
	ds_read_b128 v[152:155], v210 offset:2048
	ds_read_b128 v[156:159], v210 offset:3072
	ds_read_b128 v[160:163], v210 offset:4096
	ds_read_b128 v[164:167], v210 offset:5120
	ds_read_b128 v[168:171], v210 offset:6144
	ds_read_b128 v[172:175], v210 offset:7168
	global_load_lds_dwordx4 v[192:193], off
	v_lshl_add_u64 v[192:193], s[54:55], 0, v[186:187]
	s_add_i32 m0, s21, 0xe000
	s_nop 0
	global_load_lds_dwordx4 v[192:193], off
	s_waitcnt lgkmcnt(8)
	s_barrier
	s_waitcnt lgkmcnt(0)
	s_nop 0
	s_waitcnt lgkmcnt(0)
	v_mfma_f32_16x16x32_bf16 v[124:127], v[128:131], v[144:147], v[124:127]
	v_mfma_f32_16x16x32_bf16 v[120:123], v[136:139], v[144:147], v[120:123]
	v_mfma_f32_16x16x32_bf16 v[108:111], v[128:131], v[152:155], v[108:111]
	v_mfma_f32_16x16x32_bf16 v[104:107], v[136:139], v[152:155], v[104:107]
	v_mfma_f32_16x16x32_bf16 v[92:95], v[128:131], v[160:163], v[92:95]
	v_mfma_f32_16x16x32_bf16 v[88:91], v[136:139], v[160:163], v[88:91]
	v_mfma_f32_16x16x32_bf16 v[76:79], v[128:131], v[168:171], v[76:79]
	v_mfma_f32_16x16x32_bf16 v[72:75], v[136:139], v[168:171], v[72:75]
	v_mfma_f32_16x16x32_bf16 v[124:127], v[132:135], v[148:151], v[124:127]
	v_mfma_f32_16x16x32_bf16 v[120:123], v[140:143], v[148:151], v[120:123]
	v_mfma_f32_16x16x32_bf16 v[108:111], v[132:135], v[156:159], v[108:111]
	v_mfma_f32_16x16x32_bf16 v[104:107], v[140:143], v[156:159], v[104:107]
	v_mfma_f32_16x16x32_bf16 v[92:95], v[132:135], v[164:167], v[92:95]
	v_mfma_f32_16x16x32_bf16 v[88:91], v[140:143], v[164:167], v[88:91]
	v_mfma_f32_16x16x32_bf16 v[76:79], v[132:135], v[172:175], v[76:79]
	v_mfma_f32_16x16x32_bf16 v[72:75], v[140:143], v[172:175], v[72:75]
	s_nop 0
	s_barrier
	s_add_i32 s63, s48, s20
	v_lshl_add_u64 v[216:217], s[56:57], 0, v[178:179]
	s_mov_b32 m0, s63
	ds_read_b128 v[192:195], v211
	ds_read_b128 v[196:199], v211 offset:1024
	ds_read_b128 v[200:203], v211 offset:2048
	ds_read_b128 v[212:215], v211 offset:3072
	global_load_lds_dwordx4 v[216:217], off
	v_lshl_add_u64 v[218:219], s[56:57], 0, v[182:183]
	s_add_i32 m0, s63, 0x2000
	s_nop 0
	global_load_lds_dwordx4 v[218:219], off
	s_barrier
	s_waitcnt lgkmcnt(0)
	s_nop 0
	s_waitcnt lgkmcnt(0)
	v_mfma_f32_16x16x32_bf16 v[116:119], v[192:195], v[144:147], v[116:119]
	v_mfma_f32_16x16x32_bf16 v[112:115], v[200:203], v[144:147], v[112:115]
	v_mfma_f32_16x16x32_bf16 v[100:103], v[192:195], v[152:155], v[100:103]
	v_mfma_f32_16x16x32_bf16 v[96:99], v[200:203], v[152:155], v[96:99]
	v_mfma_f32_16x16x32_bf16 v[84:87], v[192:195], v[160:163], v[84:87]
	v_mfma_f32_16x16x32_bf16 v[80:83], v[200:203], v[160:163], v[80:83]
	v_mfma_f32_16x16x32_bf16 v[68:71], v[192:195], v[168:171], v[68:71]
	v_mfma_f32_16x16x32_bf16 v[64:67], v[200:203], v[168:171], v[64:67]
	v_mfma_f32_16x16x32_bf16 v[116:119], v[196:199], v[148:151], v[116:119]
	v_mfma_f32_16x16x32_bf16 v[112:115], v[212:215], v[148:151], v[112:115]
	v_mfma_f32_16x16x32_bf16 v[100:103], v[196:199], v[156:159], v[100:103]
	v_mfma_f32_16x16x32_bf16 v[96:99], v[212:215], v[156:159], v[96:99]
	v_mfma_f32_16x16x32_bf16 v[84:87], v[196:199], v[164:167], v[84:87]
	v_mfma_f32_16x16x32_bf16 v[80:83], v[212:215], v[164:167], v[80:83]
	v_mfma_f32_16x16x32_bf16 v[68:71], v[196:199], v[172:175], v[68:71]
	v_mfma_f32_16x16x32_bf16 v[64:67], v[212:215], v[172:175], v[64:67]
	s_nop 0
	s_mov_b32 m0, s21
	v_lshl_add_u64 v[220:221], s[58:59], 0, v[176:177]
	s_barrier
	ds_read_b128 v[144:147], v210 offset:16384
	ds_read_b128 v[148:151], v210 offset:17408
	ds_read_b128 v[152:155], v210 offset:18432
	ds_read_b128 v[156:159], v210 offset:19456
	ds_read_b128 v[160:163], v210 offset:20480
	ds_read_b128 v[164:167], v210 offset:21504
	ds_read_b128 v[168:171], v210 offset:22528
	ds_read_b128 v[172:175], v210 offset:23552
	global_load_lds_dwordx4 v[220:221], off
	v_lshl_add_u64 v[222:223], s[58:59], 0, v[180:181]
	s_mov_b32 m0, s33
	s_nop 0
	global_load_lds_dwordx4 v[222:223], off
	s_barrier
	s_waitcnt lgkmcnt(0)
	s_nop 0
	s_waitcnt lgkmcnt(0)
	v_mfma_f32_16x16x32_bf16 v[60:63], v[128:131], v[144:147], v[60:63]
	v_mfma_f32_16x16x32_bf16 v[56:59], v[136:139], v[144:147], v[56:59]
	v_mfma_f32_16x16x32_bf16 v[44:47], v[128:131], v[152:155], v[44:47]
	v_mfma_f32_16x16x32_bf16 v[40:43], v[136:139], v[152:155], v[40:43]
	v_mfma_f32_16x16x32_bf16 v[28:31], v[128:131], v[160:163], v[28:31]
	v_mfma_f32_16x16x32_bf16 v[24:27], v[136:139], v[160:163], v[24:27]
	v_mfma_f32_16x16x32_bf16 v[12:15], v[128:131], v[168:171], v[12:15]
	v_mfma_f32_16x16x32_bf16 v[8:11], v[136:139], v[168:171], v[8:11]
	v_mfma_f32_16x16x32_bf16 v[60:63], v[132:135], v[148:151], v[60:63]
	v_mfma_f32_16x16x32_bf16 v[56:59], v[140:143], v[148:151], v[56:59]
	v_mfma_f32_16x16x32_bf16 v[44:47], v[132:135], v[156:159], v[44:47]
	v_mfma_f32_16x16x32_bf16 v[40:43], v[140:143], v[156:159], v[40:43]
	v_mfma_f32_16x16x32_bf16 v[28:31], v[132:135], v[164:167], v[28:31]
	v_mfma_f32_16x16x32_bf16 v[24:27], v[140:143], v[164:167], v[24:27]
	v_mfma_f32_16x16x32_bf16 v[12:15], v[132:135], v[172:175], v[12:15]
	v_mfma_f32_16x16x32_bf16 v[8:11], v[140:143], v[172:175], v[8:11]
	s_nop 0
	s_barrier
	s_add_u32 s64, s56, 0x40000
	s_addc_u32 s65, s57, 0
	s_add_i32 s63, s49, s20
	v_lshl_add_u64 v[128:129], s[64:65], 0, v[178:179]
	s_mov_b32 m0, s63
	s_nop 0
	global_load_lds_dwordx4 v[128:129], off
	v_lshl_add_u64 v[128:129], s[64:65], 0, v[182:183]
	s_add_i32 m0, s63, 0x2000
	s_nop 0
	global_load_lds_dwordx4 v[128:129], off
	s_waitcnt vmcnt(6)
	s_barrier
	s_nop 0
	v_mfma_f32_16x16x32_bf16 v[52:55], v[192:195], v[144:147], v[52:55]
	v_mfma_f32_16x16x32_bf16 v[48:51], v[200:203], v[144:147], v[48:51]
	v_mfma_f32_16x16x32_bf16 v[36:39], v[192:195], v[152:155], v[36:39]
	v_mfma_f32_16x16x32_bf16 v[32:35], v[200:203], v[152:155], v[32:35]
	v_mfma_f32_16x16x32_bf16 v[20:23], v[192:195], v[160:163], v[20:23]
	v_mfma_f32_16x16x32_bf16 v[16:19], v[200:203], v[160:163], v[16:19]
	v_mfma_f32_16x16x32_bf16 v[4:7], v[192:195], v[168:171], v[4:7]
	v_mfma_f32_16x16x32_bf16 v[0:3], v[200:203], v[168:171], v[0:3]
	v_mfma_f32_16x16x32_bf16 v[52:55], v[196:199], v[148:151], v[52:55]
	v_mfma_f32_16x16x32_bf16 v[48:51], v[212:215], v[148:151], v[48:51]
	v_mfma_f32_16x16x32_bf16 v[36:39], v[196:199], v[156:159], v[36:39]
	v_mfma_f32_16x16x32_bf16 v[32:35], v[212:215], v[156:159], v[32:35]
	v_mfma_f32_16x16x32_bf16 v[20:23], v[196:199], v[164:167], v[20:23]
	v_mfma_f32_16x16x32_bf16 v[16:19], v[212:215], v[164:167], v[16:19]
	v_mfma_f32_16x16x32_bf16 v[4:7], v[196:199], v[172:175], v[4:7]
	v_mfma_f32_16x16x32_bf16 v[0:3], v[212:215], v[172:175], v[0:3]
	s_nop 0
	s_add_i32 s63, 0, 0x18000
	v_add_u32_e32 v140, s63, v207
	s_barrier
	ds_read_b128 v[128:131], v140
	ds_read_b128 v[132:135], v140 offset:1024
	ds_read_b128 v[136:139], v140 offset:2048
	ds_read_b128 v[140:143], v140 offset:3072
	s_add_u32 s58, s58, 0x40000
	s_addc_u32 s59, s59, 0
	s_mov_b32 m0, s34
	v_lshl_add_u64 v[192:193], s[58:59], 0, v[176:177]
	ds_read_b128 v[144:147], v210 offset:32768
	ds_read_b128 v[148:151], v210 offset:33792
	ds_read_b128 v[152:155], v210 offset:34816
	ds_read_b128 v[156:159], v210 offset:35840
	ds_read_b128 v[160:163], v210 offset:36864
	ds_read_b128 v[164:167], v210 offset:37888
	ds_read_b128 v[168:171], v210 offset:38912
	ds_read_b128 v[172:175], v210 offset:39936
	global_load_lds_dwordx4 v[192:193], off
	v_lshl_add_u64 v[192:193], s[58:59], 0, v[180:181]
	s_mov_b32 m0, s35
	s_nop 0
	global_load_lds_dwordx4 v[192:193], off
	s_waitcnt lgkmcnt(8)
	s_barrier
	s_waitcnt lgkmcnt(0)
	s_nop 0
	s_waitcnt lgkmcnt(0)
	v_mfma_f32_16x16x32_bf16 v[124:127], v[128:131], v[144:147], v[124:127]
	v_mfma_f32_16x16x32_bf16 v[120:123], v[136:139], v[144:147], v[120:123]
	v_mfma_f32_16x16x32_bf16 v[108:111], v[128:131], v[152:155], v[108:111]
	v_mfma_f32_16x16x32_bf16 v[104:107], v[136:139], v[152:155], v[104:107]
	v_mfma_f32_16x16x32_bf16 v[92:95], v[128:131], v[160:163], v[92:95]
	v_mfma_f32_16x16x32_bf16 v[88:91], v[136:139], v[160:163], v[88:91]
	v_mfma_f32_16x16x32_bf16 v[76:79], v[128:131], v[168:171], v[76:79]
	v_mfma_f32_16x16x32_bf16 v[72:75], v[136:139], v[168:171], v[72:75]
	v_mfma_f32_16x16x32_bf16 v[124:127], v[132:135], v[148:151], v[124:127]
	v_mfma_f32_16x16x32_bf16 v[120:123], v[140:143], v[148:151], v[120:123]
	v_mfma_f32_16x16x32_bf16 v[108:111], v[132:135], v[156:159], v[108:111]
	v_mfma_f32_16x16x32_bf16 v[104:107], v[140:143], v[156:159], v[104:107]
	v_mfma_f32_16x16x32_bf16 v[92:95], v[132:135], v[164:167], v[92:95]
	v_mfma_f32_16x16x32_bf16 v[88:91], v[140:143], v[164:167], v[88:91]
	v_mfma_f32_16x16x32_bf16 v[76:79], v[132:135], v[172:175], v[76:79]
	v_mfma_f32_16x16x32_bf16 v[72:75], v[140:143], v[172:175], v[72:75]
	s_nop 0
	s_barrier
	s_add_i32 s58, 0, 0x1c000
	s_add_i32 s59, s63, s20
	v_add_u32_e32 v212, s58, v207
	v_lshl_add_u64 v[216:217], v[216:217], 0, s[24:25]
	s_mov_b32 m0, s59
	ds_read_b128 v[192:195], v212
	ds_read_b128 v[196:199], v212 offset:1024
	ds_read_b128 v[200:203], v212 offset:2048
	ds_read_b128 v[212:215], v212 offset:3072
	global_load_lds_dwordx4 v[216:217], off
	v_lshl_add_u64 v[216:217], v[218:219], 0, s[24:25]
	s_add_i32 m0, s59, 0x2000
	s_nop 0
	global_load_lds_dwordx4 v[216:217], off
	s_barrier
	s_waitcnt lgkmcnt(0)
	s_nop 0
	s_waitcnt lgkmcnt(0)
	v_mfma_f32_16x16x32_bf16 v[116:119], v[192:195], v[144:147], v[116:119]
	v_mfma_f32_16x16x32_bf16 v[112:115], v[200:203], v[144:147], v[112:115]
	v_mfma_f32_16x16x32_bf16 v[100:103], v[192:195], v[152:155], v[100:103]
	v_mfma_f32_16x16x32_bf16 v[96:99], v[200:203], v[152:155], v[96:99]
	v_mfma_f32_16x16x32_bf16 v[84:87], v[192:195], v[160:163], v[84:87]
	v_mfma_f32_16x16x32_bf16 v[80:83], v[200:203], v[160:163], v[80:83]
	v_mfma_f32_16x16x32_bf16 v[68:71], v[192:195], v[168:171], v[68:71]
	v_mfma_f32_16x16x32_bf16 v[64:67], v[200:203], v[168:171], v[64:67]
	v_mfma_f32_16x16x32_bf16 v[116:119], v[196:199], v[148:151], v[116:119]
	v_mfma_f32_16x16x32_bf16 v[112:115], v[212:215], v[148:151], v[112:115]
	v_mfma_f32_16x16x32_bf16 v[100:103], v[196:199], v[156:159], v[100:103]
	v_mfma_f32_16x16x32_bf16 v[96:99], v[212:215], v[156:159], v[96:99]
	v_mfma_f32_16x16x32_bf16 v[84:87], v[196:199], v[164:167], v[84:87]
	v_mfma_f32_16x16x32_bf16 v[80:83], v[212:215], v[164:167], v[80:83]
	v_mfma_f32_16x16x32_bf16 v[68:71], v[196:199], v[172:175], v[68:71]
	v_mfma_f32_16x16x32_bf16 v[64:67], v[212:215], v[172:175], v[64:67]
	s_nop 0
	s_mov_b32 m0, s43
	v_lshl_add_u64 v[216:217], v[220:221], 0, s[24:25]
	s_barrier
	ds_read_b128 v[144:147], v210 offset:49152
	ds_read_b128 v[148:151], v210 offset:50176
	ds_read_b128 v[152:155], v210 offset:51200
	ds_read_b128 v[156:159], v210 offset:52224
	ds_read_b128 v[160:163], v210 offset:53248
	ds_read_b128 v[164:167], v210 offset:54272
	ds_read_b128 v[168:171], v210 offset:55296
	ds_read_b128 v[172:175], v210 offset:56320
	global_load_lds_dwordx4 v[216:217], off
	v_lshl_add_u64 v[216:217], v[222:223], 0, s[24:25]
	s_mov_b32 m0, s44
	s_nop 0
	global_load_lds_dwordx4 v[216:217], off
	s_barrier
	s_waitcnt lgkmcnt(0)
	s_nop 0
	s_waitcnt lgkmcnt(0)
	v_mfma_f32_16x16x32_bf16 v[60:63], v[128:131], v[144:147], v[60:63]
	v_mfma_f32_16x16x32_bf16 v[56:59], v[136:139], v[144:147], v[56:59]
	v_mfma_f32_16x16x32_bf16 v[44:47], v[128:131], v[152:155], v[44:47]
	v_mfma_f32_16x16x32_bf16 v[40:43], v[136:139], v[152:155], v[40:43]
	v_mfma_f32_16x16x32_bf16 v[28:31], v[128:131], v[160:163], v[28:31]
	v_mfma_f32_16x16x32_bf16 v[24:27], v[136:139], v[160:163], v[24:27]
	v_mfma_f32_16x16x32_bf16 v[12:15], v[128:131], v[168:171], v[12:15]
	v_mfma_f32_16x16x32_bf16 v[8:11], v[136:139], v[168:171], v[8:11]
	v_mfma_f32_16x16x32_bf16 v[60:63], v[132:135], v[148:151], v[60:63]
	v_mfma_f32_16x16x32_bf16 v[56:59], v[140:143], v[148:151], v[56:59]
	v_mfma_f32_16x16x32_bf16 v[44:47], v[132:135], v[156:159], v[44:47]
	v_mfma_f32_16x16x32_bf16 v[40:43], v[140:143], v[156:159], v[40:43]
	v_mfma_f32_16x16x32_bf16 v[28:31], v[132:135], v[164:167], v[28:31]
	v_mfma_f32_16x16x32_bf16 v[24:27], v[140:143], v[164:167], v[24:27]
	v_mfma_f32_16x16x32_bf16 v[12:15], v[132:135], v[172:175], v[12:15]
	v_mfma_f32_16x16x32_bf16 v[8:11], v[140:143], v[172:175], v[8:11]
	s_nop 0
	s_barrier
	s_add_u32 s56, s56, 0x40080
	s_addc_u32 s57, s57, 0
	s_add_i32 s58, s58, s20
	v_lshl_add_u64 v[128:129], s[56:57], 0, v[178:179]
	s_mov_b32 m0, s58
	s_nop 0
	global_load_lds_dwordx4 v[128:129], off
	v_lshl_add_u64 v[128:129], s[56:57], 0, v[182:183]
	s_add_i32 m0, s58, 0x2000
	s_nop 0
	global_load_lds_dwordx4 v[128:129], off
	s_waitcnt vmcnt(6)
	s_barrier
	s_nop 0
	v_mfma_f32_16x16x32_bf16 v[52:55], v[192:195], v[144:147], v[52:55]
	v_mfma_f32_16x16x32_bf16 v[48:51], v[200:203], v[144:147], v[48:51]
	v_mfma_f32_16x16x32_bf16 v[36:39], v[192:195], v[152:155], v[36:39]
	v_mfma_f32_16x16x32_bf16 v[32:35], v[200:203], v[152:155], v[32:35]
	v_mfma_f32_16x16x32_bf16 v[20:23], v[192:195], v[160:163], v[20:23]
	v_mfma_f32_16x16x32_bf16 v[16:19], v[200:203], v[160:163], v[16:19]
	v_mfma_f32_16x16x32_bf16 v[4:7], v[192:195], v[168:171], v[4:7]
	v_mfma_f32_16x16x32_bf16 v[0:3], v[200:203], v[168:171], v[0:3]
	v_mfma_f32_16x16x32_bf16 v[52:55], v[196:199], v[148:151], v[52:55]
	v_mfma_f32_16x16x32_bf16 v[48:51], v[212:215], v[148:151], v[48:51]
	v_mfma_f32_16x16x32_bf16 v[36:39], v[196:199], v[156:159], v[36:39]
	v_mfma_f32_16x16x32_bf16 v[32:35], v[212:215], v[156:159], v[32:35]
	v_mfma_f32_16x16x32_bf16 v[20:23], v[196:199], v[164:167], v[20:23]
	v_mfma_f32_16x16x32_bf16 v[16:19], v[212:215], v[164:167], v[16:19]
	v_mfma_f32_16x16x32_bf16 v[4:7], v[196:199], v[172:175], v[4:7]
	v_mfma_f32_16x16x32_bf16 v[0:3], v[212:215], v[172:175], v[0:3]
	s_nop 0
	s_add_i32 s62, s62, 2
	s_add_u32 s54, s54, 0x100
	s_addc_u32 s55, s55, 0
	s_add_u32 s60, s60, 0x100
	s_addc_u32 s61, s61, 0
	s_cmp_gt_u32 s62, 13
	s_barrier
	s_cbranch_scc0 .LBB0_900
	v_lshl_add_u32 v194, s50, 8, v206
	v_lshl_or_b32 v192, s52, 8, v208
	v_ashrrev_i32_e32 v193, 31, v192
	v_ashrrev_i32_e32 v195, 31, v194
	v_lshl_add_u64 v[196:197], v[192:193], 2, s[10:11]
	v_lshlrev_b64 v[128:129], 12, v[194:195]
	v_or_b32_e32 v202, 16, v194
	v_lshl_add_u64 v[128:129], v[196:197], 0, v[128:129]
	v_ashrrev_i32_e32 v203, 31, v202
	global_load_dwordx4 v[214:217], v[128:129], off offset:16
	global_load_dwordx4 v[218:221], v[128:129], off
	global_load_dwordx4 v[222:225], v[128:129], off offset:528
	global_load_dwordx4 v[226:229], v[128:129], off offset:512
	v_lshlrev_b64 v[128:129], 12, v[202:203]
	v_or_b32_e32 v200, 32, v194
	v_lshl_add_u64 v[128:129], v[196:197], 0, v[128:129]
	v_ashrrev_i32_e32 v201, 31, v200
	global_load_dwordx4 v[168:171], v[128:129], off offset:16
	global_load_dwordx4 v[172:175], v[128:129], off
	global_load_dwordx4 v[160:163], v[128:129], off offset:528
	global_load_dwordx4 v[164:167], v[128:129], off offset:512
	v_lshlrev_b64 v[128:129], 12, v[200:201]
	v_or_b32_e32 v198, 48, v194
	v_lshl_add_u64 v[128:129], v[196:197], 0, v[128:129]
	v_ashrrev_i32_e32 v199, 31, v198
	global_load_dwordx4 v[152:155], v[128:129], off offset:16
	global_load_dwordx4 v[156:159], v[128:129], off
	global_load_dwordx4 v[144:147], v[128:129], off offset:528
	global_load_dwordx4 v[148:151], v[128:129], off offset:512
	v_lshlrev_b64 v[128:129], 12, v[198:199]
	v_lshl_add_u64 v[132:133], v[196:197], 0, v[128:129]
	global_load_dwordx4 v[136:139], v[132:133], off offset:16
	global_load_dwordx4 v[140:143], v[132:133], off
	global_load_dwordx4 v[128:131], v[132:133], off offset:528
	s_nop 0
	global_load_dwordx4 v[132:135], v[132:133], off offset:512
	v_and_b32_e32 v213, 64, v205
	v_xor_b32_e32 v212, 16, v205
	v_add_u32_e32 v230, 64, v213
	v_cmp_lt_i32_e32 vcc, v212, v230
	s_nop 1
	v_cndmask_b32_e32 v212, v205, v212, vcc
	v_lshlrev_b32_e32 v213, 2, v212
	v_xor_b32_e32 v212, 32, v205
	v_cmp_lt_i32_e32 vcc, v212, v230
	s_nop 1
	v_cndmask_b32_e32 v212, v205, v212, vcc
	v_lshlrev_b32_e32 v212, 2, v212
	s_waitcnt vmcnt(0)
	v_pk_add_f32 v[214:215], v[120:121], v[214:215]
	v_pk_add_f32 v[124:125], v[124:125], v[218:219]
	v_pk_add_f32 v[216:217], v[122:123], v[216:217]
	v_cvt_pk_bf16_f32 v122, v214, v215
	v_mul_f32_e32 v214, v214, v214
	v_cvt_pk_bf16_f32 v120, v124, v125
	v_fmac_f32_e32 v214, v124, v124
	v_mul_f32_e32 v124, v215, v215
	v_pk_add_f32 v[126:127], v[126:127], v[220:221]
	v_fmac_f32_e32 v124, v125, v125
	v_mul_f32_e32 v125, v216, v216
	v_add_f32_e32 v124, v214, v124
	v_fmac_f32_e32 v125, v126, v126
	v_add_f32_e32 v124, v125, v124
	v_mul_f32_e32 v125, v217, v217
	v_cvt_pk_bf16_f32 v121, v126, v127
	v_fmac_f32_e32 v125, v127, v127
	v_pk_add_f32 v[126:127], v[112:113], v[222:223]
	v_pk_add_f32 v[116:117], v[116:117], v[226:227]
	v_mul_f32_e32 v112, v126, v126
	v_add_f32_e32 v214, v125, v124
	v_fmac_f32_e32 v112, v116, v116
	v_mul_f32_e32 v113, v127, v127
	v_pk_add_f32 v[124:125], v[114:115], v[224:225]
	v_add_f32_e32 v112, v112, v214
	v_fmac_f32_e32 v113, v117, v117
	v_pk_add_f32 v[118:119], v[118:119], v[228:229]
	v_add_f32_e32 v112, v113, v112
	v_mul_f32_e32 v113, v124, v124
	v_fmac_f32_e32 v113, v118, v118
	v_add_f32_e32 v112, v113, v112
	v_mul_f32_e32 v113, v125, v125
	v_fmac_f32_e32 v113, v119, v119
	v_add_f32_e32 v115, v113, v112
	v_cvt_pk_bf16_f32 v123, v216, v217
	ds_bpermute_b32 v216, v213, v115
	v_lshlrev_b64 v[230:231], 11, v[194:195]
	v_lshl_add_u64 v[112:113], s[16:17], 0, v[230:231]
	v_lshl_add_u64 v[214:215], v[192:193], 1, v[112:113]
	v_cvt_pk_bf16_f32 v114, v116, v117
	s_waitcnt lgkmcnt(0)
	v_add_f32_e32 v112, v115, v216
	ds_bpermute_b32 v113, v212, v112
	v_cvt_pk_bf16_f32 v115, v118, v119
	v_cvt_pk_bf16_f32 v116, v126, v127
	v_cvt_pk_bf16_f32 v117, v124, v125
	global_store_dwordx4 v[214:215], v[120:123], off
	global_store_dwordx4 v[214:215], v[114:117], off offset:256
	s_and_saveexec_b64 s[50:51], s[6:7]
	s_cbranch_execz .LBB0_903
	s_waitcnt lgkmcnt(0)
	v_add_f32_e32 v112, v112, v113
	v_mul_f32_e32 v112, 0x4b800000, v112
	v_trunc_f32_e32 v112, v112
	v_mul_f32_e32 v113, 0x2f800000, v112
	v_floor_f32_e32 v113, v113
	v_fmac_f32_e32 v112, 0xcf800000, v113
	v_cvt_u32_f32_e32 v112, v112
	v_cvt_u32_f32_e32 v113, v113
	v_lshl_add_u64 v[114:115], v[194:195], 3, s[18:19]
	global_atomic_add_x2 v[114:115], v[112:113], off

.LBB0_972:
	s_or_b64 exec, exec, s[6:7]
	v_readlane_b32 s0, v238, 16
	v_readlane_b32 s1, v238, 17
	s_waitcnt lgkmcnt(0)
	s_barrier
	v_readfirstlane_b32 s101, v204
	s_nop 3
	s_lshr_b32 s101, s101, 6
	s_cmp_ge_u32 s101, 4
	s_cbranch_scc0 .Lprio_2
	s_setprio 1
.Lprio_2:
	s_load_dwordx2 s[14:15], s[0:1], 0xb8
	v_mov_b32_e32 v8, v204
	v_cndmask_b32_e64 v0, 0, 1, s[28:29]
	v_cmp_ne_u32_e64 s[6:7], 1, v0
	s_andn2_b64 vcc, exec, s[28:29]
	v_readfirstlane_b32 s0, v8
	s_cbranch_vccnz .LBB0_992
	s_ashr_i32 s1, s97, 31
	s_lshr_b32 s2, s1, 29
	s_add_i32 s2, s97, s2
	s_and_b32 s8, s2, -8
	s_sub_i32 s11, s97, s8
	s_cmp_gt_i32 s11, -1
	s_cbranch_scc0 .LBB0_975
	s_lshl_b32 s10, s11, 8
	s_cbranch_execz .LBB0_976
	s_branch .LBB0_977

.LBB0_986:
	s_ashr_i32 s51, s50, 31
	v_cmp_lt_i64_e32 vcc, s[52:53], v[140:141]
	s_lshl_b64 s[52:53], s[50:51], 19
	s_add_u32 s52, s2, s52
	s_addc_u32 s53, s20, s53
	s_and_b64 s[54:55], vcc, exec
	s_cselect_b32 s11, s53, s13
	s_cselect_b32 s51, s52, s12
	s_ashr_i32 s39, s38, 31
	s_lshl_b64 s[54:55], s[38:39], 19
	s_add_u32 s54, s21, s54
	s_addc_u32 s55, s33, s55
	s_and_b64 s[58:59], vcc, exec
	s_cselect_b32 s39, s55, s57
	s_cselect_b32 s68, s54, s56
	s_add_u32 s12, s12, 0x40080
	s_addc_u32 s13, s13, 0
	s_add_u32 s69, s56, 0x100

	s_addc_u32 s70, s57, 0
	s_mov_b32 s71, -2


	ds_read_b128 v[164:167], v155
	ds_read_b128 v[168:171], v155 offset:1024
	ds_read_b128 v[172:175], v155 offset:2048
	ds_read_b128 v[176:179], v155 offset:3072
	s_add_u32 s56, s12, 0xfffc0080
	s_addc_u32 s57, s13, -1
	s_cmp_eq_u32 s71, 12
	s_cselect_b32 s59, s11, s57
	s_cselect_b32 s58, s51, s56
	s_cselect_b32 s57, s39, s70
	s_cselect_b32 s56, s68, s69
	v_lshl_add_u64 v[146:147], s[12:13], 0, v[136:137]
	s_add_i32 m0, s35, 0xc000
	ds_read_b128 v[180:183], v159
	ds_read_b128 v[184:187], v159 offset:1024
	ds_read_b128 v[188:191], v159 offset:2048
	ds_read_b128 v[192:195], v159 offset:3072
	ds_read_b128 v[196:199], v159 offset:4096
	ds_read_b128 v[200:203], v159 offset:5120
	ds_read_b128 v[206:209], v159 offset:6144
	ds_read_b128 v[210:213], v159 offset:7168
	global_load_lds_dwordx4 v[146:147], off
	v_lshl_add_u64 v[146:147], s[12:13], 0, v[138:139]
	s_add_i32 m0, s35, 0xe000
	s_nop 0
	global_load_lds_dwordx4 v[146:147], off
	s_waitcnt lgkmcnt(8)
	s_barrier
	s_waitcnt lgkmcnt(0)
	s_nop 0
	s_waitcnt lgkmcnt(0)
	v_mfma_f32_16x16x32_bf16 v[124:127], v[164:167], v[180:183], 0
	v_mfma_f32_16x16x32_bf16 v[120:123], v[172:175], v[180:183], 0
	v_mfma_f32_16x16x32_bf16 v[108:111], v[164:167], v[188:191], 0
	v_mfma_f32_16x16x32_bf16 v[104:107], v[172:175], v[188:191], 0
	v_mfma_f32_16x16x32_bf16 v[92:95], v[164:167], v[196:199], 0
	v_mfma_f32_16x16x32_bf16 v[88:91], v[172:175], v[196:199], 0
	v_mfma_f32_16x16x32_bf16 v[76:79], v[164:167], v[206:209], 0
	v_mfma_f32_16x16x32_bf16 v[72:75], v[172:175], v[206:209], 0
	v_mfma_f32_16x16x32_bf16 v[124:127], v[168:171], v[184:187], v[124:127]
	v_mfma_f32_16x16x32_bf16 v[120:123], v[176:179], v[184:187], v[120:123]
	v_mfma_f32_16x16x32_bf16 v[108:111], v[168:171], v[192:195], v[108:111]
	v_mfma_f32_16x16x32_bf16 v[104:107], v[176:179], v[192:195], v[104:107]
	v_mfma_f32_16x16x32_bf16 v[92:95], v[168:171], v[200:203], v[92:95]
	v_mfma_f32_16x16x32_bf16 v[88:91], v[176:179], v[200:203], v[88:91]
	v_mfma_f32_16x16x32_bf16 v[76:79], v[168:171], v[210:213], v[76:79]
	v_mfma_f32_16x16x32_bf16 v[72:75], v[176:179], v[210:213], v[72:75]
	s_nop 0
	s_barrier
	s_add_i32 s72, s60, s34
	v_lshl_add_u64 v[146:147], s[56:57], 0, v[130:131]
	s_mov_b32 m0, s72
	ds_read_b128 v[214:217], v162
	ds_read_b128 v[218:221], v162 offset:1024
	ds_read_b128 v[222:225], v162 offset:2048
	ds_read_b128 v[226:229], v162 offset:3072
	global_load_lds_dwordx4 v[146:147], off
	v_lshl_add_u64 v[152:153], s[56:57], 0, v[134:135]
	s_add_i32 m0, s72, 0x2000
	s_nop 0
	global_load_lds_dwordx4 v[152:153], off
	s_barrier
	s_waitcnt lgkmcnt(0)
	s_nop 0
	s_waitcnt lgkmcnt(0)
	v_mfma_f32_16x16x32_bf16 v[116:119], v[214:217], v[180:183], 0
	v_mfma_f32_16x16x32_bf16 v[112:115], v[222:225], v[180:183], 0
	v_mfma_f32_16x16x32_bf16 v[100:103], v[214:217], v[188:191], 0
	v_mfma_f32_16x16x32_bf16 v[96:99], v[222:225], v[188:191], 0
	v_mfma_f32_16x16x32_bf16 v[84:87], v[214:217], v[196:199], 0
	v_mfma_f32_16x16x32_bf16 v[80:83], v[222:225], v[196:199], 0
	v_mfma_f32_16x16x32_bf16 v[68:71], v[214:217], v[206:209], 0
	v_mfma_f32_16x16x32_bf16 v[64:67], v[222:225], v[206:209], 0
	v_mfma_f32_16x16x32_bf16 v[116:119], v[218:221], v[184:187], v[116:119]
	v_mfma_f32_16x16x32_bf16 v[112:115], v[226:229], v[184:187], v[112:115]
	v_mfma_f32_16x16x32_bf16 v[100:103], v[218:221], v[192:195], v[100:103]
	v_mfma_f32_16x16x32_bf16 v[96:99], v[226:229], v[192:195], v[96:99]
	v_mfma_f32_16x16x32_bf16 v[84:87], v[218:221], v[200:203], v[84:87]
	v_mfma_f32_16x16x32_bf16 v[80:83], v[226:229], v[200:203], v[80:83]
	v_mfma_f32_16x16x32_bf16 v[68:71], v[218:221], v[210:213], v[68:71]
	v_mfma_f32_16x16x32_bf16 v[64:67], v[226:229], v[210:213], v[64:67]
	s_nop 0
	s_mov_b32 m0, s35
	v_lshl_add_u64 v[156:157], s[58:59], 0, v[128:129]
	s_barrier
	ds_read_b128 v[180:183], v159 offset:16384
	ds_read_b128 v[184:187], v159 offset:17408
	ds_read_b128 v[188:191], v159 offset:18432
	ds_read_b128 v[192:195], v159 offset:19456
	ds_read_b128 v[196:199], v159 offset:20480
	ds_read_b128 v[200:203], v159 offset:21504
	ds_read_b128 v[206:209], v159 offset:22528
	ds_read_b128 v[210:213], v159 offset:23552
	global_load_lds_dwordx4 v[156:157], off
	v_lshl_add_u64 v[160:161], s[58:59], 0, v[132:133]
	s_mov_b32 m0, s42
	s_nop 0
	global_load_lds_dwordx4 v[160:161], off
	s_barrier
	s_waitcnt lgkmcnt(0)
	s_nop 0
	s_waitcnt lgkmcnt(0)
	v_mfma_f32_16x16x32_bf16 v[60:63], v[164:167], v[180:183], 0
	v_mfma_f32_16x16x32_bf16 v[56:59], v[172:175], v[180:183], 0
	v_mfma_f32_16x16x32_bf16 v[44:47], v[164:167], v[188:191], 0
	v_mfma_f32_16x16x32_bf16 v[40:43], v[172:175], v[188:191], 0
	v_mfma_f32_16x16x32_bf16 v[28:31], v[164:167], v[196:199], 0
	v_mfma_f32_16x16x32_bf16 v[24:27], v[172:175], v[196:199], 0
	v_mfma_f32_16x16x32_bf16 v[12:15], v[164:167], v[206:209], 0
	v_mfma_f32_16x16x32_bf16 v[8:11], v[172:175], v[206:209], 0
	v_mfma_f32_16x16x32_bf16 v[60:63], v[168:171], v[184:187], v[60:63]
	v_mfma_f32_16x16x32_bf16 v[56:59], v[176:179], v[184:187], v[56:59]
	v_mfma_f32_16x16x32_bf16 v[44:47], v[168:171], v[192:195], v[44:47]
	v_mfma_f32_16x16x32_bf16 v[40:43], v[176:179], v[192:195], v[40:43]
	v_mfma_f32_16x16x32_bf16 v[28:31], v[168:171], v[200:203], v[28:31]
	v_mfma_f32_16x16x32_bf16 v[24:27], v[176:179], v[200:203], v[24:27]
	v_mfma_f32_16x16x32_bf16 v[12:15], v[168:171], v[210:213], v[12:15]
	v_mfma_f32_16x16x32_bf16 v[8:11], v[176:179], v[210:213], v[8:11]
	s_nop 0
	s_barrier
	s_add_u32 s72, s56, 0x40000
	s_addc_u32 s73, s57, 0
	s_add_i32 s74, s61, s34
	v_lshl_add_u64 v[164:165], s[72:73], 0, v[130:131]
	s_mov_b32 m0, s74
	s_nop 0
	global_load_lds_dwordx4 v[164:165], off
	v_lshl_add_u64 v[164:165], s[72:73], 0, v[134:135]
	s_add_i32 m0, s74, 0x2000
	s_nop 0
	global_load_lds_dwordx4 v[164:165], off
	s_waitcnt vmcnt(6)
	s_barrier
	s_nop 0
	v_mfma_f32_16x16x32_bf16 v[52:55], v[214:217], v[180:183], 0
	v_mfma_f32_16x16x32_bf16 v[48:51], v[222:225], v[180:183], 0
	v_mfma_f32_16x16x32_bf16 v[36:39], v[214:217], v[188:191], 0
	v_mfma_f32_16x16x32_bf16 v[32:35], v[222:225], v[188:191], 0
	v_mfma_f32_16x16x32_bf16 v[20:23], v[214:217], v[196:199], 0
	v_mfma_f32_16x16x32_bf16 v[16:19], v[222:225], v[196:199], 0
	v_mfma_f32_16x16x32_bf16 v[4:7], v[214:217], v[206:209], 0
	v_mfma_f32_16x16x32_bf16 v[0:3], v[222:225], v[206:209], 0
	v_mfma_f32_16x16x32_bf16 v[52:55], v[218:221], v[184:187], v[52:55]
	v_mfma_f32_16x16x32_bf16 v[48:51], v[226:229], v[184:187], v[48:51]
	v_mfma_f32_16x16x32_bf16 v[36:39], v[218:221], v[192:195], v[36:39]
	v_mfma_f32_16x16x32_bf16 v[32:35], v[226:229], v[192:195], v[32:35]
	v_mfma_f32_16x16x32_bf16 v[20:23], v[218:221], v[200:203], v[20:23]
	v_mfma_f32_16x16x32_bf16 v[16:19], v[226:229], v[200:203], v[16:19]
	v_mfma_f32_16x16x32_bf16 v[4:7], v[218:221], v[210:213], v[4:7]
	v_mfma_f32_16x16x32_bf16 v[0:3], v[226:229], v[210:213], v[0:3]
	s_nop 0
	s_add_i32 s72, 0, 0x18000
	v_add_u32_e32 v144, s72, v149
	s_barrier
	ds_read_b128 v[164:167], v144
	ds_read_b128 v[168:171], v144 offset:1024
	ds_read_b128 v[172:175], v144 offset:2048
	ds_read_b128 v[176:179], v144 offset:3072
	s_add_u32 s58, s58, 0x40000
	s_addc_u32 s59, s59, 0
	s_mov_b32 m0, s43
	v_lshl_add_u64 v[214:215], s[58:59], 0, v[128:129]
	ds_read_b128 v[180:183], v159 offset:32768
	ds_read_b128 v[184:187], v159 offset:33792
	ds_read_b128 v[188:191], v159 offset:34816
	ds_read_b128 v[192:195], v159 offset:35840
	ds_read_b128 v[196:199], v159 offset:36864
	ds_read_b128 v[200:203], v159 offset:37888
	ds_read_b128 v[206:209], v159 offset:38912
	ds_read_b128 v[210:213], v159 offset:39936
	global_load_lds_dwordx4 v[214:215], off
	v_lshl_add_u64 v[214:215], s[58:59], 0, v[132:133]
	s_mov_b32 m0, s44
	s_nop 0
	global_load_lds_dwordx4 v[214:215], off
	s_waitcnt lgkmcnt(8)
	s_barrier
	s_waitcnt lgkmcnt(0)
	s_nop 0
	s_waitcnt lgkmcnt(0)
	v_mfma_f32_16x16x32_bf16 v[124:127], v[164:167], v[180:183], v[124:127]
	v_mfma_f32_16x16x32_bf16 v[120:123], v[172:175], v[180:183], v[120:123]
	v_mfma_f32_16x16x32_bf16 v[108:111], v[164:167], v[188:191], v[108:111]
	v_mfma_f32_16x16x32_bf16 v[104:107], v[172:175], v[188:191], v[104:107]
	v_mfma_f32_16x16x32_bf16 v[92:95], v[164:167], v[196:199], v[92:95]
	v_mfma_f32_16x16x32_bf16 v[88:91], v[172:175], v[196:199], v[88:91]
	v_mfma_f32_16x16x32_bf16 v[76:79], v[164:167], v[206:209], v[76:79]
	v_mfma_f32_16x16x32_bf16 v[72:75], v[172:175], v[206:209], v[72:75]
	v_mfma_f32_16x16x32_bf16 v[124:127], v[168:171], v[184:187], v[124:127]
	v_mfma_f32_16x16x32_bf16 v[120:123], v[176:179], v[184:187], v[120:123]
	v_mfma_f32_16x16x32_bf16 v[108:111], v[168:171], v[192:195], v[108:111]
	v_mfma_f32_16x16x32_bf16 v[104:107], v[176:179], v[192:195], v[104:107]
	v_mfma_f32_16x16x32_bf16 v[92:95], v[168:171], v[200:203], v[92:95]
	v_mfma_f32_16x16x32_bf16 v[88:91], v[176:179], v[200:203], v[88:91]
	v_mfma_f32_16x16x32_bf16 v[76:79], v[168:171], v[210:213], v[76:79]
	v_mfma_f32_16x16x32_bf16 v[72:75], v[176:179], v[210:213], v[72:75]
	s_nop 0
	s_barrier
	s_add_i32 s58, 0, 0x1c000
	s_add_i32 s59, s72, s34
	v_add_u32_e32 v144, s58, v149
	v_lshl_add_u64 v[146:147], v[146:147], 0, s[24:25]
	s_mov_b32 m0, s59
	ds_read_b128 v[214:217], v144
	ds_read_b128 v[218:221], v144 offset:1024
	ds_read_b128 v[222:225], v144 offset:2048
	ds_read_b128 v[226:229], v144 offset:3072
	global_load_lds_dwordx4 v[146:147], off
	v_lshl_add_u64 v[146:147], v[152:153], 0, s[24:25]
	s_add_i32 m0, s59, 0x2000
	s_nop 0
	global_load_lds_dwordx4 v[146:147], off
	s_barrier
	s_waitcnt lgkmcnt(0)
	s_nop 0
	s_waitcnt lgkmcnt(0)
	v_mfma_f32_16x16x32_bf16 v[116:119], v[214:217], v[180:183], v[116:119]
	v_mfma_f32_16x16x32_bf16 v[112:115], v[222:225], v[180:183], v[112:115]
	v_mfma_f32_16x16x32_bf16 v[100:103], v[214:217], v[188:191], v[100:103]
	v_mfma_f32_16x16x32_bf16 v[96:99], v[222:225], v[188:191], v[96:99]
	v_mfma_f32_16x16x32_bf16 v[84:87], v[214:217], v[196:199], v[84:87]
	v_mfma_f32_16x16x32_bf16 v[80:83], v[222:225], v[196:199], v[80:83]
	v_mfma_f32_16x16x32_bf16 v[68:71], v[214:217], v[206:209], v[68:71]
	v_mfma_f32_16x16x32_bf16 v[64:67], v[222:225], v[206:209], v[64:67]
	v_mfma_f32_16x16x32_bf16 v[116:119], v[218:221], v[184:187], v[116:119]
	v_mfma_f32_16x16x32_bf16 v[112:115], v[226:229], v[184:187], v[112:115]
	v_mfma_f32_16x16x32_bf16 v[100:103], v[218:221], v[192:195], v[100:103]
	v_mfma_f32_16x16x32_bf16 v[96:99], v[226:229], v[192:195], v[96:99]
	v_mfma_f32_16x16x32_bf16 v[84:87], v[218:221], v[200:203], v[84:87]
	v_mfma_f32_16x16x32_bf16 v[80:83], v[226:229], v[200:203], v[80:83]
	v_mfma_f32_16x16x32_bf16 v[68:71], v[218:221], v[210:213], v[68:71]
	v_mfma_f32_16x16x32_bf16 v[64:67], v[226:229], v[210:213], v[64:67]
	s_nop 0
	s_mov_b32 m0, s46
	v_lshl_add_u64 v[146:147], v[156:157], 0, s[24:25]
	s_barrier
	ds_read_b128 v[180:183], v159 offset:49152
	ds_read_b128 v[184:187], v159 offset:50176
	ds_read_b128 v[188:191], v159 offset:51200
	ds_read_b128 v[192:195], v159 offset:52224
	ds_read_b128 v[196:199], v159 offset:53248
	ds_read_b128 v[200:203], v159 offset:54272
	ds_read_b128 v[206:209], v159 offset:55296
	ds_read_b128 v[210:213], v159 offset:56320
	global_load_lds_dwordx4 v[146:147], off
	v_lshl_add_u64 v[146:147], v[160:161], 0, s[24:25]
	s_mov_b32 m0, s47
	s_nop 0
	global_load_lds_dwordx4 v[146:147], off
	s_barrier
	s_waitcnt lgkmcnt(0)
	s_nop 0
	s_waitcnt lgkmcnt(0)
	v_mfma_f32_16x16x32_bf16 v[60:63], v[164:167], v[180:183], v[60:63]
	v_mfma_f32_16x16x32_bf16 v[56:59], v[172:175], v[180:183], v[56:59]
	v_mfma_f32_16x16x32_bf16 v[44:47], v[164:167], v[188:191], v[44:47]
	v_mfma_f32_16x16x32_bf16 v[40:43], v[172:175], v[188:191], v[40:43]
	v_mfma_f32_16x16x32_bf16 v[28:31], v[164:167], v[196:199], v[28:31]
	v_mfma_f32_16x16x32_bf16 v[24:27], v[172:175], v[196:199], v[24:27]
	v_mfma_f32_16x16x32_bf16 v[12:15], v[164:167], v[206:209], v[12:15]
	v_mfma_f32_16x16x32_bf16 v[8:11], v[172:175], v[206:209], v[8:11]
	v_mfma_f32_16x16x32_bf16 v[60:63], v[168:171], v[184:187], v[60:63]
	v_mfma_f32_16x16x32_bf16 v[56:59], v[176:179], v[184:187], v[56:59]
	v_mfma_f32_16x16x32_bf16 v[44:47], v[168:171], v[192:195], v[44:47]
	v_mfma_f32_16x16x32_bf16 v[40:43], v[176:179], v[192:195], v[40:43]
	v_mfma_f32_16x16x32_bf16 v[28:31], v[168:171], v[200:203], v[28:31]
	v_mfma_f32_16x16x32_bf16 v[24:27], v[176:179], v[200:203], v[24:27]
	v_mfma_f32_16x16x32_bf16 v[12:15], v[168:171], v[210:213], v[12:15]
	v_mfma_f32_16x16x32_bf16 v[8:11], v[176:179], v[210:213], v[8:11]
	s_nop 0
	s_barrier
	s_add_u32 s56, s56, 0x40080
	s_addc_u32 s57, s57, 0
	s_add_i32 s58, s58, s34
	v_lshl_add_u64 v[146:147], s[56:57], 0, v[130:131]
	s_mov_b32 m0, s58
	s_nop 0
	global_load_lds_dwordx4 v[146:147], off
	v_lshl_add_u64 v[146:147], s[56:57], 0, v[134:135]
	s_add_i32 m0, s58, 0x2000
	s_nop 0
	global_load_lds_dwordx4 v[146:147], off
	s_waitcnt vmcnt(6)
	s_barrier
	s_nop 0
	v_mfma_f32_16x16x32_bf16 v[52:55], v[214:217], v[180:183], v[52:55]
	v_mfma_f32_16x16x32_bf16 v[48:51], v[222:225], v[180:183], v[48:51]
	v_mfma_f32_16x16x32_bf16 v[36:39], v[214:217], v[188:191], v[36:39]
	v_mfma_f32_16x16x32_bf16 v[32:35], v[222:225], v[188:191], v[32:35]
	v_mfma_f32_16x16x32_bf16 v[20:23], v[214:217], v[196:199], v[20:23]
	v_mfma_f32_16x16x32_bf16 v[16:19], v[222:225], v[196:199], v[16:19]
	v_mfma_f32_16x16x32_bf16 v[4:7], v[214:217], v[206:209], v[4:7]
	v_mfma_f32_16x16x32_bf16 v[0:3], v[222:225], v[206:209], v[0:3]
	v_mfma_f32_16x16x32_bf16 v[52:55], v[218:221], v[184:187], v[52:55]
	v_mfma_f32_16x16x32_bf16 v[48:51], v[226:229], v[184:187], v[48:51]
	v_mfma_f32_16x16x32_bf16 v[36:39], v[218:221], v[192:195], v[36:39]
	v_mfma_f32_16x16x32_bf16 v[32:35], v[226:229], v[192:195], v[32:35]
	v_mfma_f32_16x16x32_bf16 v[20:23], v[218:221], v[200:203], v[20:23]
	v_mfma_f32_16x16x32_bf16 v[16:19], v[226:229], v[200:203], v[16:19]
	v_mfma_f32_16x16x32_bf16 v[4:7], v[218:221], v[210:213], v[4:7]
	v_mfma_f32_16x16x32_bf16 v[0:3], v[226:229], v[210:213], v[0:3]
	s_nop 0
	s_add_i32 s71, s71, 2
	s_add_u32 s12, s12, 0x100
	s_addc_u32 s13, s13, 0
	s_add_u32 s69, s69, 0x100
	s_addc_u32 s70, s70, 0
	s_cmp_gt_u32 s71, 13
	s_barrier
.LBB0_987:
	ds_read_b128 v[164:167], v155
	ds_read_b128 v[168:171], v155 offset:1024
	ds_read_b128 v[172:175], v155 offset:2048
	ds_read_b128 v[176:179], v155 offset:3072
	s_add_u32 s56, s12, 0xfffc0080
	s_addc_u32 s57, s13, -1
	s_cmp_eq_u32 s71, 12
	s_cselect_b32 s59, s11, s57
	s_cselect_b32 s58, s51, s56
	s_cselect_b32 s57, s39, s70
	s_cselect_b32 s56, s68, s69
	v_lshl_add_u64 v[146:147], s[12:13], 0, v[136:137]
	s_add_i32 m0, s35, 0xc000
	ds_read_b128 v[180:183], v159
	ds_read_b128 v[184:187], v159 offset:1024
	ds_read_b128 v[188:191], v159 offset:2048
	ds_read_b128 v[192:195], v159 offset:3072
	ds_read_b128 v[196:199], v159 offset:4096
	ds_read_b128 v[200:203], v159 offset:5120
	ds_read_b128 v[206:209], v159 offset:6144
	ds_read_b128 v[210:213], v159 offset:7168
	global_load_lds_dwordx4 v[146:147], off
	v_lshl_add_u64 v[146:147], s[12:13], 0, v[138:139]
	s_add_i32 m0, s35, 0xe000
	s_nop 0
	global_load_lds_dwordx4 v[146:147], off
	s_waitcnt lgkmcnt(8)
	s_barrier
	s_waitcnt lgkmcnt(0)
	s_nop 0
	s_waitcnt lgkmcnt(0)
	v_mfma_f32_16x16x32_bf16 v[124:127], v[164:167], v[180:183], v[124:127]
	v_mfma_f32_16x16x32_bf16 v[120:123], v[172:175], v[180:183], v[120:123]
	v_mfma_f32_16x16x32_bf16 v[108:111], v[164:167], v[188:191], v[108:111]
	v_mfma_f32_16x16x32_bf16 v[104:107], v[172:175], v[188:191], v[104:107]
	v_mfma_f32_16x16x32_bf16 v[92:95], v[164:167], v[196:199], v[92:95]
	v_mfma_f32_16x16x32_bf16 v[88:91], v[172:175], v[196:199], v[88:91]
	v_mfma_f32_16x16x32_bf16 v[76:79], v[164:167], v[206:209], v[76:79]
	v_mfma_f32_16x16x32_bf16 v[72:75], v[172:175], v[206:209], v[72:75]
	v_mfma_f32_16x16x32_bf16 v[124:127], v[168:171], v[184:187], v[124:127]
	v_mfma_f32_16x16x32_bf16 v[120:123], v[176:179], v[184:187], v[120:123]
	v_mfma_f32_16x16x32_bf16 v[108:111], v[168:171], v[192:195], v[108:111]
	v_mfma_f32_16x16x32_bf16 v[104:107], v[176:179], v[192:195], v[104:107]
	v_mfma_f32_16x16x32_bf16 v[92:95], v[168:171], v[200:203], v[92:95]
	v_mfma_f32_16x16x32_bf16 v[88:91], v[176:179], v[200:203], v[88:91]
	v_mfma_f32_16x16x32_bf16 v[76:79], v[168:171], v[210:213], v[76:79]
	v_mfma_f32_16x16x32_bf16 v[72:75], v[176:179], v[210:213], v[72:75]
	s_nop 0
	s_barrier
	s_add_i32 s72, s60, s34
	v_lshl_add_u64 v[146:147], s[56:57], 0, v[130:131]
	s_mov_b32 m0, s72
	ds_read_b128 v[214:217], v162
	ds_read_b128 v[218:221], v162 offset:1024
	ds_read_b128 v[222:225], v162 offset:2048
	ds_read_b128 v[226:229], v162 offset:3072
	global_load_lds_dwordx4 v[146:147], off
	v_lshl_add_u64 v[152:153], s[56:57], 0, v[134:135]
	s_add_i32 m0, s72, 0x2000
	s_nop 0
	global_load_lds_dwordx4 v[152:153], off
	s_barrier
	s_waitcnt lgkmcnt(0)
	s_nop 0
	s_waitcnt lgkmcnt(0)
	v_mfma_f32_16x16x32_bf16 v[116:119], v[214:217], v[180:183], v[116:119]
	v_mfma_f32_16x16x32_bf16 v[112:115], v[222:225], v[180:183], v[112:115]
	v_mfma_f32_16x16x32_bf16 v[100:103], v[214:217], v[188:191], v[100:103]
	v_mfma_f32_16x16x32_bf16 v[96:99], v[222:225], v[188:191], v[96:99]
	v_mfma_f32_16x16x32_bf16 v[84:87], v[214:217], v[196:199], v[84:87]
	v_mfma_f32_16x16x32_bf16 v[80:83], v[222:225], v[196:199], v[80:83]
	v_mfma_f32_16x16x32_bf16 v[68:71], v[214:217], v[206:209], v[68:71]
	v_mfma_f32_16x16x32_bf16 v[64:67], v[222:225], v[206:209], v[64:67]
	v_mfma_f32_16x16x32_bf16 v[116:119], v[218:221], v[184:187], v[116:119]
	v_mfma_f32_16x16x32_bf16 v[112:115], v[226:229], v[184:187], v[112:115]
	v_mfma_f32_16x16x32_bf16 v[100:103], v[218:221], v[192:195], v[100:103]
	v_mfma_f32_16x16x32_bf16 v[96:99], v[226:229], v[192:195], v[96:99]
	v_mfma_f32_16x16x32_bf16 v[84:87], v[218:221], v[200:203], v[84:87]
	v_mfma_f32_16x16x32_bf16 v[80:83], v[226:229], v[200:203], v[80:83]
	v_mfma_f32_16x16x32_bf16 v[68:71], v[218:221], v[210:213], v[68:71]
	v_mfma_f32_16x16x32_bf16 v[64:67], v[226:229], v[210:213], v[64:67]
	s_nop 0
	s_mov_b32 m0, s35
	v_lshl_add_u64 v[156:157], s[58:59], 0, v[128:129]
	s_barrier
	ds_read_b128 v[180:183], v159 offset:16384
	ds_read_b128 v[184:187], v159 offset:17408
	ds_read_b128 v[188:191], v159 offset:18432
	ds_read_b128 v[192:195], v159 offset:19456
	ds_read_b128 v[196:199], v159 offset:20480
	ds_read_b128 v[200:203], v159 offset:21504
	ds_read_b128 v[206:209], v159 offset:22528
	ds_read_b128 v[210:213], v159 offset:23552
	global_load_lds_dwordx4 v[156:157], off
	v_lshl_add_u64 v[160:161], s[58:59], 0, v[132:133]
	s_mov_b32 m0, s42
	s_nop 0
	global_load_lds_dwordx4 v[160:161], off
	s_barrier
	s_waitcnt lgkmcnt(0)
	s_nop 0
	s_waitcnt lgkmcnt(0)
	v_mfma_f32_16x16x32_bf16 v[60:63], v[164:167], v[180:183], v[60:63]
	v_mfma_f32_16x16x32_bf16 v[56:59], v[172:175], v[180:183], v[56:59]
	v_mfma_f32_16x16x32_bf16 v[44:47], v[164:167], v[188:191], v[44:47]
	v_mfma_f32_16x16x32_bf16 v[40:43], v[172:175], v[188:191], v[40:43]
	v_mfma_f32_16x16x32_bf16 v[28:31], v[164:167], v[196:199], v[28:31]
	v_mfma_f32_16x16x32_bf16 v[24:27], v[172:175], v[196:199], v[24:27]
	v_mfma_f32_16x16x32_bf16 v[12:15], v[164:167], v[206:209], v[12:15]
	v_mfma_f32_16x16x32_bf16 v[8:11], v[172:175], v[206:209], v[8:11]
	v_mfma_f32_16x16x32_bf16 v[60:63], v[168:171], v[184:187], v[60:63]
	v_mfma_f32_16x16x32_bf16 v[56:59], v[176:179], v[184:187], v[56:59]
	v_mfma_f32_16x16x32_bf16 v[44:47], v[168:171], v[192:195], v[44:47]
	v_mfma_f32_16x16x32_bf16 v[40:43], v[176:179], v[192:195], v[40:43]
	v_mfma_f32_16x16x32_bf16 v[28:31], v[168:171], v[200:203], v[28:31]
	v_mfma_f32_16x16x32_bf16 v[24:27], v[176:179], v[200:203], v[24:27]
	v_mfma_f32_16x16x32_bf16 v[12:15], v[168:171], v[210:213], v[12:15]
	v_mfma_f32_16x16x32_bf16 v[8:11], v[176:179], v[210:213], v[8:11]
	s_nop 0
	s_barrier
	s_add_u32 s72, s56, 0x40000
	s_addc_u32 s73, s57, 0
	s_add_i32 s74, s61, s34
	v_lshl_add_u64 v[164:165], s[72:73], 0, v[130:131]
	s_mov_b32 m0, s74
	s_nop 0
	global_load_lds_dwordx4 v[164:165], off
	v_lshl_add_u64 v[164:165], s[72:73], 0, v[134:135]
	s_add_i32 m0, s74, 0x2000
	s_nop 0
	global_load_lds_dwordx4 v[164:165], off
	s_waitcnt vmcnt(6)
	s_cmp_gt_u32 s71, 10
	s_cbranch_scc1 .Lds_P6_a_done
	s_cmp_lt_u32 s71, 6
	s_cbranch_scc1 .Lds_P6_a_st
	s_cmp_eq_u32 s71, 6
	s_cbranch_scc1 .Lds_P6_a_pf
	s_cmp_eq_u32 s71, 8
	s_cbranch_scc1 .Lds_P6_a_c8
	v_ffbh_u32_e32 v252, v241
	v_min_u32_e32 v252, 32, v252
	v_lshlrev_b64 v[240:241], v252, v[240:241]
	v_min_u32_e32 v240, 1, v240
	v_or_b32_e32 v241, v241, v240
	v_cvt_f32_u32_e32 v241, v241
	v_sub_u32_e32 v252, -2, v252
	v_ldexp_f32 v241, v241, v252
	v_add_f32_e32 v241, 0x358637bd, v241
	v_rsq_f32_e32 v252, v241
	v_ffbh_u32_e32 v253, v243
	v_min_u32_e32 v253, 32, v253
	v_lshlrev_b64 v[242:243], v253, v[242:243]
	v_min_u32_e32 v242, 1, v242
	v_or_b32_e32 v243, v243, v242
	v_cvt_f32_u32_e32 v243, v243
	v_sub_u32_e32 v253, -2, v253
	v_ldexp_f32 v243, v243, v253
	v_add_f32_e32 v243, 0x358637bd, v243
	v_rsq_f32_e32 v253, v243
	s_branch .Lds_P6_a_done

.Lds_P6_a_done:
	s_barrier
	s_nop 0
	v_mfma_f32_16x16x32_bf16 v[52:55], v[214:217], v[180:183], v[52:55]
	v_mfma_f32_16x16x32_bf16 v[48:51], v[222:225], v[180:183], v[48:51]
	v_mfma_f32_16x16x32_bf16 v[36:39], v[214:217], v[188:191], v[36:39]
	v_mfma_f32_16x16x32_bf16 v[32:35], v[222:225], v[188:191], v[32:35]
	v_mfma_f32_16x16x32_bf16 v[20:23], v[214:217], v[196:199], v[20:23]
	v_mfma_f32_16x16x32_bf16 v[16:19], v[222:225], v[196:199], v[16:19]
	v_mfma_f32_16x16x32_bf16 v[4:7], v[214:217], v[206:209], v[4:7]
	v_mfma_f32_16x16x32_bf16 v[0:3], v[222:225], v[206:209], v[0:3]
	v_mfma_f32_16x16x32_bf16 v[52:55], v[218:221], v[184:187], v[52:55]
	v_mfma_f32_16x16x32_bf16 v[48:51], v[226:229], v[184:187], v[48:51]
	v_mfma_f32_16x16x32_bf16 v[36:39], v[218:221], v[192:195], v[36:39]
	v_mfma_f32_16x16x32_bf16 v[32:35], v[226:229], v[192:195], v[32:35]
	v_mfma_f32_16x16x32_bf16 v[20:23], v[218:221], v[200:203], v[20:23]
	v_mfma_f32_16x16x32_bf16 v[16:19], v[226:229], v[200:203], v[16:19]
	v_mfma_f32_16x16x32_bf16 v[4:7], v[218:221], v[210:213], v[4:7]
	v_mfma_f32_16x16x32_bf16 v[0:3], v[226:229], v[210:213], v[0:3]
	s_nop 0
	s_add_i32 s72, 0, 0x18000
	v_add_u32_e32 v144, s72, v149
	s_barrier
	ds_read_b128 v[164:167], v144
	ds_read_b128 v[168:171], v144 offset:1024
	ds_read_b128 v[172:175], v144 offset:2048
	ds_read_b128 v[176:179], v144 offset:3072
	s_add_u32 s58, s58, 0x40000
	s_addc_u32 s59, s59, 0
	s_mov_b32 m0, s43
	v_lshl_add_u64 v[214:215], s[58:59], 0, v[128:129]
	ds_read_b128 v[180:183], v159 offset:32768
	ds_read_b128 v[184:187], v159 offset:33792
	ds_read_b128 v[188:191], v159 offset:34816
	ds_read_b128 v[192:195], v159 offset:35840
	ds_read_b128 v[196:199], v159 offset:36864
	ds_read_b128 v[200:203], v159 offset:37888
	ds_read_b128 v[206:209], v159 offset:38912
	ds_read_b128 v[210:213], v159 offset:39936
	global_load_lds_dwordx4 v[214:215], off
	v_lshl_add_u64 v[214:215], s[58:59], 0, v[132:133]
	s_mov_b32 m0, s44
	s_nop 0
	global_load_lds_dwordx4 v[214:215], off
	s_waitcnt lgkmcnt(8)
	s_barrier
	s_waitcnt lgkmcnt(0)
	s_nop 0
	s_waitcnt lgkmcnt(0)
	v_mfma_f32_16x16x32_bf16 v[124:127], v[164:167], v[180:183], v[124:127]
	v_mfma_f32_16x16x32_bf16 v[120:123], v[172:175], v[180:183], v[120:123]
	v_mfma_f32_16x16x32_bf16 v[108:111], v[164:167], v[188:191], v[108:111]
	v_mfma_f32_16x16x32_bf16 v[104:107], v[172:175], v[188:191], v[104:107]
	v_mfma_f32_16x16x32_bf16 v[92:95], v[164:167], v[196:199], v[92:95]
	v_mfma_f32_16x16x32_bf16 v[88:91], v[172:175], v[196:199], v[88:91]
	v_mfma_f32_16x16x32_bf16 v[76:79], v[164:167], v[206:209], v[76:79]
	v_mfma_f32_16x16x32_bf16 v[72:75], v[172:175], v[206:209], v[72:75]
	v_mfma_f32_16x16x32_bf16 v[124:127], v[168:171], v[184:187], v[124:127]
	v_mfma_f32_16x16x32_bf16 v[120:123], v[176:179], v[184:187], v[120:123]
	v_mfma_f32_16x16x32_bf16 v[108:111], v[168:171], v[192:195], v[108:111]
	v_mfma_f32_16x16x32_bf16 v[104:107], v[176:179], v[192:195], v[104:107]
	v_mfma_f32_16x16x32_bf16 v[92:95], v[168:171], v[200:203], v[92:95]
	v_mfma_f32_16x16x32_bf16 v[88:91], v[176:179], v[200:203], v[88:91]
	v_mfma_f32_16x16x32_bf16 v[76:79], v[168:171], v[210:213], v[76:79]
	v_mfma_f32_16x16x32_bf16 v[72:75], v[176:179], v[210:213], v[72:75]
	s_nop 0
	s_barrier
	s_add_i32 s58, 0, 0x1c000
	s_add_i32 s59, s72, s34
	v_add_u32_e32 v144, s58, v149
	v_lshl_add_u64 v[146:147], v[146:147], 0, s[24:25]
	s_mov_b32 m0, s59
	ds_read_b128 v[214:217], v144
	ds_read_b128 v[218:221], v144 offset:1024
	ds_read_b128 v[222:225], v144 offset:2048
	ds_read_b128 v[226:229], v144 offset:3072
	global_load_lds_dwordx4 v[146:147], off
	v_lshl_add_u64 v[146:147], v[152:153], 0, s[24:25]
	s_add_i32 m0, s59, 0x2000
	s_nop 0
	global_load_lds_dwordx4 v[146:147], off
	s_barrier
	s_waitcnt lgkmcnt(0)
	s_nop 0
	s_waitcnt lgkmcnt(0)
	v_mfma_f32_16x16x32_bf16 v[116:119], v[214:217], v[180:183], v[116:119]
	v_mfma_f32_16x16x32_bf16 v[112:115], v[222:225], v[180:183], v[112:115]
	v_mfma_f32_16x16x32_bf16 v[100:103], v[214:217], v[188:191], v[100:103]
	v_mfma_f32_16x16x32_bf16 v[96:99], v[222:225], v[188:191], v[96:99]
	v_mfma_f32_16x16x32_bf16 v[84:87], v[214:217], v[196:199], v[84:87]
	v_mfma_f32_16x16x32_bf16 v[80:83], v[222:225], v[196:199], v[80:83]
	v_mfma_f32_16x16x32_bf16 v[68:71], v[214:217], v[206:209], v[68:71]
	v_mfma_f32_16x16x32_bf16 v[64:67], v[222:225], v[206:209], v[64:67]
	v_mfma_f32_16x16x32_bf16 v[116:119], v[218:221], v[184:187], v[116:119]
	v_mfma_f32_16x16x32_bf16 v[112:115], v[226:229], v[184:187], v[112:115]
	v_mfma_f32_16x16x32_bf16 v[100:103], v[218:221], v[192:195], v[100:103]
	v_mfma_f32_16x16x32_bf16 v[96:99], v[226:229], v[192:195], v[96:99]
	v_mfma_f32_16x16x32_bf16 v[84:87], v[218:221], v[200:203], v[84:87]
	v_mfma_f32_16x16x32_bf16 v[80:83], v[226:229], v[200:203], v[80:83]
	v_mfma_f32_16x16x32_bf16 v[68:71], v[218:221], v[210:213], v[68:71]
	v_mfma_f32_16x16x32_bf16 v[64:67], v[226:229], v[210:213], v[64:67]
	s_nop 0
	s_mov_b32 m0, s46
	v_lshl_add_u64 v[146:147], v[156:157], 0, s[24:25]
	s_barrier
	ds_read_b128 v[180:183], v159 offset:49152
	ds_read_b128 v[184:187], v159 offset:50176
	ds_read_b128 v[188:191], v159 offset:51200
	ds_read_b128 v[192:195], v159 offset:52224
	ds_read_b128 v[196:199], v159 offset:53248
	ds_read_b128 v[200:203], v159 offset:54272
	ds_read_b128 v[206:209], v159 offset:55296
	ds_read_b128 v[210:213], v159 offset:56320
	global_load_lds_dwordx4 v[146:147], off
	v_lshl_add_u64 v[146:147], v[160:161], 0, s[24:25]
	s_mov_b32 m0, s47
	s_nop 0
	global_load_lds_dwordx4 v[146:147], off
	s_barrier
	s_waitcnt lgkmcnt(0)
	s_nop 0
	s_waitcnt lgkmcnt(0)
	v_mfma_f32_16x16x32_bf16 v[60:63], v[164:167], v[180:183], v[60:63]
	v_mfma_f32_16x16x32_bf16 v[56:59], v[172:175], v[180:183], v[56:59]
	v_mfma_f32_16x16x32_bf16 v[44:47], v[164:167], v[188:191], v[44:47]
	v_mfma_f32_16x16x32_bf16 v[40:43], v[172:175], v[188:191], v[40:43]
	v_mfma_f32_16x16x32_bf16 v[28:31], v[164:167], v[196:199], v[28:31]
	v_mfma_f32_16x16x32_bf16 v[24:27], v[172:175], v[196:199], v[24:27]
	v_mfma_f32_16x16x32_bf16 v[12:15], v[164:167], v[206:209], v[12:15]
	v_mfma_f32_16x16x32_bf16 v[8:11], v[172:175], v[206:209], v[8:11]
	v_mfma_f32_16x16x32_bf16 v[60:63], v[168:171], v[184:187], v[60:63]
	v_mfma_f32_16x16x32_bf16 v[56:59], v[176:179], v[184:187], v[56:59]
	v_mfma_f32_16x16x32_bf16 v[44:47], v[168:171], v[192:195], v[44:47]
	v_mfma_f32_16x16x32_bf16 v[40:43], v[176:179], v[192:195], v[40:43]
	v_mfma_f32_16x16x32_bf16 v[28:31], v[168:171], v[200:203], v[28:31]
	v_mfma_f32_16x16x32_bf16 v[24:27], v[176:179], v[200:203], v[24:27]
	v_mfma_f32_16x16x32_bf16 v[12:15], v[168:171], v[210:213], v[12:15]
	v_mfma_f32_16x16x32_bf16 v[8:11], v[176:179], v[210:213], v[8:11]
	s_nop 0
	s_barrier
	s_add_u32 s56, s56, 0x40080
	s_addc_u32 s57, s57, 0
	s_add_i32 s58, s58, s34
	v_lshl_add_u64 v[146:147], s[56:57], 0, v[130:131]
	s_mov_b32 m0, s58
	s_nop 0
	global_load_lds_dwordx4 v[146:147], off
	v_lshl_add_u64 v[146:147], s[56:57], 0, v[134:135]
	s_add_i32 m0, s58, 0x2000
	s_nop 0
	global_load_lds_dwordx4 v[146:147], off
	s_waitcnt vmcnt(6)
	s_cmp_gt_u32 s71, 10
	s_cbranch_scc1 .Lds_P6_b_done
	s_cmp_lt_u32 s71, 6
	s_cbranch_scc1 .Lds_P6_b_st
	s_cmp_eq_u32 s71, 6
	s_cbranch_scc1 .Lds_P6_b_l6
	s_cmp_eq_u32 s71, 8
	s_cbranch_scc1 .Lds_P6_b_c8
	v_ffbh_u32_e32 v254, v245
	v_min_u32_e32 v254, 32, v254
	v_lshlrev_b64 v[244:245], v254, v[244:245]
	v_min_u32_e32 v244, 1, v244
	v_or_b32_e32 v245, v245, v244
	v_cvt_f32_u32_e32 v245, v245
	v_sub_u32_e32 v254, -2, v254
	v_ldexp_f32 v245, v245, v254
	v_add_f32_e32 v245, 0x358637bd, v245
	v_rsq_f32_e32 v254, v245
	v_ffbh_u32_e32 v255, v247
	v_min_u32_e32 v255, 32, v255
	v_lshlrev_b64 v[246:247], v255, v[246:247]
	v_min_u32_e32 v246, 1, v246
	v_or_b32_e32 v247, v247, v246
	v_cvt_f32_u32_e32 v247, v247
	v_sub_u32_e32 v255, -2, v255
	v_ldexp_f32 v247, v247, v255
	v_add_f32_e32 v247, 0x358637bd, v247
	v_rsq_f32_e32 v255, v247
	s_branch .Lds_P6_b_done

.Lds_P6_b_done:
	s_barrier
	s_nop 0
	v_mfma_f32_16x16x32_bf16 v[52:55], v[214:217], v[180:183], v[52:55]
	v_mfma_f32_16x16x32_bf16 v[48:51], v[222:225], v[180:183], v[48:51]
	v_mfma_f32_16x16x32_bf16 v[36:39], v[214:217], v[188:191], v[36:39]
	v_mfma_f32_16x16x32_bf16 v[32:35], v[222:225], v[188:191], v[32:35]
	v_mfma_f32_16x16x32_bf16 v[20:23], v[214:217], v[196:199], v[20:23]
	v_mfma_f32_16x16x32_bf16 v[16:19], v[222:225], v[196:199], v[16:19]
	v_mfma_f32_16x16x32_bf16 v[4:7], v[214:217], v[206:209], v[4:7]
	v_mfma_f32_16x16x32_bf16 v[0:3], v[222:225], v[206:209], v[0:3]
	v_mfma_f32_16x16x32_bf16 v[52:55], v[218:221], v[184:187], v[52:55]
	v_mfma_f32_16x16x32_bf16 v[48:51], v[226:229], v[184:187], v[48:51]
	v_mfma_f32_16x16x32_bf16 v[36:39], v[218:221], v[192:195], v[36:39]
	v_mfma_f32_16x16x32_bf16 v[32:35], v[226:229], v[192:195], v[32:35]
	v_mfma_f32_16x16x32_bf16 v[20:23], v[218:221], v[200:203], v[20:23]
	v_mfma_f32_16x16x32_bf16 v[16:19], v[226:229], v[200:203], v[16:19]
	v_mfma_f32_16x16x32_bf16 v[4:7], v[218:221], v[210:213], v[4:7]
	v_mfma_f32_16x16x32_bf16 v[0:3], v[226:229], v[210:213], v[0:3]
	s_nop 0
	s_add_i32 s71, s71, 2
	s_add_u32 s12, s12, 0x100
	s_addc_u32 s13, s13, 0
	s_add_u32 s69, s69, 0x100
	s_addc_u32 s70, s70, 0
	s_cmp_gt_u32 s71, 13
	s_barrier
	s_cbranch_scc0 .LBB0_987

.LBB0_1044:
	s_or_b64 exec, exec, s[8:9]
	v_readlane_b32 s0, v238, 16
	v_readlane_b32 s1, v238, 17
	s_waitcnt lgkmcnt(0)
	s_barrier
	v_readfirstlane_b32 s101, v204
	s_nop 3
	s_lshr_b32 s101, s101, 6
	s_cmp_ge_u32 s101, 4
	s_cbranch_scc0 .Lprio_3
	s_setprio 1
.Lprio_3:
	s_load_dwordx2 s[12:13], s[0:1], 0xb8
	v_mov_b32_e32 v8, v204
	s_and_b64 vcc, exec, s[4:5]
	v_readfirstlane_b32 s0, v8
	s_cbranch_vccnz .LBB0_1050
	s_ashr_i32 s1, s97, 31
	s_lshr_b32 s1, s1, 29
	s_add_i32 s1, s97, s1
	s_and_b32 s2, s1, -8
	s_sub_i32 s2, s97, s2
	s_cmp_gt_i32 s2, -1
	s_cbranch_scc0 .LBB0_1047
	s_lshl_b32 s10, s2, 6
	s_cbranch_execz .LBB0_1048
	s_branch .LBB0_1049

.LBB0_1061:
	s_ashr_i32 s27, s26, 31
	v_cmp_lt_i64_e32 vcc, s[28:29], v[164:165]
	s_lshl_b64 s[28:29], s[26:27], 21
	s_add_u32 s28, s1, s28
	s_addc_u32 s29, s2, s29
	s_and_b64 s[30:31], vcc, exec
	s_cselect_b32 s27, s29, s51
	s_cselect_b32 s37, s28, s50
	s_ashr_i32 s25, s24, 31
	s_lshl_b64 s[30:31], s[24:25], 21
	s_add_u32 s30, s20, s30
	s_addc_u32 s31, s21, s31
	s_and_b64 s[54:55], vcc, exec
	s_cselect_b32 s25, s31, s53
	s_cselect_b32 s57, s30, s52
	s_add_u32 s50, s50, 0x100080
	s_addc_u32 s51, s51, 0
	s_add_u32 s58, s52, 0x100

	s_addc_u32 s59, s53, 0
	s_mov_b32 s60, -2
	s_waitcnt lgkmcnt(0)


	ds_read_b128 v[128:131], v189
	ds_read_b128 v[132:135], v189 offset:1024
	ds_read_b128 v[136:139], v189 offset:2048
	ds_read_b128 v[140:143], v189 offset:3072
	s_add_u32 s52, s50, 0xfff00080
	s_addc_u32 s53, s51, -1
	s_cmp_eq_u32 s60, 60
	s_cselect_b32 s55, s27, s53
	s_cselect_b32 s54, s37, s52
	s_cselect_b32 s53, s25, s59
	s_cselect_b32 s52, s57, s58
	v_lshl_add_u64 v[184:185], s[50:51], 0, v[160:161]
	s_add_i32 m0, s34, 0xc000
	ds_read_b128 v[144:147], v190
	ds_read_b128 v[148:151], v190 offset:1024
	ds_read_b128 v[168:171], v190 offset:2048
	ds_read_b128 v[172:175], v190 offset:3072
	ds_read_b128 v[176:179], v190 offset:4096
	ds_read_b128 v[180:183], v190 offset:5120
	ds_read_b128 v[192:195], v190 offset:6144
	ds_read_b128 v[196:199], v190 offset:7168
	global_load_lds_dwordx4 v[184:185], off
	v_lshl_add_u64 v[184:185], s[50:51], 0, v[162:163]
	s_add_i32 m0, s34, 0xe000
	s_nop 0
	global_load_lds_dwordx4 v[184:185], off
	s_waitcnt lgkmcnt(8)
	s_barrier
	s_waitcnt lgkmcnt(0)
	s_nop 0
	s_waitcnt lgkmcnt(0)
	v_mfma_f32_16x16x32_bf16 v[124:127], v[128:131], v[144:147], 0
	v_mfma_f32_16x16x32_bf16 v[120:123], v[136:139], v[144:147], 0
	v_mfma_f32_16x16x32_bf16 v[108:111], v[128:131], v[168:171], 0
	v_mfma_f32_16x16x32_bf16 v[104:107], v[136:139], v[168:171], 0
	v_mfma_f32_16x16x32_bf16 v[92:95], v[128:131], v[176:179], 0
	v_mfma_f32_16x16x32_bf16 v[88:91], v[136:139], v[176:179], 0
	v_mfma_f32_16x16x32_bf16 v[76:79], v[128:131], v[192:195], 0
	v_mfma_f32_16x16x32_bf16 v[72:75], v[136:139], v[192:195], 0
	v_mfma_f32_16x16x32_bf16 v[124:127], v[132:135], v[148:151], v[124:127]
	v_mfma_f32_16x16x32_bf16 v[120:123], v[140:143], v[148:151], v[120:123]
	v_mfma_f32_16x16x32_bf16 v[108:111], v[132:135], v[172:175], v[108:111]
	v_mfma_f32_16x16x32_bf16 v[104:107], v[140:143], v[172:175], v[104:107]
	v_mfma_f32_16x16x32_bf16 v[92:95], v[132:135], v[180:183], v[92:95]
	v_mfma_f32_16x16x32_bf16 v[88:91], v[140:143], v[180:183], v[88:91]
	v_mfma_f32_16x16x32_bf16 v[76:79], v[132:135], v[196:199], v[76:79]
	v_mfma_f32_16x16x32_bf16 v[72:75], v[140:143], v[196:199], v[72:75]
	s_nop 0
	s_barrier
	s_add_i32 s61, s49, s33
	v_lshl_add_u64 v[184:185], s[52:53], 0, v[154:155]
	s_mov_b32 m0, s61
	ds_read_b128 v[200:203], v191
	ds_read_b128 v[206:209], v191 offset:1024
	ds_read_b128 v[210:213], v191 offset:2048
	ds_read_b128 v[214:217], v191 offset:3072
	global_load_lds_dwordx4 v[184:185], off
	v_lshl_add_u64 v[218:219], s[52:53], 0, v[158:159]
	s_add_i32 m0, s61, 0x2000
	s_nop 0
	global_load_lds_dwordx4 v[218:219], off
	s_barrier
	s_waitcnt lgkmcnt(0)
	s_nop 0
	s_waitcnt lgkmcnt(0)
	v_mfma_f32_16x16x32_bf16 v[116:119], v[200:203], v[144:147], 0
	v_mfma_f32_16x16x32_bf16 v[112:115], v[210:213], v[144:147], 0
	v_mfma_f32_16x16x32_bf16 v[100:103], v[200:203], v[168:171], 0
	v_mfma_f32_16x16x32_bf16 v[96:99], v[210:213], v[168:171], 0
	v_mfma_f32_16x16x32_bf16 v[84:87], v[200:203], v[176:179], 0
	v_mfma_f32_16x16x32_bf16 v[80:83], v[210:213], v[176:179], 0
	v_mfma_f32_16x16x32_bf16 v[68:71], v[200:203], v[192:195], 0
	v_mfma_f32_16x16x32_bf16 v[64:67], v[210:213], v[192:195], 0
	v_mfma_f32_16x16x32_bf16 v[116:119], v[206:209], v[148:151], v[116:119]
	v_mfma_f32_16x16x32_bf16 v[112:115], v[214:217], v[148:151], v[112:115]
	v_mfma_f32_16x16x32_bf16 v[100:103], v[206:209], v[172:175], v[100:103]
	v_mfma_f32_16x16x32_bf16 v[96:99], v[214:217], v[172:175], v[96:99]
	v_mfma_f32_16x16x32_bf16 v[84:87], v[206:209], v[180:183], v[84:87]
	v_mfma_f32_16x16x32_bf16 v[80:83], v[214:217], v[180:183], v[80:83]
	v_mfma_f32_16x16x32_bf16 v[68:71], v[206:209], v[196:199], v[68:71]
	v_mfma_f32_16x16x32_bf16 v[64:67], v[214:217], v[196:199], v[64:67]
	s_nop 0
	s_mov_b32 m0, s34
	v_lshl_add_u64 v[220:221], s[54:55], 0, v[152:153]
	s_barrier
	ds_read_b128 v[144:147], v190 offset:16384
	ds_read_b128 v[148:151], v190 offset:17408
	ds_read_b128 v[168:171], v190 offset:18432
	ds_read_b128 v[172:175], v190 offset:19456
	ds_read_b128 v[176:179], v190 offset:20480
	ds_read_b128 v[180:183], v190 offset:21504
	ds_read_b128 v[192:195], v190 offset:22528
	ds_read_b128 v[196:199], v190 offset:23552
	global_load_lds_dwordx4 v[220:221], off
	v_lshl_add_u64 v[222:223], s[54:55], 0, v[156:157]
	s_mov_b32 m0, s35
	s_nop 0
	global_load_lds_dwordx4 v[222:223], off
	s_barrier
	s_waitcnt lgkmcnt(0)
	s_nop 0
	s_waitcnt lgkmcnt(0)
	v_mfma_f32_16x16x32_bf16 v[60:63], v[128:131], v[144:147], 0
	v_mfma_f32_16x16x32_bf16 v[56:59], v[136:139], v[144:147], 0
	v_mfma_f32_16x16x32_bf16 v[44:47], v[128:131], v[168:171], 0
	v_mfma_f32_16x16x32_bf16 v[40:43], v[136:139], v[168:171], 0
	v_mfma_f32_16x16x32_bf16 v[28:31], v[128:131], v[176:179], 0
	v_mfma_f32_16x16x32_bf16 v[24:27], v[136:139], v[176:179], 0
	v_mfma_f32_16x16x32_bf16 v[12:15], v[128:131], v[192:195], 0
	v_mfma_f32_16x16x32_bf16 v[8:11], v[136:139], v[192:195], 0
	v_mfma_f32_16x16x32_bf16 v[60:63], v[132:135], v[148:151], v[60:63]
	v_mfma_f32_16x16x32_bf16 v[56:59], v[140:143], v[148:151], v[56:59]
	v_mfma_f32_16x16x32_bf16 v[44:47], v[132:135], v[172:175], v[44:47]
	v_mfma_f32_16x16x32_bf16 v[40:43], v[140:143], v[172:175], v[40:43]
	v_mfma_f32_16x16x32_bf16 v[28:31], v[132:135], v[180:183], v[28:31]
	v_mfma_f32_16x16x32_bf16 v[24:27], v[140:143], v[180:183], v[24:27]
	v_mfma_f32_16x16x32_bf16 v[12:15], v[132:135], v[196:199], v[12:15]
	v_mfma_f32_16x16x32_bf16 v[8:11], v[140:143], v[196:199], v[8:11]
	s_nop 0
	s_barrier
	s_add_u32 s62, s52, 0x100000
	s_addc_u32 s63, s53, 0
	s_add_i32 s61, s56, s33
	v_lshl_add_u64 v[128:129], s[62:63], 0, v[154:155]
	s_mov_b32 m0, s61
	s_nop 0
	global_load_lds_dwordx4 v[128:129], off
	v_lshl_add_u64 v[128:129], s[62:63], 0, v[158:159]
	s_add_i32 m0, s61, 0x2000
	s_nop 0
	global_load_lds_dwordx4 v[128:129], off
	s_waitcnt vmcnt(6)
	s_barrier
	s_nop 0
	v_mfma_f32_16x16x32_bf16 v[52:55], v[200:203], v[144:147], 0
	v_mfma_f32_16x16x32_bf16 v[48:51], v[210:213], v[144:147], 0
	v_mfma_f32_16x16x32_bf16 v[36:39], v[200:203], v[168:171], 0
	v_mfma_f32_16x16x32_bf16 v[32:35], v[210:213], v[168:171], 0
	v_mfma_f32_16x16x32_bf16 v[20:23], v[200:203], v[176:179], 0
	v_mfma_f32_16x16x32_bf16 v[16:19], v[210:213], v[176:179], 0
	v_mfma_f32_16x16x32_bf16 v[4:7], v[200:203], v[192:195], 0
	v_mfma_f32_16x16x32_bf16 v[0:3], v[210:213], v[192:195], 0
	v_mfma_f32_16x16x32_bf16 v[52:55], v[206:209], v[148:151], v[52:55]
	v_mfma_f32_16x16x32_bf16 v[48:51], v[214:217], v[148:151], v[48:51]
	v_mfma_f32_16x16x32_bf16 v[36:39], v[206:209], v[172:175], v[36:39]
	v_mfma_f32_16x16x32_bf16 v[32:35], v[214:217], v[172:175], v[32:35]
	v_mfma_f32_16x16x32_bf16 v[20:23], v[206:209], v[180:183], v[20:23]
	v_mfma_f32_16x16x32_bf16 v[16:19], v[214:217], v[180:183], v[16:19]
	v_mfma_f32_16x16x32_bf16 v[4:7], v[206:209], v[196:199], v[4:7]
	v_mfma_f32_16x16x32_bf16 v[0:3], v[214:217], v[196:199], v[0:3]
	s_nop 0
	s_add_i32 s61, 0, 0x18000
	v_add_u32_e32 v140, s61, v187
	s_barrier
	ds_read_b128 v[128:131], v140
	ds_read_b128 v[132:135], v140 offset:1024
	ds_read_b128 v[136:139], v140 offset:2048
	ds_read_b128 v[140:143], v140 offset:3072
	s_add_u32 s54, s54, 0x100000
	s_addc_u32 s55, s55, 0
	s_mov_b32 m0, s39
	v_lshl_add_u64 v[200:201], s[54:55], 0, v[152:153]
	ds_read_b128 v[144:147], v190 offset:32768
	ds_read_b128 v[148:151], v190 offset:33792
	ds_read_b128 v[168:171], v190 offset:34816
	ds_read_b128 v[172:175], v190 offset:35840
	ds_read_b128 v[176:179], v190 offset:36864
	ds_read_b128 v[180:183], v190 offset:37888
	ds_read_b128 v[192:195], v190 offset:38912
	ds_read_b128 v[196:199], v190 offset:39936
	global_load_lds_dwordx4 v[200:201], off
	v_lshl_add_u64 v[200:201], s[54:55], 0, v[156:157]
	s_mov_b32 m0, s42
	s_nop 0
	global_load_lds_dwordx4 v[200:201], off
	s_waitcnt lgkmcnt(8)
	s_barrier
	s_waitcnt lgkmcnt(0)
	s_nop 0
	s_waitcnt lgkmcnt(0)
	v_mfma_f32_16x16x32_bf16 v[124:127], v[128:131], v[144:147], v[124:127]
	v_mfma_f32_16x16x32_bf16 v[120:123], v[136:139], v[144:147], v[120:123]
	v_mfma_f32_16x16x32_bf16 v[108:111], v[128:131], v[168:171], v[108:111]
	v_mfma_f32_16x16x32_bf16 v[104:107], v[136:139], v[168:171], v[104:107]
	v_mfma_f32_16x16x32_bf16 v[92:95], v[128:131], v[176:179], v[92:95]
	v_mfma_f32_16x16x32_bf16 v[88:91], v[136:139], v[176:179], v[88:91]
	v_mfma_f32_16x16x32_bf16 v[76:79], v[128:131], v[192:195], v[76:79]
	v_mfma_f32_16x16x32_bf16 v[72:75], v[136:139], v[192:195], v[72:75]
	v_mfma_f32_16x16x32_bf16 v[124:127], v[132:135], v[148:151], v[124:127]
	v_mfma_f32_16x16x32_bf16 v[120:123], v[140:143], v[148:151], v[120:123]
	v_mfma_f32_16x16x32_bf16 v[108:111], v[132:135], v[172:175], v[108:111]
	v_mfma_f32_16x16x32_bf16 v[104:107], v[140:143], v[172:175], v[104:107]
	v_mfma_f32_16x16x32_bf16 v[92:95], v[132:135], v[180:183], v[92:95]
	v_mfma_f32_16x16x32_bf16 v[88:91], v[140:143], v[180:183], v[88:91]
	v_mfma_f32_16x16x32_bf16 v[76:79], v[132:135], v[196:199], v[76:79]
	v_mfma_f32_16x16x32_bf16 v[72:75], v[140:143], v[196:199], v[72:75]
	s_nop 0
	s_barrier
	s_add_i32 s54, 0, 0x1c000
	s_add_i32 s55, s61, s33
	v_add_u32_e32 v214, s54, v187
	v_lshl_add_u64 v[184:185], v[184:185], 0, s[18:19]
	s_mov_b32 m0, s55
	ds_read_b128 v[200:203], v214
	ds_read_b128 v[206:209], v214 offset:1024
	ds_read_b128 v[210:213], v214 offset:2048
	ds_read_b128 v[214:217], v214 offset:3072
	global_load_lds_dwordx4 v[184:185], off
	v_lshl_add_u64 v[184:185], v[218:219], 0, s[18:19]
	s_add_i32 m0, s55, 0x2000
	s_nop 0
	global_load_lds_dwordx4 v[184:185], off
	s_barrier
	s_waitcnt lgkmcnt(0)
	s_nop 0
	s_waitcnt lgkmcnt(0)
	v_mfma_f32_16x16x32_bf16 v[116:119], v[200:203], v[144:147], v[116:119]
	v_mfma_f32_16x16x32_bf16 v[112:115], v[210:213], v[144:147], v[112:115]
	v_mfma_f32_16x16x32_bf16 v[100:103], v[200:203], v[168:171], v[100:103]
	v_mfma_f32_16x16x32_bf16 v[96:99], v[210:213], v[168:171], v[96:99]
	v_mfma_f32_16x16x32_bf16 v[84:87], v[200:203], v[176:179], v[84:87]
	v_mfma_f32_16x16x32_bf16 v[80:83], v[210:213], v[176:179], v[80:83]
	v_mfma_f32_16x16x32_bf16 v[68:71], v[200:203], v[192:195], v[68:71]
	v_mfma_f32_16x16x32_bf16 v[64:67], v[210:213], v[192:195], v[64:67]
	v_mfma_f32_16x16x32_bf16 v[116:119], v[206:209], v[148:151], v[116:119]
	v_mfma_f32_16x16x32_bf16 v[112:115], v[214:217], v[148:151], v[112:115]
	v_mfma_f32_16x16x32_bf16 v[100:103], v[206:209], v[172:175], v[100:103]
	v_mfma_f32_16x16x32_bf16 v[96:99], v[214:217], v[172:175], v[96:99]
	v_mfma_f32_16x16x32_bf16 v[84:87], v[206:209], v[180:183], v[84:87]
	v_mfma_f32_16x16x32_bf16 v[80:83], v[214:217], v[180:183], v[80:83]
	v_mfma_f32_16x16x32_bf16 v[68:71], v[206:209], v[196:199], v[68:71]
	v_mfma_f32_16x16x32_bf16 v[64:67], v[214:217], v[196:199], v[64:67]
	s_nop 0
	s_mov_b32 m0, s44
	v_lshl_add_u64 v[184:185], v[220:221], 0, s[18:19]
	s_barrier
	ds_read_b128 v[144:147], v190 offset:49152
	ds_read_b128 v[148:151], v190 offset:50176
	ds_read_b128 v[168:171], v190 offset:51200
	ds_read_b128 v[172:175], v190 offset:52224
	ds_read_b128 v[176:179], v190 offset:53248
	ds_read_b128 v[180:183], v190 offset:54272
	ds_read_b128 v[192:195], v190 offset:55296
	ds_read_b128 v[196:199], v190 offset:56320
	global_load_lds_dwordx4 v[184:185], off
	v_lshl_add_u64 v[184:185], v[222:223], 0, s[18:19]
	s_mov_b32 m0, s45
	s_nop 0
	global_load_lds_dwordx4 v[184:185], off
	s_barrier
	s_waitcnt lgkmcnt(0)
	s_nop 0
	s_waitcnt lgkmcnt(0)
	v_mfma_f32_16x16x32_bf16 v[60:63], v[128:131], v[144:147], v[60:63]
	v_mfma_f32_16x16x32_bf16 v[56:59], v[136:139], v[144:147], v[56:59]
	v_mfma_f32_16x16x32_bf16 v[44:47], v[128:131], v[168:171], v[44:47]
	v_mfma_f32_16x16x32_bf16 v[40:43], v[136:139], v[168:171], v[40:43]
	v_mfma_f32_16x16x32_bf16 v[28:31], v[128:131], v[176:179], v[28:31]
	v_mfma_f32_16x16x32_bf16 v[24:27], v[136:139], v[176:179], v[24:27]
	v_mfma_f32_16x16x32_bf16 v[12:15], v[128:131], v[192:195], v[12:15]
	v_mfma_f32_16x16x32_bf16 v[8:11], v[136:139], v[192:195], v[8:11]
	v_mfma_f32_16x16x32_bf16 v[60:63], v[132:135], v[148:151], v[60:63]
	v_mfma_f32_16x16x32_bf16 v[56:59], v[140:143], v[148:151], v[56:59]
	v_mfma_f32_16x16x32_bf16 v[44:47], v[132:135], v[172:175], v[44:47]
	v_mfma_f32_16x16x32_bf16 v[40:43], v[140:143], v[172:175], v[40:43]
	v_mfma_f32_16x16x32_bf16 v[28:31], v[132:135], v[180:183], v[28:31]
	v_mfma_f32_16x16x32_bf16 v[24:27], v[140:143], v[180:183], v[24:27]
	v_mfma_f32_16x16x32_bf16 v[12:15], v[132:135], v[196:199], v[12:15]
	v_mfma_f32_16x16x32_bf16 v[8:11], v[140:143], v[196:199], v[8:11]
	s_nop 0
	s_barrier
	s_add_u32 s52, s52, 0x100080
	s_addc_u32 s53, s53, 0
	s_add_i32 s54, s54, s33
	v_lshl_add_u64 v[128:129], s[52:53], 0, v[154:155]
	s_mov_b32 m0, s54
	s_nop 0
	global_load_lds_dwordx4 v[128:129], off
	v_lshl_add_u64 v[128:129], s[52:53], 0, v[158:159]
	s_add_i32 m0, s54, 0x2000
	s_nop 0
	global_load_lds_dwordx4 v[128:129], off
	s_waitcnt vmcnt(6)
	s_barrier
	s_nop 0
	v_mfma_f32_16x16x32_bf16 v[52:55], v[200:203], v[144:147], v[52:55]
	v_mfma_f32_16x16x32_bf16 v[48:51], v[210:213], v[144:147], v[48:51]
	v_mfma_f32_16x16x32_bf16 v[36:39], v[200:203], v[168:171], v[36:39]
	v_mfma_f32_16x16x32_bf16 v[32:35], v[210:213], v[168:171], v[32:35]
	v_mfma_f32_16x16x32_bf16 v[20:23], v[200:203], v[176:179], v[20:23]
	v_mfma_f32_16x16x32_bf16 v[16:19], v[210:213], v[176:179], v[16:19]
	v_mfma_f32_16x16x32_bf16 v[4:7], v[200:203], v[192:195], v[4:7]
	v_mfma_f32_16x16x32_bf16 v[0:3], v[210:213], v[192:195], v[0:3]
	v_mfma_f32_16x16x32_bf16 v[52:55], v[206:209], v[148:151], v[52:55]
	v_mfma_f32_16x16x32_bf16 v[48:51], v[214:217], v[148:151], v[48:51]
	v_mfma_f32_16x16x32_bf16 v[36:39], v[206:209], v[172:175], v[36:39]
	v_mfma_f32_16x16x32_bf16 v[32:35], v[214:217], v[172:175], v[32:35]
	v_mfma_f32_16x16x32_bf16 v[20:23], v[206:209], v[180:183], v[20:23]
	v_mfma_f32_16x16x32_bf16 v[16:19], v[214:217], v[180:183], v[16:19]
	v_mfma_f32_16x16x32_bf16 v[4:7], v[206:209], v[196:199], v[4:7]
	v_mfma_f32_16x16x32_bf16 v[0:3], v[214:217], v[196:199], v[0:3]
	s_nop 0
	s_add_i32 s60, s60, 2
	s_add_u32 s50, s50, 0x100
	s_addc_u32 s51, s51, 0
	s_add_u32 s58, s58, 0x100
	s_addc_u32 s59, s59, 0
	s_cmp_gt_u32 s60, 61
	s_barrier
.LBB0_1062:
	ds_read_b128 v[128:131], v189
	ds_read_b128 v[132:135], v189 offset:1024
	ds_read_b128 v[136:139], v189 offset:2048
	ds_read_b128 v[140:143], v189 offset:3072
	s_add_u32 s52, s50, 0xfff00080
	s_addc_u32 s53, s51, -1
	s_cmp_eq_u32 s60, 60
	s_cselect_b32 s55, s27, s53
	s_cselect_b32 s54, s37, s52
	s_cselect_b32 s53, s25, s59
	s_cselect_b32 s52, s57, s58
	v_lshl_add_u64 v[184:185], s[50:51], 0, v[160:161]
	s_add_i32 m0, s34, 0xc000
	ds_read_b128 v[144:147], v190
	ds_read_b128 v[148:151], v190 offset:1024
	ds_read_b128 v[168:171], v190 offset:2048
	ds_read_b128 v[172:175], v190 offset:3072
	ds_read_b128 v[176:179], v190 offset:4096
	ds_read_b128 v[180:183], v190 offset:5120
	ds_read_b128 v[192:195], v190 offset:6144
	ds_read_b128 v[196:199], v190 offset:7168
	global_load_lds_dwordx4 v[184:185], off
	v_lshl_add_u64 v[184:185], s[50:51], 0, v[162:163]
	s_add_i32 m0, s34, 0xe000
	s_nop 0
	global_load_lds_dwordx4 v[184:185], off
	s_waitcnt lgkmcnt(8)
	s_barrier
	s_waitcnt lgkmcnt(0)
	s_nop 0
	s_waitcnt lgkmcnt(0)
	v_mfma_f32_16x16x32_bf16 v[124:127], v[128:131], v[144:147], v[124:127]
	v_mfma_f32_16x16x32_bf16 v[120:123], v[136:139], v[144:147], v[120:123]
	v_mfma_f32_16x16x32_bf16 v[108:111], v[128:131], v[168:171], v[108:111]
	v_mfma_f32_16x16x32_bf16 v[104:107], v[136:139], v[168:171], v[104:107]
	v_mfma_f32_16x16x32_bf16 v[92:95], v[128:131], v[176:179], v[92:95]
	v_mfma_f32_16x16x32_bf16 v[88:91], v[136:139], v[176:179], v[88:91]
	v_mfma_f32_16x16x32_bf16 v[76:79], v[128:131], v[192:195], v[76:79]
	v_mfma_f32_16x16x32_bf16 v[72:75], v[136:139], v[192:195], v[72:75]
	v_mfma_f32_16x16x32_bf16 v[124:127], v[132:135], v[148:151], v[124:127]
	v_mfma_f32_16x16x32_bf16 v[120:123], v[140:143], v[148:151], v[120:123]
	v_mfma_f32_16x16x32_bf16 v[108:111], v[132:135], v[172:175], v[108:111]
	v_mfma_f32_16x16x32_bf16 v[104:107], v[140:143], v[172:175], v[104:107]
	v_mfma_f32_16x16x32_bf16 v[92:95], v[132:135], v[180:183], v[92:95]
	v_mfma_f32_16x16x32_bf16 v[88:91], v[140:143], v[180:183], v[88:91]
	v_mfma_f32_16x16x32_bf16 v[76:79], v[132:135], v[196:199], v[76:79]
	v_mfma_f32_16x16x32_bf16 v[72:75], v[140:143], v[196:199], v[72:75]
	s_nop 0
	s_barrier
	s_add_i32 s61, s49, s33
	v_lshl_add_u64 v[184:185], s[52:53], 0, v[154:155]
	s_mov_b32 m0, s61
	ds_read_b128 v[200:203], v191
	ds_read_b128 v[206:209], v191 offset:1024
	ds_read_b128 v[210:213], v191 offset:2048
	ds_read_b128 v[214:217], v191 offset:3072
	global_load_lds_dwordx4 v[184:185], off
	v_lshl_add_u64 v[218:219], s[52:53], 0, v[158:159]
	s_add_i32 m0, s61, 0x2000
	s_nop 0
	global_load_lds_dwordx4 v[218:219], off
	s_barrier
	s_waitcnt lgkmcnt(0)
	s_nop 0
	s_waitcnt lgkmcnt(0)
	v_mfma_f32_16x16x32_bf16 v[116:119], v[200:203], v[144:147], v[116:119]
	v_mfma_f32_16x16x32_bf16 v[112:115], v[210:213], v[144:147], v[112:115]
	v_mfma_f32_16x16x32_bf16 v[100:103], v[200:203], v[168:171], v[100:103]
	v_mfma_f32_16x16x32_bf16 v[96:99], v[210:213], v[168:171], v[96:99]
	v_mfma_f32_16x16x32_bf16 v[84:87], v[200:203], v[176:179], v[84:87]
	v_mfma_f32_16x16x32_bf16 v[80:83], v[210:213], v[176:179], v[80:83]
	v_mfma_f32_16x16x32_bf16 v[68:71], v[200:203], v[192:195], v[68:71]
	v_mfma_f32_16x16x32_bf16 v[64:67], v[210:213], v[192:195], v[64:67]
	v_mfma_f32_16x16x32_bf16 v[116:119], v[206:209], v[148:151], v[116:119]
	v_mfma_f32_16x16x32_bf16 v[112:115], v[214:217], v[148:151], v[112:115]
	v_mfma_f32_16x16x32_bf16 v[100:103], v[206:209], v[172:175], v[100:103]
	v_mfma_f32_16x16x32_bf16 v[96:99], v[214:217], v[172:175], v[96:99]
	v_mfma_f32_16x16x32_bf16 v[84:87], v[206:209], v[180:183], v[84:87]
	v_mfma_f32_16x16x32_bf16 v[80:83], v[214:217], v[180:183], v[80:83]
	v_mfma_f32_16x16x32_bf16 v[68:71], v[206:209], v[196:199], v[68:71]
	v_mfma_f32_16x16x32_bf16 v[64:67], v[214:217], v[196:199], v[64:67]
	s_nop 0
	s_mov_b32 m0, s34
	v_lshl_add_u64 v[220:221], s[54:55], 0, v[152:153]
	s_barrier
	ds_read_b128 v[144:147], v190 offset:16384
	ds_read_b128 v[148:151], v190 offset:17408
	ds_read_b128 v[168:171], v190 offset:18432
	ds_read_b128 v[172:175], v190 offset:19456
	ds_read_b128 v[176:179], v190 offset:20480
	ds_read_b128 v[180:183], v190 offset:21504
	ds_read_b128 v[192:195], v190 offset:22528
	ds_read_b128 v[196:199], v190 offset:23552
	global_load_lds_dwordx4 v[220:221], off
	v_lshl_add_u64 v[222:223], s[54:55], 0, v[156:157]
	s_mov_b32 m0, s35
	s_nop 0
	global_load_lds_dwordx4 v[222:223], off
	s_barrier
	s_waitcnt lgkmcnt(0)
	s_nop 0
	s_waitcnt lgkmcnt(0)
	v_mfma_f32_16x16x32_bf16 v[60:63], v[128:131], v[144:147], v[60:63]
	v_mfma_f32_16x16x32_bf16 v[56:59], v[136:139], v[144:147], v[56:59]
	v_mfma_f32_16x16x32_bf16 v[44:47], v[128:131], v[168:171], v[44:47]
	v_mfma_f32_16x16x32_bf16 v[40:43], v[136:139], v[168:171], v[40:43]
	v_mfma_f32_16x16x32_bf16 v[28:31], v[128:131], v[176:179], v[28:31]
	v_mfma_f32_16x16x32_bf16 v[24:27], v[136:139], v[176:179], v[24:27]
	v_mfma_f32_16x16x32_bf16 v[12:15], v[128:131], v[192:195], v[12:15]
	v_mfma_f32_16x16x32_bf16 v[8:11], v[136:139], v[192:195], v[8:11]
	v_mfma_f32_16x16x32_bf16 v[60:63], v[132:135], v[148:151], v[60:63]
	v_mfma_f32_16x16x32_bf16 v[56:59], v[140:143], v[148:151], v[56:59]
	v_mfma_f32_16x16x32_bf16 v[44:47], v[132:135], v[172:175], v[44:47]
	v_mfma_f32_16x16x32_bf16 v[40:43], v[140:143], v[172:175], v[40:43]
	v_mfma_f32_16x16x32_bf16 v[28:31], v[132:135], v[180:183], v[28:31]
	v_mfma_f32_16x16x32_bf16 v[24:27], v[140:143], v[180:183], v[24:27]
	v_mfma_f32_16x16x32_bf16 v[12:15], v[132:135], v[196:199], v[12:15]
	v_mfma_f32_16x16x32_bf16 v[8:11], v[140:143], v[196:199], v[8:11]
	s_nop 0
	s_barrier
	s_add_u32 s62, s52, 0x100000
	s_addc_u32 s63, s53, 0
	s_add_i32 s61, s56, s33
	v_lshl_add_u64 v[128:129], s[62:63], 0, v[154:155]
	s_mov_b32 m0, s61
	s_nop 0
	global_load_lds_dwordx4 v[128:129], off
	v_lshl_add_u64 v[128:129], s[62:63], 0, v[158:159]
	s_add_i32 m0, s61, 0x2000
	s_nop 0
	global_load_lds_dwordx4 v[128:129], off
	s_waitcnt vmcnt(6)
	s_barrier
	s_nop 0
	v_mfma_f32_16x16x32_bf16 v[52:55], v[200:203], v[144:147], v[52:55]
	v_mfma_f32_16x16x32_bf16 v[48:51], v[210:213], v[144:147], v[48:51]
	v_mfma_f32_16x16x32_bf16 v[36:39], v[200:203], v[168:171], v[36:39]
	v_mfma_f32_16x16x32_bf16 v[32:35], v[210:213], v[168:171], v[32:35]
	v_mfma_f32_16x16x32_bf16 v[20:23], v[200:203], v[176:179], v[20:23]
	v_mfma_f32_16x16x32_bf16 v[16:19], v[210:213], v[176:179], v[16:19]
	v_mfma_f32_16x16x32_bf16 v[4:7], v[200:203], v[192:195], v[4:7]
	v_mfma_f32_16x16x32_bf16 v[0:3], v[210:213], v[192:195], v[0:3]
	v_mfma_f32_16x16x32_bf16 v[52:55], v[206:209], v[148:151], v[52:55]
	v_mfma_f32_16x16x32_bf16 v[48:51], v[214:217], v[148:151], v[48:51]
	v_mfma_f32_16x16x32_bf16 v[36:39], v[206:209], v[172:175], v[36:39]
	v_mfma_f32_16x16x32_bf16 v[32:35], v[214:217], v[172:175], v[32:35]
	v_mfma_f32_16x16x32_bf16 v[20:23], v[206:209], v[180:183], v[20:23]
	v_mfma_f32_16x16x32_bf16 v[16:19], v[214:217], v[180:183], v[16:19]
	v_mfma_f32_16x16x32_bf16 v[4:7], v[206:209], v[196:199], v[4:7]
	v_mfma_f32_16x16x32_bf16 v[0:3], v[214:217], v[196:199], v[0:3]
	s_nop 0
	s_add_i32 s61, 0, 0x18000
	v_add_u32_e32 v140, s61, v187
	s_barrier
	ds_read_b128 v[128:131], v140
	ds_read_b128 v[132:135], v140 offset:1024
	ds_read_b128 v[136:139], v140 offset:2048
	ds_read_b128 v[140:143], v140 offset:3072
	s_add_u32 s54, s54, 0x100000
	s_addc_u32 s55, s55, 0
	s_mov_b32 m0, s39
	v_lshl_add_u64 v[200:201], s[54:55], 0, v[152:153]
	ds_read_b128 v[144:147], v190 offset:32768
	ds_read_b128 v[148:151], v190 offset:33792
	ds_read_b128 v[168:171], v190 offset:34816
	ds_read_b128 v[172:175], v190 offset:35840
	ds_read_b128 v[176:179], v190 offset:36864
	ds_read_b128 v[180:183], v190 offset:37888
	ds_read_b128 v[192:195], v190 offset:38912
	ds_read_b128 v[196:199], v190 offset:39936
	global_load_lds_dwordx4 v[200:201], off
	v_lshl_add_u64 v[200:201], s[54:55], 0, v[156:157]
	s_mov_b32 m0, s42
	s_nop 0
	global_load_lds_dwordx4 v[200:201], off
	s_waitcnt lgkmcnt(8)
	s_barrier
	s_waitcnt lgkmcnt(0)
	s_nop 0
	s_waitcnt lgkmcnt(0)
	v_mfma_f32_16x16x32_bf16 v[124:127], v[128:131], v[144:147], v[124:127]
	v_mfma_f32_16x16x32_bf16 v[120:123], v[136:139], v[144:147], v[120:123]
	v_mfma_f32_16x16x32_bf16 v[108:111], v[128:131], v[168:171], v[108:111]
	v_mfma_f32_16x16x32_bf16 v[104:107], v[136:139], v[168:171], v[104:107]
	v_mfma_f32_16x16x32_bf16 v[92:95], v[128:131], v[176:179], v[92:95]
	v_mfma_f32_16x16x32_bf16 v[88:91], v[136:139], v[176:179], v[88:91]
	v_mfma_f32_16x16x32_bf16 v[76:79], v[128:131], v[192:195], v[76:79]
	v_mfma_f32_16x16x32_bf16 v[72:75], v[136:139], v[192:195], v[72:75]
	v_mfma_f32_16x16x32_bf16 v[124:127], v[132:135], v[148:151], v[124:127]
	v_mfma_f32_16x16x32_bf16 v[120:123], v[140:143], v[148:151], v[120:123]
	v_mfma_f32_16x16x32_bf16 v[108:111], v[132:135], v[172:175], v[108:111]
	v_mfma_f32_16x16x32_bf16 v[104:107], v[140:143], v[172:175], v[104:107]
	v_mfma_f32_16x16x32_bf16 v[92:95], v[132:135], v[180:183], v[92:95]
	v_mfma_f32_16x16x32_bf16 v[88:91], v[140:143], v[180:183], v[88:91]
	v_mfma_f32_16x16x32_bf16 v[76:79], v[132:135], v[196:199], v[76:79]
	v_mfma_f32_16x16x32_bf16 v[72:75], v[140:143], v[196:199], v[72:75]
	s_nop 0
	s_barrier
	s_add_i32 s54, 0, 0x1c000
	s_add_i32 s55, s61, s33
	v_add_u32_e32 v214, s54, v187
	v_lshl_add_u64 v[184:185], v[184:185], 0, s[18:19]
	s_mov_b32 m0, s55
	ds_read_b128 v[200:203], v214
	ds_read_b128 v[206:209], v214 offset:1024
	ds_read_b128 v[210:213], v214 offset:2048
	ds_read_b128 v[214:217], v214 offset:3072
	global_load_lds_dwordx4 v[184:185], off
	v_lshl_add_u64 v[184:185], v[218:219], 0, s[18:19]
	s_add_i32 m0, s55, 0x2000
	s_nop 0
	global_load_lds_dwordx4 v[184:185], off
	s_barrier
	s_waitcnt lgkmcnt(0)
	s_nop 0
	s_waitcnt lgkmcnt(0)
	v_mfma_f32_16x16x32_bf16 v[116:119], v[200:203], v[144:147], v[116:119]
	v_mfma_f32_16x16x32_bf16 v[112:115], v[210:213], v[144:147], v[112:115]
	v_mfma_f32_16x16x32_bf16 v[100:103], v[200:203], v[168:171], v[100:103]
	v_mfma_f32_16x16x32_bf16 v[96:99], v[210:213], v[168:171], v[96:99]
	v_mfma_f32_16x16x32_bf16 v[84:87], v[200:203], v[176:179], v[84:87]
	v_mfma_f32_16x16x32_bf16 v[80:83], v[210:213], v[176:179], v[80:83]
	v_mfma_f32_16x16x32_bf16 v[68:71], v[200:203], v[192:195], v[68:71]
	v_mfma_f32_16x16x32_bf16 v[64:67], v[210:213], v[192:195], v[64:67]
	v_mfma_f32_16x16x32_bf16 v[116:119], v[206:209], v[148:151], v[116:119]
	v_mfma_f32_16x16x32_bf16 v[112:115], v[214:217], v[148:151], v[112:115]
	v_mfma_f32_16x16x32_bf16 v[100:103], v[206:209], v[172:175], v[100:103]
	v_mfma_f32_16x16x32_bf16 v[96:99], v[214:217], v[172:175], v[96:99]
	v_mfma_f32_16x16x32_bf16 v[84:87], v[206:209], v[180:183], v[84:87]
	v_mfma_f32_16x16x32_bf16 v[80:83], v[214:217], v[180:183], v[80:83]
	v_mfma_f32_16x16x32_bf16 v[68:71], v[206:209], v[196:199], v[68:71]
	v_mfma_f32_16x16x32_bf16 v[64:67], v[214:217], v[196:199], v[64:67]
	s_nop 0
	s_mov_b32 m0, s44
	v_lshl_add_u64 v[184:185], v[220:221], 0, s[18:19]
	s_barrier
	ds_read_b128 v[144:147], v190 offset:49152
	ds_read_b128 v[148:151], v190 offset:50176
	ds_read_b128 v[168:171], v190 offset:51200
	ds_read_b128 v[172:175], v190 offset:52224
	ds_read_b128 v[176:179], v190 offset:53248
	ds_read_b128 v[180:183], v190 offset:54272
	ds_read_b128 v[192:195], v190 offset:55296
	ds_read_b128 v[196:199], v190 offset:56320
	global_load_lds_dwordx4 v[184:185], off
	v_lshl_add_u64 v[184:185], v[222:223], 0, s[18:19]
	s_mov_b32 m0, s45
	s_nop 0
	global_load_lds_dwordx4 v[184:185], off
	s_barrier
	s_waitcnt lgkmcnt(0)
	s_nop 0
	s_waitcnt lgkmcnt(0)
	v_mfma_f32_16x16x32_bf16 v[60:63], v[128:131], v[144:147], v[60:63]
	v_mfma_f32_16x16x32_bf16 v[56:59], v[136:139], v[144:147], v[56:59]
	v_mfma_f32_16x16x32_bf16 v[44:47], v[128:131], v[168:171], v[44:47]
	v_mfma_f32_16x16x32_bf16 v[40:43], v[136:139], v[168:171], v[40:43]
	v_mfma_f32_16x16x32_bf16 v[28:31], v[128:131], v[176:179], v[28:31]
	v_mfma_f32_16x16x32_bf16 v[24:27], v[136:139], v[176:179], v[24:27]
	v_mfma_f32_16x16x32_bf16 v[12:15], v[128:131], v[192:195], v[12:15]
	v_mfma_f32_16x16x32_bf16 v[8:11], v[136:139], v[192:195], v[8:11]
	v_mfma_f32_16x16x32_bf16 v[60:63], v[132:135], v[148:151], v[60:63]
	v_mfma_f32_16x16x32_bf16 v[56:59], v[140:143], v[148:151], v[56:59]
	v_mfma_f32_16x16x32_bf16 v[44:47], v[132:135], v[172:175], v[44:47]
	v_mfma_f32_16x16x32_bf16 v[40:43], v[140:143], v[172:175], v[40:43]
	v_mfma_f32_16x16x32_bf16 v[28:31], v[132:135], v[180:183], v[28:31]
	v_mfma_f32_16x16x32_bf16 v[24:27], v[140:143], v[180:183], v[24:27]
	v_mfma_f32_16x16x32_bf16 v[12:15], v[132:135], v[196:199], v[12:15]
	v_mfma_f32_16x16x32_bf16 v[8:11], v[140:143], v[196:199], v[8:11]
	s_nop 0
	s_barrier
	s_add_u32 s52, s52, 0x100080
	s_addc_u32 s53, s53, 0
	s_add_i32 s54, s54, s33
	v_lshl_add_u64 v[128:129], s[52:53], 0, v[154:155]
	s_mov_b32 m0, s54
	s_nop 0
	global_load_lds_dwordx4 v[128:129], off
	v_lshl_add_u64 v[128:129], s[52:53], 0, v[158:159]
	s_add_i32 m0, s54, 0x2000
	s_nop 0
	global_load_lds_dwordx4 v[128:129], off
	s_waitcnt vmcnt(6)
	s_cmp_eq_u32 s60, 58
	s_cbranch_scc0 .Ler_1062_skip
	s_lshl_b32 s84, s36, 19
	s_lshl_b32 s85, s38, 9
	s_add_u32 s84, s84, s85
	s_add_u32 s84, s14, s84
	s_addc_u32 s85, s15, 0
	v_lshlrev_b32_e32 v236, 11, v186
	v_lshl_add_u32 v236, v188, 1, v236
	global_load_dwordx4 v[224:227], v236, s[84:85]
	global_load_dwordx4 v[228:231], v236, s[84:85] offset:256
	s_add_u32 s86, s84, 0x8000
	s_addc_u32 s87, s85, 0
	global_load_dwordx4 v[232:235], v236, s[86:87]
	global_load_dwordx4 v[240:243], v236, s[86:87] offset:256
	s_add_u32 s86, s84, 0x10000
	s_addc_u32 s87, s85, 0
	global_load_dwordx4 v[244:247], v236, s[86:87]
	global_load_dwordx4 v[248:251], v236, s[86:87] offset:256
	s_add_u32 s86, s84, 0x18000
	s_addc_u32 s87, s85, 0
	global_load_dwordx4 v[252:255], v236, s[86:87]
.Ler_1062_skip:
	s_barrier
	s_nop 0
	v_mfma_f32_16x16x32_bf16 v[52:55], v[200:203], v[144:147], v[52:55]
	v_mfma_f32_16x16x32_bf16 v[48:51], v[210:213], v[144:147], v[48:51]
	v_mfma_f32_16x16x32_bf16 v[36:39], v[200:203], v[168:171], v[36:39]
	v_mfma_f32_16x16x32_bf16 v[32:35], v[210:213], v[168:171], v[32:35]
	v_mfma_f32_16x16x32_bf16 v[20:23], v[200:203], v[176:179], v[20:23]
	v_mfma_f32_16x16x32_bf16 v[16:19], v[210:213], v[176:179], v[16:19]
	v_mfma_f32_16x16x32_bf16 v[4:7], v[200:203], v[192:195], v[4:7]
	v_mfma_f32_16x16x32_bf16 v[0:3], v[210:213], v[192:195], v[0:3]
	v_mfma_f32_16x16x32_bf16 v[52:55], v[206:209], v[148:151], v[52:55]
	v_mfma_f32_16x16x32_bf16 v[48:51], v[214:217], v[148:151], v[48:51]
	v_mfma_f32_16x16x32_bf16 v[36:39], v[206:209], v[172:175], v[36:39]
	v_mfma_f32_16x16x32_bf16 v[32:35], v[214:217], v[172:175], v[32:35]
	v_mfma_f32_16x16x32_bf16 v[20:23], v[206:209], v[180:183], v[20:23]
	v_mfma_f32_16x16x32_bf16 v[16:19], v[214:217], v[180:183], v[16:19]
	v_mfma_f32_16x16x32_bf16 v[4:7], v[206:209], v[196:199], v[4:7]
	v_mfma_f32_16x16x32_bf16 v[0:3], v[214:217], v[196:199], v[0:3]
	s_nop 0
	s_add_i32 s60, s60, 2
	s_add_u32 s50, s50, 0x100
	s_addc_u32 s51, s51, 0
	s_add_u32 s58, s58, 0x100
	s_addc_u32 s59, s59, 0
	s_cmp_gt_u32 s60, 61
	s_barrier
	s_cbranch_scc0 .LBB0_1062
	v_lshl_or_b32 v168, s38, 8, v188
	v_lshl_add_u32 v170, s36, 8, v186
	v_ashrrev_i32_e32 v169, 31, v168
	v_lshlrev_b64 v[202:203], 1, v[168:169]
	v_ashrrev_i32_e32 v171, 31, v170
	v_or_b32_e32 v182, 16, v170
	v_lshl_add_u64 v[172:173], s[14:15], 0, v[202:203]
	v_lshlrev_b64 v[206:207], 11, v[170:171]
	v_ashrrev_i32_e32 v183, 31, v182
	v_or_b32_e32 v178, 32, v170
	v_lshl_add_u64 v[128:129], v[172:173], 0, v[206:207]
	v_lshlrev_b64 v[184:185], 11, v[182:183]
	v_ashrrev_i32_e32 v179, 31, v178
	v_or_b32_e32 v174, 48, v170
	v_mov_b32_e32 v194, v224
	v_mov_b32_e32 v195, v225
	v_mov_b32_e32 v196, v226
	v_mov_b32_e32 v197, v227
	v_mov_b32_e32 v198, v228
	v_mov_b32_e32 v199, v229
	v_mov_b32_e32 v200, v230
	v_mov_b32_e32 v201, v231
	v_lshl_add_u64 v[128:129], v[172:173], 0, v[184:185]
	v_lshlrev_b64 v[180:181], 11, v[178:179]
	v_ashrrev_i32_e32 v175, 31, v174
	v_mov_b32_e32 v148, v232
	v_mov_b32_e32 v149, v233
	v_mov_b32_e32 v150, v234
	v_mov_b32_e32 v151, v235
	v_mov_b32_e32 v144, v240
	v_mov_b32_e32 v145, v241
	v_mov_b32_e32 v146, v242
	v_mov_b32_e32 v147, v243
	v_lshl_add_u64 v[128:129], v[172:173], 0, v[180:181]
	v_lshlrev_b64 v[176:177], 11, v[174:175]
	v_mov_b32_e32 v140, v244
	v_mov_b32_e32 v141, v245
	v_mov_b32_e32 v142, v246
	v_mov_b32_e32 v143, v247
	v_mov_b32_e32 v136, v248
	v_mov_b32_e32 v137, v249
	v_mov_b32_e32 v138, v250
	v_mov_b32_e32 v139, v251
	v_lshl_add_u64 v[128:129], v[172:173], 0, v[176:177]
	v_mov_b32_e32 v132, v252
	v_mov_b32_e32 v133, v253
	v_mov_b32_e32 v134, v254
	v_mov_b32_e32 v135, v255
	s_nop 0
	global_load_dwordx4 v[128:131], v[128:129], off offset:256
	v_and_b32_e32 v193, 64, v205
	v_xor_b32_e32 v192, 16, v205
	v_add_u32_e32 v208, 64, v193
	v_cmp_lt_i32_e32 vcc, v192, v208
	s_nop 1
	v_cndmask_b32_e32 v192, v205, v192, vcc
	v_lshlrev_b32_e32 v193, 2, v192
	v_xor_b32_e32 v192, 32, v205
	v_cmp_lt_i32_e32 vcc, v192, v208
	s_nop 1
	v_cndmask_b32_e32 v192, v205, v192, vcc
	v_lshlrev_b32_e32 v192, 2, v192
	v_add_u32_e32 v236, 0x80, v170
	v_ashrrev_i32_e32 v237, 31, v236
	v_lshlrev_b64 v[236:237], 11, v[236:237]
	v_lshl_add_u64 v[236:237], v[172:173], 0, v[236:237]
	global_load_dwordx4 v[224:227], v[236:237], off
	global_load_dwordx4 v[228:231], v[236:237], off offset:256
	v_add_u32_e32 v236, 0x90, v170
	v_ashrrev_i32_e32 v237, 31, v236
	v_lshlrev_b64 v[236:237], 11, v[236:237]
	v_lshl_add_u64 v[236:237], v[172:173], 0, v[236:237]
	global_load_dwordx4 v[232:235], v[236:237], off
	global_load_dwordx4 v[240:243], v[236:237], off offset:256
	v_add_u32_e32 v236, 0xa0, v170
	v_ashrrev_i32_e32 v237, 31, v236
	v_lshlrev_b64 v[236:237], 11, v[236:237]
	v_lshl_add_u64 v[236:237], v[172:173], 0, v[236:237]
	global_load_dwordx4 v[244:247], v[236:237], off
	global_load_dwordx4 v[248:251], v[236:237], off offset:256
	v_add_u32_e32 v236, 0xb0, v170
	v_ashrrev_i32_e32 v237, 31, v236
	v_lshlrev_b64 v[236:237], 11, v[236:237]
	v_lshl_add_u64 v[236:237], v[172:173], 0, v[236:237]
	global_load_dwordx4 v[252:255], v[236:237], off
	s_waitcnt vmcnt(24)
	v_lshlrev_b32_e32 v208, 16, v194
	v_and_b32_e32 v209, 0xffff0000, v194
	v_lshlrev_b32_e32 v194, 16, v195
	v_and_b32_e32 v195, 0xffff0000, v195
	v_lshlrev_b32_e32 v210, 16, v196
	v_and_b32_e32 v211, 0xffff0000, v196
	v_lshlrev_b32_e32 v196, 16, v197
	v_and_b32_e32 v197, 0xffff0000, v197
	v_pk_add_f32 v[126:127], v[126:127], v[194:195]
	v_pk_add_f32 v[194:195], v[122:123], v[196:197]
	v_pk_add_f32 v[196:197], v[120:121], v[210:211]
	v_pk_add_f32 v[124:125], v[124:125], v[208:209]
	v_cvt_pk_bf16_f32 v122, v196, v197
	v_mul_f32_e32 v196, v196, v196
	v_cvt_pk_bf16_f32 v120, v124, v125
	v_fmac_f32_e32 v196, v124, v124
	v_mul_f32_e32 v124, v197, v197
	v_fmac_f32_e32 v124, v125, v125
	v_mul_f32_e32 v125, v194, v194
	v_add_f32_e32 v124, v196, v124
	v_fmac_f32_e32 v125, v126, v126
	v_add_f32_e32 v124, v125, v124
	v_mul_f32_e32 v125, v195, v195
	v_cvt_pk_bf16_f32 v121, v126, v127
	v_cvt_pk_bf16_f32 v123, v194, v195
	v_fmac_f32_e32 v125, v127, v127
	v_lshlrev_b32_e32 v126, 16, v199
	v_and_b32_e32 v127, 0xffff0000, v199
	v_lshlrev_b32_e32 v194, 16, v200
	v_and_b32_e32 v195, 0xffff0000, v200
	v_add_f32_e32 v208, v125, v124
	v_lshlrev_b32_e32 v124, 16, v198
	v_and_b32_e32 v125, 0xffff0000, v198
	v_pk_add_f32 v[118:119], v[118:119], v[126:127]
	v_pk_add_f32 v[126:127], v[112:113], v[194:195]
	v_pk_add_f32 v[116:117], v[116:117], v[124:125]
	v_mul_f32_e32 v112, v126, v126
	v_lshlrev_b32_e32 v196, 16, v201
	v_and_b32_e32 v197, 0xffff0000, v201
	v_fmac_f32_e32 v112, v116, v116
	v_mul_f32_e32 v113, v127, v127
	v_pk_add_f32 v[124:125], v[114:115], v[196:197]
	v_add_f32_e32 v112, v112, v208
	v_fmac_f32_e32 v113, v117, v117
	v_add_f32_e32 v112, v113, v112
	v_mul_f32_e32 v113, v124, v124
	v_fmac_f32_e32 v113, v118, v118
	v_add_f32_e32 v112, v113, v112
	v_mul_f32_e32 v113, v125, v125
	v_fmac_f32_e32 v113, v119, v119
	v_add_f32_e32 v115, v113, v112
	ds_bpermute_b32 v196, v193, v115
	v_lshl_add_u64 v[112:113], s[14:15], 0, v[206:207]
	v_lshl_add_u64 v[194:195], v[112:113], 0, v[202:203]
	v_cvt_pk_bf16_f32 v114, v116, v117
	v_cvt_pk_bf16_f32 v116, v126, v127
	s_waitcnt lgkmcnt(0)
	v_add_f32_e32 v112, v115, v196
	ds_bpermute_b32 v113, v192, v112
	v_cvt_pk_bf16_f32 v115, v118, v119
	v_cvt_pk_bf16_f32 v117, v124, v125
	global_store_dwordx4 v[194:195], v[120:123], off
	global_store_dwordx4 v[194:195], v[114:117], off offset:256
	s_and_saveexec_b64 s[36:37], s[8:9]
	s_cbranch_execz .LBB0_1065
	s_waitcnt lgkmcnt(0)
	v_add_f32_e32 v112, v112, v113
	v_mul_f32_e32 v112, 0x4b800000, v112
	v_trunc_f32_e32 v112, v112
	v_mul_f32_e32 v113, 0x2f800000, v112
	v_floor_f32_e32 v113, v113
	v_fmac_f32_e32 v112, 0xcf800000, v113
	v_cvt_u32_f32_e32 v112, v112
	v_cvt_u32_f32_e32 v113, v113
	v_lshl_add_u64 v[114:115], v[170:171], 3, s[16:17]
	global_atomic_add_x2 v[114:115], v[112:113], off

.Lprio_4:
	s_load_dwordx2 s[14:15], s[0:1], 0xb8
	s_load_dwordx4 s[16:19], s[0:1], 0x88
	s_load_dwordx4 s[36:39], s[0:1], 0x8
	s_load_dwordx8 s[24:31], s[0:1], 0x20
	v_mov_b32_e32 v9, v204
	s_waitcnt lgkmcnt(0)
	s_add_u32 s50, s14, 0x1900000
	s_addc_u32 s51, s15, 0
	s_cmpk_gt_i32 s97, 0x67f
	v_readfirstlane_b32 s0, v9
	s_cbranch_scc1 .LBB0_1146
	v_lshlrev_b32_e32 v0, 4, v9
	v_add_u32_e32 v1, 0x2000, v0
	v_ashrrev_i32_e32 v2, 31, v1
	v_lshrrev_b32_e32 v2, 22, v2
	v_add_u32_e32 v2, v1, v2
	v_ashrrev_i32_e32 v8, 10, v2
	v_mul_i32_i24_e32 v2, 0x400, v8
	v_sub_u32_e32 v1, v1, v2
	v_lshrrev_b32_e32 v2, 4, v1
	v_bitop3_b32 v1, v2, v1, 32 bitop3:0x6c
	v_ashrrev_i32_e32 v2, 31, v1
	v_lshrrev_b32_e32 v2, 26, v2
	v_add_u32_e32 v2, v1, v2
	v_lshlrev_b32_e32 v3, 3, v8
	v_ashrrev_i32_e32 v10, 6, v2
	v_and_b32_e32 v3, -16, v3
	v_add_u32_e32 v3, v10, v3
	v_and_b32_e32 v4, 3, v10
	s_mov_b32 s8, 0x1fffe0
	v_lshrrev_b32_e32 v5, 2, v3
	v_lshlrev_b32_e32 v6, 1, v3
	v_and_b32_e32 v2, 0xc0, v2
	v_and_or_b32 v4, v3, s8, v4
	v_and_b32_e32 v5, 4, v5
	v_and_b32_e32 v6, 24, v6
	v_sub_u32_e32 v1, v1, v2
	v_mov_b32_e32 v2, 1
	v_or3_b32 v4, v4, v5, v6
	v_lshlrev_b32_e32 v5, 5, v8
	v_ashrrev_i16_sdwa v1, v2, sext(v1) dst_sel:DWORD dst_unused:UNUSED_PAD src0_sel:DWORD src1_sel:BYTE_0
	v_and_b32_e32 v5, 32, v5
	v_bfe_i32 v11, v1, 0, 16
	v_add_lshl_u32 v1, v5, v11, 1
	v_lshl_add_u32 v128, v4, 11, v1
	v_lshl_add_u32 v130, v3, 11, v1
	v_bfe_i32 v1, v9, 27, 1
	v_lshrrev_b32_e32 v1, 22, v1
	v_add_u32_e32 v1, v0, v1
	v_and_b32_e32 v1, 0xfffffc00, v1
	v_sub_u32_e32 v0, v0, v1
	v_lshrrev_b32_e32 v1, 4, v0
	v_bitop3_b32 v1, v1, v0, 32 bitop3:0x6c
	v_ashrrev_i32_e32 v0, 31, v0
	v_lshrrev_b32_e32 v0, 26, v0
	v_add_u32_e32 v0, v1, v0
	s_waitcnt vmcnt(2)
	v_ashrrev_i32_e32 v12, 6, v0
	v_ashrrev_i32_e32 v0, 31, v9
	v_lshrrev_b32_e32 v0, 26, v0
	v_add_u32_e32 v0, v9, v0
	v_ashrrev_i32_e32 v13, 6, v0
	v_lshlrev_b32_e32 v0, 3, v13
	s_add_u32 s1, s14, 0x3a00000
	v_and_b32_e32 v0, -16, v0
	s_addc_u32 s2, s15, 0
	v_add_u32_e32 v0, v12, v0
	v_and_b32_e32 v3, 3, v12
	s_ashr_i32 s21, s97, 31
	v_and_or_b32 v3, v0, s8, v3
	s_lshr_b32 s8, s21, 29
	s_add_i32 s8, s97, s8
	s_ashr_i32 s45, s0, 6
	s_ashr_i32 s10, s8, 3
	s_and_b32 s8, s8, -8
	s_ashr_i32 s9, s0, 8
	s_lshl_b32 s20, s45, 10
	s_sub_i32 s8, s97, s8
	s_cmp_lt_i32 s8, 0
	s_movk_i32 s33, 0xd1
	s_cselect_b32 s11, s33, 0xd0
	s_mul_i32 s8, s11, s8
	s_add_i32 s8, s8, s10
	s_mul_hi_i32 s10, s8, 0x4ec4ec4f
	s_lshr_b32 s11, s10, 31
	s_ashr_i32 s10, s10, 4
	s_add_i32 s10, s10, s11
	s_lshl_b32 s11, s10, 2
	s_mul_i32 s10, s10, 52
	s_sub_i32 s10, s8, s10
	s_bfe_i32 s8, s10, 0x80000
	s_bfe_u32 s8, s8, 0x2000d
	s_add_i32 s12, s10, s8
	s_bfe_i32 s8, s12, 0x80000
	s_and_b32 s12, s12, 0xfc
	v_lshrrev_b32_e32 v4, 2, v0
	v_lshlrev_b32_e32 v5, 1, v0
	s_sub_i32 s10, s10, s12
	v_and_b32_e32 v4, 4, v4
	v_and_b32_e32 v5, 24, v5
	s_sext_i32_i16 s8, s8
	s_sext_i32_i8 s10, s10
	v_or3_b32 v3, v3, v4, v5
	v_mul_i32_i24_e32 v5, 64, v12
	s_lshr_b32 s8, s8, 2
	s_add_i32 s10, s11, s10
	v_sub_u32_e32 v1, v1, v5
	s_ashr_i32 s11, s10, 31
	s_bfe_i64 s[34:35], s[8:9], 0x100000
	v_lshlrev_b32_e32 v4, 5, v13
	v_ashrrev_i16_sdwa v1, v2, sext(v1) dst_sel:DWORD dst_unused:UNUSED_PAD src0_sel:DWORD src1_sel:BYTE_0
	s_lshl_b64 s[12:13], s[10:11], 19
	s_lshl_b64 s[34:35], s[34:35], 19
	v_and_b32_e32 v4, 32, v4
	v_bfe_i32 v14, v1, 0, 16
	s_add_u32 s66, s50, s34
	v_add_lshl_u32 v1, v4, v14, 1
	s_addc_u32 s67, s51, s35
	s_add_i32 s34, s20, 0
	v_lshl_add_u32 v132, v3, 11, v1
	s_add_i32 m0, s34, 0x10000
	v_lshl_add_u32 v134, v0, 11, v1
	global_load_lds_dwordx4 v132, s[66:67]
	s_add_i32 m0, s34, 0x12000
	s_add_u32 s12, s1, s12
	global_load_lds_dwordx4 v128, s[66:67]
	s_addc_u32 s13, s2, s13
	s_mov_b32 m0, s34
	s_add_i32 s35, s34, 0x2000
	global_load_lds_dwordx4 v134, s[12:13]
	s_mov_b32 m0, s35
	s_add_u32 s42, s66, 0x40000
	global_load_lds_dwordx4 v130, s[12:13]
	s_addc_u32 s43, s67, 0
	s_add_i32 m0, s34, 0x14000
	v_mov_b32_e32 v133, 0
	global_load_lds_dwordx4 v132, s[42:43]
	s_add_i32 m0, s34, 0x16000
	s_add_u32 s46, s12, 0x40000
	global_load_lds_dwordx4 v128, s[42:43]
	s_addc_u32 s47, s13, 0
	s_add_i32 s42, s34, 0x4000
	s_mov_b32 m0, s42
	s_add_i32 s43, s34, 0x6000
	global_load_lds_dwordx4 v134, s[46:47]
	s_mov_b32 m0, s43
	v_mov_b32_e32 v129, v133
	global_load_lds_dwordx4 v130, s[46:47]
	v_mov_b32_e32 v135, v133
	v_mov_b32_e32 v131, v133
	s_mov_b32 s44, 0
	v_lshl_add_u64 v[6:7], s[66:67], 0, v[132:133]
	v_lshl_add_u64 v[4:5], s[66:67], 0, v[128:129]
	v_lshl_add_u64 v[2:3], s[12:13], 0, v[134:135]
	s_cmp_lg_u32 s9, 1
	v_lshl_add_u64 v[0:1], s[12:13], 0, v[130:131]
	s_cbranch_scc1 .LBB0_1137
	s_barrier

.LBB0_1140:
	s_ashr_i32 s61, s60, 31
	v_cmp_lt_i64_e32 vcc, s[62:63], v[140:141]
	s_lshl_b64 s[62:63], s[60:61], 19
	s_add_u32 s62, s1, s62
	s_addc_u32 s63, s2, s63
	s_and_b64 s[64:65], vcc, exec
	s_cselect_b32 s11, s63, s13
	s_cselect_b32 s61, s62, s12
	s_ashr_i32 s59, s58, 31
	s_lshl_b64 s[64:65], s[58:59], 19
	s_add_u32 s64, s50, s64
	s_addc_u32 s65, s51, s65
	s_and_b64 s[68:69], vcc, exec
	s_cselect_b32 s59, s65, s67
	s_cselect_b32 s74, s64, s66
	s_add_u32 s12, s12, 0x40080
	s_addc_u32 s13, s13, 0
	s_add_u32 s75, s66, 0x100

	s_addc_u32 s76, s67, 0
	s_mov_b32 s77, -2


	ds_read_b128 v[144:147], v159
	ds_read_b128 v[150:153], v159 offset:1024
	ds_read_b128 v[164:167], v159 offset:2048
	ds_read_b128 v[168:171], v159 offset:3072
	s_add_u32 s66, s12, 0xfffc0080
	s_addc_u32 s67, s13, -1
	s_cmp_eq_u32 s77, 12
	s_cselect_b32 s69, s11, s67
	s_cselect_b32 s68, s61, s66
	s_cselect_b32 s67, s59, s76
	s_cselect_b32 s66, s74, s75
	v_lshl_add_u64 v[154:155], s[12:13], 0, v[136:137]
	s_add_i32 m0, s34, 0xc000
	ds_read_b128 v[172:175], v160
	ds_read_b128 v[176:179], v160 offset:1024
	ds_read_b128 v[180:183], v160 offset:2048
	ds_read_b128 v[184:187], v160 offset:3072
	ds_read_b128 v[188:191], v160 offset:4096
	ds_read_b128 v[192:195], v160 offset:5120
	ds_read_b128 v[196:199], v160 offset:6144
	ds_read_b128 v[200:203], v160 offset:7168
	global_load_lds_dwordx4 v[154:155], off
	v_lshl_add_u64 v[154:155], s[12:13], 0, v[138:139]
	s_add_i32 m0, s34, 0xe000
	s_nop 0
	global_load_lds_dwordx4 v[154:155], off
	s_waitcnt lgkmcnt(8)
	s_barrier
	s_waitcnt lgkmcnt(0)
	s_nop 0
	s_waitcnt lgkmcnt(0)
	v_mfma_f32_16x16x32_bf16 v[124:127], v[144:147], v[172:175], 0
	v_mfma_f32_16x16x32_bf16 v[120:123], v[164:167], v[172:175], 0
	v_mfma_f32_16x16x32_bf16 v[116:119], v[144:147], v[180:183], 0
	v_mfma_f32_16x16x32_bf16 v[108:111], v[164:167], v[180:183], 0
	v_mfma_f32_16x16x32_bf16 v[100:103], v[144:147], v[188:191], 0
	v_mfma_f32_16x16x32_bf16 v[92:95], v[164:167], v[188:191], 0
	v_mfma_f32_16x16x32_bf16 v[84:87], v[144:147], v[196:199], 0
	v_mfma_f32_16x16x32_bf16 v[76:79], v[164:167], v[196:199], 0
	v_mfma_f32_16x16x32_bf16 v[124:127], v[150:153], v[176:179], v[124:127]
	v_mfma_f32_16x16x32_bf16 v[120:123], v[168:171], v[176:179], v[120:123]
	v_mfma_f32_16x16x32_bf16 v[116:119], v[150:153], v[184:187], v[116:119]
	v_mfma_f32_16x16x32_bf16 v[108:111], v[168:171], v[184:187], v[108:111]
	v_mfma_f32_16x16x32_bf16 v[100:103], v[150:153], v[192:195], v[100:103]
	v_mfma_f32_16x16x32_bf16 v[92:95], v[168:171], v[192:195], v[92:95]
	v_mfma_f32_16x16x32_bf16 v[84:87], v[150:153], v[200:203], v[84:87]
	v_mfma_f32_16x16x32_bf16 v[76:79], v[168:171], v[200:203], v[76:79]
	s_nop 0
	s_barrier
	s_add_i32 s78, s49, s20
	v_lshl_add_u64 v[154:155], s[66:67], 0, v[132:133]
	s_mov_b32 m0, s78
	ds_read_b128 v[206:209], v161
	ds_read_b128 v[210:213], v161 offset:1024
	ds_read_b128 v[214:217], v161 offset:2048
	ds_read_b128 v[218:221], v161 offset:3072
	global_load_lds_dwordx4 v[154:155], off
	v_lshl_add_u64 v[222:223], s[66:67], 0, v[128:129]
	s_add_i32 m0, s78, 0x2000
	s_nop 0
	global_load_lds_dwordx4 v[222:223], off
	s_barrier
	s_waitcnt lgkmcnt(0)
	s_nop 0
	s_waitcnt lgkmcnt(0)
	v_mfma_f32_16x16x32_bf16 v[112:115], v[206:209], v[172:175], 0
	v_mfma_f32_16x16x32_bf16 v[104:107], v[214:217], v[172:175], 0
	v_mfma_f32_16x16x32_bf16 v[96:99], v[206:209], v[180:183], 0
	v_mfma_f32_16x16x32_bf16 v[88:91], v[214:217], v[180:183], 0
	v_mfma_f32_16x16x32_bf16 v[80:83], v[206:209], v[188:191], 0
	v_mfma_f32_16x16x32_bf16 v[72:75], v[214:217], v[188:191], 0
	v_mfma_f32_16x16x32_bf16 v[68:71], v[206:209], v[196:199], 0
	v_mfma_f32_16x16x32_bf16 v[64:67], v[214:217], v[196:199], 0
	v_mfma_f32_16x16x32_bf16 v[112:115], v[210:213], v[176:179], v[112:115]
	v_mfma_f32_16x16x32_bf16 v[104:107], v[218:221], v[176:179], v[104:107]
	v_mfma_f32_16x16x32_bf16 v[96:99], v[210:213], v[184:187], v[96:99]
	v_mfma_f32_16x16x32_bf16 v[88:91], v[218:221], v[184:187], v[88:91]
	v_mfma_f32_16x16x32_bf16 v[80:83], v[210:213], v[192:195], v[80:83]
	v_mfma_f32_16x16x32_bf16 v[72:75], v[218:221], v[192:195], v[72:75]
	v_mfma_f32_16x16x32_bf16 v[68:71], v[210:213], v[200:203], v[68:71]
	v_mfma_f32_16x16x32_bf16 v[64:67], v[218:221], v[200:203], v[64:67]
	s_nop 0
	s_mov_b32 m0, s34
	v_lshl_add_u64 v[224:225], s[68:69], 0, v[134:135]
	s_barrier
	ds_read_b128 v[172:175], v160 offset:16384
	ds_read_b128 v[176:179], v160 offset:17408
	ds_read_b128 v[180:183], v160 offset:18432
	ds_read_b128 v[184:187], v160 offset:19456
	ds_read_b128 v[188:191], v160 offset:20480
	ds_read_b128 v[192:195], v160 offset:21504
	ds_read_b128 v[196:199], v160 offset:22528
	ds_read_b128 v[200:203], v160 offset:23552
	global_load_lds_dwordx4 v[224:225], off
	v_lshl_add_u64 v[226:227], s[68:69], 0, v[130:131]
	s_mov_b32 m0, s35
	s_nop 0
	global_load_lds_dwordx4 v[226:227], off
	s_barrier
	s_waitcnt lgkmcnt(0)
	s_nop 0
	s_waitcnt lgkmcnt(0)
	v_mfma_f32_16x16x32_bf16 v[60:63], v[144:147], v[172:175], 0
	v_mfma_f32_16x16x32_bf16 v[56:59], v[164:167], v[172:175], 0
	v_mfma_f32_16x16x32_bf16 v[52:55], v[144:147], v[180:183], 0
	v_mfma_f32_16x16x32_bf16 v[44:47], v[164:167], v[180:183], 0
	v_mfma_f32_16x16x32_bf16 v[36:39], v[144:147], v[188:191], 0
	v_mfma_f32_16x16x32_bf16 v[28:31], v[164:167], v[188:191], 0
	v_mfma_f32_16x16x32_bf16 v[20:23], v[144:147], v[196:199], 0
	v_mfma_f32_16x16x32_bf16 v[12:15], v[164:167], v[196:199], 0
	v_mfma_f32_16x16x32_bf16 v[60:63], v[150:153], v[176:179], v[60:63]
	v_mfma_f32_16x16x32_bf16 v[56:59], v[168:171], v[176:179], v[56:59]
	v_mfma_f32_16x16x32_bf16 v[52:55], v[150:153], v[184:187], v[52:55]
	v_mfma_f32_16x16x32_bf16 v[44:47], v[168:171], v[184:187], v[44:47]
	v_mfma_f32_16x16x32_bf16 v[36:39], v[150:153], v[192:195], v[36:39]
	v_mfma_f32_16x16x32_bf16 v[28:31], v[168:171], v[192:195], v[28:31]
	v_mfma_f32_16x16x32_bf16 v[20:23], v[150:153], v[200:203], v[20:23]
	v_mfma_f32_16x16x32_bf16 v[12:15], v[168:171], v[200:203], v[12:15]
	s_nop 0
	s_barrier
	s_add_u32 s78, s66, 0x40000
	s_addc_u32 s79, s67, 0
	s_add_i32 s80, s70, s20
	v_lshl_add_u64 v[144:145], s[78:79], 0, v[132:133]
	s_mov_b32 m0, s80
	s_nop 0
	global_load_lds_dwordx4 v[144:145], off
	v_lshl_add_u64 v[144:145], s[78:79], 0, v[128:129]
	s_add_i32 m0, s80, 0x2000
	s_nop 0
	global_load_lds_dwordx4 v[144:145], off
	s_waitcnt vmcnt(6)
	s_barrier
	s_nop 0
	v_mfma_f32_16x16x32_bf16 v[48:51], v[206:209], v[172:175], 0
	v_mfma_f32_16x16x32_bf16 v[40:43], v[214:217], v[172:175], 0
	v_mfma_f32_16x16x32_bf16 v[32:35], v[206:209], v[180:183], 0
	v_mfma_f32_16x16x32_bf16 v[24:27], v[214:217], v[180:183], 0
	v_mfma_f32_16x16x32_bf16 v[16:19], v[206:209], v[188:191], 0
	v_mfma_f32_16x16x32_bf16 v[8:11], v[214:217], v[188:191], 0
	v_mfma_f32_16x16x32_bf16 v[4:7], v[206:209], v[196:199], 0
	v_mfma_f32_16x16x32_bf16 v[0:3], v[214:217], v[196:199], 0
	v_mfma_f32_16x16x32_bf16 v[48:51], v[210:213], v[176:179], v[48:51]
	v_mfma_f32_16x16x32_bf16 v[40:43], v[218:221], v[176:179], v[40:43]
	v_mfma_f32_16x16x32_bf16 v[32:35], v[210:213], v[184:187], v[32:35]
	v_mfma_f32_16x16x32_bf16 v[24:27], v[218:221], v[184:187], v[24:27]
	v_mfma_f32_16x16x32_bf16 v[16:19], v[210:213], v[192:195], v[16:19]
	v_mfma_f32_16x16x32_bf16 v[8:11], v[218:221], v[192:195], v[8:11]
	v_mfma_f32_16x16x32_bf16 v[4:7], v[210:213], v[200:203], v[4:7]
	v_mfma_f32_16x16x32_bf16 v[0:3], v[218:221], v[200:203], v[0:3]
	s_nop 0
	s_add_i32 s78, 0, 0x18000
	v_add_u32_e32 v148, s78, v157
	s_barrier
	ds_read_b128 v[144:147], v148
	ds_read_b128 v[150:153], v148 offset:1024
	ds_read_b128 v[164:167], v148 offset:2048
	ds_read_b128 v[168:171], v148 offset:3072
	s_add_u32 s68, s68, 0x40000
	s_addc_u32 s69, s69, 0
	s_mov_b32 m0, s42
	v_lshl_add_u64 v[206:207], s[68:69], 0, v[134:135]
	ds_read_b128 v[172:175], v160 offset:32768
	ds_read_b128 v[176:179], v160 offset:33792
	ds_read_b128 v[180:183], v160 offset:34816
	ds_read_b128 v[184:187], v160 offset:35840
	ds_read_b128 v[188:191], v160 offset:36864
	ds_read_b128 v[192:195], v160 offset:37888
	ds_read_b128 v[196:199], v160 offset:38912
	ds_read_b128 v[200:203], v160 offset:39936
	global_load_lds_dwordx4 v[206:207], off
	v_lshl_add_u64 v[206:207], s[68:69], 0, v[130:131]
	s_mov_b32 m0, s43
	s_nop 0
	global_load_lds_dwordx4 v[206:207], off
	s_waitcnt lgkmcnt(8)
	s_barrier
	s_waitcnt lgkmcnt(0)
	s_nop 0
	s_waitcnt lgkmcnt(0)
	v_mfma_f32_16x16x32_bf16 v[124:127], v[144:147], v[172:175], v[124:127]
	v_mfma_f32_16x16x32_bf16 v[120:123], v[164:167], v[172:175], v[120:123]
	v_mfma_f32_16x16x32_bf16 v[116:119], v[144:147], v[180:183], v[116:119]
	v_mfma_f32_16x16x32_bf16 v[108:111], v[164:167], v[180:183], v[108:111]
	v_mfma_f32_16x16x32_bf16 v[100:103], v[144:147], v[188:191], v[100:103]
	v_mfma_f32_16x16x32_bf16 v[92:95], v[164:167], v[188:191], v[92:95]
	v_mfma_f32_16x16x32_bf16 v[84:87], v[144:147], v[196:199], v[84:87]
	v_mfma_f32_16x16x32_bf16 v[76:79], v[164:167], v[196:199], v[76:79]
	v_mfma_f32_16x16x32_bf16 v[124:127], v[150:153], v[176:179], v[124:127]
	v_mfma_f32_16x16x32_bf16 v[120:123], v[168:171], v[176:179], v[120:123]
	v_mfma_f32_16x16x32_bf16 v[116:119], v[150:153], v[184:187], v[116:119]
	v_mfma_f32_16x16x32_bf16 v[108:111], v[168:171], v[184:187], v[108:111]
	v_mfma_f32_16x16x32_bf16 v[100:103], v[150:153], v[192:195], v[100:103]
	v_mfma_f32_16x16x32_bf16 v[92:95], v[168:171], v[192:195], v[92:95]
	v_mfma_f32_16x16x32_bf16 v[84:87], v[150:153], v[200:203], v[84:87]
	v_mfma_f32_16x16x32_bf16 v[76:79], v[168:171], v[200:203], v[76:79]
	s_nop 0
	s_barrier
	s_add_i32 s68, 0, 0x1c000
	s_add_i32 s69, s78, s20
	v_add_u32_e32 v148, s68, v157
	v_lshl_add_u64 v[154:155], v[154:155], 0, s[56:57]
	s_mov_b32 m0, s69
	ds_read_b128 v[206:209], v148
	ds_read_b128 v[210:213], v148 offset:1024
	ds_read_b128 v[214:217], v148 offset:2048
	ds_read_b128 v[218:221], v148 offset:3072
	global_load_lds_dwordx4 v[154:155], off
	v_lshl_add_u64 v[154:155], v[222:223], 0, s[56:57]
	s_add_i32 m0, s69, 0x2000
	s_nop 0
	global_load_lds_dwordx4 v[154:155], off
	s_barrier
	s_waitcnt lgkmcnt(0)
	s_nop 0
	s_waitcnt lgkmcnt(0)
	v_mfma_f32_16x16x32_bf16 v[112:115], v[206:209], v[172:175], v[112:115]
	v_mfma_f32_16x16x32_bf16 v[104:107], v[214:217], v[172:175], v[104:107]
	v_mfma_f32_16x16x32_bf16 v[96:99], v[206:209], v[180:183], v[96:99]
	v_mfma_f32_16x16x32_bf16 v[88:91], v[214:217], v[180:183], v[88:91]
	v_mfma_f32_16x16x32_bf16 v[80:83], v[206:209], v[188:191], v[80:83]
	v_mfma_f32_16x16x32_bf16 v[72:75], v[214:217], v[188:191], v[72:75]
	v_mfma_f32_16x16x32_bf16 v[68:71], v[206:209], v[196:199], v[68:71]
	v_mfma_f32_16x16x32_bf16 v[64:67], v[214:217], v[196:199], v[64:67]
	v_mfma_f32_16x16x32_bf16 v[112:115], v[210:213], v[176:179], v[112:115]
	v_mfma_f32_16x16x32_bf16 v[104:107], v[218:221], v[176:179], v[104:107]
	v_mfma_f32_16x16x32_bf16 v[96:99], v[210:213], v[184:187], v[96:99]
	v_mfma_f32_16x16x32_bf16 v[88:91], v[218:221], v[184:187], v[88:91]
	v_mfma_f32_16x16x32_bf16 v[80:83], v[210:213], v[192:195], v[80:83]
	v_mfma_f32_16x16x32_bf16 v[72:75], v[218:221], v[192:195], v[72:75]
	v_mfma_f32_16x16x32_bf16 v[68:71], v[210:213], v[200:203], v[68:71]
	v_mfma_f32_16x16x32_bf16 v[64:67], v[218:221], v[200:203], v[64:67]
	s_nop 0
	s_mov_b32 m0, s45
	v_lshl_add_u64 v[154:155], v[224:225], 0, s[56:57]
	s_barrier
	ds_read_b128 v[172:175], v160 offset:49152
	ds_read_b128 v[176:179], v160 offset:50176
	ds_read_b128 v[180:183], v160 offset:51200
	ds_read_b128 v[184:187], v160 offset:52224
	ds_read_b128 v[188:191], v160 offset:53248
	ds_read_b128 v[192:195], v160 offset:54272
	ds_read_b128 v[196:199], v160 offset:55296
	ds_read_b128 v[200:203], v160 offset:56320
	global_load_lds_dwordx4 v[154:155], off
	v_lshl_add_u64 v[154:155], v[226:227], 0, s[56:57]
	s_mov_b32 m0, s46
	s_nop 0
	global_load_lds_dwordx4 v[154:155], off
	s_barrier
	s_waitcnt lgkmcnt(0)
	s_nop 0
	s_waitcnt lgkmcnt(0)
	v_mfma_f32_16x16x32_bf16 v[60:63], v[144:147], v[172:175], v[60:63]
	v_mfma_f32_16x16x32_bf16 v[56:59], v[164:167], v[172:175], v[56:59]
	v_mfma_f32_16x16x32_bf16 v[52:55], v[144:147], v[180:183], v[52:55]
	v_mfma_f32_16x16x32_bf16 v[44:47], v[164:167], v[180:183], v[44:47]
	v_mfma_f32_16x16x32_bf16 v[36:39], v[144:147], v[188:191], v[36:39]
	v_mfma_f32_16x16x32_bf16 v[28:31], v[164:167], v[188:191], v[28:31]
	v_mfma_f32_16x16x32_bf16 v[20:23], v[144:147], v[196:199], v[20:23]
	v_mfma_f32_16x16x32_bf16 v[12:15], v[164:167], v[196:199], v[12:15]
	v_mfma_f32_16x16x32_bf16 v[60:63], v[150:153], v[176:179], v[60:63]
	v_mfma_f32_16x16x32_bf16 v[56:59], v[168:171], v[176:179], v[56:59]
	v_mfma_f32_16x16x32_bf16 v[52:55], v[150:153], v[184:187], v[52:55]
	v_mfma_f32_16x16x32_bf16 v[44:47], v[168:171], v[184:187], v[44:47]
	v_mfma_f32_16x16x32_bf16 v[36:39], v[150:153], v[192:195], v[36:39]
	v_mfma_f32_16x16x32_bf16 v[28:31], v[168:171], v[192:195], v[28:31]
	v_mfma_f32_16x16x32_bf16 v[20:23], v[150:153], v[200:203], v[20:23]
	v_mfma_f32_16x16x32_bf16 v[12:15], v[168:171], v[200:203], v[12:15]
	s_nop 0
	s_barrier
	s_add_u32 s66, s66, 0x40080
	s_addc_u32 s67, s67, 0
	s_add_i32 s68, s68, s20
	v_lshl_add_u64 v[144:145], s[66:67], 0, v[132:133]
	s_mov_b32 m0, s68
	s_nop 0
	global_load_lds_dwordx4 v[144:145], off
	v_lshl_add_u64 v[144:145], s[66:67], 0, v[128:129]
	s_add_i32 m0, s68, 0x2000
	s_nop 0
	global_load_lds_dwordx4 v[144:145], off
	s_waitcnt vmcnt(6)
	s_barrier
	s_nop 0
	v_mfma_f32_16x16x32_bf16 v[48:51], v[206:209], v[172:175], v[48:51]
	v_mfma_f32_16x16x32_bf16 v[40:43], v[214:217], v[172:175], v[40:43]
	v_mfma_f32_16x16x32_bf16 v[32:35], v[206:209], v[180:183], v[32:35]
	v_mfma_f32_16x16x32_bf16 v[24:27], v[214:217], v[180:183], v[24:27]
	v_mfma_f32_16x16x32_bf16 v[16:19], v[206:209], v[188:191], v[16:19]
	v_mfma_f32_16x16x32_bf16 v[8:11], v[214:217], v[188:191], v[8:11]
	v_mfma_f32_16x16x32_bf16 v[4:7], v[206:209], v[196:199], v[4:7]
	v_mfma_f32_16x16x32_bf16 v[0:3], v[214:217], v[196:199], v[0:3]
	v_mfma_f32_16x16x32_bf16 v[48:51], v[210:213], v[176:179], v[48:51]
	v_mfma_f32_16x16x32_bf16 v[40:43], v[218:221], v[176:179], v[40:43]
	v_mfma_f32_16x16x32_bf16 v[32:35], v[210:213], v[184:187], v[32:35]
	v_mfma_f32_16x16x32_bf16 v[24:27], v[218:221], v[184:187], v[24:27]
	v_mfma_f32_16x16x32_bf16 v[16:19], v[210:213], v[192:195], v[16:19]
	v_mfma_f32_16x16x32_bf16 v[8:11], v[218:221], v[192:195], v[8:11]
	v_mfma_f32_16x16x32_bf16 v[4:7], v[210:213], v[200:203], v[4:7]
	v_mfma_f32_16x16x32_bf16 v[0:3], v[218:221], v[200:203], v[0:3]
	s_nop 0
	s_add_i32 s77, s77, 2
	s_add_u32 s12, s12, 0x100
	s_addc_u32 s13, s13, 0
	s_add_u32 s75, s75, 0x100
	s_addc_u32 s76, s76, 0
	s_cmp_gt_u32 s77, 13
	s_barrier
.LBB0_1141:
	ds_read_b128 v[144:147], v159
	ds_read_b128 v[150:153], v159 offset:1024
	ds_read_b128 v[164:167], v159 offset:2048
	ds_read_b128 v[168:171], v159 offset:3072
	s_add_u32 s66, s12, 0xfffc0080
	s_addc_u32 s67, s13, -1
	s_cmp_eq_u32 s77, 12
	s_cselect_b32 s69, s11, s67
	s_cselect_b32 s68, s61, s66
	s_cselect_b32 s67, s59, s76
	s_cselect_b32 s66, s74, s75
	v_lshl_add_u64 v[154:155], s[12:13], 0, v[136:137]
	s_add_i32 m0, s34, 0xc000
	ds_read_b128 v[172:175], v160
	ds_read_b128 v[176:179], v160 offset:1024
	ds_read_b128 v[180:183], v160 offset:2048
	ds_read_b128 v[184:187], v160 offset:3072
	ds_read_b128 v[188:191], v160 offset:4096
	ds_read_b128 v[192:195], v160 offset:5120
	ds_read_b128 v[196:199], v160 offset:6144
	ds_read_b128 v[200:203], v160 offset:7168
	global_load_lds_dwordx4 v[154:155], off
	v_lshl_add_u64 v[154:155], s[12:13], 0, v[138:139]
	s_add_i32 m0, s34, 0xe000
	s_nop 0
	global_load_lds_dwordx4 v[154:155], off
	s_waitcnt lgkmcnt(8)
	s_barrier
	s_waitcnt lgkmcnt(0)
	s_nop 0
	s_waitcnt lgkmcnt(0)
	v_mfma_f32_16x16x32_bf16 v[124:127], v[144:147], v[172:175], v[124:127]
	v_mfma_f32_16x16x32_bf16 v[120:123], v[164:167], v[172:175], v[120:123]
	v_mfma_f32_16x16x32_bf16 v[116:119], v[144:147], v[180:183], v[116:119]
	v_mfma_f32_16x16x32_bf16 v[108:111], v[164:167], v[180:183], v[108:111]
	v_mfma_f32_16x16x32_bf16 v[100:103], v[144:147], v[188:191], v[100:103]
	v_mfma_f32_16x16x32_bf16 v[92:95], v[164:167], v[188:191], v[92:95]
	v_mfma_f32_16x16x32_bf16 v[84:87], v[144:147], v[196:199], v[84:87]
	v_mfma_f32_16x16x32_bf16 v[76:79], v[164:167], v[196:199], v[76:79]
	v_mfma_f32_16x16x32_bf16 v[124:127], v[150:153], v[176:179], v[124:127]
	v_mfma_f32_16x16x32_bf16 v[120:123], v[168:171], v[176:179], v[120:123]
	v_mfma_f32_16x16x32_bf16 v[116:119], v[150:153], v[184:187], v[116:119]
	v_mfma_f32_16x16x32_bf16 v[108:111], v[168:171], v[184:187], v[108:111]
	v_mfma_f32_16x16x32_bf16 v[100:103], v[150:153], v[192:195], v[100:103]
	v_mfma_f32_16x16x32_bf16 v[92:95], v[168:171], v[192:195], v[92:95]
	v_mfma_f32_16x16x32_bf16 v[84:87], v[150:153], v[200:203], v[84:87]
	v_mfma_f32_16x16x32_bf16 v[76:79], v[168:171], v[200:203], v[76:79]
	s_nop 0
	s_barrier
	s_add_i32 s78, s49, s20
	v_lshl_add_u64 v[154:155], s[66:67], 0, v[132:133]
	s_mov_b32 m0, s78
	ds_read_b128 v[206:209], v161
	ds_read_b128 v[210:213], v161 offset:1024
	ds_read_b128 v[214:217], v161 offset:2048
	ds_read_b128 v[218:221], v161 offset:3072
	global_load_lds_dwordx4 v[154:155], off
	v_lshl_add_u64 v[222:223], s[66:67], 0, v[128:129]
	s_add_i32 m0, s78, 0x2000
	s_nop 0
	global_load_lds_dwordx4 v[222:223], off
	s_barrier
	s_waitcnt lgkmcnt(0)
	s_nop 0
	s_waitcnt lgkmcnt(0)
	v_mfma_f32_16x16x32_bf16 v[112:115], v[206:209], v[172:175], v[112:115]
	v_mfma_f32_16x16x32_bf16 v[104:107], v[214:217], v[172:175], v[104:107]
	v_mfma_f32_16x16x32_bf16 v[96:99], v[206:209], v[180:183], v[96:99]
	v_mfma_f32_16x16x32_bf16 v[88:91], v[214:217], v[180:183], v[88:91]
	v_mfma_f32_16x16x32_bf16 v[80:83], v[206:209], v[188:191], v[80:83]
	v_mfma_f32_16x16x32_bf16 v[72:75], v[214:217], v[188:191], v[72:75]
	v_mfma_f32_16x16x32_bf16 v[68:71], v[206:209], v[196:199], v[68:71]
	v_mfma_f32_16x16x32_bf16 v[64:67], v[214:217], v[196:199], v[64:67]
	v_mfma_f32_16x16x32_bf16 v[112:115], v[210:213], v[176:179], v[112:115]
	v_mfma_f32_16x16x32_bf16 v[104:107], v[218:221], v[176:179], v[104:107]
	v_mfma_f32_16x16x32_bf16 v[96:99], v[210:213], v[184:187], v[96:99]
	v_mfma_f32_16x16x32_bf16 v[88:91], v[218:221], v[184:187], v[88:91]
	v_mfma_f32_16x16x32_bf16 v[80:83], v[210:213], v[192:195], v[80:83]
	v_mfma_f32_16x16x32_bf16 v[72:75], v[218:221], v[192:195], v[72:75]
	v_mfma_f32_16x16x32_bf16 v[68:71], v[210:213], v[200:203], v[68:71]
	v_mfma_f32_16x16x32_bf16 v[64:67], v[218:221], v[200:203], v[64:67]
	s_nop 0
	s_mov_b32 m0, s34
	v_lshl_add_u64 v[224:225], s[68:69], 0, v[134:135]
	s_barrier
	ds_read_b128 v[172:175], v160 offset:16384
	ds_read_b128 v[176:179], v160 offset:17408
	ds_read_b128 v[180:183], v160 offset:18432
	ds_read_b128 v[184:187], v160 offset:19456
	ds_read_b128 v[188:191], v160 offset:20480
	ds_read_b128 v[192:195], v160 offset:21504
	ds_read_b128 v[196:199], v160 offset:22528
	ds_read_b128 v[200:203], v160 offset:23552
	global_load_lds_dwordx4 v[224:225], off
	v_lshl_add_u64 v[226:227], s[68:69], 0, v[130:131]
	s_mov_b32 m0, s35
	s_nop 0
	global_load_lds_dwordx4 v[226:227], off
	s_barrier
	s_waitcnt lgkmcnt(0)
	s_nop 0
	s_waitcnt lgkmcnt(0)
	v_mfma_f32_16x16x32_bf16 v[60:63], v[144:147], v[172:175], v[60:63]
	v_mfma_f32_16x16x32_bf16 v[56:59], v[164:167], v[172:175], v[56:59]
	v_mfma_f32_16x16x32_bf16 v[52:55], v[144:147], v[180:183], v[52:55]
	v_mfma_f32_16x16x32_bf16 v[44:47], v[164:167], v[180:183], v[44:47]
	v_mfma_f32_16x16x32_bf16 v[36:39], v[144:147], v[188:191], v[36:39]
	v_mfma_f32_16x16x32_bf16 v[28:31], v[164:167], v[188:191], v[28:31]
	v_mfma_f32_16x16x32_bf16 v[20:23], v[144:147], v[196:199], v[20:23]
	v_mfma_f32_16x16x32_bf16 v[12:15], v[164:167], v[196:199], v[12:15]
	v_mfma_f32_16x16x32_bf16 v[60:63], v[150:153], v[176:179], v[60:63]
	v_mfma_f32_16x16x32_bf16 v[56:59], v[168:171], v[176:179], v[56:59]
	v_mfma_f32_16x16x32_bf16 v[52:55], v[150:153], v[184:187], v[52:55]
	v_mfma_f32_16x16x32_bf16 v[44:47], v[168:171], v[184:187], v[44:47]
	v_mfma_f32_16x16x32_bf16 v[36:39], v[150:153], v[192:195], v[36:39]
	v_mfma_f32_16x16x32_bf16 v[28:31], v[168:171], v[192:195], v[28:31]
	v_mfma_f32_16x16x32_bf16 v[20:23], v[150:153], v[200:203], v[20:23]
	v_mfma_f32_16x16x32_bf16 v[12:15], v[168:171], v[200:203], v[12:15]
	s_nop 0
	s_barrier
	s_add_u32 s78, s66, 0x40000
	s_addc_u32 s79, s67, 0
	s_add_i32 s80, s70, s20
	v_lshl_add_u64 v[144:145], s[78:79], 0, v[132:133]
	s_mov_b32 m0, s80
	s_nop 0
	global_load_lds_dwordx4 v[144:145], off
	v_lshl_add_u64 v[144:145], s[78:79], 0, v[128:129]
	s_add_i32 m0, s80, 0x2000
	s_nop 0
	global_load_lds_dwordx4 v[144:145], off
	s_waitcnt vmcnt(6)
	s_cmp_gt_u32 s77, 10
	s_cbranch_scc1 .Lds_P8_a_done
	s_cmp_lt_u32 s77, 6
	s_cbranch_scc1 .Lds_P8_a_st
	s_cmp_eq_u32 s77, 6
	s_cbranch_scc1 .Lds_P8_a_pf
	s_cmp_eq_u32 s77, 8
	s_cbranch_scc1 .Lds_P8_a_c8
	v_ffbh_u32_e32 v252, v241
	v_min_u32_e32 v252, 32, v252
	v_lshlrev_b64 v[240:241], v252, v[240:241]
	v_min_u32_e32 v240, 1, v240
	v_or_b32_e32 v241, v241, v240
	v_cvt_f32_u32_e32 v241, v241
	v_sub_u32_e32 v252, -2, v252
	v_ldexp_f32 v241, v241, v252
	v_add_f32_e32 v241, 0x358637bd, v241
	v_rsq_f32_e32 v252, v241
	v_ffbh_u32_e32 v253, v243
	v_min_u32_e32 v253, 32, v253
	v_lshlrev_b64 v[242:243], v253, v[242:243]
	v_min_u32_e32 v242, 1, v242
	v_or_b32_e32 v243, v243, v242
	v_cvt_f32_u32_e32 v243, v243
	v_sub_u32_e32 v253, -2, v253
	v_ldexp_f32 v243, v243, v253
	v_add_f32_e32 v243, 0x358637bd, v243
	v_rsq_f32_e32 v253, v243
	s_branch .Lds_P8_a_done

.Lds_P8_a_done:
	s_barrier
	s_nop 0
	v_mfma_f32_16x16x32_bf16 v[48:51], v[206:209], v[172:175], v[48:51]
	v_mfma_f32_16x16x32_bf16 v[40:43], v[214:217], v[172:175], v[40:43]
	v_mfma_f32_16x16x32_bf16 v[32:35], v[206:209], v[180:183], v[32:35]
	v_mfma_f32_16x16x32_bf16 v[24:27], v[214:217], v[180:183], v[24:27]
	v_mfma_f32_16x16x32_bf16 v[16:19], v[206:209], v[188:191], v[16:19]
	v_mfma_f32_16x16x32_bf16 v[8:11], v[214:217], v[188:191], v[8:11]
	v_mfma_f32_16x16x32_bf16 v[4:7], v[206:209], v[196:199], v[4:7]
	v_mfma_f32_16x16x32_bf16 v[0:3], v[214:217], v[196:199], v[0:3]
	v_mfma_f32_16x16x32_bf16 v[48:51], v[210:213], v[176:179], v[48:51]
	v_mfma_f32_16x16x32_bf16 v[40:43], v[218:221], v[176:179], v[40:43]
	v_mfma_f32_16x16x32_bf16 v[32:35], v[210:213], v[184:187], v[32:35]
	v_mfma_f32_16x16x32_bf16 v[24:27], v[218:221], v[184:187], v[24:27]
	v_mfma_f32_16x16x32_bf16 v[16:19], v[210:213], v[192:195], v[16:19]
	v_mfma_f32_16x16x32_bf16 v[8:11], v[218:221], v[192:195], v[8:11]
	v_mfma_f32_16x16x32_bf16 v[4:7], v[210:213], v[200:203], v[4:7]
	v_mfma_f32_16x16x32_bf16 v[0:3], v[218:221], v[200:203], v[0:3]
	s_nop 0
	s_add_i32 s78, 0, 0x18000
	v_add_u32_e32 v148, s78, v157
	s_barrier
	ds_read_b128 v[144:147], v148
	ds_read_b128 v[150:153], v148 offset:1024
	ds_read_b128 v[164:167], v148 offset:2048
	ds_read_b128 v[168:171], v148 offset:3072
	s_add_u32 s68, s68, 0x40000
	s_addc_u32 s69, s69, 0
	s_mov_b32 m0, s42
	v_lshl_add_u64 v[206:207], s[68:69], 0, v[134:135]
	ds_read_b128 v[172:175], v160 offset:32768
	ds_read_b128 v[176:179], v160 offset:33792
	ds_read_b128 v[180:183], v160 offset:34816
	ds_read_b128 v[184:187], v160 offset:35840
	ds_read_b128 v[188:191], v160 offset:36864
	ds_read_b128 v[192:195], v160 offset:37888
	ds_read_b128 v[196:199], v160 offset:38912
	ds_read_b128 v[200:203], v160 offset:39936
	global_load_lds_dwordx4 v[206:207], off
	v_lshl_add_u64 v[206:207], s[68:69], 0, v[130:131]
	s_mov_b32 m0, s43
	s_nop 0
	global_load_lds_dwordx4 v[206:207], off
	s_waitcnt lgkmcnt(8)
	s_barrier
	s_waitcnt lgkmcnt(0)
	s_nop 0
	s_waitcnt lgkmcnt(0)
	v_mfma_f32_16x16x32_bf16 v[124:127], v[144:147], v[172:175], v[124:127]
	v_mfma_f32_16x16x32_bf16 v[120:123], v[164:167], v[172:175], v[120:123]
	v_mfma_f32_16x16x32_bf16 v[116:119], v[144:147], v[180:183], v[116:119]
	v_mfma_f32_16x16x32_bf16 v[108:111], v[164:167], v[180:183], v[108:111]
	v_mfma_f32_16x16x32_bf16 v[100:103], v[144:147], v[188:191], v[100:103]
	v_mfma_f32_16x16x32_bf16 v[92:95], v[164:167], v[188:191], v[92:95]
	v_mfma_f32_16x16x32_bf16 v[84:87], v[144:147], v[196:199], v[84:87]
	v_mfma_f32_16x16x32_bf16 v[76:79], v[164:167], v[196:199], v[76:79]
	v_mfma_f32_16x16x32_bf16 v[124:127], v[150:153], v[176:179], v[124:127]
	v_mfma_f32_16x16x32_bf16 v[120:123], v[168:171], v[176:179], v[120:123]
	v_mfma_f32_16x16x32_bf16 v[116:119], v[150:153], v[184:187], v[116:119]
	v_mfma_f32_16x16x32_bf16 v[108:111], v[168:171], v[184:187], v[108:111]
	v_mfma_f32_16x16x32_bf16 v[100:103], v[150:153], v[192:195], v[100:103]
	v_mfma_f32_16x16x32_bf16 v[92:95], v[168:171], v[192:195], v[92:95]
	v_mfma_f32_16x16x32_bf16 v[84:87], v[150:153], v[200:203], v[84:87]
	v_mfma_f32_16x16x32_bf16 v[76:79], v[168:171], v[200:203], v[76:79]
	s_nop 0
	s_barrier
	s_add_i32 s68, 0, 0x1c000
	s_add_i32 s69, s78, s20
	v_add_u32_e32 v148, s68, v157
	v_lshl_add_u64 v[154:155], v[154:155], 0, s[56:57]
	s_mov_b32 m0, s69
	ds_read_b128 v[206:209], v148
	ds_read_b128 v[210:213], v148 offset:1024
	ds_read_b128 v[214:217], v148 offset:2048
	ds_read_b128 v[218:221], v148 offset:3072
	global_load_lds_dwordx4 v[154:155], off
	v_lshl_add_u64 v[154:155], v[222:223], 0, s[56:57]
	s_add_i32 m0, s69, 0x2000
	s_nop 0
	global_load_lds_dwordx4 v[154:155], off
	s_barrier
	s_waitcnt lgkmcnt(0)
	s_nop 0
	s_waitcnt lgkmcnt(0)
	v_mfma_f32_16x16x32_bf16 v[112:115], v[206:209], v[172:175], v[112:115]
	v_mfma_f32_16x16x32_bf16 v[104:107], v[214:217], v[172:175], v[104:107]
	v_mfma_f32_16x16x32_bf16 v[96:99], v[206:209], v[180:183], v[96:99]
	v_mfma_f32_16x16x32_bf16 v[88:91], v[214:217], v[180:183], v[88:91]
	v_mfma_f32_16x16x32_bf16 v[80:83], v[206:209], v[188:191], v[80:83]
	v_mfma_f32_16x16x32_bf16 v[72:75], v[214:217], v[188:191], v[72:75]
	v_mfma_f32_16x16x32_bf16 v[68:71], v[206:209], v[196:199], v[68:71]
	v_mfma_f32_16x16x32_bf16 v[64:67], v[214:217], v[196:199], v[64:67]
	v_mfma_f32_16x16x32_bf16 v[112:115], v[210:213], v[176:179], v[112:115]
	v_mfma_f32_16x16x32_bf16 v[104:107], v[218:221], v[176:179], v[104:107]
	v_mfma_f32_16x16x32_bf16 v[96:99], v[210:213], v[184:187], v[96:99]
	v_mfma_f32_16x16x32_bf16 v[88:91], v[218:221], v[184:187], v[88:91]
	v_mfma_f32_16x16x32_bf16 v[80:83], v[210:213], v[192:195], v[80:83]
	v_mfma_f32_16x16x32_bf16 v[72:75], v[218:221], v[192:195], v[72:75]
	v_mfma_f32_16x16x32_bf16 v[68:71], v[210:213], v[200:203], v[68:71]
	v_mfma_f32_16x16x32_bf16 v[64:67], v[218:221], v[200:203], v[64:67]
	s_nop 0
	s_mov_b32 m0, s45
	v_lshl_add_u64 v[154:155], v[224:225], 0, s[56:57]
	s_barrier
	ds_read_b128 v[172:175], v160 offset:49152
	ds_read_b128 v[176:179], v160 offset:50176
	ds_read_b128 v[180:183], v160 offset:51200
	ds_read_b128 v[184:187], v160 offset:52224
	ds_read_b128 v[188:191], v160 offset:53248
	ds_read_b128 v[192:195], v160 offset:54272
	ds_read_b128 v[196:199], v160 offset:55296
	ds_read_b128 v[200:203], v160 offset:56320
	global_load_lds_dwordx4 v[154:155], off
	v_lshl_add_u64 v[154:155], v[226:227], 0, s[56:57]
	s_mov_b32 m0, s46
	s_nop 0
	global_load_lds_dwordx4 v[154:155], off
	s_barrier
	s_waitcnt lgkmcnt(0)
	s_nop 0
	s_waitcnt lgkmcnt(0)
	v_mfma_f32_16x16x32_bf16 v[60:63], v[144:147], v[172:175], v[60:63]
	v_mfma_f32_16x16x32_bf16 v[56:59], v[164:167], v[172:175], v[56:59]
	v_mfma_f32_16x16x32_bf16 v[52:55], v[144:147], v[180:183], v[52:55]
	v_mfma_f32_16x16x32_bf16 v[44:47], v[164:167], v[180:183], v[44:47]
	v_mfma_f32_16x16x32_bf16 v[36:39], v[144:147], v[188:191], v[36:39]
	v_mfma_f32_16x16x32_bf16 v[28:31], v[164:167], v[188:191], v[28:31]
	v_mfma_f32_16x16x32_bf16 v[20:23], v[144:147], v[196:199], v[20:23]
	v_mfma_f32_16x16x32_bf16 v[12:15], v[164:167], v[196:199], v[12:15]
	v_mfma_f32_16x16x32_bf16 v[60:63], v[150:153], v[176:179], v[60:63]
	v_mfma_f32_16x16x32_bf16 v[56:59], v[168:171], v[176:179], v[56:59]
	v_mfma_f32_16x16x32_bf16 v[52:55], v[150:153], v[184:187], v[52:55]
	v_mfma_f32_16x16x32_bf16 v[44:47], v[168:171], v[184:187], v[44:47]
	v_mfma_f32_16x16x32_bf16 v[36:39], v[150:153], v[192:195], v[36:39]
	v_mfma_f32_16x16x32_bf16 v[28:31], v[168:171], v[192:195], v[28:31]
	v_mfma_f32_16x16x32_bf16 v[20:23], v[150:153], v[200:203], v[20:23]
	v_mfma_f32_16x16x32_bf16 v[12:15], v[168:171], v[200:203], v[12:15]
	s_nop 0
	s_barrier
	s_add_u32 s66, s66, 0x40080
	s_addc_u32 s67, s67, 0
	s_add_i32 s68, s68, s20
	v_lshl_add_u64 v[144:145], s[66:67], 0, v[132:133]
	s_mov_b32 m0, s68
	s_nop 0
	global_load_lds_dwordx4 v[144:145], off
	v_lshl_add_u64 v[144:145], s[66:67], 0, v[128:129]
	s_add_i32 m0, s68, 0x2000
	s_nop 0
	global_load_lds_dwordx4 v[144:145], off
	s_waitcnt vmcnt(6)
	s_cmp_gt_u32 s77, 10
	s_cbranch_scc1 .Lds_P8_b_done
	s_cmp_lt_u32 s77, 6
	s_cbranch_scc1 .Lds_P8_b_st
	s_cmp_eq_u32 s77, 6
	s_cbranch_scc1 .Lds_P8_b_l6
	s_cmp_eq_u32 s77, 8
	s_cbranch_scc1 .Lds_P8_b_c8
	v_ffbh_u32_e32 v254, v245
	v_min_u32_e32 v254, 32, v254
	v_lshlrev_b64 v[244:245], v254, v[244:245]
	v_min_u32_e32 v244, 1, v244
	v_or_b32_e32 v245, v245, v244
	v_cvt_f32_u32_e32 v245, v245
	v_sub_u32_e32 v254, -2, v254
	v_ldexp_f32 v245, v245, v254
	v_add_f32_e32 v245, 0x358637bd, v245
	v_rsq_f32_e32 v254, v245
	v_ffbh_u32_e32 v255, v247
	v_min_u32_e32 v255, 32, v255
	v_lshlrev_b64 v[246:247], v255, v[246:247]
	v_min_u32_e32 v246, 1, v246
	v_or_b32_e32 v247, v247, v246
	v_cvt_f32_u32_e32 v247, v247
	v_sub_u32_e32 v255, -2, v255
	v_ldexp_f32 v247, v247, v255
	v_add_f32_e32 v247, 0x358637bd, v247
	v_rsq_f32_e32 v255, v247
	s_branch .Lds_P8_b_done

.Lds_P8_b_done:
	s_barrier
	s_nop 0
	v_mfma_f32_16x16x32_bf16 v[48:51], v[206:209], v[172:175], v[48:51]
	v_mfma_f32_16x16x32_bf16 v[40:43], v[214:217], v[172:175], v[40:43]
	v_mfma_f32_16x16x32_bf16 v[32:35], v[206:209], v[180:183], v[32:35]
	v_mfma_f32_16x16x32_bf16 v[24:27], v[214:217], v[180:183], v[24:27]
	v_mfma_f32_16x16x32_bf16 v[16:19], v[206:209], v[188:191], v[16:19]
	v_mfma_f32_16x16x32_bf16 v[8:11], v[214:217], v[188:191], v[8:11]
	v_mfma_f32_16x16x32_bf16 v[4:7], v[206:209], v[196:199], v[4:7]
	v_mfma_f32_16x16x32_bf16 v[0:3], v[214:217], v[196:199], v[0:3]
	v_mfma_f32_16x16x32_bf16 v[48:51], v[210:213], v[176:179], v[48:51]
	v_mfma_f32_16x16x32_bf16 v[40:43], v[218:221], v[176:179], v[40:43]
	v_mfma_f32_16x16x32_bf16 v[32:35], v[210:213], v[184:187], v[32:35]
	v_mfma_f32_16x16x32_bf16 v[24:27], v[218:221], v[184:187], v[24:27]
	v_mfma_f32_16x16x32_bf16 v[16:19], v[210:213], v[192:195], v[16:19]
	v_mfma_f32_16x16x32_bf16 v[8:11], v[218:221], v[192:195], v[8:11]
	v_mfma_f32_16x16x32_bf16 v[4:7], v[210:213], v[200:203], v[4:7]
	v_mfma_f32_16x16x32_bf16 v[0:3], v[218:221], v[200:203], v[0:3]
	s_nop 0
	s_add_i32 s77, s77, 2
	s_add_u32 s12, s12, 0x100
	s_addc_u32 s13, s13, 0
	s_add_u32 s75, s75, 0x100
	s_addc_u32 s76, s76, 0
	s_cmp_gt_u32 s77, 13
	s_barrier
	s_cbranch_scc0 .LBB0_1141

.LBB0_1291:
	s_or_b64 exec, exec, s[8:9]
	v_readlane_b32 s0, v238, 16
	v_readlane_b32 s1, v238, 17
	s_waitcnt lgkmcnt(0)
	s_barrier
	s_setprio 0
	s_load_dwordx2 s[24:25], s[0:1], 0xa0
	s_load_dwordx4 s[16:19], s[0:1], 0xb0
	s_cmpk_lt_i32 s97, 0x400
	s_cselect_b64 s[10:11], -1, 0
	s_cmpk_gt_i32 s97, 0x3ff
	s_mov_b32 s9, 0
	s_cbranch_scc1 .LBB0_1293
	s_waitcnt vmcnt(0)
	v_mov_b32_e32 v24, v204
	s_bfe_u32 s2, s97, 0x20006
	v_ashrrev_i32_e32 v0, 31, v24
	v_lshrrev_b32_e32 v0, 27, v0
	v_add_u32_e32 v1, v24, v0
	v_ashrrev_i32_e32 v0, 5, v1
	v_and_b32_e32 v1, 0x1fffffe0, v1
	s_waitcnt lgkmcnt(0)
	s_add_u32 s0, s18, 0x7a00000
	v_sub_u32_e32 v1, v24, v1
	s_addc_u32 s1, s19, 0
	v_lshlrev_b32_e32 v2, 3, v1
	v_ashrrev_i32_e32 v1, 31, v0
	v_lshl_add_u64 v[0:1], s[40:41], 0, v[0:1]
	s_movk_i32 s14, 0x1a00
	v_mov_b64_e32 v[8:9], s[0:1]
	v_mad_u64_u32 v[4:5], s[0:1], v0, s14, v[8:9]
	v_mov_b32_e32 v0, v5
	v_mad_u64_u32 v[0:1], s[0:1], v1, s14, v[0:1]
	v_mov_b32_e32 v5, v0
	s_lshl_b32 s0, s2, 9
	s_mov_b32 s1, s9
	v_lshl_add_u64 v[0:1], v[4:5], 0, s[0:1]
	v_ashrrev_i32_e32 v3, 31, v2
	v_lshl_add_u64 v[10:11], v[2:3], 1, v[0:1]
	v_add_u32_e32 v1, 0x200, v24
	v_ashrrev_i32_e32 v0, 31, v1
	v_lshrrev_b32_e32 v0, 27, v0
	v_add_u32_e32 v2, v1, v0
	v_ashrrev_i32_e32 v0, 5, v2
	v_and_b32_e32 v2, 0x1fffffe0, v2
	v_sub_u32_e32 v1, v1, v2
	v_lshlrev_b32_e32 v2, 3, v1
	v_ashrrev_i32_e32 v1, 31, v0
	v_lshl_add_u64 v[0:1], s[40:41], 0, v[0:1]
	v_mad_u64_u32 v[4:5], s[12:13], v0, s14, v[8:9]
	v_mov_b32_e32 v0, v5
	v_mad_u64_u32 v[0:1], s[12:13], v1, s14, v[0:1]
	v_mov_b32_e32 v5, v0
	v_lshl_add_u64 v[0:1], v[4:5], 0, s[0:1]
	v_ashrrev_i32_e32 v3, 31, v2
	v_lshl_add_u64 v[12:13], v[2:3], 1, v[0:1]
	global_load_dwordx4 v[0:3], v[10:11], off offset:2048
	global_load_dwordx4 v[4:7], v[12:13], off offset:2048
	v_add_u32_e32 v11, 0x400, v24
	v_ashrrev_i32_e32 v10, 31, v11
	v_lshrrev_b32_e32 v10, 27, v10
	v_add_u32_e32 v12, v11, v10
	v_ashrrev_i32_e32 v10, 5, v12
	v_and_b32_e32 v12, 0x1fffffe0, v12
	v_sub_u32_e32 v11, v11, v12
	v_lshlrev_b32_e32 v12, 3, v11
	v_ashrrev_i32_e32 v11, 31, v10
	v_lshl_add_u64 v[10:11], s[40:41], 0, v[10:11]
	v_mad_u64_u32 v[14:15], s[12:13], v10, s14, v[8:9]
	v_mov_b32_e32 v10, v15
	v_mad_u64_u32 v[10:11], s[12:13], v11, s14, v[10:11]
	v_mov_b32_e32 v15, v10
	v_lshl_add_u64 v[10:11], v[14:15], 0, s[0:1]
	v_ashrrev_i32_e32 v13, 31, v12
	v_lshl_add_u64 v[10:11], v[12:13], 1, v[10:11]
	v_add_u32_e32 v13, 0x600, v24
	v_ashrrev_i32_e32 v12, 31, v13
	v_lshrrev_b32_e32 v12, 27, v12
	v_add_u32_e32 v14, v13, v12
	v_ashrrev_i32_e32 v12, 5, v14
	v_and_b32_e32 v14, 0x1fffffe0, v14
	v_sub_u32_e32 v13, v13, v14
	v_lshlrev_b32_e32 v14, 3, v13
	v_ashrrev_i32_e32 v13, 31, v12
	v_lshl_add_u64 v[12:13], s[40:41], 0, v[12:13]
	v_mad_u64_u32 v[16:17], s[12:13], v12, s14, v[8:9]
	v_mov_b32_e32 v12, v17
	v_mad_u64_u32 v[12:13], s[12:13], v13, s14, v[12:13]
	v_mov_b32_e32 v17, v12
	v_lshl_add_u64 v[12:13], v[16:17], 0, s[0:1]
	v_ashrrev_i32_e32 v15, 31, v14
	v_lshl_add_u64 v[20:21], v[14:15], 1, v[12:13]
	global_load_dwordx4 v[12:15], v[10:11], off offset:2048
	global_load_dwordx4 v[16:19], v[20:21], off offset:2048
	v_ashrrev_i32_e32 v10, 4, v24
	v_ashrrev_i32_e32 v11, 31, v10
	v_lshl_add_u64 v[20:21], s[40:41], 0, v[10:11]
	v_mad_u64_u32 v[22:23], s[0:1], v20, s14, v[8:9]
	v_mov_b32_e32 v20, v23
	v_mad_u64_u32 v[20:21], s[0:1], v21, s14, v[20:21]
	s_lshl_b32 s8, s2, 8
	v_mov_b32_e32 v23, v20
	v_lshlrev_b32_e32 v11, 4, v24
	v_add_u32_e32 v10, 32, v10
	v_lshl_add_u64 v[20:21], v[22:23], 0, s[8:9]
	v_and_b32_e32 v22, 0xf0, v11
	v_ashrrev_i32_e32 v11, 31, v10
	v_lshl_add_u64 v[10:11], s[40:41], 0, v[10:11]
	v_mad_u64_u32 v[8:9], s[0:1], v10, s14, v[8:9]
	v_mov_b32_e32 v10, v9
	v_mad_u64_u32 v[10:11], s[0:1], v11, s14, v[10:11]
	v_mov_b32_e32 v23, 0
	v_mov_b32_e32 v9, v10
	v_lshl_add_u64 v[24:25], v[20:21], 0, v[22:23]
	v_lshl_add_u64 v[8:9], v[8:9], 0, s[8:9]
	v_lshl_add_u64 v[8:9], v[8:9], 0, v[22:23]
	global_load_dwordx4 v[32:35], v[24:25], off offset:1024
	global_load_dwordx4 v[20:23], v[8:9], off offset:1024
	v_cndmask_b32_e64 v8, 0, 1, s[10:11]
	v_cmp_ne_u32_e64 s[8:9], 1, v8
	s_andn2_b64 vcc, exec, s[10:11]
	s_cbranch_vccz .LBB0_1294
	s_branch .LBB0_1374

.LBB0_1876:
	s_or_b64 exec, exec, s[8:9]
	s_mov_b64 s[8:9], s[70:71]
	v_mov_b32_e32 v8, v204
	s_waitcnt lgkmcnt(0)
	s_barrier
	v_readfirstlane_b32 s101, v204
	s_nop 3
	s_lshr_b32 s101, s101, 6
	s_cmp_ge_u32 s101, 4
	s_cbranch_scc0 .Lprio_5
	s_setprio 1
.Lprio_5:
	s_and_b64 vcc, exec, s[4:5]
	v_readfirstlane_b32 s0, v8
	s_cbranch_vccnz .LBB0_1882
	s_ashr_i32 s1, s97, 31
	s_lshr_b32 s1, s1, 29
	s_add_i32 s1, s97, s1
	s_and_b32 s2, s1, -8
	s_sub_i32 s2, s97, s2
	s_cmp_gt_i32 s2, -1
	s_cbranch_scc0 .LBB0_1879
	s_lshl_b32 s3, s2, 6
	s_cbranch_execz .LBB0_1880
	s_branch .LBB0_1881

.LBB0_1893:
	s_ashr_i32 s29, s28, 31
	v_cmp_lt_i64_e32 vcc, s[30:31], v[164:165]
	s_lshl_b64 s[30:31], s[28:29], 19
	s_add_u32 s30, s12, s30
	s_addc_u32 s31, s13, s31
	s_and_b64 s[34:35], vcc, exec
	s_cselect_b32 s29, s31, s41
	s_cselect_b32 s37, s30, s40
	s_ashr_i32 s27, s26, 31
	s_lshl_b64 s[34:35], s[26:27], 19
	s_add_u32 s34, s1, s34
	s_addc_u32 s35, s2, s35
	s_and_b64 s[44:45], vcc, exec
	s_cselect_b32 s27, s35, s43
	s_cselect_b32 s54, s34, s42
	s_add_u32 s40, s40, 0x40080
	s_addc_u32 s41, s41, 0
	s_add_u32 s55, s42, 0x100

	s_addc_u32 s56, s43, 0
	s_mov_b32 s57, -2
	s_waitcnt lgkmcnt(0)


	ds_read_b128 v[128:131], v189
	ds_read_b128 v[132:135], v189 offset:1024
	ds_read_b128 v[136:139], v189 offset:2048
	ds_read_b128 v[140:143], v189 offset:3072
	s_add_u32 s42, s40, 0xfffc0080
	s_addc_u32 s43, s41, -1
	s_cmp_eq_u32 s57, 12
	s_cselect_b32 s45, s29, s43
	s_cselect_b32 s44, s37, s42
	s_cselect_b32 s43, s27, s56
	s_cselect_b32 s42, s54, s55
	v_lshl_add_u64 v[184:185], s[40:41], 0, v[160:161]
	s_add_i32 m0, s20, 0xc000
	ds_read_b128 v[144:147], v190
	ds_read_b128 v[148:151], v190 offset:1024
	ds_read_b128 v[168:171], v190 offset:2048
	ds_read_b128 v[172:175], v190 offset:3072
	ds_read_b128 v[176:179], v190 offset:4096
	ds_read_b128 v[180:183], v190 offset:5120
	ds_read_b128 v[192:195], v190 offset:6144
	ds_read_b128 v[196:199], v190 offset:7168
	global_load_lds_dwordx4 v[184:185], off
	v_lshl_add_u64 v[184:185], s[40:41], 0, v[162:163]
	s_add_i32 m0, s20, 0xe000
	s_nop 0
	global_load_lds_dwordx4 v[184:185], off
	s_waitcnt lgkmcnt(8)
	s_barrier
	s_waitcnt lgkmcnt(0)
	s_nop 0
	s_waitcnt lgkmcnt(0)
	v_mfma_f32_16x16x32_bf16 v[124:127], v[128:131], v[144:147], 0
	v_mfma_f32_16x16x32_bf16 v[120:123], v[136:139], v[144:147], 0
	v_mfma_f32_16x16x32_bf16 v[108:111], v[128:131], v[168:171], 0
	v_mfma_f32_16x16x32_bf16 v[104:107], v[136:139], v[168:171], 0
	v_mfma_f32_16x16x32_bf16 v[92:95], v[128:131], v[176:179], 0
	v_mfma_f32_16x16x32_bf16 v[88:91], v[136:139], v[176:179], 0
	v_mfma_f32_16x16x32_bf16 v[76:79], v[128:131], v[192:195], 0
	v_mfma_f32_16x16x32_bf16 v[72:75], v[136:139], v[192:195], 0
	v_mfma_f32_16x16x32_bf16 v[124:127], v[132:135], v[148:151], v[124:127]
	v_mfma_f32_16x16x32_bf16 v[120:123], v[140:143], v[148:151], v[120:123]
	v_mfma_f32_16x16x32_bf16 v[108:111], v[132:135], v[172:175], v[108:111]
	v_mfma_f32_16x16x32_bf16 v[104:107], v[140:143], v[172:175], v[104:107]
	v_mfma_f32_16x16x32_bf16 v[92:95], v[132:135], v[180:183], v[92:95]
	v_mfma_f32_16x16x32_bf16 v[88:91], v[140:143], v[180:183], v[88:91]
	v_mfma_f32_16x16x32_bf16 v[76:79], v[132:135], v[196:199], v[76:79]
	v_mfma_f32_16x16x32_bf16 v[72:75], v[140:143], v[196:199], v[72:75]
	s_nop 0
	s_barrier
	s_add_i32 s58, s52, s3
	v_lshl_add_u64 v[184:185], s[42:43], 0, v[154:155]
	s_mov_b32 m0, s58
	ds_read_b128 v[200:203], v191
	ds_read_b128 v[206:209], v191 offset:1024
	ds_read_b128 v[210:213], v191 offset:2048
	ds_read_b128 v[214:217], v191 offset:3072
	global_load_lds_dwordx4 v[184:185], off
	v_lshl_add_u64 v[218:219], s[42:43], 0, v[158:159]
	s_add_i32 m0, s58, 0x2000
	s_nop 0
	global_load_lds_dwordx4 v[218:219], off
	s_barrier
	s_waitcnt lgkmcnt(0)
	s_nop 0
	s_waitcnt lgkmcnt(0)
	v_mfma_f32_16x16x32_bf16 v[116:119], v[200:203], v[144:147], 0
	v_mfma_f32_16x16x32_bf16 v[112:115], v[210:213], v[144:147], 0
	v_mfma_f32_16x16x32_bf16 v[100:103], v[200:203], v[168:171], 0
	v_mfma_f32_16x16x32_bf16 v[96:99], v[210:213], v[168:171], 0
	v_mfma_f32_16x16x32_bf16 v[84:87], v[200:203], v[176:179], 0
	v_mfma_f32_16x16x32_bf16 v[80:83], v[210:213], v[176:179], 0
	v_mfma_f32_16x16x32_bf16 v[68:71], v[200:203], v[192:195], 0
	v_mfma_f32_16x16x32_bf16 v[64:67], v[210:213], v[192:195], 0
	v_mfma_f32_16x16x32_bf16 v[116:119], v[206:209], v[148:151], v[116:119]
	v_mfma_f32_16x16x32_bf16 v[112:115], v[214:217], v[148:151], v[112:115]
	v_mfma_f32_16x16x32_bf16 v[100:103], v[206:209], v[172:175], v[100:103]
	v_mfma_f32_16x16x32_bf16 v[96:99], v[214:217], v[172:175], v[96:99]
	v_mfma_f32_16x16x32_bf16 v[84:87], v[206:209], v[180:183], v[84:87]
	v_mfma_f32_16x16x32_bf16 v[80:83], v[214:217], v[180:183], v[80:83]
	v_mfma_f32_16x16x32_bf16 v[68:71], v[206:209], v[196:199], v[68:71]
	v_mfma_f32_16x16x32_bf16 v[64:67], v[214:217], v[196:199], v[64:67]
	s_nop 0
	s_mov_b32 m0, s20
	v_lshl_add_u64 v[220:221], s[44:45], 0, v[152:153]
	s_barrier
	ds_read_b128 v[144:147], v190 offset:16384
	ds_read_b128 v[148:151], v190 offset:17408
	ds_read_b128 v[168:171], v190 offset:18432
	ds_read_b128 v[172:175], v190 offset:19456
	ds_read_b128 v[176:179], v190 offset:20480
	ds_read_b128 v[180:183], v190 offset:21504
	ds_read_b128 v[192:195], v190 offset:22528
	ds_read_b128 v[196:199], v190 offset:23552
	global_load_lds_dwordx4 v[220:221], off
	v_lshl_add_u64 v[222:223], s[44:45], 0, v[156:157]
	s_mov_b32 m0, s21
	s_nop 0
	global_load_lds_dwordx4 v[222:223], off
	s_barrier
	s_waitcnt lgkmcnt(0)
	s_nop 0
	s_waitcnt lgkmcnt(0)
	v_mfma_f32_16x16x32_bf16 v[60:63], v[128:131], v[144:147], 0
	v_mfma_f32_16x16x32_bf16 v[56:59], v[136:139], v[144:147], 0
	v_mfma_f32_16x16x32_bf16 v[44:47], v[128:131], v[168:171], 0
	v_mfma_f32_16x16x32_bf16 v[40:43], v[136:139], v[168:171], 0
	v_mfma_f32_16x16x32_bf16 v[28:31], v[128:131], v[176:179], 0
	v_mfma_f32_16x16x32_bf16 v[24:27], v[136:139], v[176:179], 0
	v_mfma_f32_16x16x32_bf16 v[12:15], v[128:131], v[192:195], 0
	v_mfma_f32_16x16x32_bf16 v[8:11], v[136:139], v[192:195], 0
	v_mfma_f32_16x16x32_bf16 v[60:63], v[132:135], v[148:151], v[60:63]
	v_mfma_f32_16x16x32_bf16 v[56:59], v[140:143], v[148:151], v[56:59]
	v_mfma_f32_16x16x32_bf16 v[44:47], v[132:135], v[172:175], v[44:47]
	v_mfma_f32_16x16x32_bf16 v[40:43], v[140:143], v[172:175], v[40:43]
	v_mfma_f32_16x16x32_bf16 v[28:31], v[132:135], v[180:183], v[28:31]
	v_mfma_f32_16x16x32_bf16 v[24:27], v[140:143], v[180:183], v[24:27]
	v_mfma_f32_16x16x32_bf16 v[12:15], v[132:135], v[196:199], v[12:15]
	v_mfma_f32_16x16x32_bf16 v[8:11], v[140:143], v[196:199], v[8:11]
	s_nop 0
	s_barrier
	s_add_u32 s58, s42, 0x40000
	s_addc_u32 s59, s43, 0
	s_add_i32 s60, s53, s3
	v_lshl_add_u64 v[128:129], s[58:59], 0, v[154:155]
	s_mov_b32 m0, s60
	s_nop 0
	global_load_lds_dwordx4 v[128:129], off
	v_lshl_add_u64 v[128:129], s[58:59], 0, v[158:159]
	s_add_i32 m0, s60, 0x2000
	s_nop 0
	global_load_lds_dwordx4 v[128:129], off
	s_waitcnt vmcnt(6)
	s_barrier
	s_nop 0
	v_mfma_f32_16x16x32_bf16 v[52:55], v[200:203], v[144:147], 0
	v_mfma_f32_16x16x32_bf16 v[48:51], v[210:213], v[144:147], 0
	v_mfma_f32_16x16x32_bf16 v[36:39], v[200:203], v[168:171], 0
	v_mfma_f32_16x16x32_bf16 v[32:35], v[210:213], v[168:171], 0
	v_mfma_f32_16x16x32_bf16 v[20:23], v[200:203], v[176:179], 0
	v_mfma_f32_16x16x32_bf16 v[16:19], v[210:213], v[176:179], 0
	v_mfma_f32_16x16x32_bf16 v[4:7], v[200:203], v[192:195], 0
	v_mfma_f32_16x16x32_bf16 v[0:3], v[210:213], v[192:195], 0
	v_mfma_f32_16x16x32_bf16 v[52:55], v[206:209], v[148:151], v[52:55]
	v_mfma_f32_16x16x32_bf16 v[48:51], v[214:217], v[148:151], v[48:51]
	v_mfma_f32_16x16x32_bf16 v[36:39], v[206:209], v[172:175], v[36:39]
	v_mfma_f32_16x16x32_bf16 v[32:35], v[214:217], v[172:175], v[32:35]
	v_mfma_f32_16x16x32_bf16 v[20:23], v[206:209], v[180:183], v[20:23]
	v_mfma_f32_16x16x32_bf16 v[16:19], v[214:217], v[180:183], v[16:19]
	v_mfma_f32_16x16x32_bf16 v[4:7], v[206:209], v[196:199], v[4:7]
	v_mfma_f32_16x16x32_bf16 v[0:3], v[214:217], v[196:199], v[0:3]
	s_nop 0
	s_add_i32 s58, 0, 0x18000
	v_add_u32_e32 v140, s58, v187
	s_barrier
	ds_read_b128 v[128:131], v140
	ds_read_b128 v[132:135], v140 offset:1024
	ds_read_b128 v[136:139], v140 offset:2048
	ds_read_b128 v[140:143], v140 offset:3072
	s_add_u32 s44, s44, 0x40000
	s_addc_u32 s45, s45, 0
	s_mov_b32 m0, s33
	v_lshl_add_u64 v[200:201], s[44:45], 0, v[152:153]
	ds_read_b128 v[144:147], v190 offset:32768
	ds_read_b128 v[148:151], v190 offset:33792
	ds_read_b128 v[168:171], v190 offset:34816
	ds_read_b128 v[172:175], v190 offset:35840
	ds_read_b128 v[176:179], v190 offset:36864
	ds_read_b128 v[180:183], v190 offset:37888
	ds_read_b128 v[192:195], v190 offset:38912
	ds_read_b128 v[196:199], v190 offset:39936
	global_load_lds_dwordx4 v[200:201], off
	v_lshl_add_u64 v[200:201], s[44:45], 0, v[156:157]
	s_mov_b32 m0, s39
	s_nop 0
	global_load_lds_dwordx4 v[200:201], off
	s_waitcnt lgkmcnt(8)
	s_barrier
	s_waitcnt lgkmcnt(0)
	s_nop 0
	s_waitcnt lgkmcnt(0)
	v_mfma_f32_16x16x32_bf16 v[124:127], v[128:131], v[144:147], v[124:127]
	v_mfma_f32_16x16x32_bf16 v[120:123], v[136:139], v[144:147], v[120:123]
	v_mfma_f32_16x16x32_bf16 v[108:111], v[128:131], v[168:171], v[108:111]
	v_mfma_f32_16x16x32_bf16 v[104:107], v[136:139], v[168:171], v[104:107]
	v_mfma_f32_16x16x32_bf16 v[92:95], v[128:131], v[176:179], v[92:95]
	v_mfma_f32_16x16x32_bf16 v[88:91], v[136:139], v[176:179], v[88:91]
	v_mfma_f32_16x16x32_bf16 v[76:79], v[128:131], v[192:195], v[76:79]
	v_mfma_f32_16x16x32_bf16 v[72:75], v[136:139], v[192:195], v[72:75]
	v_mfma_f32_16x16x32_bf16 v[124:127], v[132:135], v[148:151], v[124:127]
	v_mfma_f32_16x16x32_bf16 v[120:123], v[140:143], v[148:151], v[120:123]
	v_mfma_f32_16x16x32_bf16 v[108:111], v[132:135], v[172:175], v[108:111]
	v_mfma_f32_16x16x32_bf16 v[104:107], v[140:143], v[172:175], v[104:107]
	v_mfma_f32_16x16x32_bf16 v[92:95], v[132:135], v[180:183], v[92:95]
	v_mfma_f32_16x16x32_bf16 v[88:91], v[140:143], v[180:183], v[88:91]
	v_mfma_f32_16x16x32_bf16 v[76:79], v[132:135], v[196:199], v[76:79]
	v_mfma_f32_16x16x32_bf16 v[72:75], v[140:143], v[196:199], v[72:75]
	s_nop 0
	s_barrier
	s_add_i32 s44, 0, 0x1c000
	s_add_i32 s45, s58, s3
	v_add_u32_e32 v214, s44, v187
	v_lshl_add_u64 v[184:185], v[184:185], 0, s[24:25]
	s_mov_b32 m0, s45
	ds_read_b128 v[200:203], v214
	ds_read_b128 v[206:209], v214 offset:1024
	ds_read_b128 v[210:213], v214 offset:2048
	ds_read_b128 v[214:217], v214 offset:3072
	global_load_lds_dwordx4 v[184:185], off
	v_lshl_add_u64 v[184:185], v[218:219], 0, s[24:25]
	s_add_i32 m0, s45, 0x2000
	s_nop 0
	global_load_lds_dwordx4 v[184:185], off
	s_barrier
	s_waitcnt lgkmcnt(0)
	s_nop 0
	s_waitcnt lgkmcnt(0)
	v_mfma_f32_16x16x32_bf16 v[116:119], v[200:203], v[144:147], v[116:119]
	v_mfma_f32_16x16x32_bf16 v[112:115], v[210:213], v[144:147], v[112:115]
	v_mfma_f32_16x16x32_bf16 v[100:103], v[200:203], v[168:171], v[100:103]
	v_mfma_f32_16x16x32_bf16 v[96:99], v[210:213], v[168:171], v[96:99]
	v_mfma_f32_16x16x32_bf16 v[84:87], v[200:203], v[176:179], v[84:87]
	v_mfma_f32_16x16x32_bf16 v[80:83], v[210:213], v[176:179], v[80:83]
	v_mfma_f32_16x16x32_bf16 v[68:71], v[200:203], v[192:195], v[68:71]
	v_mfma_f32_16x16x32_bf16 v[64:67], v[210:213], v[192:195], v[64:67]
	v_mfma_f32_16x16x32_bf16 v[116:119], v[206:209], v[148:151], v[116:119]
	v_mfma_f32_16x16x32_bf16 v[112:115], v[214:217], v[148:151], v[112:115]
	v_mfma_f32_16x16x32_bf16 v[100:103], v[206:209], v[172:175], v[100:103]
	v_mfma_f32_16x16x32_bf16 v[96:99], v[214:217], v[172:175], v[96:99]
	v_mfma_f32_16x16x32_bf16 v[84:87], v[206:209], v[180:183], v[84:87]
	v_mfma_f32_16x16x32_bf16 v[80:83], v[214:217], v[180:183], v[80:83]
	v_mfma_f32_16x16x32_bf16 v[68:71], v[206:209], v[196:199], v[68:71]
	v_mfma_f32_16x16x32_bf16 v[64:67], v[214:217], v[196:199], v[64:67]
	s_nop 0
	s_mov_b32 m0, s47
	v_lshl_add_u64 v[184:185], v[220:221], 0, s[24:25]
	s_barrier
	ds_read_b128 v[144:147], v190 offset:49152
	ds_read_b128 v[148:151], v190 offset:50176
	ds_read_b128 v[168:171], v190 offset:51200
	ds_read_b128 v[172:175], v190 offset:52224
	ds_read_b128 v[176:179], v190 offset:53248
	ds_read_b128 v[180:183], v190 offset:54272
	ds_read_b128 v[192:195], v190 offset:55296
	ds_read_b128 v[196:199], v190 offset:56320
	global_load_lds_dwordx4 v[184:185], off
	v_lshl_add_u64 v[184:185], v[222:223], 0, s[24:25]
	s_mov_b32 m0, s48
	s_nop 0
	global_load_lds_dwordx4 v[184:185], off
	s_barrier
	s_waitcnt lgkmcnt(0)
	s_nop 0
	s_waitcnt lgkmcnt(0)
	v_mfma_f32_16x16x32_bf16 v[60:63], v[128:131], v[144:147], v[60:63]
	v_mfma_f32_16x16x32_bf16 v[56:59], v[136:139], v[144:147], v[56:59]
	v_mfma_f32_16x16x32_bf16 v[44:47], v[128:131], v[168:171], v[44:47]
	v_mfma_f32_16x16x32_bf16 v[40:43], v[136:139], v[168:171], v[40:43]
	v_mfma_f32_16x16x32_bf16 v[28:31], v[128:131], v[176:179], v[28:31]
	v_mfma_f32_16x16x32_bf16 v[24:27], v[136:139], v[176:179], v[24:27]
	v_mfma_f32_16x16x32_bf16 v[12:15], v[128:131], v[192:195], v[12:15]
	v_mfma_f32_16x16x32_bf16 v[8:11], v[136:139], v[192:195], v[8:11]
	v_mfma_f32_16x16x32_bf16 v[60:63], v[132:135], v[148:151], v[60:63]
	v_mfma_f32_16x16x32_bf16 v[56:59], v[140:143], v[148:151], v[56:59]
	v_mfma_f32_16x16x32_bf16 v[44:47], v[132:135], v[172:175], v[44:47]
	v_mfma_f32_16x16x32_bf16 v[40:43], v[140:143], v[172:175], v[40:43]
	v_mfma_f32_16x16x32_bf16 v[28:31], v[132:135], v[180:183], v[28:31]
	v_mfma_f32_16x16x32_bf16 v[24:27], v[140:143], v[180:183], v[24:27]
	v_mfma_f32_16x16x32_bf16 v[12:15], v[132:135], v[196:199], v[12:15]
	v_mfma_f32_16x16x32_bf16 v[8:11], v[140:143], v[196:199], v[8:11]
	s_nop 0
	s_barrier
	s_add_u32 s42, s42, 0x40080
	s_addc_u32 s43, s43, 0
	s_add_i32 s44, s44, s3
	v_lshl_add_u64 v[128:129], s[42:43], 0, v[154:155]
	s_mov_b32 m0, s44
	s_nop 0
	global_load_lds_dwordx4 v[128:129], off
	v_lshl_add_u64 v[128:129], s[42:43], 0, v[158:159]
	s_add_i32 m0, s44, 0x2000
	s_nop 0
	global_load_lds_dwordx4 v[128:129], off
	s_waitcnt vmcnt(6)
	s_barrier
	s_nop 0
	v_mfma_f32_16x16x32_bf16 v[52:55], v[200:203], v[144:147], v[52:55]
	v_mfma_f32_16x16x32_bf16 v[48:51], v[210:213], v[144:147], v[48:51]
	v_mfma_f32_16x16x32_bf16 v[36:39], v[200:203], v[168:171], v[36:39]
	v_mfma_f32_16x16x32_bf16 v[32:35], v[210:213], v[168:171], v[32:35]
	v_mfma_f32_16x16x32_bf16 v[20:23], v[200:203], v[176:179], v[20:23]
	v_mfma_f32_16x16x32_bf16 v[16:19], v[210:213], v[176:179], v[16:19]
	v_mfma_f32_16x16x32_bf16 v[4:7], v[200:203], v[192:195], v[4:7]
	v_mfma_f32_16x16x32_bf16 v[0:3], v[210:213], v[192:195], v[0:3]
	v_mfma_f32_16x16x32_bf16 v[52:55], v[206:209], v[148:151], v[52:55]
	v_mfma_f32_16x16x32_bf16 v[48:51], v[214:217], v[148:151], v[48:51]
	v_mfma_f32_16x16x32_bf16 v[36:39], v[206:209], v[172:175], v[36:39]
	v_mfma_f32_16x16x32_bf16 v[32:35], v[214:217], v[172:175], v[32:35]
	v_mfma_f32_16x16x32_bf16 v[20:23], v[206:209], v[180:183], v[20:23]
	v_mfma_f32_16x16x32_bf16 v[16:19], v[214:217], v[180:183], v[16:19]
	v_mfma_f32_16x16x32_bf16 v[4:7], v[206:209], v[196:199], v[4:7]
	v_mfma_f32_16x16x32_bf16 v[0:3], v[214:217], v[196:199], v[0:3]
	s_nop 0
	s_add_i32 s57, s57, 2
	s_add_u32 s40, s40, 0x100
	s_addc_u32 s41, s41, 0
	s_add_u32 s55, s55, 0x100
	s_addc_u32 s56, s56, 0
	s_cmp_gt_u32 s57, 13
	s_barrier
.LBB0_1894:
	ds_read_b128 v[128:131], v189
	ds_read_b128 v[132:135], v189 offset:1024
	ds_read_b128 v[136:139], v189 offset:2048
	ds_read_b128 v[140:143], v189 offset:3072
	s_add_u32 s42, s40, 0xfffc0080
	s_addc_u32 s43, s41, -1
	s_cmp_eq_u32 s57, 12
	s_cselect_b32 s45, s29, s43
	s_cselect_b32 s44, s37, s42
	s_cselect_b32 s43, s27, s56
	s_cselect_b32 s42, s54, s55
	v_lshl_add_u64 v[184:185], s[40:41], 0, v[160:161]
	s_add_i32 m0, s20, 0xc000
	ds_read_b128 v[144:147], v190
	ds_read_b128 v[148:151], v190 offset:1024
	ds_read_b128 v[168:171], v190 offset:2048
	ds_read_b128 v[172:175], v190 offset:3072
	ds_read_b128 v[176:179], v190 offset:4096
	ds_read_b128 v[180:183], v190 offset:5120
	ds_read_b128 v[192:195], v190 offset:6144
	ds_read_b128 v[196:199], v190 offset:7168
	global_load_lds_dwordx4 v[184:185], off
	v_lshl_add_u64 v[184:185], s[40:41], 0, v[162:163]
	s_add_i32 m0, s20, 0xe000
	s_nop 0
	global_load_lds_dwordx4 v[184:185], off
	s_waitcnt lgkmcnt(8)
	s_barrier
	s_waitcnt lgkmcnt(0)
	s_nop 0
	s_waitcnt lgkmcnt(0)
	v_mfma_f32_16x16x32_bf16 v[124:127], v[128:131], v[144:147], v[124:127]
	v_mfma_f32_16x16x32_bf16 v[120:123], v[136:139], v[144:147], v[120:123]
	v_mfma_f32_16x16x32_bf16 v[108:111], v[128:131], v[168:171], v[108:111]
	v_mfma_f32_16x16x32_bf16 v[104:107], v[136:139], v[168:171], v[104:107]
	v_mfma_f32_16x16x32_bf16 v[92:95], v[128:131], v[176:179], v[92:95]
	v_mfma_f32_16x16x32_bf16 v[88:91], v[136:139], v[176:179], v[88:91]
	v_mfma_f32_16x16x32_bf16 v[76:79], v[128:131], v[192:195], v[76:79]
	v_mfma_f32_16x16x32_bf16 v[72:75], v[136:139], v[192:195], v[72:75]
	v_mfma_f32_16x16x32_bf16 v[124:127], v[132:135], v[148:151], v[124:127]
	v_mfma_f32_16x16x32_bf16 v[120:123], v[140:143], v[148:151], v[120:123]
	v_mfma_f32_16x16x32_bf16 v[108:111], v[132:135], v[172:175], v[108:111]
	v_mfma_f32_16x16x32_bf16 v[104:107], v[140:143], v[172:175], v[104:107]
	v_mfma_f32_16x16x32_bf16 v[92:95], v[132:135], v[180:183], v[92:95]
	v_mfma_f32_16x16x32_bf16 v[88:91], v[140:143], v[180:183], v[88:91]
	v_mfma_f32_16x16x32_bf16 v[76:79], v[132:135], v[196:199], v[76:79]
	v_mfma_f32_16x16x32_bf16 v[72:75], v[140:143], v[196:199], v[72:75]
	s_nop 0
	s_barrier
	s_add_i32 s58, s52, s3
	v_lshl_add_u64 v[184:185], s[42:43], 0, v[154:155]
	s_mov_b32 m0, s58
	ds_read_b128 v[200:203], v191
	ds_read_b128 v[206:209], v191 offset:1024
	ds_read_b128 v[210:213], v191 offset:2048
	ds_read_b128 v[214:217], v191 offset:3072
	global_load_lds_dwordx4 v[184:185], off
	v_lshl_add_u64 v[218:219], s[42:43], 0, v[158:159]
	s_add_i32 m0, s58, 0x2000
	s_nop 0
	global_load_lds_dwordx4 v[218:219], off
	s_barrier
	s_waitcnt lgkmcnt(0)
	s_nop 0
	s_waitcnt lgkmcnt(0)
	v_mfma_f32_16x16x32_bf16 v[116:119], v[200:203], v[144:147], v[116:119]
	v_mfma_f32_16x16x32_bf16 v[112:115], v[210:213], v[144:147], v[112:115]
	v_mfma_f32_16x16x32_bf16 v[100:103], v[200:203], v[168:171], v[100:103]
	v_mfma_f32_16x16x32_bf16 v[96:99], v[210:213], v[168:171], v[96:99]
	v_mfma_f32_16x16x32_bf16 v[84:87], v[200:203], v[176:179], v[84:87]
	v_mfma_f32_16x16x32_bf16 v[80:83], v[210:213], v[176:179], v[80:83]
	v_mfma_f32_16x16x32_bf16 v[68:71], v[200:203], v[192:195], v[68:71]
	v_mfma_f32_16x16x32_bf16 v[64:67], v[210:213], v[192:195], v[64:67]
	v_mfma_f32_16x16x32_bf16 v[116:119], v[206:209], v[148:151], v[116:119]
	v_mfma_f32_16x16x32_bf16 v[112:115], v[214:217], v[148:151], v[112:115]
	v_mfma_f32_16x16x32_bf16 v[100:103], v[206:209], v[172:175], v[100:103]
	v_mfma_f32_16x16x32_bf16 v[96:99], v[214:217], v[172:175], v[96:99]
	v_mfma_f32_16x16x32_bf16 v[84:87], v[206:209], v[180:183], v[84:87]
	v_mfma_f32_16x16x32_bf16 v[80:83], v[214:217], v[180:183], v[80:83]
	v_mfma_f32_16x16x32_bf16 v[68:71], v[206:209], v[196:199], v[68:71]
	v_mfma_f32_16x16x32_bf16 v[64:67], v[214:217], v[196:199], v[64:67]
	s_nop 0
	s_mov_b32 m0, s20
	v_lshl_add_u64 v[220:221], s[44:45], 0, v[152:153]
	s_barrier
	ds_read_b128 v[144:147], v190 offset:16384
	ds_read_b128 v[148:151], v190 offset:17408
	ds_read_b128 v[168:171], v190 offset:18432
	ds_read_b128 v[172:175], v190 offset:19456
	ds_read_b128 v[176:179], v190 offset:20480
	ds_read_b128 v[180:183], v190 offset:21504
	ds_read_b128 v[192:195], v190 offset:22528
	ds_read_b128 v[196:199], v190 offset:23552
	global_load_lds_dwordx4 v[220:221], off
	v_lshl_add_u64 v[222:223], s[44:45], 0, v[156:157]
	s_mov_b32 m0, s21
	s_nop 0
	global_load_lds_dwordx4 v[222:223], off
	s_barrier
	s_waitcnt lgkmcnt(0)
	s_nop 0
	s_waitcnt lgkmcnt(0)
	v_mfma_f32_16x16x32_bf16 v[60:63], v[128:131], v[144:147], v[60:63]
	v_mfma_f32_16x16x32_bf16 v[56:59], v[136:139], v[144:147], v[56:59]
	v_mfma_f32_16x16x32_bf16 v[44:47], v[128:131], v[168:171], v[44:47]
	v_mfma_f32_16x16x32_bf16 v[40:43], v[136:139], v[168:171], v[40:43]
	v_mfma_f32_16x16x32_bf16 v[28:31], v[128:131], v[176:179], v[28:31]
	v_mfma_f32_16x16x32_bf16 v[24:27], v[136:139], v[176:179], v[24:27]
	v_mfma_f32_16x16x32_bf16 v[12:15], v[128:131], v[192:195], v[12:15]
	v_mfma_f32_16x16x32_bf16 v[8:11], v[136:139], v[192:195], v[8:11]
	v_mfma_f32_16x16x32_bf16 v[60:63], v[132:135], v[148:151], v[60:63]
	v_mfma_f32_16x16x32_bf16 v[56:59], v[140:143], v[148:151], v[56:59]
	v_mfma_f32_16x16x32_bf16 v[44:47], v[132:135], v[172:175], v[44:47]
	v_mfma_f32_16x16x32_bf16 v[40:43], v[140:143], v[172:175], v[40:43]
	v_mfma_f32_16x16x32_bf16 v[28:31], v[132:135], v[180:183], v[28:31]
	v_mfma_f32_16x16x32_bf16 v[24:27], v[140:143], v[180:183], v[24:27]
	v_mfma_f32_16x16x32_bf16 v[12:15], v[132:135], v[196:199], v[12:15]
	v_mfma_f32_16x16x32_bf16 v[8:11], v[140:143], v[196:199], v[8:11]
	s_nop 0
	s_barrier
	s_add_u32 s58, s42, 0x40000
	s_addc_u32 s59, s43, 0
	s_add_i32 s60, s53, s3
	v_lshl_add_u64 v[128:129], s[58:59], 0, v[154:155]
	s_mov_b32 m0, s60
	s_nop 0
	global_load_lds_dwordx4 v[128:129], off
	v_lshl_add_u64 v[128:129], s[58:59], 0, v[158:159]
	s_add_i32 m0, s60, 0x2000
	s_nop 0
	global_load_lds_dwordx4 v[128:129], off
	s_waitcnt vmcnt(6)
	s_barrier
	s_nop 0
	v_mfma_f32_16x16x32_bf16 v[52:55], v[200:203], v[144:147], v[52:55]
	v_mfma_f32_16x16x32_bf16 v[48:51], v[210:213], v[144:147], v[48:51]
	v_mfma_f32_16x16x32_bf16 v[36:39], v[200:203], v[168:171], v[36:39]
	v_mfma_f32_16x16x32_bf16 v[32:35], v[210:213], v[168:171], v[32:35]
	v_mfma_f32_16x16x32_bf16 v[20:23], v[200:203], v[176:179], v[20:23]
	v_mfma_f32_16x16x32_bf16 v[16:19], v[210:213], v[176:179], v[16:19]
	v_mfma_f32_16x16x32_bf16 v[4:7], v[200:203], v[192:195], v[4:7]
	v_mfma_f32_16x16x32_bf16 v[0:3], v[210:213], v[192:195], v[0:3]
	v_mfma_f32_16x16x32_bf16 v[52:55], v[206:209], v[148:151], v[52:55]
	v_mfma_f32_16x16x32_bf16 v[48:51], v[214:217], v[148:151], v[48:51]
	v_mfma_f32_16x16x32_bf16 v[36:39], v[206:209], v[172:175], v[36:39]
	v_mfma_f32_16x16x32_bf16 v[32:35], v[214:217], v[172:175], v[32:35]
	v_mfma_f32_16x16x32_bf16 v[20:23], v[206:209], v[180:183], v[20:23]
	v_mfma_f32_16x16x32_bf16 v[16:19], v[214:217], v[180:183], v[16:19]
	v_mfma_f32_16x16x32_bf16 v[4:7], v[206:209], v[196:199], v[4:7]
	v_mfma_f32_16x16x32_bf16 v[0:3], v[214:217], v[196:199], v[0:3]
	s_nop 0
	s_add_i32 s58, 0, 0x18000
	v_add_u32_e32 v140, s58, v187
	s_barrier
	ds_read_b128 v[128:131], v140
	ds_read_b128 v[132:135], v140 offset:1024
	ds_read_b128 v[136:139], v140 offset:2048
	ds_read_b128 v[140:143], v140 offset:3072
	s_add_u32 s44, s44, 0x40000
	s_addc_u32 s45, s45, 0
	s_mov_b32 m0, s33
	v_lshl_add_u64 v[200:201], s[44:45], 0, v[152:153]
	ds_read_b128 v[144:147], v190 offset:32768
	ds_read_b128 v[148:151], v190 offset:33792
	ds_read_b128 v[168:171], v190 offset:34816
	ds_read_b128 v[172:175], v190 offset:35840
	ds_read_b128 v[176:179], v190 offset:36864
	ds_read_b128 v[180:183], v190 offset:37888
	ds_read_b128 v[192:195], v190 offset:38912
	ds_read_b128 v[196:199], v190 offset:39936
	global_load_lds_dwordx4 v[200:201], off
	v_lshl_add_u64 v[200:201], s[44:45], 0, v[156:157]
	s_mov_b32 m0, s39
	s_nop 0
	global_load_lds_dwordx4 v[200:201], off
	s_waitcnt lgkmcnt(8)
	s_barrier
	s_waitcnt lgkmcnt(0)
	s_nop 0
	s_waitcnt lgkmcnt(0)
	v_mfma_f32_16x16x32_bf16 v[124:127], v[128:131], v[144:147], v[124:127]
	v_mfma_f32_16x16x32_bf16 v[120:123], v[136:139], v[144:147], v[120:123]
	v_mfma_f32_16x16x32_bf16 v[108:111], v[128:131], v[168:171], v[108:111]
	v_mfma_f32_16x16x32_bf16 v[104:107], v[136:139], v[168:171], v[104:107]
	v_mfma_f32_16x16x32_bf16 v[92:95], v[128:131], v[176:179], v[92:95]
	v_mfma_f32_16x16x32_bf16 v[88:91], v[136:139], v[176:179], v[88:91]
	v_mfma_f32_16x16x32_bf16 v[76:79], v[128:131], v[192:195], v[76:79]
	v_mfma_f32_16x16x32_bf16 v[72:75], v[136:139], v[192:195], v[72:75]
	v_mfma_f32_16x16x32_bf16 v[124:127], v[132:135], v[148:151], v[124:127]
	v_mfma_f32_16x16x32_bf16 v[120:123], v[140:143], v[148:151], v[120:123]
	v_mfma_f32_16x16x32_bf16 v[108:111], v[132:135], v[172:175], v[108:111]
	v_mfma_f32_16x16x32_bf16 v[104:107], v[140:143], v[172:175], v[104:107]
	v_mfma_f32_16x16x32_bf16 v[92:95], v[132:135], v[180:183], v[92:95]
	v_mfma_f32_16x16x32_bf16 v[88:91], v[140:143], v[180:183], v[88:91]
	v_mfma_f32_16x16x32_bf16 v[76:79], v[132:135], v[196:199], v[76:79]
	v_mfma_f32_16x16x32_bf16 v[72:75], v[140:143], v[196:199], v[72:75]
	s_nop 0
	s_barrier
	s_add_i32 s44, 0, 0x1c000
	s_add_i32 s45, s58, s3
	v_add_u32_e32 v214, s44, v187
	v_lshl_add_u64 v[184:185], v[184:185], 0, s[24:25]
	s_mov_b32 m0, s45
	ds_read_b128 v[200:203], v214
	ds_read_b128 v[206:209], v214 offset:1024
	ds_read_b128 v[210:213], v214 offset:2048
	ds_read_b128 v[214:217], v214 offset:3072
	global_load_lds_dwordx4 v[184:185], off
	v_lshl_add_u64 v[184:185], v[218:219], 0, s[24:25]
	s_add_i32 m0, s45, 0x2000
	s_nop 0
	global_load_lds_dwordx4 v[184:185], off
	s_barrier
	s_waitcnt lgkmcnt(0)
	s_nop 0
	s_waitcnt lgkmcnt(0)
	v_mfma_f32_16x16x32_bf16 v[116:119], v[200:203], v[144:147], v[116:119]
	v_mfma_f32_16x16x32_bf16 v[112:115], v[210:213], v[144:147], v[112:115]
	v_mfma_f32_16x16x32_bf16 v[100:103], v[200:203], v[168:171], v[100:103]
	v_mfma_f32_16x16x32_bf16 v[96:99], v[210:213], v[168:171], v[96:99]
	v_mfma_f32_16x16x32_bf16 v[84:87], v[200:203], v[176:179], v[84:87]
	v_mfma_f32_16x16x32_bf16 v[80:83], v[210:213], v[176:179], v[80:83]
	v_mfma_f32_16x16x32_bf16 v[68:71], v[200:203], v[192:195], v[68:71]
	v_mfma_f32_16x16x32_bf16 v[64:67], v[210:213], v[192:195], v[64:67]
	v_mfma_f32_16x16x32_bf16 v[116:119], v[206:209], v[148:151], v[116:119]
	v_mfma_f32_16x16x32_bf16 v[112:115], v[214:217], v[148:151], v[112:115]
	v_mfma_f32_16x16x32_bf16 v[100:103], v[206:209], v[172:175], v[100:103]
	v_mfma_f32_16x16x32_bf16 v[96:99], v[214:217], v[172:175], v[96:99]
	v_mfma_f32_16x16x32_bf16 v[84:87], v[206:209], v[180:183], v[84:87]
	v_mfma_f32_16x16x32_bf16 v[80:83], v[214:217], v[180:183], v[80:83]
	v_mfma_f32_16x16x32_bf16 v[68:71], v[206:209], v[196:199], v[68:71]
	v_mfma_f32_16x16x32_bf16 v[64:67], v[214:217], v[196:199], v[64:67]
	s_nop 0
	s_mov_b32 m0, s47
	v_lshl_add_u64 v[184:185], v[220:221], 0, s[24:25]
	s_barrier
	ds_read_b128 v[144:147], v190 offset:49152
	ds_read_b128 v[148:151], v190 offset:50176
	ds_read_b128 v[168:171], v190 offset:51200
	ds_read_b128 v[172:175], v190 offset:52224
	ds_read_b128 v[176:179], v190 offset:53248
	ds_read_b128 v[180:183], v190 offset:54272
	ds_read_b128 v[192:195], v190 offset:55296
	ds_read_b128 v[196:199], v190 offset:56320
	global_load_lds_dwordx4 v[184:185], off
	v_lshl_add_u64 v[184:185], v[222:223], 0, s[24:25]
	s_mov_b32 m0, s48
	s_nop 0
	global_load_lds_dwordx4 v[184:185], off
	s_barrier
	s_waitcnt lgkmcnt(0)
	s_nop 0
	s_waitcnt lgkmcnt(0)
	v_mfma_f32_16x16x32_bf16 v[60:63], v[128:131], v[144:147], v[60:63]
	v_mfma_f32_16x16x32_bf16 v[56:59], v[136:139], v[144:147], v[56:59]
	v_mfma_f32_16x16x32_bf16 v[44:47], v[128:131], v[168:171], v[44:47]
	v_mfma_f32_16x16x32_bf16 v[40:43], v[136:139], v[168:171], v[40:43]
	v_mfma_f32_16x16x32_bf16 v[28:31], v[128:131], v[176:179], v[28:31]
	v_mfma_f32_16x16x32_bf16 v[24:27], v[136:139], v[176:179], v[24:27]
	v_mfma_f32_16x16x32_bf16 v[12:15], v[128:131], v[192:195], v[12:15]
	v_mfma_f32_16x16x32_bf16 v[8:11], v[136:139], v[192:195], v[8:11]
	v_mfma_f32_16x16x32_bf16 v[60:63], v[132:135], v[148:151], v[60:63]
	v_mfma_f32_16x16x32_bf16 v[56:59], v[140:143], v[148:151], v[56:59]
	v_mfma_f32_16x16x32_bf16 v[44:47], v[132:135], v[172:175], v[44:47]
	v_mfma_f32_16x16x32_bf16 v[40:43], v[140:143], v[172:175], v[40:43]
	v_mfma_f32_16x16x32_bf16 v[28:31], v[132:135], v[180:183], v[28:31]
	v_mfma_f32_16x16x32_bf16 v[24:27], v[140:143], v[180:183], v[24:27]
	v_mfma_f32_16x16x32_bf16 v[12:15], v[132:135], v[196:199], v[12:15]
	v_mfma_f32_16x16x32_bf16 v[8:11], v[140:143], v[196:199], v[8:11]
	s_nop 0
	s_barrier
	s_add_u32 s42, s42, 0x40080
	s_addc_u32 s43, s43, 0
	s_add_i32 s44, s44, s3
	v_lshl_add_u64 v[128:129], s[42:43], 0, v[154:155]
	s_mov_b32 m0, s44
	s_nop 0
	global_load_lds_dwordx4 v[128:129], off
	v_lshl_add_u64 v[128:129], s[42:43], 0, v[158:159]
	s_add_i32 m0, s44, 0x2000
	s_nop 0
	global_load_lds_dwordx4 v[128:129], off
	s_waitcnt vmcnt(6)
	s_cmp_eq_u32 s57, 10
	s_cbranch_scc0 .Ler_1894_skip
	s_lshl_b32 s84, s36, 19
	s_lshl_b32 s85, s38, 9
	s_add_u32 s84, s84, s85
	s_add_u32 s84, s16, s84
	s_addc_u32 s85, s17, 0
	v_lshlrev_b32_e32 v236, 11, v186
	v_lshl_add_u32 v236, v188, 1, v236
	global_load_dwordx4 v[224:227], v236, s[84:85]
	global_load_dwordx4 v[228:231], v236, s[84:85] offset:256
	s_add_u32 s86, s84, 0x8000
	s_addc_u32 s87, s85, 0
	global_load_dwordx4 v[232:235], v236, s[86:87]
	global_load_dwordx4 v[240:243], v236, s[86:87] offset:256
	s_add_u32 s86, s84, 0x10000
	s_addc_u32 s87, s85, 0
	global_load_dwordx4 v[244:247], v236, s[86:87]
	global_load_dwordx4 v[248:251], v236, s[86:87] offset:256
	s_add_u32 s86, s84, 0x18000
	s_addc_u32 s87, s85, 0
	global_load_dwordx4 v[252:255], v236, s[86:87]
.Ler_1894_skip:
	s_barrier
	s_nop 0
	v_mfma_f32_16x16x32_bf16 v[52:55], v[200:203], v[144:147], v[52:55]
	v_mfma_f32_16x16x32_bf16 v[48:51], v[210:213], v[144:147], v[48:51]
	v_mfma_f32_16x16x32_bf16 v[36:39], v[200:203], v[168:171], v[36:39]
	v_mfma_f32_16x16x32_bf16 v[32:35], v[210:213], v[168:171], v[32:35]
	v_mfma_f32_16x16x32_bf16 v[20:23], v[200:203], v[176:179], v[20:23]
	v_mfma_f32_16x16x32_bf16 v[16:19], v[210:213], v[176:179], v[16:19]
	v_mfma_f32_16x16x32_bf16 v[4:7], v[200:203], v[192:195], v[4:7]
	v_mfma_f32_16x16x32_bf16 v[0:3], v[210:213], v[192:195], v[0:3]
	v_mfma_f32_16x16x32_bf16 v[52:55], v[206:209], v[148:151], v[52:55]
	v_mfma_f32_16x16x32_bf16 v[48:51], v[214:217], v[148:151], v[48:51]
	v_mfma_f32_16x16x32_bf16 v[36:39], v[206:209], v[172:175], v[36:39]
	v_mfma_f32_16x16x32_bf16 v[32:35], v[214:217], v[172:175], v[32:35]
	v_mfma_f32_16x16x32_bf16 v[20:23], v[206:209], v[180:183], v[20:23]
	v_mfma_f32_16x16x32_bf16 v[16:19], v[214:217], v[180:183], v[16:19]
	v_mfma_f32_16x16x32_bf16 v[4:7], v[206:209], v[196:199], v[4:7]
	v_mfma_f32_16x16x32_bf16 v[0:3], v[214:217], v[196:199], v[0:3]
	s_nop 0
	s_add_i32 s57, s57, 2
	s_add_u32 s40, s40, 0x100
	s_addc_u32 s41, s41, 0
	s_add_u32 s55, s55, 0x100
	s_addc_u32 s56, s56, 0
	s_cmp_gt_u32 s57, 13
	s_barrier
	s_cbranch_scc0 .LBB0_1894
	v_lshl_or_b32 v168, s38, 8, v188
	v_lshl_add_u32 v170, s36, 8, v186
	v_ashrrev_i32_e32 v169, 31, v168
	v_lshlrev_b64 v[202:203], 1, v[168:169]
	v_ashrrev_i32_e32 v171, 31, v170
	v_or_b32_e32 v182, 16, v170
	v_lshl_add_u64 v[172:173], s[16:17], 0, v[202:203]
	v_lshlrev_b64 v[206:207], 11, v[170:171]
	v_ashrrev_i32_e32 v183, 31, v182
	v_or_b32_e32 v178, 32, v170
	v_lshl_add_u64 v[128:129], v[172:173], 0, v[206:207]
	v_lshlrev_b64 v[184:185], 11, v[182:183]
	v_ashrrev_i32_e32 v179, 31, v178
	v_or_b32_e32 v174, 48, v170
	v_mov_b32_e32 v194, v224
	v_mov_b32_e32 v195, v225
	v_mov_b32_e32 v196, v226
	v_mov_b32_e32 v197, v227
	v_mov_b32_e32 v198, v228
	v_mov_b32_e32 v199, v229
	v_mov_b32_e32 v200, v230
	v_mov_b32_e32 v201, v231
	v_lshl_add_u64 v[128:129], v[172:173], 0, v[184:185]
	v_lshlrev_b64 v[180:181], 11, v[178:179]
	v_ashrrev_i32_e32 v175, 31, v174
	v_mov_b32_e32 v148, v232
	v_mov_b32_e32 v149, v233
	v_mov_b32_e32 v150, v234
	v_mov_b32_e32 v151, v235
	v_mov_b32_e32 v144, v240
	v_mov_b32_e32 v145, v241
	v_mov_b32_e32 v146, v242
	v_mov_b32_e32 v147, v243
	v_lshl_add_u64 v[128:129], v[172:173], 0, v[180:181]
	v_lshlrev_b64 v[176:177], 11, v[174:175]
	v_mov_b32_e32 v140, v244
	v_mov_b32_e32 v141, v245
	v_mov_b32_e32 v142, v246
	v_mov_b32_e32 v143, v247
	v_mov_b32_e32 v136, v248
	v_mov_b32_e32 v137, v249
	v_mov_b32_e32 v138, v250
	v_mov_b32_e32 v139, v251
	v_lshl_add_u64 v[128:129], v[172:173], 0, v[176:177]
	v_mov_b32_e32 v132, v252
	v_mov_b32_e32 v133, v253
	v_mov_b32_e32 v134, v254
	v_mov_b32_e32 v135, v255
	s_nop 0
	global_load_dwordx4 v[128:131], v[128:129], off offset:256
	v_and_b32_e32 v193, 64, v205
	v_xor_b32_e32 v192, 16, v205
	v_add_u32_e32 v208, 64, v193
	v_cmp_lt_i32_e32 vcc, v192, v208
	s_nop 1
	v_cndmask_b32_e32 v192, v205, v192, vcc
	v_lshlrev_b32_e32 v193, 2, v192
	v_xor_b32_e32 v192, 32, v205
	v_cmp_lt_i32_e32 vcc, v192, v208
	s_nop 1
	v_cndmask_b32_e32 v192, v205, v192, vcc
	v_lshlrev_b32_e32 v192, 2, v192
	v_add_u32_e32 v236, 0x80, v170
	v_ashrrev_i32_e32 v237, 31, v236
	v_lshlrev_b64 v[236:237], 11, v[236:237]
	v_lshl_add_u64 v[236:237], v[172:173], 0, v[236:237]
	global_load_dwordx4 v[224:227], v[236:237], off
	global_load_dwordx4 v[228:231], v[236:237], off offset:256
	v_add_u32_e32 v236, 0x90, v170
	v_ashrrev_i32_e32 v237, 31, v236
	v_lshlrev_b64 v[236:237], 11, v[236:237]
	v_lshl_add_u64 v[236:237], v[172:173], 0, v[236:237]
	global_load_dwordx4 v[232:235], v[236:237], off
	global_load_dwordx4 v[240:243], v[236:237], off offset:256
	v_add_u32_e32 v236, 0xa0, v170
	v_ashrrev_i32_e32 v237, 31, v236
	v_lshlrev_b64 v[236:237], 11, v[236:237]
	v_lshl_add_u64 v[236:237], v[172:173], 0, v[236:237]
	global_load_dwordx4 v[244:247], v[236:237], off
	global_load_dwordx4 v[248:251], v[236:237], off offset:256
	v_add_u32_e32 v236, 0xb0, v170
	v_ashrrev_i32_e32 v237, 31, v236
	v_lshlrev_b64 v[236:237], 11, v[236:237]
	v_lshl_add_u64 v[236:237], v[172:173], 0, v[236:237]
	global_load_dwordx4 v[252:255], v[236:237], off
	s_waitcnt vmcnt(24)
	v_lshlrev_b32_e32 v208, 16, v194
	v_and_b32_e32 v209, 0xffff0000, v194
	v_lshlrev_b32_e32 v194, 16, v195
	v_and_b32_e32 v195, 0xffff0000, v195
	v_lshlrev_b32_e32 v210, 16, v196
	v_and_b32_e32 v211, 0xffff0000, v196
	v_lshlrev_b32_e32 v196, 16, v197
	v_and_b32_e32 v197, 0xffff0000, v197
	v_pk_add_f32 v[126:127], v[126:127], v[194:195]
	v_pk_add_f32 v[194:195], v[122:123], v[196:197]
	v_pk_add_f32 v[196:197], v[120:121], v[210:211]
	v_pk_add_f32 v[124:125], v[124:125], v[208:209]
	v_cvt_pk_bf16_f32 v122, v196, v197
	v_mul_f32_e32 v196, v196, v196
	v_cvt_pk_bf16_f32 v120, v124, v125
	v_fmac_f32_e32 v196, v124, v124
	v_mul_f32_e32 v124, v197, v197
	v_fmac_f32_e32 v124, v125, v125
	v_mul_f32_e32 v125, v194, v194
	v_add_f32_e32 v124, v196, v124
	v_fmac_f32_e32 v125, v126, v126
	v_add_f32_e32 v124, v125, v124
	v_mul_f32_e32 v125, v195, v195
	v_cvt_pk_bf16_f32 v121, v126, v127
	v_cvt_pk_bf16_f32 v123, v194, v195
	v_fmac_f32_e32 v125, v127, v127
	v_lshlrev_b32_e32 v126, 16, v199
	v_and_b32_e32 v127, 0xffff0000, v199
	v_lshlrev_b32_e32 v194, 16, v200
	v_and_b32_e32 v195, 0xffff0000, v200
	v_add_f32_e32 v208, v125, v124
	v_lshlrev_b32_e32 v124, 16, v198
	v_and_b32_e32 v125, 0xffff0000, v198
	v_pk_add_f32 v[118:119], v[118:119], v[126:127]
	v_pk_add_f32 v[126:127], v[112:113], v[194:195]
	v_pk_add_f32 v[116:117], v[116:117], v[124:125]
	v_mul_f32_e32 v112, v126, v126
	v_lshlrev_b32_e32 v196, 16, v201
	v_and_b32_e32 v197, 0xffff0000, v201
	v_fmac_f32_e32 v112, v116, v116
	v_mul_f32_e32 v113, v127, v127
	v_pk_add_f32 v[124:125], v[114:115], v[196:197]
	v_add_f32_e32 v112, v112, v208
	v_fmac_f32_e32 v113, v117, v117
	v_add_f32_e32 v112, v113, v112
	v_mul_f32_e32 v113, v124, v124
	v_fmac_f32_e32 v113, v118, v118
	v_add_f32_e32 v112, v113, v112
	v_mul_f32_e32 v113, v125, v125
	v_fmac_f32_e32 v113, v119, v119
	v_add_f32_e32 v115, v113, v112
	ds_bpermute_b32 v196, v193, v115
	v_lshl_add_u64 v[112:113], s[16:17], 0, v[206:207]
	v_lshl_add_u64 v[194:195], v[112:113], 0, v[202:203]
	v_cvt_pk_bf16_f32 v114, v116, v117
	v_cvt_pk_bf16_f32 v116, v126, v127
	s_waitcnt lgkmcnt(0)
	v_add_f32_e32 v112, v115, v196
	ds_bpermute_b32 v113, v192, v112
	v_cvt_pk_bf16_f32 v115, v118, v119
	v_cvt_pk_bf16_f32 v117, v124, v125
	global_store_dwordx4 v[194:195], v[120:123], off
	global_store_dwordx4 v[194:195], v[114:117], off offset:256
	s_and_saveexec_b64 s[36:37], s[8:9]
	s_cbranch_execz .LBB0_1897
	s_waitcnt lgkmcnt(0)
	v_add_f32_e32 v112, v112, v113
	v_mul_f32_e32 v112, 0x4b800000, v112
	v_trunc_f32_e32 v112, v112
	v_mul_f32_e32 v113, 0x2f800000, v112
	v_floor_f32_e32 v113, v113
	v_fmac_f32_e32 v112, 0xcf800000, v113
	v_cvt_u32_f32_e32 v112, v112
	v_cvt_u32_f32_e32 v113, v113
	v_lshl_add_u64 v[114:115], v[170:171], 3, s[18:19]
	global_atomic_add_x2 v[114:115], v[112:113], off

.LBB0_1966:
	s_or_b64 exec, exec, s[8:9]
	s_mov_b64 s[0:1], s[70:71]
	s_waitcnt lgkmcnt(0)
	s_barrier
	v_readfirstlane_b32 s101, v204
	s_nop 3
	s_lshr_b32 s101, s101, 6
	s_cmp_ge_u32 s101, 4
	s_cbranch_scc0 .Lprio_6
	s_setprio 1
.Lprio_6:
	s_load_dwordx2 s[12:13], s[0:1], 0xb8
	v_mov_b32_e32 v8, v204
	s_and_b64 vcc, exec, s[6:7]
	v_readfirstlane_b32 s0, v8
	s_cbranch_vccnz .LBB0_1986
	s_ashr_i32 s1, s97, 31
	s_lshr_b32 s2, s1, 29
	s_add_i32 s2, s97, s2
	s_and_b32 s3, s2, -8
	s_sub_i32 s3, s97, s3
	s_cmp_gt_i32 s3, -1
	s_cbranch_scc0 .LBB0_1969
	s_lshl_b32 s8, s3, 8
	s_cbranch_execz .LBB0_1970
	s_branch .LBB0_1971

.LBB0_1980:
	s_ashr_i32 s37, s36, 31
	v_cmp_lt_i64_e32 vcc, s[38:39], v[140:141]
	s_lshl_b64 s[38:39], s[36:37], 19
	s_add_u32 s38, s2, s38
	s_addc_u32 s39, s3, s39
	s_and_b64 s[40:41], vcc, exec
	s_cselect_b32 s9, s39, s11
	s_cselect_b32 s37, s38, s10
	s_ashr_i32 s35, s34, 31
	s_lshl_b64 s[40:41], s[34:35], 19
	s_add_u32 s40, s20, s40
	s_addc_u32 s41, s21, s41
	s_and_b64 s[44:45], vcc, exec
	s_cselect_b32 s35, s41, s43
	s_cselect_b32 s63, s40, s42
	s_add_u32 s10, s10, 0x40080
	s_addc_u32 s11, s11, 0
	s_add_u32 s64, s42, 0x100

	s_addc_u32 s65, s43, 0
	s_mov_b32 s66, -2


	ds_read_b128 v[164:167], v155
	ds_read_b128 v[168:171], v155 offset:1024
	ds_read_b128 v[172:175], v155 offset:2048
	ds_read_b128 v[176:179], v155 offset:3072
	s_add_u32 s42, s10, 0xfffc0080
	s_addc_u32 s43, s11, -1
	s_cmp_eq_u32 s66, 12
	s_cselect_b32 s45, s9, s43
	s_cselect_b32 s44, s37, s42
	s_cselect_b32 s43, s35, s65
	s_cselect_b32 s42, s63, s64
	v_lshl_add_u64 v[146:147], s[10:11], 0, v[136:137]
	s_add_i32 m0, s46, 0xc000
	ds_read_b128 v[180:183], v159
	ds_read_b128 v[184:187], v159 offset:1024
	ds_read_b128 v[188:191], v159 offset:2048
	ds_read_b128 v[192:195], v159 offset:3072
	ds_read_b128 v[196:199], v159 offset:4096
	ds_read_b128 v[200:203], v159 offset:5120
	ds_read_b128 v[206:209], v159 offset:6144
	ds_read_b128 v[210:213], v159 offset:7168
	global_load_lds_dwordx4 v[146:147], off
	v_lshl_add_u64 v[146:147], s[10:11], 0, v[138:139]
	s_add_i32 m0, s46, 0xe000
	s_nop 0
	global_load_lds_dwordx4 v[146:147], off
	s_waitcnt lgkmcnt(8)
	s_barrier
	s_waitcnt lgkmcnt(0)
	s_nop 0
	s_waitcnt lgkmcnt(0)
	v_mfma_f32_16x16x32_bf16 v[124:127], v[164:167], v[180:183], 0
	v_mfma_f32_16x16x32_bf16 v[120:123], v[172:175], v[180:183], 0
	v_mfma_f32_16x16x32_bf16 v[108:111], v[164:167], v[188:191], 0
	v_mfma_f32_16x16x32_bf16 v[104:107], v[172:175], v[188:191], 0
	v_mfma_f32_16x16x32_bf16 v[92:95], v[164:167], v[196:199], 0
	v_mfma_f32_16x16x32_bf16 v[88:91], v[172:175], v[196:199], 0
	v_mfma_f32_16x16x32_bf16 v[76:79], v[164:167], v[206:209], 0
	v_mfma_f32_16x16x32_bf16 v[72:75], v[172:175], v[206:209], 0
	v_mfma_f32_16x16x32_bf16 v[124:127], v[168:171], v[184:187], v[124:127]
	v_mfma_f32_16x16x32_bf16 v[120:123], v[176:179], v[184:187], v[120:123]
	v_mfma_f32_16x16x32_bf16 v[108:111], v[168:171], v[192:195], v[108:111]
	v_mfma_f32_16x16x32_bf16 v[104:107], v[176:179], v[192:195], v[104:107]
	v_mfma_f32_16x16x32_bf16 v[92:95], v[168:171], v[200:203], v[92:95]
	v_mfma_f32_16x16x32_bf16 v[88:91], v[176:179], v[200:203], v[88:91]
	v_mfma_f32_16x16x32_bf16 v[76:79], v[168:171], v[210:213], v[76:79]
	v_mfma_f32_16x16x32_bf16 v[72:75], v[176:179], v[210:213], v[72:75]
	s_nop 0
	s_barrier
	s_add_i32 s67, s55, s33
	v_lshl_add_u64 v[146:147], s[42:43], 0, v[130:131]
	s_mov_b32 m0, s67
	ds_read_b128 v[214:217], v162
	ds_read_b128 v[218:221], v162 offset:1024
	ds_read_b128 v[222:225], v162 offset:2048
	ds_read_b128 v[226:229], v162 offset:3072
	global_load_lds_dwordx4 v[146:147], off
	v_lshl_add_u64 v[152:153], s[42:43], 0, v[134:135]
	s_add_i32 m0, s67, 0x2000
	s_nop 0
	global_load_lds_dwordx4 v[152:153], off
	s_barrier
	s_waitcnt lgkmcnt(0)
	s_nop 0
	s_waitcnt lgkmcnt(0)
	v_mfma_f32_16x16x32_bf16 v[116:119], v[214:217], v[180:183], 0
	v_mfma_f32_16x16x32_bf16 v[112:115], v[222:225], v[180:183], 0
	v_mfma_f32_16x16x32_bf16 v[100:103], v[214:217], v[188:191], 0
	v_mfma_f32_16x16x32_bf16 v[96:99], v[222:225], v[188:191], 0
	v_mfma_f32_16x16x32_bf16 v[84:87], v[214:217], v[196:199], 0
	v_mfma_f32_16x16x32_bf16 v[80:83], v[222:225], v[196:199], 0
	v_mfma_f32_16x16x32_bf16 v[68:71], v[214:217], v[206:209], 0
	v_mfma_f32_16x16x32_bf16 v[64:67], v[222:225], v[206:209], 0
	v_mfma_f32_16x16x32_bf16 v[116:119], v[218:221], v[184:187], v[116:119]
	v_mfma_f32_16x16x32_bf16 v[112:115], v[226:229], v[184:187], v[112:115]
	v_mfma_f32_16x16x32_bf16 v[100:103], v[218:221], v[192:195], v[100:103]
	v_mfma_f32_16x16x32_bf16 v[96:99], v[226:229], v[192:195], v[96:99]
	v_mfma_f32_16x16x32_bf16 v[84:87], v[218:221], v[200:203], v[84:87]
	v_mfma_f32_16x16x32_bf16 v[80:83], v[226:229], v[200:203], v[80:83]
	v_mfma_f32_16x16x32_bf16 v[68:71], v[218:221], v[210:213], v[68:71]
	v_mfma_f32_16x16x32_bf16 v[64:67], v[226:229], v[210:213], v[64:67]
	s_nop 0
	s_mov_b32 m0, s46
	v_lshl_add_u64 v[156:157], s[44:45], 0, v[128:129]
	s_barrier
	ds_read_b128 v[180:183], v159 offset:16384
	ds_read_b128 v[184:187], v159 offset:17408
	ds_read_b128 v[188:191], v159 offset:18432
	ds_read_b128 v[192:195], v159 offset:19456
	ds_read_b128 v[196:199], v159 offset:20480
	ds_read_b128 v[200:203], v159 offset:21504
	ds_read_b128 v[206:209], v159 offset:22528
	ds_read_b128 v[210:213], v159 offset:23552
	global_load_lds_dwordx4 v[156:157], off
	v_lshl_add_u64 v[160:161], s[44:45], 0, v[132:133]
	s_mov_b32 m0, s47
	s_nop 0
	global_load_lds_dwordx4 v[160:161], off
	s_barrier
	s_waitcnt lgkmcnt(0)
	s_nop 0
	s_waitcnt lgkmcnt(0)
	v_mfma_f32_16x16x32_bf16 v[60:63], v[164:167], v[180:183], 0
	v_mfma_f32_16x16x32_bf16 v[56:59], v[172:175], v[180:183], 0
	v_mfma_f32_16x16x32_bf16 v[44:47], v[164:167], v[188:191], 0
	v_mfma_f32_16x16x32_bf16 v[40:43], v[172:175], v[188:191], 0
	v_mfma_f32_16x16x32_bf16 v[28:31], v[164:167], v[196:199], 0
	v_mfma_f32_16x16x32_bf16 v[24:27], v[172:175], v[196:199], 0
	v_mfma_f32_16x16x32_bf16 v[12:15], v[164:167], v[206:209], 0
	v_mfma_f32_16x16x32_bf16 v[8:11], v[172:175], v[206:209], 0
	v_mfma_f32_16x16x32_bf16 v[60:63], v[168:171], v[184:187], v[60:63]
	v_mfma_f32_16x16x32_bf16 v[56:59], v[176:179], v[184:187], v[56:59]
	v_mfma_f32_16x16x32_bf16 v[44:47], v[168:171], v[192:195], v[44:47]
	v_mfma_f32_16x16x32_bf16 v[40:43], v[176:179], v[192:195], v[40:43]
	v_mfma_f32_16x16x32_bf16 v[28:31], v[168:171], v[200:203], v[28:31]
	v_mfma_f32_16x16x32_bf16 v[24:27], v[176:179], v[200:203], v[24:27]
	v_mfma_f32_16x16x32_bf16 v[12:15], v[168:171], v[210:213], v[12:15]
	v_mfma_f32_16x16x32_bf16 v[8:11], v[176:179], v[210:213], v[8:11]
	s_nop 0
	s_barrier
	s_add_u32 s68, s42, 0x40000
	s_addc_u32 s69, s43, 0
	s_add_i32 s67, s56, s33
	v_lshl_add_u64 v[164:165], s[68:69], 0, v[130:131]
	s_mov_b32 m0, s67
	s_nop 0
	global_load_lds_dwordx4 v[164:165], off
	v_lshl_add_u64 v[164:165], s[68:69], 0, v[134:135]
	s_add_i32 m0, s67, 0x2000
	s_nop 0
	global_load_lds_dwordx4 v[164:165], off
	s_waitcnt vmcnt(6)
	s_barrier
	s_nop 0
	v_mfma_f32_16x16x32_bf16 v[52:55], v[214:217], v[180:183], 0
	v_mfma_f32_16x16x32_bf16 v[48:51], v[222:225], v[180:183], 0
	v_mfma_f32_16x16x32_bf16 v[36:39], v[214:217], v[188:191], 0
	v_mfma_f32_16x16x32_bf16 v[32:35], v[222:225], v[188:191], 0
	v_mfma_f32_16x16x32_bf16 v[20:23], v[214:217], v[196:199], 0
	v_mfma_f32_16x16x32_bf16 v[16:19], v[222:225], v[196:199], 0
	v_mfma_f32_16x16x32_bf16 v[4:7], v[214:217], v[206:209], 0
	v_mfma_f32_16x16x32_bf16 v[0:3], v[222:225], v[206:209], 0
	v_mfma_f32_16x16x32_bf16 v[52:55], v[218:221], v[184:187], v[52:55]
	v_mfma_f32_16x16x32_bf16 v[48:51], v[226:229], v[184:187], v[48:51]
	v_mfma_f32_16x16x32_bf16 v[36:39], v[218:221], v[192:195], v[36:39]
	v_mfma_f32_16x16x32_bf16 v[32:35], v[226:229], v[192:195], v[32:35]
	v_mfma_f32_16x16x32_bf16 v[20:23], v[218:221], v[200:203], v[20:23]
	v_mfma_f32_16x16x32_bf16 v[16:19], v[226:229], v[200:203], v[16:19]
	v_mfma_f32_16x16x32_bf16 v[4:7], v[218:221], v[210:213], v[4:7]
	v_mfma_f32_16x16x32_bf16 v[0:3], v[226:229], v[210:213], v[0:3]
	s_nop 0
	s_add_i32 s67, 0, 0x18000
	v_add_u32_e32 v144, s67, v149
	s_barrier
	ds_read_b128 v[164:167], v144
	ds_read_b128 v[168:171], v144 offset:1024
	ds_read_b128 v[172:175], v144 offset:2048
	ds_read_b128 v[176:179], v144 offset:3072
	s_add_u32 s44, s44, 0x40000
	s_addc_u32 s45, s45, 0
	s_mov_b32 m0, s48
	v_lshl_add_u64 v[214:215], s[44:45], 0, v[128:129]
	ds_read_b128 v[180:183], v159 offset:32768
	ds_read_b128 v[184:187], v159 offset:33792
	ds_read_b128 v[188:191], v159 offset:34816
	ds_read_b128 v[192:195], v159 offset:35840
	ds_read_b128 v[196:199], v159 offset:36864
	ds_read_b128 v[200:203], v159 offset:37888
	ds_read_b128 v[206:209], v159 offset:38912
	ds_read_b128 v[210:213], v159 offset:39936
	global_load_lds_dwordx4 v[214:215], off
	v_lshl_add_u64 v[214:215], s[44:45], 0, v[132:133]
	s_mov_b32 m0, s49
	s_nop 0
	global_load_lds_dwordx4 v[214:215], off
	s_waitcnt lgkmcnt(8)
	s_barrier
	s_waitcnt lgkmcnt(0)
	s_nop 0
	s_waitcnt lgkmcnt(0)
	v_mfma_f32_16x16x32_bf16 v[124:127], v[164:167], v[180:183], v[124:127]
	v_mfma_f32_16x16x32_bf16 v[120:123], v[172:175], v[180:183], v[120:123]
	v_mfma_f32_16x16x32_bf16 v[108:111], v[164:167], v[188:191], v[108:111]
	v_mfma_f32_16x16x32_bf16 v[104:107], v[172:175], v[188:191], v[104:107]
	v_mfma_f32_16x16x32_bf16 v[92:95], v[164:167], v[196:199], v[92:95]
	v_mfma_f32_16x16x32_bf16 v[88:91], v[172:175], v[196:199], v[88:91]
	v_mfma_f32_16x16x32_bf16 v[76:79], v[164:167], v[206:209], v[76:79]
	v_mfma_f32_16x16x32_bf16 v[72:75], v[172:175], v[206:209], v[72:75]
	v_mfma_f32_16x16x32_bf16 v[124:127], v[168:171], v[184:187], v[124:127]
	v_mfma_f32_16x16x32_bf16 v[120:123], v[176:179], v[184:187], v[120:123]
	v_mfma_f32_16x16x32_bf16 v[108:111], v[168:171], v[192:195], v[108:111]
	v_mfma_f32_16x16x32_bf16 v[104:107], v[176:179], v[192:195], v[104:107]
	v_mfma_f32_16x16x32_bf16 v[92:95], v[168:171], v[200:203], v[92:95]
	v_mfma_f32_16x16x32_bf16 v[88:91], v[176:179], v[200:203], v[88:91]
	v_mfma_f32_16x16x32_bf16 v[76:79], v[168:171], v[210:213], v[76:79]
	v_mfma_f32_16x16x32_bf16 v[72:75], v[176:179], v[210:213], v[72:75]
	s_nop 0
	s_barrier
	s_add_i32 s44, 0, 0x1c000
	s_add_i32 s45, s67, s33
	v_add_u32_e32 v144, s44, v149
	v_lshl_add_u64 v[146:147], v[146:147], 0, s[18:19]
	s_mov_b32 m0, s45
	ds_read_b128 v[214:217], v144
	ds_read_b128 v[218:221], v144 offset:1024
	ds_read_b128 v[222:225], v144 offset:2048
	ds_read_b128 v[226:229], v144 offset:3072
	global_load_lds_dwordx4 v[146:147], off
	v_lshl_add_u64 v[146:147], v[152:153], 0, s[18:19]
	s_add_i32 m0, s45, 0x2000
	s_nop 0
	global_load_lds_dwordx4 v[146:147], off
	s_barrier
	s_waitcnt lgkmcnt(0)
	s_nop 0
	s_waitcnt lgkmcnt(0)
	v_mfma_f32_16x16x32_bf16 v[116:119], v[214:217], v[180:183], v[116:119]
	v_mfma_f32_16x16x32_bf16 v[112:115], v[222:225], v[180:183], v[112:115]
	v_mfma_f32_16x16x32_bf16 v[100:103], v[214:217], v[188:191], v[100:103]
	v_mfma_f32_16x16x32_bf16 v[96:99], v[222:225], v[188:191], v[96:99]
	v_mfma_f32_16x16x32_bf16 v[84:87], v[214:217], v[196:199], v[84:87]
	v_mfma_f32_16x16x32_bf16 v[80:83], v[222:225], v[196:199], v[80:83]
	v_mfma_f32_16x16x32_bf16 v[68:71], v[214:217], v[206:209], v[68:71]
	v_mfma_f32_16x16x32_bf16 v[64:67], v[222:225], v[206:209], v[64:67]
	v_mfma_f32_16x16x32_bf16 v[116:119], v[218:221], v[184:187], v[116:119]
	v_mfma_f32_16x16x32_bf16 v[112:115], v[226:229], v[184:187], v[112:115]
	v_mfma_f32_16x16x32_bf16 v[100:103], v[218:221], v[192:195], v[100:103]
	v_mfma_f32_16x16x32_bf16 v[96:99], v[226:229], v[192:195], v[96:99]
	v_mfma_f32_16x16x32_bf16 v[84:87], v[218:221], v[200:203], v[84:87]
	v_mfma_f32_16x16x32_bf16 v[80:83], v[226:229], v[200:203], v[80:83]
	v_mfma_f32_16x16x32_bf16 v[68:71], v[218:221], v[210:213], v[68:71]
	v_mfma_f32_16x16x32_bf16 v[64:67], v[226:229], v[210:213], v[64:67]
	s_nop 0
	s_mov_b32 m0, s51
	v_lshl_add_u64 v[146:147], v[156:157], 0, s[18:19]
	s_barrier
	ds_read_b128 v[180:183], v159 offset:49152
	ds_read_b128 v[184:187], v159 offset:50176
	ds_read_b128 v[188:191], v159 offset:51200
	ds_read_b128 v[192:195], v159 offset:52224
	ds_read_b128 v[196:199], v159 offset:53248
	ds_read_b128 v[200:203], v159 offset:54272
	ds_read_b128 v[206:209], v159 offset:55296
	ds_read_b128 v[210:213], v159 offset:56320
	global_load_lds_dwordx4 v[146:147], off
	v_lshl_add_u64 v[146:147], v[160:161], 0, s[18:19]
	s_mov_b32 m0, s52
	s_nop 0
	global_load_lds_dwordx4 v[146:147], off
	s_barrier
	s_waitcnt lgkmcnt(0)
	s_nop 0
	s_waitcnt lgkmcnt(0)
	v_mfma_f32_16x16x32_bf16 v[60:63], v[164:167], v[180:183], v[60:63]
	v_mfma_f32_16x16x32_bf16 v[56:59], v[172:175], v[180:183], v[56:59]
	v_mfma_f32_16x16x32_bf16 v[44:47], v[164:167], v[188:191], v[44:47]
	v_mfma_f32_16x16x32_bf16 v[40:43], v[172:175], v[188:191], v[40:43]
	v_mfma_f32_16x16x32_bf16 v[28:31], v[164:167], v[196:199], v[28:31]
	v_mfma_f32_16x16x32_bf16 v[24:27], v[172:175], v[196:199], v[24:27]
	v_mfma_f32_16x16x32_bf16 v[12:15], v[164:167], v[206:209], v[12:15]
	v_mfma_f32_16x16x32_bf16 v[8:11], v[172:175], v[206:209], v[8:11]
	v_mfma_f32_16x16x32_bf16 v[60:63], v[168:171], v[184:187], v[60:63]
	v_mfma_f32_16x16x32_bf16 v[56:59], v[176:179], v[184:187], v[56:59]
	v_mfma_f32_16x16x32_bf16 v[44:47], v[168:171], v[192:195], v[44:47]
	v_mfma_f32_16x16x32_bf16 v[40:43], v[176:179], v[192:195], v[40:43]
	v_mfma_f32_16x16x32_bf16 v[28:31], v[168:171], v[200:203], v[28:31]
	v_mfma_f32_16x16x32_bf16 v[24:27], v[176:179], v[200:203], v[24:27]
	v_mfma_f32_16x16x32_bf16 v[12:15], v[168:171], v[210:213], v[12:15]
	v_mfma_f32_16x16x32_bf16 v[8:11], v[176:179], v[210:213], v[8:11]
	s_nop 0
	s_barrier
	s_add_u32 s42, s42, 0x40080
	s_addc_u32 s43, s43, 0
	s_add_i32 s44, s44, s33
	v_lshl_add_u64 v[146:147], s[42:43], 0, v[130:131]
	s_mov_b32 m0, s44
	s_nop 0
	global_load_lds_dwordx4 v[146:147], off
	v_lshl_add_u64 v[146:147], s[42:43], 0, v[134:135]
	s_add_i32 m0, s44, 0x2000
	s_nop 0
	global_load_lds_dwordx4 v[146:147], off
	s_waitcnt vmcnt(6)
	s_barrier
	s_nop 0
	v_mfma_f32_16x16x32_bf16 v[52:55], v[214:217], v[180:183], v[52:55]
	v_mfma_f32_16x16x32_bf16 v[48:51], v[222:225], v[180:183], v[48:51]
	v_mfma_f32_16x16x32_bf16 v[36:39], v[214:217], v[188:191], v[36:39]
	v_mfma_f32_16x16x32_bf16 v[32:35], v[222:225], v[188:191], v[32:35]
	v_mfma_f32_16x16x32_bf16 v[20:23], v[214:217], v[196:199], v[20:23]
	v_mfma_f32_16x16x32_bf16 v[16:19], v[222:225], v[196:199], v[16:19]
	v_mfma_f32_16x16x32_bf16 v[4:7], v[214:217], v[206:209], v[4:7]
	v_mfma_f32_16x16x32_bf16 v[0:3], v[222:225], v[206:209], v[0:3]
	v_mfma_f32_16x16x32_bf16 v[52:55], v[218:221], v[184:187], v[52:55]
	v_mfma_f32_16x16x32_bf16 v[48:51], v[226:229], v[184:187], v[48:51]
	v_mfma_f32_16x16x32_bf16 v[36:39], v[218:221], v[192:195], v[36:39]
	v_mfma_f32_16x16x32_bf16 v[32:35], v[226:229], v[192:195], v[32:35]
	v_mfma_f32_16x16x32_bf16 v[20:23], v[218:221], v[200:203], v[20:23]
	v_mfma_f32_16x16x32_bf16 v[16:19], v[226:229], v[200:203], v[16:19]
	v_mfma_f32_16x16x32_bf16 v[4:7], v[218:221], v[210:213], v[4:7]
	v_mfma_f32_16x16x32_bf16 v[0:3], v[226:229], v[210:213], v[0:3]
	s_nop 0
	s_add_i32 s66, s66, 2
	s_add_u32 s10, s10, 0x100
	s_addc_u32 s11, s11, 0
	s_add_u32 s64, s64, 0x100
	s_addc_u32 s65, s65, 0
	s_cmp_gt_u32 s66, 13
	s_barrier
.LBB0_1981:
	ds_read_b128 v[164:167], v155
	ds_read_b128 v[168:171], v155 offset:1024
	ds_read_b128 v[172:175], v155 offset:2048
	ds_read_b128 v[176:179], v155 offset:3072
	s_add_u32 s42, s10, 0xfffc0080
	s_addc_u32 s43, s11, -1
	s_cmp_eq_u32 s66, 12
	s_cselect_b32 s45, s9, s43
	s_cselect_b32 s44, s37, s42
	s_cselect_b32 s43, s35, s65
	s_cselect_b32 s42, s63, s64
	v_lshl_add_u64 v[146:147], s[10:11], 0, v[136:137]
	s_add_i32 m0, s46, 0xc000
	ds_read_b128 v[180:183], v159
	ds_read_b128 v[184:187], v159 offset:1024
	ds_read_b128 v[188:191], v159 offset:2048
	ds_read_b128 v[192:195], v159 offset:3072
	ds_read_b128 v[196:199], v159 offset:4096
	ds_read_b128 v[200:203], v159 offset:5120
	ds_read_b128 v[206:209], v159 offset:6144
	ds_read_b128 v[210:213], v159 offset:7168
	global_load_lds_dwordx4 v[146:147], off
	v_lshl_add_u64 v[146:147], s[10:11], 0, v[138:139]
	s_add_i32 m0, s46, 0xe000
	s_nop 0
	global_load_lds_dwordx4 v[146:147], off
	s_waitcnt lgkmcnt(8)
	s_barrier
	s_waitcnt lgkmcnt(0)
	s_nop 0
	s_waitcnt lgkmcnt(0)
	v_mfma_f32_16x16x32_bf16 v[124:127], v[164:167], v[180:183], v[124:127]
	v_mfma_f32_16x16x32_bf16 v[120:123], v[172:175], v[180:183], v[120:123]
	v_mfma_f32_16x16x32_bf16 v[108:111], v[164:167], v[188:191], v[108:111]
	v_mfma_f32_16x16x32_bf16 v[104:107], v[172:175], v[188:191], v[104:107]
	v_mfma_f32_16x16x32_bf16 v[92:95], v[164:167], v[196:199], v[92:95]
	v_mfma_f32_16x16x32_bf16 v[88:91], v[172:175], v[196:199], v[88:91]
	v_mfma_f32_16x16x32_bf16 v[76:79], v[164:167], v[206:209], v[76:79]
	v_mfma_f32_16x16x32_bf16 v[72:75], v[172:175], v[206:209], v[72:75]
	v_mfma_f32_16x16x32_bf16 v[124:127], v[168:171], v[184:187], v[124:127]
	v_mfma_f32_16x16x32_bf16 v[120:123], v[176:179], v[184:187], v[120:123]
	v_mfma_f32_16x16x32_bf16 v[108:111], v[168:171], v[192:195], v[108:111]
	v_mfma_f32_16x16x32_bf16 v[104:107], v[176:179], v[192:195], v[104:107]
	v_mfma_f32_16x16x32_bf16 v[92:95], v[168:171], v[200:203], v[92:95]
	v_mfma_f32_16x16x32_bf16 v[88:91], v[176:179], v[200:203], v[88:91]
	v_mfma_f32_16x16x32_bf16 v[76:79], v[168:171], v[210:213], v[76:79]
	v_mfma_f32_16x16x32_bf16 v[72:75], v[176:179], v[210:213], v[72:75]
	s_nop 0
	s_barrier
	s_add_i32 s67, s55, s33
	v_lshl_add_u64 v[146:147], s[42:43], 0, v[130:131]
	s_mov_b32 m0, s67
	ds_read_b128 v[214:217], v162
	ds_read_b128 v[218:221], v162 offset:1024
	ds_read_b128 v[222:225], v162 offset:2048
	ds_read_b128 v[226:229], v162 offset:3072
	global_load_lds_dwordx4 v[146:147], off
	v_lshl_add_u64 v[152:153], s[42:43], 0, v[134:135]
	s_add_i32 m0, s67, 0x2000
	s_nop 0
	global_load_lds_dwordx4 v[152:153], off
	s_barrier
	s_waitcnt lgkmcnt(0)
	s_nop 0
	s_waitcnt lgkmcnt(0)
	v_mfma_f32_16x16x32_bf16 v[116:119], v[214:217], v[180:183], v[116:119]
	v_mfma_f32_16x16x32_bf16 v[112:115], v[222:225], v[180:183], v[112:115]
	v_mfma_f32_16x16x32_bf16 v[100:103], v[214:217], v[188:191], v[100:103]
	v_mfma_f32_16x16x32_bf16 v[96:99], v[222:225], v[188:191], v[96:99]
	v_mfma_f32_16x16x32_bf16 v[84:87], v[214:217], v[196:199], v[84:87]
	v_mfma_f32_16x16x32_bf16 v[80:83], v[222:225], v[196:199], v[80:83]
	v_mfma_f32_16x16x32_bf16 v[68:71], v[214:217], v[206:209], v[68:71]
	v_mfma_f32_16x16x32_bf16 v[64:67], v[222:225], v[206:209], v[64:67]
	v_mfma_f32_16x16x32_bf16 v[116:119], v[218:221], v[184:187], v[116:119]
	v_mfma_f32_16x16x32_bf16 v[112:115], v[226:229], v[184:187], v[112:115]
	v_mfma_f32_16x16x32_bf16 v[100:103], v[218:221], v[192:195], v[100:103]
	v_mfma_f32_16x16x32_bf16 v[96:99], v[226:229], v[192:195], v[96:99]
	v_mfma_f32_16x16x32_bf16 v[84:87], v[218:221], v[200:203], v[84:87]
	v_mfma_f32_16x16x32_bf16 v[80:83], v[226:229], v[200:203], v[80:83]
	v_mfma_f32_16x16x32_bf16 v[68:71], v[218:221], v[210:213], v[68:71]
	v_mfma_f32_16x16x32_bf16 v[64:67], v[226:229], v[210:213], v[64:67]
	s_nop 0
	s_mov_b32 m0, s46
	v_lshl_add_u64 v[156:157], s[44:45], 0, v[128:129]
	s_barrier
	ds_read_b128 v[180:183], v159 offset:16384
	ds_read_b128 v[184:187], v159 offset:17408
	ds_read_b128 v[188:191], v159 offset:18432
	ds_read_b128 v[192:195], v159 offset:19456
	ds_read_b128 v[196:199], v159 offset:20480
	ds_read_b128 v[200:203], v159 offset:21504
	ds_read_b128 v[206:209], v159 offset:22528
	ds_read_b128 v[210:213], v159 offset:23552
	global_load_lds_dwordx4 v[156:157], off
	v_lshl_add_u64 v[160:161], s[44:45], 0, v[132:133]
	s_mov_b32 m0, s47
	s_nop 0
	global_load_lds_dwordx4 v[160:161], off
	s_barrier
	s_waitcnt lgkmcnt(0)
	s_nop 0
	s_waitcnt lgkmcnt(0)
	v_mfma_f32_16x16x32_bf16 v[60:63], v[164:167], v[180:183], v[60:63]
	v_mfma_f32_16x16x32_bf16 v[56:59], v[172:175], v[180:183], v[56:59]
	v_mfma_f32_16x16x32_bf16 v[44:47], v[164:167], v[188:191], v[44:47]
	v_mfma_f32_16x16x32_bf16 v[40:43], v[172:175], v[188:191], v[40:43]
	v_mfma_f32_16x16x32_bf16 v[28:31], v[164:167], v[196:199], v[28:31]
	v_mfma_f32_16x16x32_bf16 v[24:27], v[172:175], v[196:199], v[24:27]
	v_mfma_f32_16x16x32_bf16 v[12:15], v[164:167], v[206:209], v[12:15]
	v_mfma_f32_16x16x32_bf16 v[8:11], v[172:175], v[206:209], v[8:11]
	v_mfma_f32_16x16x32_bf16 v[60:63], v[168:171], v[184:187], v[60:63]
	v_mfma_f32_16x16x32_bf16 v[56:59], v[176:179], v[184:187], v[56:59]
	v_mfma_f32_16x16x32_bf16 v[44:47], v[168:171], v[192:195], v[44:47]
	v_mfma_f32_16x16x32_bf16 v[40:43], v[176:179], v[192:195], v[40:43]
	v_mfma_f32_16x16x32_bf16 v[28:31], v[168:171], v[200:203], v[28:31]
	v_mfma_f32_16x16x32_bf16 v[24:27], v[176:179], v[200:203], v[24:27]
	v_mfma_f32_16x16x32_bf16 v[12:15], v[168:171], v[210:213], v[12:15]
	v_mfma_f32_16x16x32_bf16 v[8:11], v[176:179], v[210:213], v[8:11]
	s_nop 0
	s_barrier
	s_add_u32 s68, s42, 0x40000
	s_addc_u32 s69, s43, 0
	s_add_i32 s67, s56, s33
	v_lshl_add_u64 v[164:165], s[68:69], 0, v[130:131]
	s_mov_b32 m0, s67
	s_nop 0
	global_load_lds_dwordx4 v[164:165], off
	v_lshl_add_u64 v[164:165], s[68:69], 0, v[134:135]
	s_add_i32 m0, s67, 0x2000
	s_nop 0
	global_load_lds_dwordx4 v[164:165], off
	s_waitcnt vmcnt(6)
	s_cmp_gt_u32 s66, 10
	s_cbranch_scc1 .Lds_P16_a_done
	s_cmp_lt_u32 s66, 6
	s_cbranch_scc1 .Lds_P16_a_st
	s_cmp_eq_u32 s66, 6
	s_cbranch_scc1 .Lds_P16_a_pf
	s_cmp_eq_u32 s66, 8
	s_cbranch_scc1 .Lds_P16_a_c8
	v_ffbh_u32_e32 v252, v241
	v_min_u32_e32 v252, 32, v252
	v_lshlrev_b64 v[240:241], v252, v[240:241]
	v_min_u32_e32 v240, 1, v240
	v_or_b32_e32 v241, v241, v240
	v_cvt_f32_u32_e32 v241, v241
	v_sub_u32_e32 v252, -2, v252
	v_ldexp_f32 v241, v241, v252
	v_add_f32_e32 v241, 0x358637bd, v241
	v_rsq_f32_e32 v252, v241
	v_ffbh_u32_e32 v253, v243
	v_min_u32_e32 v253, 32, v253
	v_lshlrev_b64 v[242:243], v253, v[242:243]
	v_min_u32_e32 v242, 1, v242
	v_or_b32_e32 v243, v243, v242
	v_cvt_f32_u32_e32 v243, v243
	v_sub_u32_e32 v253, -2, v253
	v_ldexp_f32 v243, v243, v253
	v_add_f32_e32 v243, 0x358637bd, v243
	v_rsq_f32_e32 v253, v243
	s_branch .Lds_P16_a_done

.Lds_P16_a_done:
	s_barrier
	s_nop 0
	v_mfma_f32_16x16x32_bf16 v[52:55], v[214:217], v[180:183], v[52:55]
	v_mfma_f32_16x16x32_bf16 v[48:51], v[222:225], v[180:183], v[48:51]
	v_mfma_f32_16x16x32_bf16 v[36:39], v[214:217], v[188:191], v[36:39]
	v_mfma_f32_16x16x32_bf16 v[32:35], v[222:225], v[188:191], v[32:35]
	v_mfma_f32_16x16x32_bf16 v[20:23], v[214:217], v[196:199], v[20:23]
	v_mfma_f32_16x16x32_bf16 v[16:19], v[222:225], v[196:199], v[16:19]
	v_mfma_f32_16x16x32_bf16 v[4:7], v[214:217], v[206:209], v[4:7]
	v_mfma_f32_16x16x32_bf16 v[0:3], v[222:225], v[206:209], v[0:3]
	v_mfma_f32_16x16x32_bf16 v[52:55], v[218:221], v[184:187], v[52:55]
	v_mfma_f32_16x16x32_bf16 v[48:51], v[226:229], v[184:187], v[48:51]
	v_mfma_f32_16x16x32_bf16 v[36:39], v[218:221], v[192:195], v[36:39]
	v_mfma_f32_16x16x32_bf16 v[32:35], v[226:229], v[192:195], v[32:35]
	v_mfma_f32_16x16x32_bf16 v[20:23], v[218:221], v[200:203], v[20:23]
	v_mfma_f32_16x16x32_bf16 v[16:19], v[226:229], v[200:203], v[16:19]
	v_mfma_f32_16x16x32_bf16 v[4:7], v[218:221], v[210:213], v[4:7]
	v_mfma_f32_16x16x32_bf16 v[0:3], v[226:229], v[210:213], v[0:3]
	s_nop 0
	s_add_i32 s67, 0, 0x18000
	v_add_u32_e32 v144, s67, v149
	s_barrier
	ds_read_b128 v[164:167], v144
	ds_read_b128 v[168:171], v144 offset:1024
	ds_read_b128 v[172:175], v144 offset:2048
	ds_read_b128 v[176:179], v144 offset:3072
	s_add_u32 s44, s44, 0x40000
	s_addc_u32 s45, s45, 0
	s_mov_b32 m0, s48
	v_lshl_add_u64 v[214:215], s[44:45], 0, v[128:129]
	ds_read_b128 v[180:183], v159 offset:32768
	ds_read_b128 v[184:187], v159 offset:33792
	ds_read_b128 v[188:191], v159 offset:34816
	ds_read_b128 v[192:195], v159 offset:35840
	ds_read_b128 v[196:199], v159 offset:36864
	ds_read_b128 v[200:203], v159 offset:37888
	ds_read_b128 v[206:209], v159 offset:38912
	ds_read_b128 v[210:213], v159 offset:39936
	global_load_lds_dwordx4 v[214:215], off
	v_lshl_add_u64 v[214:215], s[44:45], 0, v[132:133]
	s_mov_b32 m0, s49
	s_nop 0
	global_load_lds_dwordx4 v[214:215], off
	s_waitcnt lgkmcnt(8)
	s_barrier
	s_waitcnt lgkmcnt(0)
	s_nop 0
	s_waitcnt lgkmcnt(0)
	v_mfma_f32_16x16x32_bf16 v[124:127], v[164:167], v[180:183], v[124:127]
	v_mfma_f32_16x16x32_bf16 v[120:123], v[172:175], v[180:183], v[120:123]
	v_mfma_f32_16x16x32_bf16 v[108:111], v[164:167], v[188:191], v[108:111]
	v_mfma_f32_16x16x32_bf16 v[104:107], v[172:175], v[188:191], v[104:107]
	v_mfma_f32_16x16x32_bf16 v[92:95], v[164:167], v[196:199], v[92:95]
	v_mfma_f32_16x16x32_bf16 v[88:91], v[172:175], v[196:199], v[88:91]
	v_mfma_f32_16x16x32_bf16 v[76:79], v[164:167], v[206:209], v[76:79]
	v_mfma_f32_16x16x32_bf16 v[72:75], v[172:175], v[206:209], v[72:75]
	v_mfma_f32_16x16x32_bf16 v[124:127], v[168:171], v[184:187], v[124:127]
	v_mfma_f32_16x16x32_bf16 v[120:123], v[176:179], v[184:187], v[120:123]
	v_mfma_f32_16x16x32_bf16 v[108:111], v[168:171], v[192:195], v[108:111]
	v_mfma_f32_16x16x32_bf16 v[104:107], v[176:179], v[192:195], v[104:107]
	v_mfma_f32_16x16x32_bf16 v[92:95], v[168:171], v[200:203], v[92:95]
	v_mfma_f32_16x16x32_bf16 v[88:91], v[176:179], v[200:203], v[88:91]
	v_mfma_f32_16x16x32_bf16 v[76:79], v[168:171], v[210:213], v[76:79]
	v_mfma_f32_16x16x32_bf16 v[72:75], v[176:179], v[210:213], v[72:75]
	s_nop 0
	s_barrier
	s_add_i32 s44, 0, 0x1c000
	s_add_i32 s45, s67, s33
	v_add_u32_e32 v144, s44, v149
	v_lshl_add_u64 v[146:147], v[146:147], 0, s[18:19]
	s_mov_b32 m0, s45
	ds_read_b128 v[214:217], v144
	ds_read_b128 v[218:221], v144 offset:1024
	ds_read_b128 v[222:225], v144 offset:2048
	ds_read_b128 v[226:229], v144 offset:3072
	global_load_lds_dwordx4 v[146:147], off
	v_lshl_add_u64 v[146:147], v[152:153], 0, s[18:19]
	s_add_i32 m0, s45, 0x2000
	s_nop 0
	global_load_lds_dwordx4 v[146:147], off
	s_barrier
	s_waitcnt lgkmcnt(0)
	s_nop 0
	s_waitcnt lgkmcnt(0)
	v_mfma_f32_16x16x32_bf16 v[116:119], v[214:217], v[180:183], v[116:119]
	v_mfma_f32_16x16x32_bf16 v[112:115], v[222:225], v[180:183], v[112:115]
	v_mfma_f32_16x16x32_bf16 v[100:103], v[214:217], v[188:191], v[100:103]
	v_mfma_f32_16x16x32_bf16 v[96:99], v[222:225], v[188:191], v[96:99]
	v_mfma_f32_16x16x32_bf16 v[84:87], v[214:217], v[196:199], v[84:87]
	v_mfma_f32_16x16x32_bf16 v[80:83], v[222:225], v[196:199], v[80:83]
	v_mfma_f32_16x16x32_bf16 v[68:71], v[214:217], v[206:209], v[68:71]
	v_mfma_f32_16x16x32_bf16 v[64:67], v[222:225], v[206:209], v[64:67]
	v_mfma_f32_16x16x32_bf16 v[116:119], v[218:221], v[184:187], v[116:119]
	v_mfma_f32_16x16x32_bf16 v[112:115], v[226:229], v[184:187], v[112:115]
	v_mfma_f32_16x16x32_bf16 v[100:103], v[218:221], v[192:195], v[100:103]
	v_mfma_f32_16x16x32_bf16 v[96:99], v[226:229], v[192:195], v[96:99]
	v_mfma_f32_16x16x32_bf16 v[84:87], v[218:221], v[200:203], v[84:87]
	v_mfma_f32_16x16x32_bf16 v[80:83], v[226:229], v[200:203], v[80:83]
	v_mfma_f32_16x16x32_bf16 v[68:71], v[218:221], v[210:213], v[68:71]
	v_mfma_f32_16x16x32_bf16 v[64:67], v[226:229], v[210:213], v[64:67]
	s_nop 0
	s_mov_b32 m0, s51
	v_lshl_add_u64 v[146:147], v[156:157], 0, s[18:19]
	s_barrier
	ds_read_b128 v[180:183], v159 offset:49152
	ds_read_b128 v[184:187], v159 offset:50176
	ds_read_b128 v[188:191], v159 offset:51200
	ds_read_b128 v[192:195], v159 offset:52224
	ds_read_b128 v[196:199], v159 offset:53248
	ds_read_b128 v[200:203], v159 offset:54272
	ds_read_b128 v[206:209], v159 offset:55296
	ds_read_b128 v[210:213], v159 offset:56320
	global_load_lds_dwordx4 v[146:147], off
	v_lshl_add_u64 v[146:147], v[160:161], 0, s[18:19]
	s_mov_b32 m0, s52
	s_nop 0
	global_load_lds_dwordx4 v[146:147], off
	s_barrier
	s_waitcnt lgkmcnt(0)
	s_nop 0
	s_waitcnt lgkmcnt(0)
	v_mfma_f32_16x16x32_bf16 v[60:63], v[164:167], v[180:183], v[60:63]
	v_mfma_f32_16x16x32_bf16 v[56:59], v[172:175], v[180:183], v[56:59]
	v_mfma_f32_16x16x32_bf16 v[44:47], v[164:167], v[188:191], v[44:47]
	v_mfma_f32_16x16x32_bf16 v[40:43], v[172:175], v[188:191], v[40:43]
	v_mfma_f32_16x16x32_bf16 v[28:31], v[164:167], v[196:199], v[28:31]
	v_mfma_f32_16x16x32_bf16 v[24:27], v[172:175], v[196:199], v[24:27]
	v_mfma_f32_16x16x32_bf16 v[12:15], v[164:167], v[206:209], v[12:15]
	v_mfma_f32_16x16x32_bf16 v[8:11], v[172:175], v[206:209], v[8:11]
	v_mfma_f32_16x16x32_bf16 v[60:63], v[168:171], v[184:187], v[60:63]
	v_mfma_f32_16x16x32_bf16 v[56:59], v[176:179], v[184:187], v[56:59]
	v_mfma_f32_16x16x32_bf16 v[44:47], v[168:171], v[192:195], v[44:47]
	v_mfma_f32_16x16x32_bf16 v[40:43], v[176:179], v[192:195], v[40:43]
	v_mfma_f32_16x16x32_bf16 v[28:31], v[168:171], v[200:203], v[28:31]
	v_mfma_f32_16x16x32_bf16 v[24:27], v[176:179], v[200:203], v[24:27]
	v_mfma_f32_16x16x32_bf16 v[12:15], v[168:171], v[210:213], v[12:15]
	v_mfma_f32_16x16x32_bf16 v[8:11], v[176:179], v[210:213], v[8:11]
	s_nop 0
	s_barrier
	s_add_u32 s42, s42, 0x40080
	s_addc_u32 s43, s43, 0
	s_add_i32 s44, s44, s33
	v_lshl_add_u64 v[146:147], s[42:43], 0, v[130:131]
	s_mov_b32 m0, s44
	s_nop 0
	global_load_lds_dwordx4 v[146:147], off
	v_lshl_add_u64 v[146:147], s[42:43], 0, v[134:135]
	s_add_i32 m0, s44, 0x2000
	s_nop 0
	global_load_lds_dwordx4 v[146:147], off
	s_waitcnt vmcnt(6)
	s_cmp_gt_u32 s66, 10
	s_cbranch_scc1 .Lds_P16_b_done
	s_cmp_lt_u32 s66, 6
	s_cbranch_scc1 .Lds_P16_b_st
	s_cmp_eq_u32 s66, 6
	s_cbranch_scc1 .Lds_P16_b_l6
	s_cmp_eq_u32 s66, 8
	s_cbranch_scc1 .Lds_P16_b_c8
	v_ffbh_u32_e32 v254, v245
	v_min_u32_e32 v254, 32, v254
	v_lshlrev_b64 v[244:245], v254, v[244:245]
	v_min_u32_e32 v244, 1, v244
	v_or_b32_e32 v245, v245, v244
	v_cvt_f32_u32_e32 v245, v245
	v_sub_u32_e32 v254, -2, v254
	v_ldexp_f32 v245, v245, v254
	v_add_f32_e32 v245, 0x358637bd, v245
	v_rsq_f32_e32 v254, v245
	v_ffbh_u32_e32 v255, v247
	v_min_u32_e32 v255, 32, v255
	v_lshlrev_b64 v[246:247], v255, v[246:247]
	v_min_u32_e32 v246, 1, v246
	v_or_b32_e32 v247, v247, v246
	v_cvt_f32_u32_e32 v247, v247
	v_sub_u32_e32 v255, -2, v255
	v_ldexp_f32 v247, v247, v255
	v_add_f32_e32 v247, 0x358637bd, v247
	v_rsq_f32_e32 v255, v247
	s_branch .Lds_P16_b_done

.Lds_P16_b_done:
	s_barrier
	s_nop 0
	v_mfma_f32_16x16x32_bf16 v[52:55], v[214:217], v[180:183], v[52:55]
	v_mfma_f32_16x16x32_bf16 v[48:51], v[222:225], v[180:183], v[48:51]
	v_mfma_f32_16x16x32_bf16 v[36:39], v[214:217], v[188:191], v[36:39]
	v_mfma_f32_16x16x32_bf16 v[32:35], v[222:225], v[188:191], v[32:35]
	v_mfma_f32_16x16x32_bf16 v[20:23], v[214:217], v[196:199], v[20:23]
	v_mfma_f32_16x16x32_bf16 v[16:19], v[222:225], v[196:199], v[16:19]
	v_mfma_f32_16x16x32_bf16 v[4:7], v[214:217], v[206:209], v[4:7]
	v_mfma_f32_16x16x32_bf16 v[0:3], v[222:225], v[206:209], v[0:3]
	v_mfma_f32_16x16x32_bf16 v[52:55], v[218:221], v[184:187], v[52:55]
	v_mfma_f32_16x16x32_bf16 v[48:51], v[226:229], v[184:187], v[48:51]
	v_mfma_f32_16x16x32_bf16 v[36:39], v[218:221], v[192:195], v[36:39]
	v_mfma_f32_16x16x32_bf16 v[32:35], v[226:229], v[192:195], v[32:35]
	v_mfma_f32_16x16x32_bf16 v[20:23], v[218:221], v[200:203], v[20:23]
	v_mfma_f32_16x16x32_bf16 v[16:19], v[226:229], v[200:203], v[16:19]
	v_mfma_f32_16x16x32_bf16 v[4:7], v[218:221], v[210:213], v[4:7]
	v_mfma_f32_16x16x32_bf16 v[0:3], v[226:229], v[210:213], v[0:3]
	s_nop 0
	s_add_i32 s66, s66, 2
	s_add_u32 s10, s10, 0x100
	s_addc_u32 s11, s11, 0
	s_add_u32 s64, s64, 0x100
	s_addc_u32 s65, s65, 0
	s_cmp_gt_u32 s66, 13
	s_barrier
	s_cbranch_scc0 .LBB0_1981

.LBB0_2038:
	s_or_b64 exec, exec, s[6:7]
	s_mov_b64 s[0:1], s[70:71]
	s_waitcnt lgkmcnt(0)
	s_barrier
	v_readfirstlane_b32 s101, v204
	s_nop 3
	s_lshr_b32 s101, s101, 6
	s_cmp_ge_u32 s101, 4
	s_cbranch_scc0 .Lprio_7
	s_setprio 1
.Lprio_7:
	s_load_dwordx2 s[8:9], s[0:1], 0xb8
	v_mov_b32_e32 v8, v204
	s_and_b64 vcc, exec, s[4:5]
	v_readfirstlane_b32 s0, v8
	s_cbranch_vccnz .LBB0_2044
	s_ashr_i32 s1, s97, 31
	s_lshr_b32 s1, s1, 29
	s_add_i32 s3, s97, s1
	s_and_b32 s1, s3, -8
	s_sub_i32 s1, s97, s1
	s_cmp_gt_i32 s1, -1
	s_cbranch_scc0 .LBB0_2041
	s_lshl_b32 s2, s1, 6
	s_ashr_i32 s3, s3, 3
	s_cbranch_execz .LBB0_2042
	s_branch .LBB0_2043

.LBB0_2055:
	s_ashr_i32 s19, s18, 31
	v_cmp_lt_i64_e32 vcc, s[24:25], v[164:165]
	s_lshl_b64 s[24:25], s[18:19], 21
	s_add_u32 s24, s1, s24
	s_addc_u32 s25, s2, s25
	s_and_b64 s[26:27], vcc, exec
	s_cselect_b32 s19, s25, s35
	s_cselect_b32 s29, s24, s34
	s_ashr_i32 s17, s16, 31
	s_lshl_b64 s[26:27], s[16:17], 21
	s_add_u32 s26, s3, s26
	s_addc_u32 s27, s20, s27
	s_and_b64 s[38:39], vcc, exec
	s_cselect_b32 s17, s27, s37
	s_cselect_b32 s50, s26, s36
	s_add_u32 s34, s34, 0x100080
	s_addc_u32 s35, s35, 0
	s_add_u32 s51, s36, 0x100

	s_addc_u32 s52, s37, 0
	s_mov_b32 s53, -2
	s_waitcnt lgkmcnt(0)


	ds_read_b128 v[128:131], v189
	ds_read_b128 v[132:135], v189 offset:1024
	ds_read_b128 v[136:139], v189 offset:2048
	ds_read_b128 v[140:143], v189 offset:3072
	s_add_u32 s36, s34, 0xfff00080
	s_addc_u32 s37, s35, -1
	s_cmp_eq_u32 s53, 60
	s_cselect_b32 s39, s19, s37
	s_cselect_b32 s38, s29, s36
	s_cselect_b32 s37, s17, s52
	s_cselect_b32 s36, s50, s51
	v_lshl_add_u64 v[184:185], s[34:35], 0, v[160:161]
	s_add_i32 m0, s31, 0xc000
	ds_read_b128 v[144:147], v190
	ds_read_b128 v[148:151], v190 offset:1024
	ds_read_b128 v[168:171], v190 offset:2048
	ds_read_b128 v[172:175], v190 offset:3072
	ds_read_b128 v[176:179], v190 offset:4096
	ds_read_b128 v[180:183], v190 offset:5120
	ds_read_b128 v[192:195], v190 offset:6144
	ds_read_b128 v[196:199], v190 offset:7168
	global_load_lds_dwordx4 v[184:185], off
	v_lshl_add_u64 v[184:185], s[34:35], 0, v[162:163]
	s_add_i32 m0, s31, 0xe000
	s_nop 0
	global_load_lds_dwordx4 v[184:185], off
	s_waitcnt lgkmcnt(8)
	s_barrier
	s_waitcnt lgkmcnt(0)
	s_nop 0
	s_waitcnt lgkmcnt(0)
	v_mfma_f32_16x16x32_bf16 v[124:127], v[128:131], v[144:147], 0
	v_mfma_f32_16x16x32_bf16 v[120:123], v[136:139], v[144:147], 0
	v_mfma_f32_16x16x32_bf16 v[108:111], v[128:131], v[168:171], 0
	v_mfma_f32_16x16x32_bf16 v[104:107], v[136:139], v[168:171], 0
	v_mfma_f32_16x16x32_bf16 v[92:95], v[128:131], v[176:179], 0
	v_mfma_f32_16x16x32_bf16 v[88:91], v[136:139], v[176:179], 0
	v_mfma_f32_16x16x32_bf16 v[76:79], v[128:131], v[192:195], 0
	v_mfma_f32_16x16x32_bf16 v[72:75], v[136:139], v[192:195], 0
	v_mfma_f32_16x16x32_bf16 v[124:127], v[132:135], v[148:151], v[124:127]
	v_mfma_f32_16x16x32_bf16 v[120:123], v[140:143], v[148:151], v[120:123]
	v_mfma_f32_16x16x32_bf16 v[108:111], v[132:135], v[172:175], v[108:111]
	v_mfma_f32_16x16x32_bf16 v[104:107], v[140:143], v[172:175], v[104:107]
	v_mfma_f32_16x16x32_bf16 v[92:95], v[132:135], v[180:183], v[92:95]
	v_mfma_f32_16x16x32_bf16 v[88:91], v[140:143], v[180:183], v[88:91]
	v_mfma_f32_16x16x32_bf16 v[76:79], v[132:135], v[196:199], v[76:79]
	v_mfma_f32_16x16x32_bf16 v[72:75], v[140:143], v[196:199], v[72:75]
	s_nop 0
	s_barrier
	s_add_i32 s54, s48, s21
	v_lshl_add_u64 v[184:185], s[36:37], 0, v[154:155]
	s_mov_b32 m0, s54
	ds_read_b128 v[200:203], v191
	ds_read_b128 v[206:209], v191 offset:1024
	ds_read_b128 v[210:213], v191 offset:2048
	ds_read_b128 v[214:217], v191 offset:3072
	global_load_lds_dwordx4 v[184:185], off
	v_lshl_add_u64 v[218:219], s[36:37], 0, v[158:159]
	s_add_i32 m0, s54, 0x2000
	s_nop 0
	global_load_lds_dwordx4 v[218:219], off
	s_barrier
	s_waitcnt lgkmcnt(0)
	s_nop 0
	s_waitcnt lgkmcnt(0)
	v_mfma_f32_16x16x32_bf16 v[116:119], v[200:203], v[144:147], 0
	v_mfma_f32_16x16x32_bf16 v[112:115], v[210:213], v[144:147], 0
	v_mfma_f32_16x16x32_bf16 v[100:103], v[200:203], v[168:171], 0
	v_mfma_f32_16x16x32_bf16 v[96:99], v[210:213], v[168:171], 0
	v_mfma_f32_16x16x32_bf16 v[84:87], v[200:203], v[176:179], 0
	v_mfma_f32_16x16x32_bf16 v[80:83], v[210:213], v[176:179], 0
	v_mfma_f32_16x16x32_bf16 v[68:71], v[200:203], v[192:195], 0
	v_mfma_f32_16x16x32_bf16 v[64:67], v[210:213], v[192:195], 0
	v_mfma_f32_16x16x32_bf16 v[116:119], v[206:209], v[148:151], v[116:119]
	v_mfma_f32_16x16x32_bf16 v[112:115], v[214:217], v[148:151], v[112:115]
	v_mfma_f32_16x16x32_bf16 v[100:103], v[206:209], v[172:175], v[100:103]
	v_mfma_f32_16x16x32_bf16 v[96:99], v[214:217], v[172:175], v[96:99]
	v_mfma_f32_16x16x32_bf16 v[84:87], v[206:209], v[180:183], v[84:87]
	v_mfma_f32_16x16x32_bf16 v[80:83], v[214:217], v[180:183], v[80:83]
	v_mfma_f32_16x16x32_bf16 v[68:71], v[206:209], v[196:199], v[68:71]
	v_mfma_f32_16x16x32_bf16 v[64:67], v[214:217], v[196:199], v[64:67]
	s_nop 0
	s_mov_b32 m0, s31
	v_lshl_add_u64 v[220:221], s[38:39], 0, v[152:153]
	s_barrier
	ds_read_b128 v[144:147], v190 offset:16384
	ds_read_b128 v[148:151], v190 offset:17408
	ds_read_b128 v[168:171], v190 offset:18432
	ds_read_b128 v[172:175], v190 offset:19456
	ds_read_b128 v[176:179], v190 offset:20480
	ds_read_b128 v[180:183], v190 offset:21504
	ds_read_b128 v[192:195], v190 offset:22528
	ds_read_b128 v[196:199], v190 offset:23552
	global_load_lds_dwordx4 v[220:221], off
	v_lshl_add_u64 v[222:223], s[38:39], 0, v[156:157]
	s_mov_b32 m0, s33
	s_nop 0
	global_load_lds_dwordx4 v[222:223], off
	s_barrier
	s_waitcnt lgkmcnt(0)
	s_nop 0
	s_waitcnt lgkmcnt(0)
	v_mfma_f32_16x16x32_bf16 v[60:63], v[128:131], v[144:147], 0
	v_mfma_f32_16x16x32_bf16 v[56:59], v[136:139], v[144:147], 0
	v_mfma_f32_16x16x32_bf16 v[44:47], v[128:131], v[168:171], 0
	v_mfma_f32_16x16x32_bf16 v[40:43], v[136:139], v[168:171], 0
	v_mfma_f32_16x16x32_bf16 v[28:31], v[128:131], v[176:179], 0
	v_mfma_f32_16x16x32_bf16 v[24:27], v[136:139], v[176:179], 0
	v_mfma_f32_16x16x32_bf16 v[12:15], v[128:131], v[192:195], 0
	v_mfma_f32_16x16x32_bf16 v[8:11], v[136:139], v[192:195], 0
	v_mfma_f32_16x16x32_bf16 v[60:63], v[132:135], v[148:151], v[60:63]
	v_mfma_f32_16x16x32_bf16 v[56:59], v[140:143], v[148:151], v[56:59]
	v_mfma_f32_16x16x32_bf16 v[44:47], v[132:135], v[172:175], v[44:47]
	v_mfma_f32_16x16x32_bf16 v[40:43], v[140:143], v[172:175], v[40:43]
	v_mfma_f32_16x16x32_bf16 v[28:31], v[132:135], v[180:183], v[28:31]
	v_mfma_f32_16x16x32_bf16 v[24:27], v[140:143], v[180:183], v[24:27]
	v_mfma_f32_16x16x32_bf16 v[12:15], v[132:135], v[196:199], v[12:15]
	v_mfma_f32_16x16x32_bf16 v[8:11], v[140:143], v[196:199], v[8:11]
	s_nop 0
	s_barrier
	s_add_u32 s54, s36, 0x100000
	s_addc_u32 s55, s37, 0
	s_add_i32 s56, s49, s21
	v_lshl_add_u64 v[128:129], s[54:55], 0, v[154:155]
	s_mov_b32 m0, s56
	s_nop 0
	global_load_lds_dwordx4 v[128:129], off
	v_lshl_add_u64 v[128:129], s[54:55], 0, v[158:159]
	s_add_i32 m0, s56, 0x2000
	s_nop 0
	global_load_lds_dwordx4 v[128:129], off
	s_waitcnt vmcnt(6)
	s_barrier
	s_nop 0
	v_mfma_f32_16x16x32_bf16 v[52:55], v[200:203], v[144:147], 0
	v_mfma_f32_16x16x32_bf16 v[48:51], v[210:213], v[144:147], 0
	v_mfma_f32_16x16x32_bf16 v[36:39], v[200:203], v[168:171], 0
	v_mfma_f32_16x16x32_bf16 v[32:35], v[210:213], v[168:171], 0
	v_mfma_f32_16x16x32_bf16 v[20:23], v[200:203], v[176:179], 0
	v_mfma_f32_16x16x32_bf16 v[16:19], v[210:213], v[176:179], 0
	v_mfma_f32_16x16x32_bf16 v[4:7], v[200:203], v[192:195], 0
	v_mfma_f32_16x16x32_bf16 v[0:3], v[210:213], v[192:195], 0
	v_mfma_f32_16x16x32_bf16 v[52:55], v[206:209], v[148:151], v[52:55]
	v_mfma_f32_16x16x32_bf16 v[48:51], v[214:217], v[148:151], v[48:51]
	v_mfma_f32_16x16x32_bf16 v[36:39], v[206:209], v[172:175], v[36:39]
	v_mfma_f32_16x16x32_bf16 v[32:35], v[214:217], v[172:175], v[32:35]
	v_mfma_f32_16x16x32_bf16 v[20:23], v[206:209], v[180:183], v[20:23]
	v_mfma_f32_16x16x32_bf16 v[16:19], v[214:217], v[180:183], v[16:19]
	v_mfma_f32_16x16x32_bf16 v[4:7], v[206:209], v[196:199], v[4:7]
	v_mfma_f32_16x16x32_bf16 v[0:3], v[214:217], v[196:199], v[0:3]
	s_nop 0
	s_add_i32 s54, 0, 0x18000
	v_add_u32_e32 v140, s54, v187
	s_barrier
	ds_read_b128 v[128:131], v140
	ds_read_b128 v[132:135], v140 offset:1024
	ds_read_b128 v[136:139], v140 offset:2048
	ds_read_b128 v[140:143], v140 offset:3072
	s_add_u32 s38, s38, 0x100000
	s_addc_u32 s39, s39, 0
	s_mov_b32 m0, s40
	v_lshl_add_u64 v[200:201], s[38:39], 0, v[152:153]
	ds_read_b128 v[144:147], v190 offset:32768
	ds_read_b128 v[148:151], v190 offset:33792
	ds_read_b128 v[168:171], v190 offset:34816
	ds_read_b128 v[172:175], v190 offset:35840
	ds_read_b128 v[176:179], v190 offset:36864
	ds_read_b128 v[180:183], v190 offset:37888
	ds_read_b128 v[192:195], v190 offset:38912
	ds_read_b128 v[196:199], v190 offset:39936
	global_load_lds_dwordx4 v[200:201], off
	v_lshl_add_u64 v[200:201], s[38:39], 0, v[156:157]
	s_mov_b32 m0, s41
	s_nop 0
	global_load_lds_dwordx4 v[200:201], off
	s_waitcnt lgkmcnt(8)
	s_barrier
	s_waitcnt lgkmcnt(0)
	s_nop 0
	s_waitcnt lgkmcnt(0)
	v_mfma_f32_16x16x32_bf16 v[124:127], v[128:131], v[144:147], v[124:127]
	v_mfma_f32_16x16x32_bf16 v[120:123], v[136:139], v[144:147], v[120:123]
	v_mfma_f32_16x16x32_bf16 v[108:111], v[128:131], v[168:171], v[108:111]
	v_mfma_f32_16x16x32_bf16 v[104:107], v[136:139], v[168:171], v[104:107]
	v_mfma_f32_16x16x32_bf16 v[92:95], v[128:131], v[176:179], v[92:95]
	v_mfma_f32_16x16x32_bf16 v[88:91], v[136:139], v[176:179], v[88:91]
	v_mfma_f32_16x16x32_bf16 v[76:79], v[128:131], v[192:195], v[76:79]
	v_mfma_f32_16x16x32_bf16 v[72:75], v[136:139], v[192:195], v[72:75]
	v_mfma_f32_16x16x32_bf16 v[124:127], v[132:135], v[148:151], v[124:127]
	v_mfma_f32_16x16x32_bf16 v[120:123], v[140:143], v[148:151], v[120:123]
	v_mfma_f32_16x16x32_bf16 v[108:111], v[132:135], v[172:175], v[108:111]
	v_mfma_f32_16x16x32_bf16 v[104:107], v[140:143], v[172:175], v[104:107]
	v_mfma_f32_16x16x32_bf16 v[92:95], v[132:135], v[180:183], v[92:95]
	v_mfma_f32_16x16x32_bf16 v[88:91], v[140:143], v[180:183], v[88:91]
	v_mfma_f32_16x16x32_bf16 v[76:79], v[132:135], v[196:199], v[76:79]
	v_mfma_f32_16x16x32_bf16 v[72:75], v[140:143], v[196:199], v[72:75]
	s_nop 0
	s_barrier
	s_add_i32 s38, 0, 0x1c000
	s_add_i32 s39, s54, s21
	v_add_u32_e32 v214, s38, v187
	v_lshl_add_u64 v[184:185], v[184:185], 0, s[14:15]
	s_mov_b32 m0, s39
	ds_read_b128 v[200:203], v214
	ds_read_b128 v[206:209], v214 offset:1024
	ds_read_b128 v[210:213], v214 offset:2048
	ds_read_b128 v[214:217], v214 offset:3072
	global_load_lds_dwordx4 v[184:185], off
	v_lshl_add_u64 v[184:185], v[218:219], 0, s[14:15]
	s_add_i32 m0, s39, 0x2000
	s_nop 0
	global_load_lds_dwordx4 v[184:185], off
	s_barrier
	s_waitcnt lgkmcnt(0)
	s_nop 0
	s_waitcnt lgkmcnt(0)
	v_mfma_f32_16x16x32_bf16 v[116:119], v[200:203], v[144:147], v[116:119]
	v_mfma_f32_16x16x32_bf16 v[112:115], v[210:213], v[144:147], v[112:115]
	v_mfma_f32_16x16x32_bf16 v[100:103], v[200:203], v[168:171], v[100:103]
	v_mfma_f32_16x16x32_bf16 v[96:99], v[210:213], v[168:171], v[96:99]
	v_mfma_f32_16x16x32_bf16 v[84:87], v[200:203], v[176:179], v[84:87]
	v_mfma_f32_16x16x32_bf16 v[80:83], v[210:213], v[176:179], v[80:83]
	v_mfma_f32_16x16x32_bf16 v[68:71], v[200:203], v[192:195], v[68:71]
	v_mfma_f32_16x16x32_bf16 v[64:67], v[210:213], v[192:195], v[64:67]
	v_mfma_f32_16x16x32_bf16 v[116:119], v[206:209], v[148:151], v[116:119]
	v_mfma_f32_16x16x32_bf16 v[112:115], v[214:217], v[148:151], v[112:115]
	v_mfma_f32_16x16x32_bf16 v[100:103], v[206:209], v[172:175], v[100:103]
	v_mfma_f32_16x16x32_bf16 v[96:99], v[214:217], v[172:175], v[96:99]
	v_mfma_f32_16x16x32_bf16 v[84:87], v[206:209], v[180:183], v[84:87]
	v_mfma_f32_16x16x32_bf16 v[80:83], v[214:217], v[180:183], v[80:83]
	v_mfma_f32_16x16x32_bf16 v[68:71], v[206:209], v[196:199], v[68:71]
	v_mfma_f32_16x16x32_bf16 v[64:67], v[214:217], v[196:199], v[64:67]
	s_nop 0
	s_mov_b32 m0, s43
	v_lshl_add_u64 v[184:185], v[220:221], 0, s[14:15]
	s_barrier
	ds_read_b128 v[144:147], v190 offset:49152
	ds_read_b128 v[148:151], v190 offset:50176
	ds_read_b128 v[168:171], v190 offset:51200
	ds_read_b128 v[172:175], v190 offset:52224
	ds_read_b128 v[176:179], v190 offset:53248
	ds_read_b128 v[180:183], v190 offset:54272
	ds_read_b128 v[192:195], v190 offset:55296
	ds_read_b128 v[196:199], v190 offset:56320
	global_load_lds_dwordx4 v[184:185], off
	v_lshl_add_u64 v[184:185], v[222:223], 0, s[14:15]
	s_mov_b32 m0, s44
	s_nop 0
	global_load_lds_dwordx4 v[184:185], off
	s_barrier
	s_waitcnt lgkmcnt(0)
	s_nop 0
	s_waitcnt lgkmcnt(0)
	v_mfma_f32_16x16x32_bf16 v[60:63], v[128:131], v[144:147], v[60:63]
	v_mfma_f32_16x16x32_bf16 v[56:59], v[136:139], v[144:147], v[56:59]
	v_mfma_f32_16x16x32_bf16 v[44:47], v[128:131], v[168:171], v[44:47]
	v_mfma_f32_16x16x32_bf16 v[40:43], v[136:139], v[168:171], v[40:43]
	v_mfma_f32_16x16x32_bf16 v[28:31], v[128:131], v[176:179], v[28:31]
	v_mfma_f32_16x16x32_bf16 v[24:27], v[136:139], v[176:179], v[24:27]
	v_mfma_f32_16x16x32_bf16 v[12:15], v[128:131], v[192:195], v[12:15]
	v_mfma_f32_16x16x32_bf16 v[8:11], v[136:139], v[192:195], v[8:11]
	v_mfma_f32_16x16x32_bf16 v[60:63], v[132:135], v[148:151], v[60:63]
	v_mfma_f32_16x16x32_bf16 v[56:59], v[140:143], v[148:151], v[56:59]
	v_mfma_f32_16x16x32_bf16 v[44:47], v[132:135], v[172:175], v[44:47]
	v_mfma_f32_16x16x32_bf16 v[40:43], v[140:143], v[172:175], v[40:43]
	v_mfma_f32_16x16x32_bf16 v[28:31], v[132:135], v[180:183], v[28:31]
	v_mfma_f32_16x16x32_bf16 v[24:27], v[140:143], v[180:183], v[24:27]
	v_mfma_f32_16x16x32_bf16 v[12:15], v[132:135], v[196:199], v[12:15]
	v_mfma_f32_16x16x32_bf16 v[8:11], v[140:143], v[196:199], v[8:11]
	s_nop 0
	s_barrier
	s_add_u32 s36, s36, 0x100080
	s_addc_u32 s37, s37, 0
	s_add_i32 s38, s38, s21
	v_lshl_add_u64 v[128:129], s[36:37], 0, v[154:155]
	s_mov_b32 m0, s38
	s_nop 0
	global_load_lds_dwordx4 v[128:129], off
	v_lshl_add_u64 v[128:129], s[36:37], 0, v[158:159]
	s_add_i32 m0, s38, 0x2000
	s_nop 0
	global_load_lds_dwordx4 v[128:129], off
	s_waitcnt vmcnt(6)
	s_barrier
	s_nop 0
	v_mfma_f32_16x16x32_bf16 v[52:55], v[200:203], v[144:147], v[52:55]
	v_mfma_f32_16x16x32_bf16 v[48:51], v[210:213], v[144:147], v[48:51]
	v_mfma_f32_16x16x32_bf16 v[36:39], v[200:203], v[168:171], v[36:39]
	v_mfma_f32_16x16x32_bf16 v[32:35], v[210:213], v[168:171], v[32:35]
	v_mfma_f32_16x16x32_bf16 v[20:23], v[200:203], v[176:179], v[20:23]
	v_mfma_f32_16x16x32_bf16 v[16:19], v[210:213], v[176:179], v[16:19]
	v_mfma_f32_16x16x32_bf16 v[4:7], v[200:203], v[192:195], v[4:7]
	v_mfma_f32_16x16x32_bf16 v[0:3], v[210:213], v[192:195], v[0:3]
	v_mfma_f32_16x16x32_bf16 v[52:55], v[206:209], v[148:151], v[52:55]
	v_mfma_f32_16x16x32_bf16 v[48:51], v[214:217], v[148:151], v[48:51]
	v_mfma_f32_16x16x32_bf16 v[36:39], v[206:209], v[172:175], v[36:39]
	v_mfma_f32_16x16x32_bf16 v[32:35], v[214:217], v[172:175], v[32:35]
	v_mfma_f32_16x16x32_bf16 v[20:23], v[206:209], v[180:183], v[20:23]
	v_mfma_f32_16x16x32_bf16 v[16:19], v[214:217], v[180:183], v[16:19]
	v_mfma_f32_16x16x32_bf16 v[4:7], v[206:209], v[196:199], v[4:7]
	v_mfma_f32_16x16x32_bf16 v[0:3], v[214:217], v[196:199], v[0:3]
	s_nop 0
	s_add_i32 s53, s53, 2
	s_add_u32 s34, s34, 0x100
	s_addc_u32 s35, s35, 0
	s_add_u32 s51, s51, 0x100
	s_addc_u32 s52, s52, 0
	s_cmp_gt_u32 s53, 61
	s_barrier
.LBB0_2056:
	ds_read_b128 v[128:131], v189
	ds_read_b128 v[132:135], v189 offset:1024
	ds_read_b128 v[136:139], v189 offset:2048
	ds_read_b128 v[140:143], v189 offset:3072
	s_add_u32 s36, s34, 0xfff00080
	s_addc_u32 s37, s35, -1
	s_cmp_eq_u32 s53, 60
	s_cselect_b32 s39, s19, s37
	s_cselect_b32 s38, s29, s36
	s_cselect_b32 s37, s17, s52
	s_cselect_b32 s36, s50, s51
	v_lshl_add_u64 v[184:185], s[34:35], 0, v[160:161]
	s_add_i32 m0, s31, 0xc000
	ds_read_b128 v[144:147], v190
	ds_read_b128 v[148:151], v190 offset:1024
	ds_read_b128 v[168:171], v190 offset:2048
	ds_read_b128 v[172:175], v190 offset:3072
	ds_read_b128 v[176:179], v190 offset:4096
	ds_read_b128 v[180:183], v190 offset:5120
	ds_read_b128 v[192:195], v190 offset:6144
	ds_read_b128 v[196:199], v190 offset:7168
	global_load_lds_dwordx4 v[184:185], off
	v_lshl_add_u64 v[184:185], s[34:35], 0, v[162:163]
	s_add_i32 m0, s31, 0xe000
	s_nop 0
	global_load_lds_dwordx4 v[184:185], off
	s_waitcnt lgkmcnt(8)
	s_barrier
	s_waitcnt lgkmcnt(0)
	s_nop 0
	s_waitcnt lgkmcnt(0)
	v_mfma_f32_16x16x32_bf16 v[124:127], v[128:131], v[144:147], v[124:127]
	v_mfma_f32_16x16x32_bf16 v[120:123], v[136:139], v[144:147], v[120:123]
	v_mfma_f32_16x16x32_bf16 v[108:111], v[128:131], v[168:171], v[108:111]
	v_mfma_f32_16x16x32_bf16 v[104:107], v[136:139], v[168:171], v[104:107]
	v_mfma_f32_16x16x32_bf16 v[92:95], v[128:131], v[176:179], v[92:95]
	v_mfma_f32_16x16x32_bf16 v[88:91], v[136:139], v[176:179], v[88:91]
	v_mfma_f32_16x16x32_bf16 v[76:79], v[128:131], v[192:195], v[76:79]
	v_mfma_f32_16x16x32_bf16 v[72:75], v[136:139], v[192:195], v[72:75]
	v_mfma_f32_16x16x32_bf16 v[124:127], v[132:135], v[148:151], v[124:127]
	v_mfma_f32_16x16x32_bf16 v[120:123], v[140:143], v[148:151], v[120:123]
	v_mfma_f32_16x16x32_bf16 v[108:111], v[132:135], v[172:175], v[108:111]
	v_mfma_f32_16x16x32_bf16 v[104:107], v[140:143], v[172:175], v[104:107]
	v_mfma_f32_16x16x32_bf16 v[92:95], v[132:135], v[180:183], v[92:95]
	v_mfma_f32_16x16x32_bf16 v[88:91], v[140:143], v[180:183], v[88:91]
	v_mfma_f32_16x16x32_bf16 v[76:79], v[132:135], v[196:199], v[76:79]
	v_mfma_f32_16x16x32_bf16 v[72:75], v[140:143], v[196:199], v[72:75]
	s_nop 0
	s_barrier
	s_add_i32 s54, s48, s21
	v_lshl_add_u64 v[184:185], s[36:37], 0, v[154:155]
	s_mov_b32 m0, s54
	ds_read_b128 v[200:203], v191
	ds_read_b128 v[206:209], v191 offset:1024
	ds_read_b128 v[210:213], v191 offset:2048
	ds_read_b128 v[214:217], v191 offset:3072
	global_load_lds_dwordx4 v[184:185], off
	v_lshl_add_u64 v[218:219], s[36:37], 0, v[158:159]
	s_add_i32 m0, s54, 0x2000
	s_nop 0
	global_load_lds_dwordx4 v[218:219], off
	s_barrier
	s_waitcnt lgkmcnt(0)
	s_nop 0
	s_waitcnt lgkmcnt(0)
	v_mfma_f32_16x16x32_bf16 v[116:119], v[200:203], v[144:147], v[116:119]
	v_mfma_f32_16x16x32_bf16 v[112:115], v[210:213], v[144:147], v[112:115]
	v_mfma_f32_16x16x32_bf16 v[100:103], v[200:203], v[168:171], v[100:103]
	v_mfma_f32_16x16x32_bf16 v[96:99], v[210:213], v[168:171], v[96:99]
	v_mfma_f32_16x16x32_bf16 v[84:87], v[200:203], v[176:179], v[84:87]
	v_mfma_f32_16x16x32_bf16 v[80:83], v[210:213], v[176:179], v[80:83]
	v_mfma_f32_16x16x32_bf16 v[68:71], v[200:203], v[192:195], v[68:71]
	v_mfma_f32_16x16x32_bf16 v[64:67], v[210:213], v[192:195], v[64:67]
	v_mfma_f32_16x16x32_bf16 v[116:119], v[206:209], v[148:151], v[116:119]
	v_mfma_f32_16x16x32_bf16 v[112:115], v[214:217], v[148:151], v[112:115]
	v_mfma_f32_16x16x32_bf16 v[100:103], v[206:209], v[172:175], v[100:103]
	v_mfma_f32_16x16x32_bf16 v[96:99], v[214:217], v[172:175], v[96:99]
	v_mfma_f32_16x16x32_bf16 v[84:87], v[206:209], v[180:183], v[84:87]
	v_mfma_f32_16x16x32_bf16 v[80:83], v[214:217], v[180:183], v[80:83]
	v_mfma_f32_16x16x32_bf16 v[68:71], v[206:209], v[196:199], v[68:71]
	v_mfma_f32_16x16x32_bf16 v[64:67], v[214:217], v[196:199], v[64:67]
	s_nop 0
	s_mov_b32 m0, s31
	v_lshl_add_u64 v[220:221], s[38:39], 0, v[152:153]
	s_barrier
	ds_read_b128 v[144:147], v190 offset:16384
	ds_read_b128 v[148:151], v190 offset:17408
	ds_read_b128 v[168:171], v190 offset:18432
	ds_read_b128 v[172:175], v190 offset:19456
	ds_read_b128 v[176:179], v190 offset:20480
	ds_read_b128 v[180:183], v190 offset:21504
	ds_read_b128 v[192:195], v190 offset:22528
	ds_read_b128 v[196:199], v190 offset:23552
	global_load_lds_dwordx4 v[220:221], off
	v_lshl_add_u64 v[222:223], s[38:39], 0, v[156:157]
	s_mov_b32 m0, s33
	s_nop 0
	global_load_lds_dwordx4 v[222:223], off
	s_barrier
	s_waitcnt lgkmcnt(0)
	s_nop 0
	s_waitcnt lgkmcnt(0)
	v_mfma_f32_16x16x32_bf16 v[60:63], v[128:131], v[144:147], v[60:63]
	v_mfma_f32_16x16x32_bf16 v[56:59], v[136:139], v[144:147], v[56:59]
	v_mfma_f32_16x16x32_bf16 v[44:47], v[128:131], v[168:171], v[44:47]
	v_mfma_f32_16x16x32_bf16 v[40:43], v[136:139], v[168:171], v[40:43]
	v_mfma_f32_16x16x32_bf16 v[28:31], v[128:131], v[176:179], v[28:31]
	v_mfma_f32_16x16x32_bf16 v[24:27], v[136:139], v[176:179], v[24:27]
	v_mfma_f32_16x16x32_bf16 v[12:15], v[128:131], v[192:195], v[12:15]
	v_mfma_f32_16x16x32_bf16 v[8:11], v[136:139], v[192:195], v[8:11]
	v_mfma_f32_16x16x32_bf16 v[60:63], v[132:135], v[148:151], v[60:63]
	v_mfma_f32_16x16x32_bf16 v[56:59], v[140:143], v[148:151], v[56:59]
	v_mfma_f32_16x16x32_bf16 v[44:47], v[132:135], v[172:175], v[44:47]
	v_mfma_f32_16x16x32_bf16 v[40:43], v[140:143], v[172:175], v[40:43]
	v_mfma_f32_16x16x32_bf16 v[28:31], v[132:135], v[180:183], v[28:31]
	v_mfma_f32_16x16x32_bf16 v[24:27], v[140:143], v[180:183], v[24:27]
	v_mfma_f32_16x16x32_bf16 v[12:15], v[132:135], v[196:199], v[12:15]
	v_mfma_f32_16x16x32_bf16 v[8:11], v[140:143], v[196:199], v[8:11]
	s_nop 0
	s_barrier
	s_add_u32 s54, s36, 0x100000
	s_addc_u32 s55, s37, 0
	s_add_i32 s56, s49, s21
	v_lshl_add_u64 v[128:129], s[54:55], 0, v[154:155]
	s_mov_b32 m0, s56
	s_nop 0
	global_load_lds_dwordx4 v[128:129], off
	v_lshl_add_u64 v[128:129], s[54:55], 0, v[158:159]
	s_add_i32 m0, s56, 0x2000
	s_nop 0
	global_load_lds_dwordx4 v[128:129], off
	s_waitcnt vmcnt(6)
	s_barrier
	s_nop 0
	v_mfma_f32_16x16x32_bf16 v[52:55], v[200:203], v[144:147], v[52:55]
	v_mfma_f32_16x16x32_bf16 v[48:51], v[210:213], v[144:147], v[48:51]
	v_mfma_f32_16x16x32_bf16 v[36:39], v[200:203], v[168:171], v[36:39]
	v_mfma_f32_16x16x32_bf16 v[32:35], v[210:213], v[168:171], v[32:35]
	v_mfma_f32_16x16x32_bf16 v[20:23], v[200:203], v[176:179], v[20:23]
	v_mfma_f32_16x16x32_bf16 v[16:19], v[210:213], v[176:179], v[16:19]
	v_mfma_f32_16x16x32_bf16 v[4:7], v[200:203], v[192:195], v[4:7]
	v_mfma_f32_16x16x32_bf16 v[0:3], v[210:213], v[192:195], v[0:3]
	v_mfma_f32_16x16x32_bf16 v[52:55], v[206:209], v[148:151], v[52:55]
	v_mfma_f32_16x16x32_bf16 v[48:51], v[214:217], v[148:151], v[48:51]
	v_mfma_f32_16x16x32_bf16 v[36:39], v[206:209], v[172:175], v[36:39]
	v_mfma_f32_16x16x32_bf16 v[32:35], v[214:217], v[172:175], v[32:35]
	v_mfma_f32_16x16x32_bf16 v[20:23], v[206:209], v[180:183], v[20:23]
	v_mfma_f32_16x16x32_bf16 v[16:19], v[214:217], v[180:183], v[16:19]
	v_mfma_f32_16x16x32_bf16 v[4:7], v[206:209], v[196:199], v[4:7]
	v_mfma_f32_16x16x32_bf16 v[0:3], v[214:217], v[196:199], v[0:3]
	s_nop 0
	s_add_i32 s54, 0, 0x18000
	v_add_u32_e32 v140, s54, v187
	s_barrier
	ds_read_b128 v[128:131], v140
	ds_read_b128 v[132:135], v140 offset:1024
	ds_read_b128 v[136:139], v140 offset:2048
	ds_read_b128 v[140:143], v140 offset:3072
	s_add_u32 s38, s38, 0x100000
	s_addc_u32 s39, s39, 0
	s_mov_b32 m0, s40
	v_lshl_add_u64 v[200:201], s[38:39], 0, v[152:153]
	ds_read_b128 v[144:147], v190 offset:32768
	ds_read_b128 v[148:151], v190 offset:33792
	ds_read_b128 v[168:171], v190 offset:34816
	ds_read_b128 v[172:175], v190 offset:35840
	ds_read_b128 v[176:179], v190 offset:36864
	ds_read_b128 v[180:183], v190 offset:37888
	ds_read_b128 v[192:195], v190 offset:38912
	ds_read_b128 v[196:199], v190 offset:39936
	global_load_lds_dwordx4 v[200:201], off
	v_lshl_add_u64 v[200:201], s[38:39], 0, v[156:157]
	s_mov_b32 m0, s41
	s_nop 0
	global_load_lds_dwordx4 v[200:201], off
	s_waitcnt lgkmcnt(8)
	s_barrier
	s_waitcnt lgkmcnt(0)
	s_nop 0
	s_waitcnt lgkmcnt(0)
	v_mfma_f32_16x16x32_bf16 v[124:127], v[128:131], v[144:147], v[124:127]
	v_mfma_f32_16x16x32_bf16 v[120:123], v[136:139], v[144:147], v[120:123]
	v_mfma_f32_16x16x32_bf16 v[108:111], v[128:131], v[168:171], v[108:111]
	v_mfma_f32_16x16x32_bf16 v[104:107], v[136:139], v[168:171], v[104:107]
	v_mfma_f32_16x16x32_bf16 v[92:95], v[128:131], v[176:179], v[92:95]
	v_mfma_f32_16x16x32_bf16 v[88:91], v[136:139], v[176:179], v[88:91]
	v_mfma_f32_16x16x32_bf16 v[76:79], v[128:131], v[192:195], v[76:79]
	v_mfma_f32_16x16x32_bf16 v[72:75], v[136:139], v[192:195], v[72:75]
	v_mfma_f32_16x16x32_bf16 v[124:127], v[132:135], v[148:151], v[124:127]
	v_mfma_f32_16x16x32_bf16 v[120:123], v[140:143], v[148:151], v[120:123]
	v_mfma_f32_16x16x32_bf16 v[108:111], v[132:135], v[172:175], v[108:111]
	v_mfma_f32_16x16x32_bf16 v[104:107], v[140:143], v[172:175], v[104:107]
	v_mfma_f32_16x16x32_bf16 v[92:95], v[132:135], v[180:183], v[92:95]
	v_mfma_f32_16x16x32_bf16 v[88:91], v[140:143], v[180:183], v[88:91]
	v_mfma_f32_16x16x32_bf16 v[76:79], v[132:135], v[196:199], v[76:79]
	v_mfma_f32_16x16x32_bf16 v[72:75], v[140:143], v[196:199], v[72:75]
	s_nop 0
	s_barrier
	s_add_i32 s38, 0, 0x1c000
	s_add_i32 s39, s54, s21
	v_add_u32_e32 v214, s38, v187
	v_lshl_add_u64 v[184:185], v[184:185], 0, s[14:15]
	s_mov_b32 m0, s39
	ds_read_b128 v[200:203], v214
	ds_read_b128 v[206:209], v214 offset:1024
	ds_read_b128 v[210:213], v214 offset:2048
	ds_read_b128 v[214:217], v214 offset:3072
	global_load_lds_dwordx4 v[184:185], off
	v_lshl_add_u64 v[184:185], v[218:219], 0, s[14:15]
	s_add_i32 m0, s39, 0x2000
	s_nop 0
	global_load_lds_dwordx4 v[184:185], off
	s_barrier
	s_waitcnt lgkmcnt(0)
	s_nop 0
	s_waitcnt lgkmcnt(0)
	v_mfma_f32_16x16x32_bf16 v[116:119], v[200:203], v[144:147], v[116:119]
	v_mfma_f32_16x16x32_bf16 v[112:115], v[210:213], v[144:147], v[112:115]
	v_mfma_f32_16x16x32_bf16 v[100:103], v[200:203], v[168:171], v[100:103]
	v_mfma_f32_16x16x32_bf16 v[96:99], v[210:213], v[168:171], v[96:99]
	v_mfma_f32_16x16x32_bf16 v[84:87], v[200:203], v[176:179], v[84:87]
	v_mfma_f32_16x16x32_bf16 v[80:83], v[210:213], v[176:179], v[80:83]
	v_mfma_f32_16x16x32_bf16 v[68:71], v[200:203], v[192:195], v[68:71]
	v_mfma_f32_16x16x32_bf16 v[64:67], v[210:213], v[192:195], v[64:67]
	v_mfma_f32_16x16x32_bf16 v[116:119], v[206:209], v[148:151], v[116:119]
	v_mfma_f32_16x16x32_bf16 v[112:115], v[214:217], v[148:151], v[112:115]
	v_mfma_f32_16x16x32_bf16 v[100:103], v[206:209], v[172:175], v[100:103]
	v_mfma_f32_16x16x32_bf16 v[96:99], v[214:217], v[172:175], v[96:99]
	v_mfma_f32_16x16x32_bf16 v[84:87], v[206:209], v[180:183], v[84:87]
	v_mfma_f32_16x16x32_bf16 v[80:83], v[214:217], v[180:183], v[80:83]
	v_mfma_f32_16x16x32_bf16 v[68:71], v[206:209], v[196:199], v[68:71]
	v_mfma_f32_16x16x32_bf16 v[64:67], v[214:217], v[196:199], v[64:67]
	s_nop 0
	s_mov_b32 m0, s43
	v_lshl_add_u64 v[184:185], v[220:221], 0, s[14:15]
	s_barrier
	ds_read_b128 v[144:147], v190 offset:49152
	ds_read_b128 v[148:151], v190 offset:50176
	ds_read_b128 v[168:171], v190 offset:51200
	ds_read_b128 v[172:175], v190 offset:52224
	ds_read_b128 v[176:179], v190 offset:53248
	ds_read_b128 v[180:183], v190 offset:54272
	ds_read_b128 v[192:195], v190 offset:55296
	ds_read_b128 v[196:199], v190 offset:56320
	global_load_lds_dwordx4 v[184:185], off
	v_lshl_add_u64 v[184:185], v[222:223], 0, s[14:15]
	s_mov_b32 m0, s44
	s_nop 0
	global_load_lds_dwordx4 v[184:185], off
	s_barrier
	s_waitcnt lgkmcnt(0)
	s_nop 0
	s_waitcnt lgkmcnt(0)
	v_mfma_f32_16x16x32_bf16 v[60:63], v[128:131], v[144:147], v[60:63]
	v_mfma_f32_16x16x32_bf16 v[56:59], v[136:139], v[144:147], v[56:59]
	v_mfma_f32_16x16x32_bf16 v[44:47], v[128:131], v[168:171], v[44:47]
	v_mfma_f32_16x16x32_bf16 v[40:43], v[136:139], v[168:171], v[40:43]
	v_mfma_f32_16x16x32_bf16 v[28:31], v[128:131], v[176:179], v[28:31]
	v_mfma_f32_16x16x32_bf16 v[24:27], v[136:139], v[176:179], v[24:27]
	v_mfma_f32_16x16x32_bf16 v[12:15], v[128:131], v[192:195], v[12:15]
	v_mfma_f32_16x16x32_bf16 v[8:11], v[136:139], v[192:195], v[8:11]
	v_mfma_f32_16x16x32_bf16 v[60:63], v[132:135], v[148:151], v[60:63]
	v_mfma_f32_16x16x32_bf16 v[56:59], v[140:143], v[148:151], v[56:59]
	v_mfma_f32_16x16x32_bf16 v[44:47], v[132:135], v[172:175], v[44:47]
	v_mfma_f32_16x16x32_bf16 v[40:43], v[140:143], v[172:175], v[40:43]
	v_mfma_f32_16x16x32_bf16 v[28:31], v[132:135], v[180:183], v[28:31]
	v_mfma_f32_16x16x32_bf16 v[24:27], v[140:143], v[180:183], v[24:27]
	v_mfma_f32_16x16x32_bf16 v[12:15], v[132:135], v[196:199], v[12:15]
	v_mfma_f32_16x16x32_bf16 v[8:11], v[140:143], v[196:199], v[8:11]
	s_nop 0
	s_barrier
	s_add_u32 s36, s36, 0x100080
	s_addc_u32 s37, s37, 0
	s_add_i32 s38, s38, s21
	v_lshl_add_u64 v[128:129], s[36:37], 0, v[154:155]
	s_mov_b32 m0, s38
	s_nop 0
	global_load_lds_dwordx4 v[128:129], off
	v_lshl_add_u64 v[128:129], s[36:37], 0, v[158:159]
	s_add_i32 m0, s38, 0x2000
	s_nop 0
	global_load_lds_dwordx4 v[128:129], off
	s_waitcnt vmcnt(6)
	s_cmp_eq_u32 s53, 58
	s_cbranch_scc0 .Ler_2056_skip
	s_lshl_b32 s84, s28, 19
	s_lshl_b32 s85, s30, 9
	s_add_u32 s84, s84, s85
	s_add_u32 s84, s10, s84
	s_addc_u32 s85, s11, 0
	v_lshlrev_b32_e32 v236, 11, v186
	v_lshl_add_u32 v236, v188, 1, v236
	global_load_dwordx4 v[224:227], v236, s[84:85]
	global_load_dwordx4 v[228:231], v236, s[84:85] offset:256
	s_add_u32 s86, s84, 0x8000
	s_addc_u32 s87, s85, 0
	global_load_dwordx4 v[232:235], v236, s[86:87]
	global_load_dwordx4 v[240:243], v236, s[86:87] offset:256
	s_add_u32 s86, s84, 0x10000
	s_addc_u32 s87, s85, 0
	global_load_dwordx4 v[244:247], v236, s[86:87]
	global_load_dwordx4 v[248:251], v236, s[86:87] offset:256
	s_add_u32 s86, s84, 0x18000
	s_addc_u32 s87, s85, 0
	global_load_dwordx4 v[252:255], v236, s[86:87]
.Ler_2056_skip:
	s_barrier
	s_nop 0
	v_mfma_f32_16x16x32_bf16 v[52:55], v[200:203], v[144:147], v[52:55]
	v_mfma_f32_16x16x32_bf16 v[48:51], v[210:213], v[144:147], v[48:51]
	v_mfma_f32_16x16x32_bf16 v[36:39], v[200:203], v[168:171], v[36:39]
	v_mfma_f32_16x16x32_bf16 v[32:35], v[210:213], v[168:171], v[32:35]
	v_mfma_f32_16x16x32_bf16 v[20:23], v[200:203], v[176:179], v[20:23]
	v_mfma_f32_16x16x32_bf16 v[16:19], v[210:213], v[176:179], v[16:19]
	v_mfma_f32_16x16x32_bf16 v[4:7], v[200:203], v[192:195], v[4:7]
	v_mfma_f32_16x16x32_bf16 v[0:3], v[210:213], v[192:195], v[0:3]
	v_mfma_f32_16x16x32_bf16 v[52:55], v[206:209], v[148:151], v[52:55]
	v_mfma_f32_16x16x32_bf16 v[48:51], v[214:217], v[148:151], v[48:51]
	v_mfma_f32_16x16x32_bf16 v[36:39], v[206:209], v[172:175], v[36:39]
	v_mfma_f32_16x16x32_bf16 v[32:35], v[214:217], v[172:175], v[32:35]
	v_mfma_f32_16x16x32_bf16 v[20:23], v[206:209], v[180:183], v[20:23]
	v_mfma_f32_16x16x32_bf16 v[16:19], v[214:217], v[180:183], v[16:19]
	v_mfma_f32_16x16x32_bf16 v[4:7], v[206:209], v[196:199], v[4:7]
	v_mfma_f32_16x16x32_bf16 v[0:3], v[214:217], v[196:199], v[0:3]
	s_nop 0
	s_add_i32 s53, s53, 2
	s_add_u32 s34, s34, 0x100
	s_addc_u32 s35, s35, 0
	s_add_u32 s51, s51, 0x100
	s_addc_u32 s52, s52, 0
	s_cmp_gt_u32 s53, 61
	s_barrier
	s_cbranch_scc0 .LBB0_2056
	v_lshl_or_b32 v168, s30, 8, v188
	v_lshl_add_u32 v170, s28, 8, v186
	v_ashrrev_i32_e32 v169, 31, v168
	v_lshlrev_b64 v[202:203], 1, v[168:169]
	v_ashrrev_i32_e32 v171, 31, v170
	v_or_b32_e32 v182, 16, v170
	v_lshl_add_u64 v[172:173], s[10:11], 0, v[202:203]
	v_lshlrev_b64 v[206:207], 11, v[170:171]
	v_ashrrev_i32_e32 v183, 31, v182
	v_or_b32_e32 v178, 32, v170
	v_lshl_add_u64 v[128:129], v[172:173], 0, v[206:207]
	v_lshlrev_b64 v[184:185], 11, v[182:183]
	v_ashrrev_i32_e32 v179, 31, v178
	v_or_b32_e32 v174, 48, v170
	v_mov_b32_e32 v194, v224
	v_mov_b32_e32 v195, v225
	v_mov_b32_e32 v196, v226
	v_mov_b32_e32 v197, v227
	v_mov_b32_e32 v198, v228
	v_mov_b32_e32 v199, v229
	v_mov_b32_e32 v200, v230
	v_mov_b32_e32 v201, v231
	v_lshl_add_u64 v[128:129], v[172:173], 0, v[184:185]
	v_lshlrev_b64 v[180:181], 11, v[178:179]
	v_ashrrev_i32_e32 v175, 31, v174
	v_mov_b32_e32 v148, v232
	v_mov_b32_e32 v149, v233
	v_mov_b32_e32 v150, v234
	v_mov_b32_e32 v151, v235
	v_mov_b32_e32 v144, v240
	v_mov_b32_e32 v145, v241
	v_mov_b32_e32 v146, v242
	v_mov_b32_e32 v147, v243
	v_lshl_add_u64 v[128:129], v[172:173], 0, v[180:181]
	v_lshlrev_b64 v[176:177], 11, v[174:175]
	v_mov_b32_e32 v140, v244
	v_mov_b32_e32 v141, v245
	v_mov_b32_e32 v142, v246
	v_mov_b32_e32 v143, v247
	v_mov_b32_e32 v136, v248
	v_mov_b32_e32 v137, v249
	v_mov_b32_e32 v138, v250
	v_mov_b32_e32 v139, v251
	v_lshl_add_u64 v[128:129], v[172:173], 0, v[176:177]
	v_mov_b32_e32 v132, v252
	v_mov_b32_e32 v133, v253
	v_mov_b32_e32 v134, v254
	v_mov_b32_e32 v135, v255
	s_nop 0
	global_load_dwordx4 v[128:131], v[128:129], off offset:256
	v_and_b32_e32 v193, 64, v205
	v_xor_b32_e32 v192, 16, v205
	v_add_u32_e32 v208, 64, v193
	v_cmp_lt_i32_e32 vcc, v192, v208
	s_nop 1
	v_cndmask_b32_e32 v192, v205, v192, vcc
	v_lshlrev_b32_e32 v193, 2, v192
	v_xor_b32_e32 v192, 32, v205
	v_cmp_lt_i32_e32 vcc, v192, v208
	s_nop 1
	v_cndmask_b32_e32 v192, v205, v192, vcc
	v_lshlrev_b32_e32 v192, 2, v192
	v_add_u32_e32 v236, 0x80, v170
	v_ashrrev_i32_e32 v237, 31, v236
	v_lshlrev_b64 v[236:237], 11, v[236:237]
	v_lshl_add_u64 v[236:237], v[172:173], 0, v[236:237]
	global_load_dwordx4 v[224:227], v[236:237], off
	global_load_dwordx4 v[228:231], v[236:237], off offset:256
	v_add_u32_e32 v236, 0x90, v170
	v_ashrrev_i32_e32 v237, 31, v236
	v_lshlrev_b64 v[236:237], 11, v[236:237]
	v_lshl_add_u64 v[236:237], v[172:173], 0, v[236:237]
	global_load_dwordx4 v[232:235], v[236:237], off
	global_load_dwordx4 v[240:243], v[236:237], off offset:256
	v_add_u32_e32 v236, 0xa0, v170
	v_ashrrev_i32_e32 v237, 31, v236
	v_lshlrev_b64 v[236:237], 11, v[236:237]
	v_lshl_add_u64 v[236:237], v[172:173], 0, v[236:237]
	global_load_dwordx4 v[244:247], v[236:237], off
	global_load_dwordx4 v[248:251], v[236:237], off offset:256
	v_add_u32_e32 v236, 0xb0, v170
	v_ashrrev_i32_e32 v237, 31, v236
	v_lshlrev_b64 v[236:237], 11, v[236:237]
	v_lshl_add_u64 v[236:237], v[172:173], 0, v[236:237]
	global_load_dwordx4 v[252:255], v[236:237], off
	s_waitcnt vmcnt(24)
	v_lshlrev_b32_e32 v208, 16, v194
	v_and_b32_e32 v209, 0xffff0000, v194
	v_lshlrev_b32_e32 v194, 16, v195
	v_and_b32_e32 v195, 0xffff0000, v195
	v_lshlrev_b32_e32 v210, 16, v196
	v_and_b32_e32 v211, 0xffff0000, v196
	v_lshlrev_b32_e32 v196, 16, v197
	v_and_b32_e32 v197, 0xffff0000, v197
	v_pk_add_f32 v[126:127], v[126:127], v[194:195]
	v_pk_add_f32 v[194:195], v[122:123], v[196:197]
	v_pk_add_f32 v[196:197], v[120:121], v[210:211]
	v_pk_add_f32 v[124:125], v[124:125], v[208:209]
	v_cvt_pk_bf16_f32 v122, v196, v197
	v_mul_f32_e32 v196, v196, v196
	v_cvt_pk_bf16_f32 v120, v124, v125
	v_fmac_f32_e32 v196, v124, v124
	v_mul_f32_e32 v124, v197, v197
	v_fmac_f32_e32 v124, v125, v125
	v_mul_f32_e32 v125, v194, v194
	v_add_f32_e32 v124, v196, v124
	v_fmac_f32_e32 v125, v126, v126
	v_add_f32_e32 v124, v125, v124
	v_mul_f32_e32 v125, v195, v195
	v_cvt_pk_bf16_f32 v121, v126, v127
	v_cvt_pk_bf16_f32 v123, v194, v195
	v_fmac_f32_e32 v125, v127, v127
	v_lshlrev_b32_e32 v126, 16, v199
	v_and_b32_e32 v127, 0xffff0000, v199
	v_lshlrev_b32_e32 v194, 16, v200
	v_and_b32_e32 v195, 0xffff0000, v200
	v_add_f32_e32 v208, v125, v124
	v_lshlrev_b32_e32 v124, 16, v198
	v_and_b32_e32 v125, 0xffff0000, v198
	v_pk_add_f32 v[118:119], v[118:119], v[126:127]
	v_pk_add_f32 v[126:127], v[112:113], v[194:195]
	v_pk_add_f32 v[116:117], v[116:117], v[124:125]
	v_mul_f32_e32 v112, v126, v126
	v_lshlrev_b32_e32 v196, 16, v201
	v_and_b32_e32 v197, 0xffff0000, v201
	v_fmac_f32_e32 v112, v116, v116
	v_mul_f32_e32 v113, v127, v127
	v_pk_add_f32 v[124:125], v[114:115], v[196:197]
	v_add_f32_e32 v112, v112, v208
	v_fmac_f32_e32 v113, v117, v117
	v_add_f32_e32 v112, v113, v112
	v_mul_f32_e32 v113, v124, v124
	v_fmac_f32_e32 v113, v118, v118
	v_add_f32_e32 v112, v113, v112
	v_mul_f32_e32 v113, v125, v125
	v_fmac_f32_e32 v113, v119, v119
	v_add_f32_e32 v115, v113, v112
	ds_bpermute_b32 v196, v193, v115
	v_lshl_add_u64 v[112:113], s[10:11], 0, v[206:207]
	v_lshl_add_u64 v[194:195], v[112:113], 0, v[202:203]
	v_cvt_pk_bf16_f32 v114, v116, v117
	v_cvt_pk_bf16_f32 v116, v126, v127
	s_waitcnt lgkmcnt(0)
	v_add_f32_e32 v112, v115, v196
	ds_bpermute_b32 v113, v192, v112
	v_cvt_pk_bf16_f32 v115, v118, v119
	v_cvt_pk_bf16_f32 v117, v124, v125
	global_store_dwordx4 v[194:195], v[120:123], off
	global_store_dwordx4 v[194:195], v[114:117], off offset:256
	s_and_saveexec_b64 s[28:29], s[4:5]
	s_cbranch_execz .LBB0_2059
	s_waitcnt lgkmcnt(0)
	v_add_f32_e32 v112, v112, v113
	v_mul_f32_e32 v112, 0x4b800000, v112
	v_trunc_f32_e32 v112, v112
	v_mul_f32_e32 v113, 0x2f800000, v112
	v_floor_f32_e32 v113, v113
	v_fmac_f32_e32 v112, 0xcf800000, v113
	v_cvt_u32_f32_e32 v112, v112
	v_cvt_u32_f32_e32 v113, v113
	v_lshl_add_u64 v[114:115], v[170:171], 3, s[12:13]
	global_atomic_add_x2 v[114:115], v[112:113], off

.LBB0_2128:
	s_or_b64 exec, exec, s[2:3]
	s_waitcnt lgkmcnt(0)
	s_barrier
	s_setprio 0
	s_mov_b32 s0, 0x8000
	s_waitcnt vmcnt(3)
	v_ashrrev_i32_e32 v0, 6, v204
	v_add_u32_e32 v0, s72, v0
	v_cmp_gt_i32_e32 vcc, s0, v0
	s_and_saveexec_b64 s[0:1], vcc
	s_cbranch_execz .LBB0_2131
	s_load_dwordx4 s[4:7], s[70:71], 0xb0
	s_load_dwordx2 s[2:3], s[70:71], 0x18
	v_lshlrev_b32_e32 v1, 3, v204
	v_and_b32_e32 v1, 0x1f8, v1
	s_waitcnt vmcnt(2)
	v_lshlrev_b32_e32 v6, 1, v1
	s_waitcnt lgkmcnt(0)
	s_add_u32 s0, s6, 0x1ff00000
	v_mov_b32_e32 v7, 0
	s_addc_u32 s1, s7, 0
	v_lshl_add_u64 v[2:3], s[6:7], 0, v[6:7]
	s_mov_b64 s[6:7], 0x3a00000
	v_lshlrev_b32_e32 v6, 2, v1
	v_lshl_add_u64 v[2:3], v[2:3], 0, s[6:7]
	v_lshl_add_u64 v[4:5], s[4:5], 0, v[6:7]
	v_lshl_add_u64 v[6:7], s[2:3], 0, v[6:7]
	s_mov_b64 s[2:3], 0
	v_mov_b32_e32 v8, 0x358637bd
	s_mov_b32 s4, 0x800000
	s_movk_i32 s5, 0x7fff
	s_load_dwordx2 s[12:13], s[70:71], 0xb8
	s_load_dwordx2 s[16:17], s[70:71], 0xb0
	v_readfirstlane_b32 s8, v0
	s_mov_b32 s41, s83
	s_lshl_b32 s42, s83, 1
	s_mul_i32 s43, s83, 3
	s_lshl_b32 s47, s83, 2
	s_mov_b32 s44, 0x8000
	s_nop 3
	s_add_u32 s10, s8, s43
	s_cmp_lt_u32 s10, s44
	s_cbranch_scc0 .Lfn_skip
	v_and_b32_e32 v48, 63, v204
	v_lshlrev_b32_e32 v50, 5, v48
	v_lshlrev_b32_e32 v48, 4, v48
	v_mov_b32_e32 v49, 0
	global_load_dwordx4 v[32:35], v[6:7], off
	global_load_dwordx4 v[36:39], v[6:7], off offset:16
	global_load_dwordx4 v[40:43], v[6:7], off offset:2048
	global_load_dwordx4 v[44:47], v[6:7], off offset:2064
	s_waitcnt lgkmcnt(0)
	s_add_u32 s12, s12, 0x3a00000
	s_addc_u32 s13, s13, 0
	s_mov_b32 s11, s8
	s_lshl_b32 s37, s11, 3
	s_add_u32 s38, s0, s37
	s_addc_u32 s39, s1, 0
	global_load_dwordx2 v[64:65], v49, s[38:39]
	s_lshl_b32 s37, s11, 11
	s_add_u32 s38, s12, s37
	s_addc_u32 s39, s13, 0
	global_load_dwordx4 v[66:69], v48, s[38:39]
	global_load_dwordx4 v[70:73], v48, s[38:39] offset:1024
	s_lshl_b32 s37, s11, 12
	s_add_u32 s20, s16, s37
	s_addc_u32 s21, s17, 0
	s_add_u32 s11, s8, s41
	s_lshl_b32 s37, s11, 3
	s_add_u32 s38, s0, s37
	s_addc_u32 s39, s1, 0
	global_load_dwordx2 v[74:75], v49, s[38:39]
	s_lshl_b32 s37, s11, 11
	s_add_u32 s38, s12, s37
	s_addc_u32 s39, s13, 0
	global_load_dwordx4 v[76:79], v48, s[38:39]
	global_load_dwordx4 v[80:83], v48, s[38:39] offset:1024
	s_lshl_b32 s37, s11, 12
	s_add_u32 s22, s16, s37
	s_addc_u32 s23, s17, 0
	s_add_u32 s11, s8, s42
	s_lshl_b32 s37, s11, 3
	s_add_u32 s38, s0, s37
	s_addc_u32 s39, s1, 0
	global_load_dwordx2 v[84:85], v49, s[38:39]
	s_lshl_b32 s37, s11, 11
	s_add_u32 s38, s12, s37
	s_addc_u32 s39, s13, 0
	global_load_dwordx4 v[86:89], v48, s[38:39]
	global_load_dwordx4 v[90:93], v48, s[38:39] offset:1024
	s_lshl_b32 s37, s11, 12
	s_add_u32 s24, s16, s37
	s_addc_u32 s25, s17, 0
	s_add_u32 s11, s8, s43
	s_lshl_b32 s37, s11, 3
	s_add_u32 s38, s0, s37
	s_addc_u32 s39, s1, 0
	global_load_dwordx2 v[94:95], v49, s[38:39]
	s_lshl_b32 s37, s11, 11
	s_add_u32 s38, s12, s37
	s_addc_u32 s39, s13, 0
	global_load_dwordx4 v[96:99], v48, s[38:39]
	global_load_dwordx4 v[100:103], v48, s[38:39] offset:1024
	s_lshl_b32 s37, s11, 12
	s_add_u32 s26, s16, s37
	s_addc_u32 s27, s17, 0
	s_add_u32 s8, s8, s47
	s_mov_b32 s36, 1
